# v34 recipe + slot-3 B-fragment LDS base kept in v250 (no VALU in front of that slot's ds_reads)
# baseline (speedup 1.0000x reference)
.Lpeel_13:
	v_add_u32_e32 v250, 0x18000, v147
	ds_read_b128 v[152:155], v149
	ds_read_b128 v[156:159], v149 offset:1024
	s_add_i32 s37, s25, 2
	s_add_u32 s40, s38, 0xfff80080
	s_addc_u32 s41, s39, -1
	s_cmp_eq_u32 s36, s25
	s_cselect_b32 s43, s27, s41
	s_cselect_b32 s42, s26, s40
	s_cselect_b32 s41, s29, s23
	s_cselect_b32 s40, s28, s21
	v_lshl_add_u64 v[144:145], s[38:39], 0, v[140:141]
	s_add_i32 m0, s35, 0xc000
	global_load_lds_dwordx4 v[144:145], off
	v_lshl_add_u64 v[144:145], s[38:39], 0, v[142:143]
	s_add_i32 m0, s35, 0xe000
	s_nop 0
	global_load_lds_dwordx4 v[144:145], off
	s_waitcnt vmcnt(8)
	s_waitcnt lgkmcnt(0)
	s_barrier
	s_setprio 1
	s_waitcnt lgkmcnt(0)
	v_mfma_f32_16x16x32_bf16 v[126:129], v[152:155], v[184:187], 0
	v_mfma_f32_16x16x32_bf16 v[122:125], v[160:163], v[184:187], 0
	v_mfma_f32_16x16x32_bf16 v[110:113], v[152:155], v[196:199], 0
	v_mfma_f32_16x16x32_bf16 v[106:109], v[160:163], v[196:199], 0
	v_mfma_f32_16x16x32_bf16 v[94:97], v[152:155], v[204:207], 0
	v_mfma_f32_16x16x32_bf16 v[90:93], v[160:163], v[204:207], 0
	v_mfma_f32_16x16x32_bf16 v[78:81], v[152:155], v[212:215], 0
	v_mfma_f32_16x16x32_bf16 v[74:77], v[160:163], v[212:215], 0
	v_mfma_f32_16x16x32_bf16 v[126:129], v[156:159], v[188:191], v[126:129]
	v_mfma_f32_16x16x32_bf16 v[122:125], v[164:167], v[188:191], v[122:125]
	v_mfma_f32_16x16x32_bf16 v[110:113], v[156:159], v[200:203], v[110:113]
	v_mfma_f32_16x16x32_bf16 v[106:109], v[164:167], v[200:203], v[106:109]
	v_mfma_f32_16x16x32_bf16 v[94:97], v[156:159], v[208:211], v[94:97]
	v_mfma_f32_16x16x32_bf16 v[90:93], v[164:167], v[208:211], v[90:93]
	v_mfma_f32_16x16x32_bf16 v[78:81], v[156:159], v[216:219], v[78:81]
	v_mfma_f32_16x16x32_bf16 v[74:77], v[164:167], v[216:219], v[74:77]
	v_mfma_f32_16x16x32_bf16 v[118:121], v[168:171], v[184:187], 0
	v_mfma_f32_16x16x32_bf16 v[114:117], v[176:179], v[184:187], 0
	v_mfma_f32_16x16x32_bf16 v[102:105], v[168:171], v[196:199], 0
	v_mfma_f32_16x16x32_bf16 v[98:101], v[176:179], v[196:199], 0
	v_mfma_f32_16x16x32_bf16 v[86:89], v[168:171], v[204:207], 0
	v_mfma_f32_16x16x32_bf16 v[82:85], v[176:179], v[204:207], 0
	v_mfma_f32_16x16x32_bf16 v[70:73], v[168:171], v[212:215], 0
	v_mfma_f32_16x16x32_bf16 v[66:69], v[176:179], v[212:215], 0
	v_mfma_f32_16x16x32_bf16 v[118:121], v[172:175], v[188:191], v[118:121]
	v_mfma_f32_16x16x32_bf16 v[114:117], v[180:183], v[188:191], v[114:117]
	v_mfma_f32_16x16x32_bf16 v[102:105], v[172:175], v[200:203], v[102:105]
	v_mfma_f32_16x16x32_bf16 v[98:101], v[180:183], v[200:203], v[98:101]
	v_mfma_f32_16x16x32_bf16 v[86:89], v[172:175], v[208:211], v[86:89]
	v_mfma_f32_16x16x32_bf16 v[82:85], v[180:183], v[208:211], v[82:85]
	v_mfma_f32_16x16x32_bf16 v[70:73], v[172:175], v[216:219], v[70:73]
	s_barrier
	v_mfma_f32_16x16x32_bf16 v[66:69], v[180:183], v[216:219], v[66:69]
	s_setprio 2
	s_add_i32 s25, s54, s33
	v_lshl_add_u64 v[144:145], s[40:41], 0, v[132:133]
	s_mov_b32 m0, s25
	ds_read_b128 v[184:187], v151 offset:16384
	ds_read_b128 v[188:191], v151 offset:17408
	ds_read_b128 v[196:199], v151 offset:18432
	ds_read_b128 v[200:203], v151 offset:19456
	ds_read_b128 v[204:207], v151 offset:20480
	ds_read_b128 v[208:211], v151 offset:21504
	ds_read_b128 v[212:215], v151 offset:22528
	ds_read_b128 v[216:219], v151 offset:23552
	global_load_lds_dwordx4 v[144:145], off
	s_add_i32 m0, s25, 0x2000
	s_add_u32 s44, s40, 0x80000
	v_lshl_add_u64 v[192:193], s[40:41], 0, v[136:137]
	s_addc_u32 s45, s41, 0
	s_add_i32 s25, s55, s33
	global_load_lds_dwordx4 v[192:193], off
	v_lshl_add_u64 v[220:221], s[44:45], 0, v[132:133]
	s_mov_b32 m0, s25
	v_lshl_add_u64 v[222:223], s[42:43], 0, v[134:135]
	global_load_lds_dwordx4 v[220:221], off
	v_lshl_add_u64 v[220:221], s[44:45], 0, v[136:137]
	s_add_i32 m0, s25, 0x2000
	s_nop 0
	global_load_lds_dwordx4 v[220:221], off
	v_lshl_add_u64 v[220:221], s[42:43], 0, v[130:131]
	s_mov_b32 m0, s35
	s_nop 0
	global_load_lds_dwordx4 v[220:221], off
	s_mov_b32 m0, s47
	s_nop 0
	global_load_lds_dwordx4 v[222:223], off
	s_waitcnt vmcnt(8)
	s_waitcnt lgkmcnt(0)
	s_barrier
	s_setprio 1
	s_waitcnt lgkmcnt(0)
	v_mfma_f32_16x16x32_bf16 v[62:65], v[152:155], v[184:187], 0
	v_mfma_f32_16x16x32_bf16 v[58:61], v[160:163], v[184:187], 0
	v_mfma_f32_16x16x32_bf16 v[46:49], v[152:155], v[196:199], 0
	v_mfma_f32_16x16x32_bf16 v[42:45], v[160:163], v[196:199], 0
	v_mfma_f32_16x16x32_bf16 v[30:33], v[152:155], v[204:207], 0
	v_mfma_f32_16x16x32_bf16 v[26:29], v[160:163], v[204:207], 0
	v_mfma_f32_16x16x32_bf16 v[14:17], v[152:155], v[212:215], 0
	v_mfma_f32_16x16x32_bf16 v[10:13], v[160:163], v[212:215], 0
	v_mfma_f32_16x16x32_bf16 v[62:65], v[156:159], v[188:191], v[62:65]
	v_mfma_f32_16x16x32_bf16 v[58:61], v[164:167], v[188:191], v[58:61]
	v_mfma_f32_16x16x32_bf16 v[46:49], v[156:159], v[200:203], v[46:49]
	v_mfma_f32_16x16x32_bf16 v[42:45], v[164:167], v[200:203], v[42:45]
	v_mfma_f32_16x16x32_bf16 v[30:33], v[156:159], v[208:211], v[30:33]
	v_mfma_f32_16x16x32_bf16 v[26:29], v[164:167], v[208:211], v[26:29]
	v_mfma_f32_16x16x32_bf16 v[14:17], v[156:159], v[216:219], v[14:17]
	v_mfma_f32_16x16x32_bf16 v[10:13], v[164:167], v[216:219], v[10:13]
	v_mfma_f32_16x16x32_bf16 v[54:57], v[168:171], v[184:187], 0
	v_mfma_f32_16x16x32_bf16 v[50:53], v[176:179], v[184:187], 0
	v_mfma_f32_16x16x32_bf16 v[38:41], v[168:171], v[196:199], 0
	v_mfma_f32_16x16x32_bf16 v[34:37], v[176:179], v[196:199], 0
	v_mfma_f32_16x16x32_bf16 v[22:25], v[168:171], v[204:207], 0
	v_mfma_f32_16x16x32_bf16 v[18:21], v[176:179], v[204:207], 0
	v_mfma_f32_16x16x32_bf16 v[6:9], v[168:171], v[212:215], 0
	v_mfma_f32_16x16x32_bf16 v[2:5], v[176:179], v[212:215], 0
	v_mfma_f32_16x16x32_bf16 v[54:57], v[172:175], v[188:191], v[54:57]
	v_mfma_f32_16x16x32_bf16 v[50:53], v[180:183], v[188:191], v[50:53]
	v_mfma_f32_16x16x32_bf16 v[38:41], v[172:175], v[200:203], v[38:41]
	v_mfma_f32_16x16x32_bf16 v[34:37], v[180:183], v[200:203], v[34:37]
	v_mfma_f32_16x16x32_bf16 v[22:25], v[172:175], v[208:211], v[22:25]
	v_mfma_f32_16x16x32_bf16 v[18:21], v[180:183], v[208:211], v[18:21]
	v_mfma_f32_16x16x32_bf16 v[6:9], v[172:175], v[216:219], v[6:9]
	s_barrier
	v_mfma_f32_16x16x32_bf16 v[2:5], v[180:183], v[216:219], v[2:5]
	s_setprio 2
	s_add_i32 s25, 0, 0x18000
	s_add_i32 s44, 0, 0x1c000
	ds_read_b128 v[152:155], v250
	ds_read_b128 v[156:159], v250 offset:1024
	ds_read_b128 v[160:163], v250 offset:2048
	ds_read_b128 v[164:167], v250 offset:3072
	ds_read_b128 v[168:171], v250 offset:16384
	ds_read_b128 v[172:175], v250 offset:17408
	ds_read_b128 v[176:179], v250 offset:18432
	ds_read_b128 v[180:183], v250 offset:19456
	s_add_u32 s42, s42, 0x80000
	s_addc_u32 s43, s43, 0
	s_mov_b32 m0, s48
	v_lshl_add_u64 v[224:225], s[42:43], 0, v[130:131]
	ds_read_b128 v[184:187], v151 offset:32768
	ds_read_b128 v[188:191], v151 offset:33792
	ds_read_b128 v[196:199], v151 offset:34816
	ds_read_b128 v[200:203], v151 offset:35840
	ds_read_b128 v[204:207], v151 offset:36864
	ds_read_b128 v[208:211], v151 offset:37888
	ds_read_b128 v[212:215], v151 offset:38912
	ds_read_b128 v[216:219], v151 offset:39936
	global_load_lds_dwordx4 v[224:225], off
	v_lshl_add_u64 v[224:225], s[42:43], 0, v[134:135]
	s_mov_b32 m0, s49
	s_nop 0
	global_load_lds_dwordx4 v[224:225], off
	s_waitcnt vmcnt(8)
	s_waitcnt lgkmcnt(0)
	s_barrier
	s_setprio 1
	s_waitcnt lgkmcnt(0)
	v_mfma_f32_16x16x32_bf16 v[126:129], v[152:155], v[184:187], v[126:129]
	v_mfma_f32_16x16x32_bf16 v[122:125], v[160:163], v[184:187], v[122:125]
	v_mfma_f32_16x16x32_bf16 v[110:113], v[152:155], v[196:199], v[110:113]
	v_mfma_f32_16x16x32_bf16 v[106:109], v[160:163], v[196:199], v[106:109]
	v_mfma_f32_16x16x32_bf16 v[94:97], v[152:155], v[204:207], v[94:97]
	v_mfma_f32_16x16x32_bf16 v[90:93], v[160:163], v[204:207], v[90:93]
	v_mfma_f32_16x16x32_bf16 v[78:81], v[152:155], v[212:215], v[78:81]
	v_mfma_f32_16x16x32_bf16 v[74:77], v[160:163], v[212:215], v[74:77]
	v_mfma_f32_16x16x32_bf16 v[126:129], v[156:159], v[188:191], v[126:129]
	v_mfma_f32_16x16x32_bf16 v[122:125], v[164:167], v[188:191], v[122:125]
	v_mfma_f32_16x16x32_bf16 v[110:113], v[156:159], v[200:203], v[110:113]
	v_mfma_f32_16x16x32_bf16 v[106:109], v[164:167], v[200:203], v[106:109]
	v_mfma_f32_16x16x32_bf16 v[94:97], v[156:159], v[208:211], v[94:97]
	v_mfma_f32_16x16x32_bf16 v[90:93], v[164:167], v[208:211], v[90:93]
	v_mfma_f32_16x16x32_bf16 v[78:81], v[156:159], v[216:219], v[78:81]
	v_mfma_f32_16x16x32_bf16 v[74:77], v[164:167], v[216:219], v[74:77]
	v_mfma_f32_16x16x32_bf16 v[118:121], v[168:171], v[184:187], v[118:121]
	v_mfma_f32_16x16x32_bf16 v[114:117], v[176:179], v[184:187], v[114:117]
	v_mfma_f32_16x16x32_bf16 v[102:105], v[168:171], v[196:199], v[102:105]
	v_mfma_f32_16x16x32_bf16 v[98:101], v[176:179], v[196:199], v[98:101]
	v_mfma_f32_16x16x32_bf16 v[86:89], v[168:171], v[204:207], v[86:89]
	v_mfma_f32_16x16x32_bf16 v[82:85], v[176:179], v[204:207], v[82:85]
	v_mfma_f32_16x16x32_bf16 v[70:73], v[168:171], v[212:215], v[70:73]
	v_mfma_f32_16x16x32_bf16 v[66:69], v[176:179], v[212:215], v[66:69]
	v_mfma_f32_16x16x32_bf16 v[118:121], v[172:175], v[188:191], v[118:121]
	v_mfma_f32_16x16x32_bf16 v[114:117], v[180:183], v[188:191], v[114:117]
	v_mfma_f32_16x16x32_bf16 v[102:105], v[172:175], v[200:203], v[102:105]
	v_mfma_f32_16x16x32_bf16 v[98:101], v[180:183], v[200:203], v[98:101]
	v_mfma_f32_16x16x32_bf16 v[86:89], v[172:175], v[208:211], v[86:89]
	v_mfma_f32_16x16x32_bf16 v[82:85], v[180:183], v[208:211], v[82:85]
	v_mfma_f32_16x16x32_bf16 v[70:73], v[172:175], v[216:219], v[70:73]
	s_barrier
	v_mfma_f32_16x16x32_bf16 v[66:69], v[180:183], v[216:219], v[66:69]
	s_setprio 2
	s_add_i32 s25, s25, s33
	v_lshl_add_u64 v[144:145], v[144:145], 0, s[16:17]
	s_mov_b32 m0, s25
	ds_read_b128 v[184:187], v151 offset:49152
	ds_read_b128 v[188:191], v151 offset:50176
	ds_read_b128 v[196:199], v151 offset:51200
	ds_read_b128 v[200:203], v151 offset:52224
	ds_read_b128 v[204:207], v151 offset:53248
	ds_read_b128 v[208:211], v151 offset:54272
	ds_read_b128 v[212:215], v151 offset:55296
	ds_read_b128 v[216:219], v151 offset:56320
	global_load_lds_dwordx4 v[144:145], off
	s_add_i32 m0, s25, 0x2000
	s_add_u32 s40, s40, 0x80080
	v_lshl_add_u64 v[144:145], v[192:193], 0, s[16:17]
	s_addc_u32 s41, s41, 0
	s_add_i32 s25, s44, s33
	global_load_lds_dwordx4 v[144:145], off
	v_lshl_add_u64 v[144:145], s[40:41], 0, v[132:133]
	s_mov_b32 m0, s25
	s_nop 0
	global_load_lds_dwordx4 v[144:145], off
	v_lshl_add_u64 v[144:145], s[40:41], 0, v[136:137]
	s_add_i32 m0, s25, 0x2000
	s_nop 0
	global_load_lds_dwordx4 v[144:145], off
	v_lshl_add_u64 v[144:145], v[220:221], 0, s[16:17]
	s_mov_b32 m0, s50
	s_nop 0
	global_load_lds_dwordx4 v[144:145], off
	v_lshl_add_u64 v[144:145], v[222:223], 0, s[16:17]
	s_mov_b32 m0, s51
	s_nop 0
	global_load_lds_dwordx4 v[144:145], off
	s_waitcnt vmcnt(8)
	s_waitcnt lgkmcnt(0)
	s_barrier
	s_setprio 1
	s_waitcnt lgkmcnt(0)
	v_mfma_f32_16x16x32_bf16 v[62:65], v[152:155], v[184:187], v[62:65]
	v_mfma_f32_16x16x32_bf16 v[58:61], v[160:163], v[184:187], v[58:61]
	v_mfma_f32_16x16x32_bf16 v[46:49], v[152:155], v[196:199], v[46:49]
	v_mfma_f32_16x16x32_bf16 v[42:45], v[160:163], v[196:199], v[42:45]
	v_mfma_f32_16x16x32_bf16 v[30:33], v[152:155], v[204:207], v[30:33]
	v_mfma_f32_16x16x32_bf16 v[26:29], v[160:163], v[204:207], v[26:29]
	v_mfma_f32_16x16x32_bf16 v[14:17], v[152:155], v[212:215], v[14:17]
	v_mfma_f32_16x16x32_bf16 v[10:13], v[160:163], v[212:215], v[10:13]
	v_mfma_f32_16x16x32_bf16 v[62:65], v[156:159], v[188:191], v[62:65]
	v_mfma_f32_16x16x32_bf16 v[58:61], v[164:167], v[188:191], v[58:61]
	v_mfma_f32_16x16x32_bf16 v[46:49], v[156:159], v[200:203], v[46:49]
	v_mfma_f32_16x16x32_bf16 v[42:45], v[164:167], v[200:203], v[42:45]
	v_mfma_f32_16x16x32_bf16 v[30:33], v[156:159], v[208:211], v[30:33]
	v_mfma_f32_16x16x32_bf16 v[26:29], v[164:167], v[208:211], v[26:29]
	v_mfma_f32_16x16x32_bf16 v[14:17], v[156:159], v[216:219], v[14:17]
	v_mfma_f32_16x16x32_bf16 v[10:13], v[164:167], v[216:219], v[10:13]
	v_mfma_f32_16x16x32_bf16 v[54:57], v[168:171], v[184:187], v[54:57]
	v_mfma_f32_16x16x32_bf16 v[50:53], v[176:179], v[184:187], v[50:53]
	v_mfma_f32_16x16x32_bf16 v[38:41], v[168:171], v[196:199], v[38:41]
	v_mfma_f32_16x16x32_bf16 v[34:37], v[176:179], v[196:199], v[34:37]
	v_mfma_f32_16x16x32_bf16 v[22:25], v[168:171], v[204:207], v[22:25]
	v_mfma_f32_16x16x32_bf16 v[18:21], v[176:179], v[204:207], v[18:21]
	v_mfma_f32_16x16x32_bf16 v[6:9], v[168:171], v[212:215], v[6:9]
	v_mfma_f32_16x16x32_bf16 v[2:5], v[176:179], v[212:215], v[2:5]
	v_mfma_f32_16x16x32_bf16 v[54:57], v[172:175], v[188:191], v[54:57]
	v_mfma_f32_16x16x32_bf16 v[50:53], v[180:183], v[188:191], v[50:53]
	v_mfma_f32_16x16x32_bf16 v[38:41], v[172:175], v[200:203], v[38:41]
	v_mfma_f32_16x16x32_bf16 v[34:37], v[180:183], v[200:203], v[34:37]
	v_mfma_f32_16x16x32_bf16 v[22:25], v[172:175], v[208:211], v[22:25]
	v_mfma_f32_16x16x32_bf16 v[18:21], v[180:183], v[208:211], v[18:21]
	v_mfma_f32_16x16x32_bf16 v[6:9], v[172:175], v[216:219], v[6:9]
	s_barrier
	v_mfma_f32_16x16x32_bf16 v[2:5], v[180:183], v[216:219], v[2:5]
	s_setprio 2
	s_add_u32 s38, s38, 0x100
	s_addc_u32 s39, s39, 0
	s_add_u32 s21, s21, 0x100
	s_addc_u32 s23, s23, 0
	s_cmp_ge_i32 s37, s62
	s_mov_b32 s25, s37
	s_cbranch_scc0 .LBB0_221
	s_branch .Lpeeldone_13
.LBB0_221:
	ds_read_b128 v[152:155], v149
	ds_read_b128 v[156:159], v149 offset:1024
	ds_read_b128 v[160:163], v149 offset:2048
	ds_read_b128 v[164:167], v149 offset:3072
	ds_read_b128 v[168:171], v150
	ds_read_b128 v[172:175], v150 offset:1024
	ds_read_b128 v[176:179], v150 offset:2048
	ds_read_b128 v[180:183], v150 offset:3072
	s_add_i32 s37, s25, 2
	s_add_u32 s40, s38, 0xfff80080
	s_addc_u32 s41, s39, -1
	s_cmp_eq_u32 s36, s25
	s_cselect_b32 s43, s27, s41
	s_cselect_b32 s42, s26, s40
	s_cselect_b32 s41, s29, s23
	s_cselect_b32 s40, s28, s21
	v_lshl_add_u64 v[144:145], s[38:39], 0, v[140:141]
	s_add_i32 m0, s35, 0xc000
	ds_read_b128 v[184:187], v151
	ds_read_b128 v[188:191], v151 offset:1024
	ds_read_b128 v[196:199], v151 offset:2048
	ds_read_b128 v[200:203], v151 offset:3072
	ds_read_b128 v[204:207], v151 offset:4096
	ds_read_b128 v[208:211], v151 offset:5120
	ds_read_b128 v[212:215], v151 offset:6144
	ds_read_b128 v[216:219], v151 offset:7168
	global_load_lds_dwordx4 v[144:145], off
	v_lshl_add_u64 v[144:145], s[38:39], 0, v[142:143]
	s_add_i32 m0, s35, 0xe000
	s_nop 0
	global_load_lds_dwordx4 v[144:145], off
	s_waitcnt vmcnt(8)
	s_waitcnt lgkmcnt(0)
	s_barrier
	s_setprio 1
	s_waitcnt lgkmcnt(0)
	v_mfma_f32_16x16x32_bf16 v[126:129], v[152:155], v[184:187], v[126:129]
	v_mfma_f32_16x16x32_bf16 v[122:125], v[160:163], v[184:187], v[122:125]
	v_mfma_f32_16x16x32_bf16 v[110:113], v[152:155], v[196:199], v[110:113]
	v_mfma_f32_16x16x32_bf16 v[106:109], v[160:163], v[196:199], v[106:109]
	v_mfma_f32_16x16x32_bf16 v[94:97], v[152:155], v[204:207], v[94:97]
	v_mfma_f32_16x16x32_bf16 v[90:93], v[160:163], v[204:207], v[90:93]
	v_mfma_f32_16x16x32_bf16 v[78:81], v[152:155], v[212:215], v[78:81]
	v_mfma_f32_16x16x32_bf16 v[74:77], v[160:163], v[212:215], v[74:77]
	v_mfma_f32_16x16x32_bf16 v[126:129], v[156:159], v[188:191], v[126:129]
	v_mfma_f32_16x16x32_bf16 v[122:125], v[164:167], v[188:191], v[122:125]
	v_mfma_f32_16x16x32_bf16 v[110:113], v[156:159], v[200:203], v[110:113]
	v_mfma_f32_16x16x32_bf16 v[106:109], v[164:167], v[200:203], v[106:109]
	v_mfma_f32_16x16x32_bf16 v[94:97], v[156:159], v[208:211], v[94:97]
	v_mfma_f32_16x16x32_bf16 v[90:93], v[164:167], v[208:211], v[90:93]
	v_mfma_f32_16x16x32_bf16 v[78:81], v[156:159], v[216:219], v[78:81]
	v_mfma_f32_16x16x32_bf16 v[74:77], v[164:167], v[216:219], v[74:77]
	v_mfma_f32_16x16x32_bf16 v[118:121], v[168:171], v[184:187], v[118:121]
	v_mfma_f32_16x16x32_bf16 v[114:117], v[176:179], v[184:187], v[114:117]
	v_mfma_f32_16x16x32_bf16 v[102:105], v[168:171], v[196:199], v[102:105]
	v_mfma_f32_16x16x32_bf16 v[98:101], v[176:179], v[196:199], v[98:101]
	v_mfma_f32_16x16x32_bf16 v[86:89], v[168:171], v[204:207], v[86:89]
	v_mfma_f32_16x16x32_bf16 v[82:85], v[176:179], v[204:207], v[82:85]
	v_mfma_f32_16x16x32_bf16 v[70:73], v[168:171], v[212:215], v[70:73]
	v_mfma_f32_16x16x32_bf16 v[66:69], v[176:179], v[212:215], v[66:69]
	v_mfma_f32_16x16x32_bf16 v[118:121], v[172:175], v[188:191], v[118:121]
	v_mfma_f32_16x16x32_bf16 v[114:117], v[180:183], v[188:191], v[114:117]
	v_mfma_f32_16x16x32_bf16 v[102:105], v[172:175], v[200:203], v[102:105]
	v_mfma_f32_16x16x32_bf16 v[98:101], v[180:183], v[200:203], v[98:101]
	v_mfma_f32_16x16x32_bf16 v[86:89], v[172:175], v[208:211], v[86:89]
	v_mfma_f32_16x16x32_bf16 v[82:85], v[180:183], v[208:211], v[82:85]
	v_mfma_f32_16x16x32_bf16 v[70:73], v[172:175], v[216:219], v[70:73]
	s_barrier
	v_mfma_f32_16x16x32_bf16 v[66:69], v[180:183], v[216:219], v[66:69]
	s_setprio 2
	s_add_i32 s25, s54, s33
	v_lshl_add_u64 v[144:145], s[40:41], 0, v[132:133]
	s_mov_b32 m0, s25
	ds_read_b128 v[184:187], v151 offset:16384
	ds_read_b128 v[188:191], v151 offset:17408
	ds_read_b128 v[196:199], v151 offset:18432
	ds_read_b128 v[200:203], v151 offset:19456
	ds_read_b128 v[204:207], v151 offset:20480
	ds_read_b128 v[208:211], v151 offset:21504
	ds_read_b128 v[212:215], v151 offset:22528
	ds_read_b128 v[216:219], v151 offset:23552
	global_load_lds_dwordx4 v[144:145], off
	s_add_i32 m0, s25, 0x2000
	s_add_u32 s44, s40, 0x80000
	v_lshl_add_u64 v[192:193], s[40:41], 0, v[136:137]
	s_addc_u32 s45, s41, 0
	s_add_i32 s25, s55, s33
	global_load_lds_dwordx4 v[192:193], off
	v_lshl_add_u64 v[220:221], s[44:45], 0, v[132:133]
	s_mov_b32 m0, s25
	v_lshl_add_u64 v[222:223], s[42:43], 0, v[134:135]
	global_load_lds_dwordx4 v[220:221], off
	v_lshl_add_u64 v[220:221], s[44:45], 0, v[136:137]
	s_add_i32 m0, s25, 0x2000
	s_nop 0
	global_load_lds_dwordx4 v[220:221], off
	v_lshl_add_u64 v[220:221], s[42:43], 0, v[130:131]
	s_mov_b32 m0, s35
	s_nop 0
	global_load_lds_dwordx4 v[220:221], off
	s_mov_b32 m0, s47
	s_nop 0
	global_load_lds_dwordx4 v[222:223], off
	s_waitcnt vmcnt(8)
	s_waitcnt lgkmcnt(0)
	s_barrier
	s_setprio 1
	s_waitcnt lgkmcnt(0)
	v_mfma_f32_16x16x32_bf16 v[62:65], v[152:155], v[184:187], v[62:65]
	v_mfma_f32_16x16x32_bf16 v[58:61], v[160:163], v[184:187], v[58:61]
	v_mfma_f32_16x16x32_bf16 v[46:49], v[152:155], v[196:199], v[46:49]
	v_mfma_f32_16x16x32_bf16 v[42:45], v[160:163], v[196:199], v[42:45]
	v_mfma_f32_16x16x32_bf16 v[30:33], v[152:155], v[204:207], v[30:33]
	v_mfma_f32_16x16x32_bf16 v[26:29], v[160:163], v[204:207], v[26:29]
	v_mfma_f32_16x16x32_bf16 v[14:17], v[152:155], v[212:215], v[14:17]
	v_mfma_f32_16x16x32_bf16 v[10:13], v[160:163], v[212:215], v[10:13]
	v_mfma_f32_16x16x32_bf16 v[62:65], v[156:159], v[188:191], v[62:65]
	v_mfma_f32_16x16x32_bf16 v[58:61], v[164:167], v[188:191], v[58:61]
	v_mfma_f32_16x16x32_bf16 v[46:49], v[156:159], v[200:203], v[46:49]
	v_mfma_f32_16x16x32_bf16 v[42:45], v[164:167], v[200:203], v[42:45]
	v_mfma_f32_16x16x32_bf16 v[30:33], v[156:159], v[208:211], v[30:33]
	v_mfma_f32_16x16x32_bf16 v[26:29], v[164:167], v[208:211], v[26:29]
	v_mfma_f32_16x16x32_bf16 v[14:17], v[156:159], v[216:219], v[14:17]
	v_mfma_f32_16x16x32_bf16 v[10:13], v[164:167], v[216:219], v[10:13]
	v_mfma_f32_16x16x32_bf16 v[54:57], v[168:171], v[184:187], v[54:57]
	v_mfma_f32_16x16x32_bf16 v[50:53], v[176:179], v[184:187], v[50:53]
	v_mfma_f32_16x16x32_bf16 v[38:41], v[168:171], v[196:199], v[38:41]
	v_mfma_f32_16x16x32_bf16 v[34:37], v[176:179], v[196:199], v[34:37]
	v_mfma_f32_16x16x32_bf16 v[22:25], v[168:171], v[204:207], v[22:25]
	v_mfma_f32_16x16x32_bf16 v[18:21], v[176:179], v[204:207], v[18:21]
	v_mfma_f32_16x16x32_bf16 v[6:9], v[168:171], v[212:215], v[6:9]
	v_mfma_f32_16x16x32_bf16 v[2:5], v[176:179], v[212:215], v[2:5]
	v_mfma_f32_16x16x32_bf16 v[54:57], v[172:175], v[188:191], v[54:57]
	v_mfma_f32_16x16x32_bf16 v[50:53], v[180:183], v[188:191], v[50:53]
	v_mfma_f32_16x16x32_bf16 v[38:41], v[172:175], v[200:203], v[38:41]
	v_mfma_f32_16x16x32_bf16 v[34:37], v[180:183], v[200:203], v[34:37]
	v_mfma_f32_16x16x32_bf16 v[22:25], v[172:175], v[208:211], v[22:25]
	v_mfma_f32_16x16x32_bf16 v[18:21], v[180:183], v[208:211], v[18:21]
	v_mfma_f32_16x16x32_bf16 v[6:9], v[172:175], v[216:219], v[6:9]
	s_barrier
	v_mfma_f32_16x16x32_bf16 v[2:5], v[180:183], v[216:219], v[2:5]
	s_setprio 2
	s_add_i32 s25, 0, 0x18000
	s_add_i32 s44, 0, 0x1c000
	ds_read_b128 v[152:155], v250
	ds_read_b128 v[156:159], v250 offset:1024
	ds_read_b128 v[160:163], v250 offset:2048
	ds_read_b128 v[164:167], v250 offset:3072
	ds_read_b128 v[168:171], v250 offset:16384
	ds_read_b128 v[172:175], v250 offset:17408
	ds_read_b128 v[176:179], v250 offset:18432
	ds_read_b128 v[180:183], v250 offset:19456
	s_add_u32 s42, s42, 0x80000
	s_addc_u32 s43, s43, 0
	s_mov_b32 m0, s48
	v_lshl_add_u64 v[224:225], s[42:43], 0, v[130:131]
	ds_read_b128 v[184:187], v151 offset:32768
	ds_read_b128 v[188:191], v151 offset:33792
	ds_read_b128 v[196:199], v151 offset:34816
	ds_read_b128 v[200:203], v151 offset:35840
	ds_read_b128 v[204:207], v151 offset:36864
	ds_read_b128 v[208:211], v151 offset:37888
	ds_read_b128 v[212:215], v151 offset:38912
	ds_read_b128 v[216:219], v151 offset:39936
	global_load_lds_dwordx4 v[224:225], off
	v_lshl_add_u64 v[224:225], s[42:43], 0, v[134:135]
	s_mov_b32 m0, s49
	s_nop 0
	global_load_lds_dwordx4 v[224:225], off
	s_waitcnt vmcnt(8)
	s_waitcnt lgkmcnt(0)
	s_barrier
	s_setprio 1
	s_waitcnt lgkmcnt(0)
	v_mfma_f32_16x16x32_bf16 v[126:129], v[152:155], v[184:187], v[126:129]
	v_mfma_f32_16x16x32_bf16 v[122:125], v[160:163], v[184:187], v[122:125]
	v_mfma_f32_16x16x32_bf16 v[110:113], v[152:155], v[196:199], v[110:113]
	v_mfma_f32_16x16x32_bf16 v[106:109], v[160:163], v[196:199], v[106:109]
	v_mfma_f32_16x16x32_bf16 v[94:97], v[152:155], v[204:207], v[94:97]
	v_mfma_f32_16x16x32_bf16 v[90:93], v[160:163], v[204:207], v[90:93]
	v_mfma_f32_16x16x32_bf16 v[78:81], v[152:155], v[212:215], v[78:81]
	v_mfma_f32_16x16x32_bf16 v[74:77], v[160:163], v[212:215], v[74:77]
	v_mfma_f32_16x16x32_bf16 v[126:129], v[156:159], v[188:191], v[126:129]
	v_mfma_f32_16x16x32_bf16 v[122:125], v[164:167], v[188:191], v[122:125]
	v_mfma_f32_16x16x32_bf16 v[110:113], v[156:159], v[200:203], v[110:113]
	v_mfma_f32_16x16x32_bf16 v[106:109], v[164:167], v[200:203], v[106:109]
	v_mfma_f32_16x16x32_bf16 v[94:97], v[156:159], v[208:211], v[94:97]
	v_mfma_f32_16x16x32_bf16 v[90:93], v[164:167], v[208:211], v[90:93]
	v_mfma_f32_16x16x32_bf16 v[78:81], v[156:159], v[216:219], v[78:81]
	v_mfma_f32_16x16x32_bf16 v[74:77], v[164:167], v[216:219], v[74:77]
	v_mfma_f32_16x16x32_bf16 v[118:121], v[168:171], v[184:187], v[118:121]
	v_mfma_f32_16x16x32_bf16 v[114:117], v[176:179], v[184:187], v[114:117]
	v_mfma_f32_16x16x32_bf16 v[102:105], v[168:171], v[196:199], v[102:105]
	v_mfma_f32_16x16x32_bf16 v[98:101], v[176:179], v[196:199], v[98:101]
	v_mfma_f32_16x16x32_bf16 v[86:89], v[168:171], v[204:207], v[86:89]
	v_mfma_f32_16x16x32_bf16 v[82:85], v[176:179], v[204:207], v[82:85]
	v_mfma_f32_16x16x32_bf16 v[70:73], v[168:171], v[212:215], v[70:73]
	v_mfma_f32_16x16x32_bf16 v[66:69], v[176:179], v[212:215], v[66:69]
	v_mfma_f32_16x16x32_bf16 v[118:121], v[172:175], v[188:191], v[118:121]
	v_mfma_f32_16x16x32_bf16 v[114:117], v[180:183], v[188:191], v[114:117]
	v_mfma_f32_16x16x32_bf16 v[102:105], v[172:175], v[200:203], v[102:105]
	v_mfma_f32_16x16x32_bf16 v[98:101], v[180:183], v[200:203], v[98:101]
	v_mfma_f32_16x16x32_bf16 v[86:89], v[172:175], v[208:211], v[86:89]
	v_mfma_f32_16x16x32_bf16 v[82:85], v[180:183], v[208:211], v[82:85]
	v_mfma_f32_16x16x32_bf16 v[70:73], v[172:175], v[216:219], v[70:73]
	s_barrier
	v_mfma_f32_16x16x32_bf16 v[66:69], v[180:183], v[216:219], v[66:69]
	s_setprio 2
	s_add_i32 s25, s25, s33
	v_lshl_add_u64 v[144:145], v[144:145], 0, s[16:17]
	s_mov_b32 m0, s25
	ds_read_b128 v[184:187], v151 offset:49152
	ds_read_b128 v[188:191], v151 offset:50176
	ds_read_b128 v[196:199], v151 offset:51200
	ds_read_b128 v[200:203], v151 offset:52224
	ds_read_b128 v[204:207], v151 offset:53248
	ds_read_b128 v[208:211], v151 offset:54272
	ds_read_b128 v[212:215], v151 offset:55296
	ds_read_b128 v[216:219], v151 offset:56320
	global_load_lds_dwordx4 v[144:145], off
	s_add_i32 m0, s25, 0x2000
	s_add_u32 s40, s40, 0x80080
	v_lshl_add_u64 v[144:145], v[192:193], 0, s[16:17]
	s_addc_u32 s41, s41, 0
	s_add_i32 s25, s44, s33
	global_load_lds_dwordx4 v[144:145], off
	v_lshl_add_u64 v[144:145], s[40:41], 0, v[132:133]
	s_mov_b32 m0, s25
	s_nop 0
	global_load_lds_dwordx4 v[144:145], off
	v_lshl_add_u64 v[144:145], s[40:41], 0, v[136:137]
	s_add_i32 m0, s25, 0x2000
	s_nop 0
	global_load_lds_dwordx4 v[144:145], off
	v_lshl_add_u64 v[144:145], v[220:221], 0, s[16:17]
	s_mov_b32 m0, s50
	s_nop 0
	global_load_lds_dwordx4 v[144:145], off
	v_lshl_add_u64 v[144:145], v[222:223], 0, s[16:17]
	s_mov_b32 m0, s51
	s_nop 0
	global_load_lds_dwordx4 v[144:145], off
	s_waitcnt vmcnt(8)
	s_waitcnt lgkmcnt(0)
	s_barrier
	s_setprio 1
	s_waitcnt lgkmcnt(0)
	v_mfma_f32_16x16x32_bf16 v[62:65], v[152:155], v[184:187], v[62:65]
	v_mfma_f32_16x16x32_bf16 v[58:61], v[160:163], v[184:187], v[58:61]
	v_mfma_f32_16x16x32_bf16 v[46:49], v[152:155], v[196:199], v[46:49]
	v_mfma_f32_16x16x32_bf16 v[42:45], v[160:163], v[196:199], v[42:45]
	v_mfma_f32_16x16x32_bf16 v[30:33], v[152:155], v[204:207], v[30:33]
	v_mfma_f32_16x16x32_bf16 v[26:29], v[160:163], v[204:207], v[26:29]
	v_mfma_f32_16x16x32_bf16 v[14:17], v[152:155], v[212:215], v[14:17]
	v_mfma_f32_16x16x32_bf16 v[10:13], v[160:163], v[212:215], v[10:13]
	v_mfma_f32_16x16x32_bf16 v[62:65], v[156:159], v[188:191], v[62:65]
	v_mfma_f32_16x16x32_bf16 v[58:61], v[164:167], v[188:191], v[58:61]
	v_mfma_f32_16x16x32_bf16 v[46:49], v[156:159], v[200:203], v[46:49]
	v_mfma_f32_16x16x32_bf16 v[42:45], v[164:167], v[200:203], v[42:45]
	v_mfma_f32_16x16x32_bf16 v[30:33], v[156:159], v[208:211], v[30:33]
	v_mfma_f32_16x16x32_bf16 v[26:29], v[164:167], v[208:211], v[26:29]
	v_mfma_f32_16x16x32_bf16 v[14:17], v[156:159], v[216:219], v[14:17]
	v_mfma_f32_16x16x32_bf16 v[10:13], v[164:167], v[216:219], v[10:13]
	v_mfma_f32_16x16x32_bf16 v[54:57], v[168:171], v[184:187], v[54:57]
	v_mfma_f32_16x16x32_bf16 v[50:53], v[176:179], v[184:187], v[50:53]
	v_mfma_f32_16x16x32_bf16 v[38:41], v[168:171], v[196:199], v[38:41]
	v_mfma_f32_16x16x32_bf16 v[34:37], v[176:179], v[196:199], v[34:37]
	v_mfma_f32_16x16x32_bf16 v[22:25], v[168:171], v[204:207], v[22:25]
	v_mfma_f32_16x16x32_bf16 v[18:21], v[176:179], v[204:207], v[18:21]
	v_mfma_f32_16x16x32_bf16 v[6:9], v[168:171], v[212:215], v[6:9]
	v_mfma_f32_16x16x32_bf16 v[2:5], v[176:179], v[212:215], v[2:5]
	v_mfma_f32_16x16x32_bf16 v[54:57], v[172:175], v[188:191], v[54:57]
	v_mfma_f32_16x16x32_bf16 v[50:53], v[180:183], v[188:191], v[50:53]
	v_mfma_f32_16x16x32_bf16 v[38:41], v[172:175], v[200:203], v[38:41]
	v_mfma_f32_16x16x32_bf16 v[34:37], v[180:183], v[200:203], v[34:37]
	v_mfma_f32_16x16x32_bf16 v[22:25], v[172:175], v[208:211], v[22:25]
	v_mfma_f32_16x16x32_bf16 v[18:21], v[180:183], v[208:211], v[18:21]
	v_mfma_f32_16x16x32_bf16 v[6:9], v[172:175], v[216:219], v[6:9]
	s_barrier
	v_mfma_f32_16x16x32_bf16 v[2:5], v[180:183], v[216:219], v[2:5]
	s_setprio 2
	s_add_u32 s38, s38, 0x100
	s_addc_u32 s39, s39, 0
	s_add_u32 s21, s21, 0x100
	s_addc_u32 s23, s23, 0
	s_cmp_ge_i32 s37, s62
	s_mov_b32 s25, s37
	s_cbranch_scc0 .LBB0_221

.Lpeel_12:
	v_add_u32_e32 v250, 0x18000, v213
	ds_read_b128 v[130:133], v215
	ds_read_b128 v[134:137], v215 offset:1024
	ds_read_b128 v[138:141], v215 offset:2048
	ds_read_b128 v[142:145], v215 offset:3072
	ds_read_b128 v[146:149], v216
	ds_read_b128 v[150:153], v216 offset:1024
	ds_read_b128 v[154:157], v216 offset:2048
	ds_read_b128 v[158:161], v216 offset:3072
	s_add_i32 s38, s34, 2
	s_add_u32 s35, s30, 0xffea0080
	s_addc_u32 s36, s31, -1
	s_cmp_eq_u32 s28, s34
	s_cselect_b32 s34, s26, s23
	s_cselect_b32 s37, s25, s36
	s_cselect_b32 s36, s24, s35
	s_cselect_b32 s35, s27, s29
	v_lshl_add_u64 v[192:193], s[30:31], 0, v[188:189]
	s_add_i32 m0, s40, 0xc000
	ds_read_b128 v[162:165], v217
	ds_read_b128 v[166:169], v217 offset:1024
	ds_read_b128 v[170:173], v217 offset:2048
	ds_read_b128 v[174:177], v217 offset:3072
	ds_read_b128 v[196:199], v217 offset:4096
	ds_read_b128 v[200:203], v217 offset:5120
	ds_read_b128 v[204:207], v217 offset:6144
	ds_read_b128 v[208:211], v217 offset:7168
	global_load_lds_dwordx4 v[192:193], off
	v_lshl_add_u64 v[192:193], s[30:31], 0, v[190:191]
	s_add_i32 m0, s40, 0xe000
	s_nop 0
	global_load_lds_dwordx4 v[192:193], off
	s_waitcnt vmcnt(8)
	s_waitcnt lgkmcnt(0)
	s_barrier
	s_setprio 1
	s_waitcnt lgkmcnt(0)
	v_mfma_f32_16x16x32_bf16 v[126:129], v[130:133], v[162:165], 0
	v_mfma_f32_16x16x32_bf16 v[122:125], v[138:141], v[162:165], 0
	v_mfma_f32_16x16x32_bf16 v[118:121], v[130:133], v[170:173], 0
	v_mfma_f32_16x16x32_bf16 v[114:117], v[138:141], v[170:173], 0
	v_mfma_f32_16x16x32_bf16 v[94:97], v[130:133], v[196:199], 0
	v_mfma_f32_16x16x32_bf16 v[90:93], v[138:141], v[196:199], 0
	v_mfma_f32_16x16x32_bf16 v[86:89], v[130:133], v[204:207], 0
	v_mfma_f32_16x16x32_bf16 v[82:85], v[138:141], v[204:207], 0
	v_mfma_f32_16x16x32_bf16 v[126:129], v[134:137], v[166:169], v[126:129]
	v_mfma_f32_16x16x32_bf16 v[122:125], v[142:145], v[166:169], v[122:125]
	v_mfma_f32_16x16x32_bf16 v[118:121], v[134:137], v[174:177], v[118:121]
	v_mfma_f32_16x16x32_bf16 v[114:117], v[142:145], v[174:177], v[114:117]
	v_mfma_f32_16x16x32_bf16 v[94:97], v[134:137], v[200:203], v[94:97]
	v_mfma_f32_16x16x32_bf16 v[90:93], v[142:145], v[200:203], v[90:93]
	v_mfma_f32_16x16x32_bf16 v[86:89], v[134:137], v[208:211], v[86:89]
	v_mfma_f32_16x16x32_bf16 v[82:85], v[142:145], v[208:211], v[82:85]
	v_mfma_f32_16x16x32_bf16 v[110:113], v[146:149], v[162:165], 0
	v_mfma_f32_16x16x32_bf16 v[106:109], v[154:157], v[162:165], 0
	v_mfma_f32_16x16x32_bf16 v[102:105], v[146:149], v[170:173], 0
	v_mfma_f32_16x16x32_bf16 v[98:101], v[154:157], v[170:173], 0
	v_mfma_f32_16x16x32_bf16 v[78:81], v[146:149], v[196:199], 0
	v_mfma_f32_16x16x32_bf16 v[74:77], v[154:157], v[196:199], 0
	v_mfma_f32_16x16x32_bf16 v[70:73], v[146:149], v[204:207], 0
	v_mfma_f32_16x16x32_bf16 v[66:69], v[154:157], v[204:207], 0
	v_mfma_f32_16x16x32_bf16 v[110:113], v[150:153], v[166:169], v[110:113]
	v_mfma_f32_16x16x32_bf16 v[106:109], v[158:161], v[166:169], v[106:109]
	v_mfma_f32_16x16x32_bf16 v[102:105], v[150:153], v[174:177], v[102:105]
	v_mfma_f32_16x16x32_bf16 v[98:101], v[158:161], v[174:177], v[98:101]
	v_mfma_f32_16x16x32_bf16 v[78:81], v[150:153], v[200:203], v[78:81]
	v_mfma_f32_16x16x32_bf16 v[74:77], v[158:161], v[200:203], v[74:77]
	v_mfma_f32_16x16x32_bf16 v[70:73], v[150:153], v[208:211], v[70:73]
	s_barrier
	v_mfma_f32_16x16x32_bf16 v[66:69], v[158:161], v[208:211], v[66:69]
	s_setprio 2
	s_add_i32 s39, s53, s33
	v_lshl_add_u64 v[192:193], s[34:35], 0, v[180:181]
	s_mov_b32 m0, s39
	ds_read_b128 v[162:165], v217 offset:16384
	ds_read_b128 v[166:169], v217 offset:17408
	ds_read_b128 v[170:173], v217 offset:18432
	ds_read_b128 v[174:177], v217 offset:19456
	ds_read_b128 v[196:199], v217 offset:20480
	ds_read_b128 v[200:203], v217 offset:21504
	ds_read_b128 v[204:207], v217 offset:22528
	ds_read_b128 v[208:211], v217 offset:23552
	global_load_lds_dwordx4 v[192:193], off
	s_add_i32 m0, s39, 0x2000
	s_add_u32 s62, s34, 0x160000
	v_lshl_add_u64 v[218:219], s[34:35], 0, v[184:185]
	s_addc_u32 s63, s35, 0
	s_add_i32 s39, s54, s33
	global_load_lds_dwordx4 v[218:219], off
	v_lshl_add_u64 v[220:221], s[62:63], 0, v[180:181]
	s_mov_b32 m0, s39
	v_lshl_add_u64 v[222:223], s[36:37], 0, v[182:183]
	global_load_lds_dwordx4 v[220:221], off
	v_lshl_add_u64 v[220:221], s[62:63], 0, v[184:185]
	s_add_i32 m0, s39, 0x2000
	s_nop 0
	global_load_lds_dwordx4 v[220:221], off
	v_lshl_add_u64 v[220:221], s[36:37], 0, v[178:179]
	s_mov_b32 m0, s40
	s_nop 0
	global_load_lds_dwordx4 v[220:221], off
	s_mov_b32 m0, s41
	s_nop 0
	global_load_lds_dwordx4 v[222:223], off
	s_waitcnt vmcnt(8)
	s_waitcnt lgkmcnt(0)
	s_barrier
	s_setprio 1
	s_waitcnt lgkmcnt(0)
	v_mfma_f32_16x16x32_bf16 v[62:65], v[130:133], v[162:165], 0
	v_mfma_f32_16x16x32_bf16 v[58:61], v[138:141], v[162:165], 0
	v_mfma_f32_16x16x32_bf16 v[54:57], v[130:133], v[170:173], 0
	v_mfma_f32_16x16x32_bf16 v[50:53], v[138:141], v[170:173], 0
	v_mfma_f32_16x16x32_bf16 v[30:33], v[130:133], v[196:199], 0
	v_mfma_f32_16x16x32_bf16 v[26:29], v[138:141], v[196:199], 0
	v_mfma_f32_16x16x32_bf16 v[22:25], v[130:133], v[204:207], 0
	v_mfma_f32_16x16x32_bf16 v[18:21], v[138:141], v[204:207], 0
	v_mfma_f32_16x16x32_bf16 v[62:65], v[134:137], v[166:169], v[62:65]
	v_mfma_f32_16x16x32_bf16 v[58:61], v[142:145], v[166:169], v[58:61]
	v_mfma_f32_16x16x32_bf16 v[54:57], v[134:137], v[174:177], v[54:57]
	v_mfma_f32_16x16x32_bf16 v[50:53], v[142:145], v[174:177], v[50:53]
	v_mfma_f32_16x16x32_bf16 v[30:33], v[134:137], v[200:203], v[30:33]
	v_mfma_f32_16x16x32_bf16 v[26:29], v[142:145], v[200:203], v[26:29]
	v_mfma_f32_16x16x32_bf16 v[22:25], v[134:137], v[208:211], v[22:25]
	v_mfma_f32_16x16x32_bf16 v[18:21], v[142:145], v[208:211], v[18:21]
	v_mfma_f32_16x16x32_bf16 v[46:49], v[146:149], v[162:165], 0
	v_mfma_f32_16x16x32_bf16 v[42:45], v[154:157], v[162:165], 0
	v_mfma_f32_16x16x32_bf16 v[38:41], v[146:149], v[170:173], 0
	v_mfma_f32_16x16x32_bf16 v[34:37], v[154:157], v[170:173], 0
	v_mfma_f32_16x16x32_bf16 v[14:17], v[146:149], v[196:199], 0
	v_mfma_f32_16x16x32_bf16 v[10:13], v[154:157], v[196:199], 0
	v_mfma_f32_16x16x32_bf16 v[6:9], v[146:149], v[204:207], 0
	v_mfma_f32_16x16x32_bf16 v[2:5], v[154:157], v[204:207], 0
	v_mfma_f32_16x16x32_bf16 v[46:49], v[150:153], v[166:169], v[46:49]
	v_mfma_f32_16x16x32_bf16 v[42:45], v[158:161], v[166:169], v[42:45]
	v_mfma_f32_16x16x32_bf16 v[38:41], v[150:153], v[174:177], v[38:41]
	v_mfma_f32_16x16x32_bf16 v[34:37], v[158:161], v[174:177], v[34:37]
	v_mfma_f32_16x16x32_bf16 v[14:17], v[150:153], v[200:203], v[14:17]
	v_mfma_f32_16x16x32_bf16 v[10:13], v[158:161], v[200:203], v[10:13]
	v_mfma_f32_16x16x32_bf16 v[6:9], v[150:153], v[208:211], v[6:9]
	s_barrier
	v_mfma_f32_16x16x32_bf16 v[2:5], v[158:161], v[208:211], v[2:5]
	s_setprio 2
	s_add_i32 s39, 0, 0x18000
	s_add_i32 s62, 0, 0x1c000
	ds_read_b128 v[130:133], v250
	ds_read_b128 v[134:137], v250 offset:1024
	ds_read_b128 v[138:141], v250 offset:2048
	ds_read_b128 v[142:145], v250 offset:3072
	ds_read_b128 v[146:149], v250 offset:16384
	ds_read_b128 v[150:153], v250 offset:17408
	ds_read_b128 v[154:157], v250 offset:18432
	ds_read_b128 v[158:161], v250 offset:19456
	s_add_u32 s36, s36, 0x160000
	s_addc_u32 s37, s37, 0
	s_mov_b32 m0, s42
	v_lshl_add_u64 v[224:225], s[36:37], 0, v[178:179]
	ds_read_b128 v[162:165], v217 offset:32768
	ds_read_b128 v[166:169], v217 offset:33792
	ds_read_b128 v[170:173], v217 offset:34816
	ds_read_b128 v[174:177], v217 offset:35840
	ds_read_b128 v[196:199], v217 offset:36864
	ds_read_b128 v[200:203], v217 offset:37888
	ds_read_b128 v[204:207], v217 offset:38912
	ds_read_b128 v[208:211], v217 offset:39936
	global_load_lds_dwordx4 v[224:225], off
	v_lshl_add_u64 v[224:225], s[36:37], 0, v[182:183]
	s_mov_b32 m0, s43
	s_nop 0
	global_load_lds_dwordx4 v[224:225], off
	s_waitcnt vmcnt(8)
	s_waitcnt lgkmcnt(0)
	s_barrier
	s_setprio 1
	s_waitcnt lgkmcnt(0)
	v_mfma_f32_16x16x32_bf16 v[126:129], v[130:133], v[162:165], v[126:129]
	v_mfma_f32_16x16x32_bf16 v[122:125], v[138:141], v[162:165], v[122:125]
	v_mfma_f32_16x16x32_bf16 v[118:121], v[130:133], v[170:173], v[118:121]
	v_mfma_f32_16x16x32_bf16 v[114:117], v[138:141], v[170:173], v[114:117]
	v_mfma_f32_16x16x32_bf16 v[94:97], v[130:133], v[196:199], v[94:97]
	v_mfma_f32_16x16x32_bf16 v[90:93], v[138:141], v[196:199], v[90:93]
	v_mfma_f32_16x16x32_bf16 v[86:89], v[130:133], v[204:207], v[86:89]
	v_mfma_f32_16x16x32_bf16 v[82:85], v[138:141], v[204:207], v[82:85]
	v_mfma_f32_16x16x32_bf16 v[126:129], v[134:137], v[166:169], v[126:129]
	v_mfma_f32_16x16x32_bf16 v[122:125], v[142:145], v[166:169], v[122:125]
	v_mfma_f32_16x16x32_bf16 v[118:121], v[134:137], v[174:177], v[118:121]
	v_mfma_f32_16x16x32_bf16 v[114:117], v[142:145], v[174:177], v[114:117]
	v_mfma_f32_16x16x32_bf16 v[94:97], v[134:137], v[200:203], v[94:97]
	v_mfma_f32_16x16x32_bf16 v[90:93], v[142:145], v[200:203], v[90:93]
	v_mfma_f32_16x16x32_bf16 v[86:89], v[134:137], v[208:211], v[86:89]
	v_mfma_f32_16x16x32_bf16 v[82:85], v[142:145], v[208:211], v[82:85]
	v_mfma_f32_16x16x32_bf16 v[110:113], v[146:149], v[162:165], v[110:113]
	v_mfma_f32_16x16x32_bf16 v[106:109], v[154:157], v[162:165], v[106:109]
	v_mfma_f32_16x16x32_bf16 v[102:105], v[146:149], v[170:173], v[102:105]
	v_mfma_f32_16x16x32_bf16 v[98:101], v[154:157], v[170:173], v[98:101]
	v_mfma_f32_16x16x32_bf16 v[78:81], v[146:149], v[196:199], v[78:81]
	v_mfma_f32_16x16x32_bf16 v[74:77], v[154:157], v[196:199], v[74:77]
	v_mfma_f32_16x16x32_bf16 v[70:73], v[146:149], v[204:207], v[70:73]
	v_mfma_f32_16x16x32_bf16 v[66:69], v[154:157], v[204:207], v[66:69]
	v_mfma_f32_16x16x32_bf16 v[110:113], v[150:153], v[166:169], v[110:113]
	v_mfma_f32_16x16x32_bf16 v[106:109], v[158:161], v[166:169], v[106:109]
	v_mfma_f32_16x16x32_bf16 v[102:105], v[150:153], v[174:177], v[102:105]
	v_mfma_f32_16x16x32_bf16 v[98:101], v[158:161], v[174:177], v[98:101]
	v_mfma_f32_16x16x32_bf16 v[78:81], v[150:153], v[200:203], v[78:81]
	v_mfma_f32_16x16x32_bf16 v[74:77], v[158:161], v[200:203], v[74:77]
	v_mfma_f32_16x16x32_bf16 v[70:73], v[150:153], v[208:211], v[70:73]
	s_barrier
	v_mfma_f32_16x16x32_bf16 v[66:69], v[158:161], v[208:211], v[66:69]
	s_setprio 2
	s_add_i32 s36, s39, s33
	v_lshl_add_u64 v[192:193], v[192:193], 0, s[18:19]
	s_mov_b32 m0, s36
	ds_read_b128 v[162:165], v217 offset:49152
	ds_read_b128 v[166:169], v217 offset:50176
	ds_read_b128 v[170:173], v217 offset:51200
	ds_read_b128 v[174:177], v217 offset:52224
	ds_read_b128 v[196:199], v217 offset:53248
	ds_read_b128 v[200:203], v217 offset:54272
	ds_read_b128 v[204:207], v217 offset:55296
	ds_read_b128 v[208:211], v217 offset:56320
	global_load_lds_dwordx4 v[192:193], off
	s_add_i32 m0, s36, 0x2000
	s_add_u32 s34, s34, 0x160080
	v_lshl_add_u64 v[192:193], v[218:219], 0, s[18:19]
	s_addc_u32 s35, s35, 0
	s_add_i32 s36, s62, s33
	global_load_lds_dwordx4 v[192:193], off
	v_lshl_add_u64 v[192:193], s[34:35], 0, v[180:181]
	s_mov_b32 m0, s36
	s_nop 0
	global_load_lds_dwordx4 v[192:193], off
	v_lshl_add_u64 v[192:193], s[34:35], 0, v[184:185]
	s_add_i32 m0, s36, 0x2000
	s_nop 0
	global_load_lds_dwordx4 v[192:193], off
	v_lshl_add_u64 v[192:193], v[220:221], 0, s[18:19]
	s_mov_b32 m0, s46
	s_nop 0
	global_load_lds_dwordx4 v[192:193], off
	v_lshl_add_u64 v[192:193], v[222:223], 0, s[18:19]
	s_mov_b32 m0, s47
	s_nop 0
	global_load_lds_dwordx4 v[192:193], off
	s_waitcnt vmcnt(8)
	s_waitcnt lgkmcnt(0)
	s_barrier
	s_setprio 1
	s_waitcnt lgkmcnt(0)
	v_mfma_f32_16x16x32_bf16 v[62:65], v[130:133], v[162:165], v[62:65]
	v_mfma_f32_16x16x32_bf16 v[58:61], v[138:141], v[162:165], v[58:61]
	v_mfma_f32_16x16x32_bf16 v[54:57], v[130:133], v[170:173], v[54:57]
	v_mfma_f32_16x16x32_bf16 v[50:53], v[138:141], v[170:173], v[50:53]
	v_mfma_f32_16x16x32_bf16 v[30:33], v[130:133], v[196:199], v[30:33]
	v_mfma_f32_16x16x32_bf16 v[26:29], v[138:141], v[196:199], v[26:29]
	v_mfma_f32_16x16x32_bf16 v[22:25], v[130:133], v[204:207], v[22:25]
	v_mfma_f32_16x16x32_bf16 v[18:21], v[138:141], v[204:207], v[18:21]
	v_mfma_f32_16x16x32_bf16 v[62:65], v[134:137], v[166:169], v[62:65]
	v_mfma_f32_16x16x32_bf16 v[58:61], v[142:145], v[166:169], v[58:61]
	v_mfma_f32_16x16x32_bf16 v[54:57], v[134:137], v[174:177], v[54:57]
	v_mfma_f32_16x16x32_bf16 v[50:53], v[142:145], v[174:177], v[50:53]
	v_mfma_f32_16x16x32_bf16 v[30:33], v[134:137], v[200:203], v[30:33]
	v_mfma_f32_16x16x32_bf16 v[26:29], v[142:145], v[200:203], v[26:29]
	v_mfma_f32_16x16x32_bf16 v[22:25], v[134:137], v[208:211], v[22:25]
	v_mfma_f32_16x16x32_bf16 v[18:21], v[142:145], v[208:211], v[18:21]
	v_mfma_f32_16x16x32_bf16 v[46:49], v[146:149], v[162:165], v[46:49]
	v_mfma_f32_16x16x32_bf16 v[42:45], v[154:157], v[162:165], v[42:45]
	v_mfma_f32_16x16x32_bf16 v[38:41], v[146:149], v[170:173], v[38:41]
	v_mfma_f32_16x16x32_bf16 v[34:37], v[154:157], v[170:173], v[34:37]
	v_mfma_f32_16x16x32_bf16 v[14:17], v[146:149], v[196:199], v[14:17]
	v_mfma_f32_16x16x32_bf16 v[10:13], v[154:157], v[196:199], v[10:13]
	v_mfma_f32_16x16x32_bf16 v[6:9], v[146:149], v[204:207], v[6:9]
	v_mfma_f32_16x16x32_bf16 v[2:5], v[154:157], v[204:207], v[2:5]
	v_mfma_f32_16x16x32_bf16 v[46:49], v[150:153], v[166:169], v[46:49]
	v_mfma_f32_16x16x32_bf16 v[42:45], v[158:161], v[166:169], v[42:45]
	v_mfma_f32_16x16x32_bf16 v[38:41], v[150:153], v[174:177], v[38:41]
	v_mfma_f32_16x16x32_bf16 v[34:37], v[158:161], v[174:177], v[34:37]
	v_mfma_f32_16x16x32_bf16 v[14:17], v[150:153], v[200:203], v[14:17]
	v_mfma_f32_16x16x32_bf16 v[10:13], v[158:161], v[200:203], v[10:13]
	v_mfma_f32_16x16x32_bf16 v[6:9], v[150:153], v[208:211], v[6:9]
	s_barrier
	v_mfma_f32_16x16x32_bf16 v[2:5], v[158:161], v[208:211], v[2:5]
	s_setprio 2
	s_add_u32 s30, s30, 0x100
	s_addc_u32 s31, s31, 0
	s_add_u32 s23, s23, 0x100
	s_addc_u32 s29, s29, 0
	s_cmp_ge_i32 s38, s61
	s_mov_b32 s34, s38
	s_cbranch_scc0 .LBB0_357
	s_branch .Lpeeldone_12
.LBB0_357:
	ds_read_b128 v[130:133], v215
	ds_read_b128 v[134:137], v215 offset:1024
	ds_read_b128 v[138:141], v215 offset:2048
	ds_read_b128 v[142:145], v215 offset:3072
	ds_read_b128 v[146:149], v216
	ds_read_b128 v[150:153], v216 offset:1024
	ds_read_b128 v[154:157], v216 offset:2048
	ds_read_b128 v[158:161], v216 offset:3072
	s_add_i32 s38, s34, 2
	s_add_u32 s35, s30, 0xffea0080
	s_addc_u32 s36, s31, -1
	s_cmp_eq_u32 s28, s34
	s_cselect_b32 s34, s26, s23
	s_cselect_b32 s37, s25, s36
	s_cselect_b32 s36, s24, s35
	s_cselect_b32 s35, s27, s29
	v_lshl_add_u64 v[192:193], s[30:31], 0, v[188:189]
	s_add_i32 m0, s40, 0xc000
	ds_read_b128 v[162:165], v217
	ds_read_b128 v[166:169], v217 offset:1024
	ds_read_b128 v[170:173], v217 offset:2048
	ds_read_b128 v[174:177], v217 offset:3072
	ds_read_b128 v[196:199], v217 offset:4096
	ds_read_b128 v[200:203], v217 offset:5120
	ds_read_b128 v[204:207], v217 offset:6144
	ds_read_b128 v[208:211], v217 offset:7168
	global_load_lds_dwordx4 v[192:193], off
	v_lshl_add_u64 v[192:193], s[30:31], 0, v[190:191]
	s_add_i32 m0, s40, 0xe000
	s_nop 0
	global_load_lds_dwordx4 v[192:193], off
	s_waitcnt vmcnt(8)
	s_waitcnt lgkmcnt(0)
	s_barrier
	s_setprio 1
	s_waitcnt lgkmcnt(0)
	v_mfma_f32_16x16x32_bf16 v[126:129], v[130:133], v[162:165], v[126:129]
	v_mfma_f32_16x16x32_bf16 v[122:125], v[138:141], v[162:165], v[122:125]
	v_mfma_f32_16x16x32_bf16 v[118:121], v[130:133], v[170:173], v[118:121]
	v_mfma_f32_16x16x32_bf16 v[114:117], v[138:141], v[170:173], v[114:117]
	v_mfma_f32_16x16x32_bf16 v[94:97], v[130:133], v[196:199], v[94:97]
	v_mfma_f32_16x16x32_bf16 v[90:93], v[138:141], v[196:199], v[90:93]
	v_mfma_f32_16x16x32_bf16 v[86:89], v[130:133], v[204:207], v[86:89]
	v_mfma_f32_16x16x32_bf16 v[82:85], v[138:141], v[204:207], v[82:85]
	v_mfma_f32_16x16x32_bf16 v[126:129], v[134:137], v[166:169], v[126:129]
	v_mfma_f32_16x16x32_bf16 v[122:125], v[142:145], v[166:169], v[122:125]
	v_mfma_f32_16x16x32_bf16 v[118:121], v[134:137], v[174:177], v[118:121]
	v_mfma_f32_16x16x32_bf16 v[114:117], v[142:145], v[174:177], v[114:117]
	v_mfma_f32_16x16x32_bf16 v[94:97], v[134:137], v[200:203], v[94:97]
	v_mfma_f32_16x16x32_bf16 v[90:93], v[142:145], v[200:203], v[90:93]
	v_mfma_f32_16x16x32_bf16 v[86:89], v[134:137], v[208:211], v[86:89]
	v_mfma_f32_16x16x32_bf16 v[82:85], v[142:145], v[208:211], v[82:85]
	v_mfma_f32_16x16x32_bf16 v[110:113], v[146:149], v[162:165], v[110:113]
	v_mfma_f32_16x16x32_bf16 v[106:109], v[154:157], v[162:165], v[106:109]
	v_mfma_f32_16x16x32_bf16 v[102:105], v[146:149], v[170:173], v[102:105]
	v_mfma_f32_16x16x32_bf16 v[98:101], v[154:157], v[170:173], v[98:101]
	v_mfma_f32_16x16x32_bf16 v[78:81], v[146:149], v[196:199], v[78:81]
	v_mfma_f32_16x16x32_bf16 v[74:77], v[154:157], v[196:199], v[74:77]
	v_mfma_f32_16x16x32_bf16 v[70:73], v[146:149], v[204:207], v[70:73]
	v_mfma_f32_16x16x32_bf16 v[66:69], v[154:157], v[204:207], v[66:69]
	v_mfma_f32_16x16x32_bf16 v[110:113], v[150:153], v[166:169], v[110:113]
	v_mfma_f32_16x16x32_bf16 v[106:109], v[158:161], v[166:169], v[106:109]
	v_mfma_f32_16x16x32_bf16 v[102:105], v[150:153], v[174:177], v[102:105]
	v_mfma_f32_16x16x32_bf16 v[98:101], v[158:161], v[174:177], v[98:101]
	v_mfma_f32_16x16x32_bf16 v[78:81], v[150:153], v[200:203], v[78:81]
	v_mfma_f32_16x16x32_bf16 v[74:77], v[158:161], v[200:203], v[74:77]
	v_mfma_f32_16x16x32_bf16 v[70:73], v[150:153], v[208:211], v[70:73]
	s_barrier
	v_mfma_f32_16x16x32_bf16 v[66:69], v[158:161], v[208:211], v[66:69]
	s_setprio 2
	s_add_i32 s39, s53, s33
	v_lshl_add_u64 v[192:193], s[34:35], 0, v[180:181]
	s_mov_b32 m0, s39
	ds_read_b128 v[162:165], v217 offset:16384
	ds_read_b128 v[166:169], v217 offset:17408
	ds_read_b128 v[170:173], v217 offset:18432
	ds_read_b128 v[174:177], v217 offset:19456
	ds_read_b128 v[196:199], v217 offset:20480
	ds_read_b128 v[200:203], v217 offset:21504
	ds_read_b128 v[204:207], v217 offset:22528
	ds_read_b128 v[208:211], v217 offset:23552
	global_load_lds_dwordx4 v[192:193], off
	s_add_i32 m0, s39, 0x2000
	s_add_u32 s62, s34, 0x160000
	v_lshl_add_u64 v[218:219], s[34:35], 0, v[184:185]
	s_addc_u32 s63, s35, 0
	s_add_i32 s39, s54, s33
	global_load_lds_dwordx4 v[218:219], off
	v_lshl_add_u64 v[220:221], s[62:63], 0, v[180:181]
	s_mov_b32 m0, s39
	v_lshl_add_u64 v[222:223], s[36:37], 0, v[182:183]
	global_load_lds_dwordx4 v[220:221], off
	v_lshl_add_u64 v[220:221], s[62:63], 0, v[184:185]
	s_add_i32 m0, s39, 0x2000
	s_nop 0
	global_load_lds_dwordx4 v[220:221], off
	v_lshl_add_u64 v[220:221], s[36:37], 0, v[178:179]
	s_mov_b32 m0, s40
	s_nop 0
	global_load_lds_dwordx4 v[220:221], off
	s_mov_b32 m0, s41
	s_nop 0
	global_load_lds_dwordx4 v[222:223], off
	s_waitcnt vmcnt(8)
	s_waitcnt lgkmcnt(0)
	s_barrier
	s_setprio 1
	s_waitcnt lgkmcnt(0)
	v_mfma_f32_16x16x32_bf16 v[62:65], v[130:133], v[162:165], v[62:65]
	v_mfma_f32_16x16x32_bf16 v[58:61], v[138:141], v[162:165], v[58:61]
	v_mfma_f32_16x16x32_bf16 v[54:57], v[130:133], v[170:173], v[54:57]
	v_mfma_f32_16x16x32_bf16 v[50:53], v[138:141], v[170:173], v[50:53]
	v_mfma_f32_16x16x32_bf16 v[30:33], v[130:133], v[196:199], v[30:33]
	v_mfma_f32_16x16x32_bf16 v[26:29], v[138:141], v[196:199], v[26:29]
	v_mfma_f32_16x16x32_bf16 v[22:25], v[130:133], v[204:207], v[22:25]
	v_mfma_f32_16x16x32_bf16 v[18:21], v[138:141], v[204:207], v[18:21]
	v_mfma_f32_16x16x32_bf16 v[62:65], v[134:137], v[166:169], v[62:65]
	v_mfma_f32_16x16x32_bf16 v[58:61], v[142:145], v[166:169], v[58:61]
	v_mfma_f32_16x16x32_bf16 v[54:57], v[134:137], v[174:177], v[54:57]
	v_mfma_f32_16x16x32_bf16 v[50:53], v[142:145], v[174:177], v[50:53]
	v_mfma_f32_16x16x32_bf16 v[30:33], v[134:137], v[200:203], v[30:33]
	v_mfma_f32_16x16x32_bf16 v[26:29], v[142:145], v[200:203], v[26:29]
	v_mfma_f32_16x16x32_bf16 v[22:25], v[134:137], v[208:211], v[22:25]
	v_mfma_f32_16x16x32_bf16 v[18:21], v[142:145], v[208:211], v[18:21]
	v_mfma_f32_16x16x32_bf16 v[46:49], v[146:149], v[162:165], v[46:49]
	v_mfma_f32_16x16x32_bf16 v[42:45], v[154:157], v[162:165], v[42:45]
	v_mfma_f32_16x16x32_bf16 v[38:41], v[146:149], v[170:173], v[38:41]
	v_mfma_f32_16x16x32_bf16 v[34:37], v[154:157], v[170:173], v[34:37]
	v_mfma_f32_16x16x32_bf16 v[14:17], v[146:149], v[196:199], v[14:17]
	v_mfma_f32_16x16x32_bf16 v[10:13], v[154:157], v[196:199], v[10:13]
	v_mfma_f32_16x16x32_bf16 v[6:9], v[146:149], v[204:207], v[6:9]
	v_mfma_f32_16x16x32_bf16 v[2:5], v[154:157], v[204:207], v[2:5]
	v_mfma_f32_16x16x32_bf16 v[46:49], v[150:153], v[166:169], v[46:49]
	v_mfma_f32_16x16x32_bf16 v[42:45], v[158:161], v[166:169], v[42:45]
	v_mfma_f32_16x16x32_bf16 v[38:41], v[150:153], v[174:177], v[38:41]
	v_mfma_f32_16x16x32_bf16 v[34:37], v[158:161], v[174:177], v[34:37]
	v_mfma_f32_16x16x32_bf16 v[14:17], v[150:153], v[200:203], v[14:17]
	v_mfma_f32_16x16x32_bf16 v[10:13], v[158:161], v[200:203], v[10:13]
	v_mfma_f32_16x16x32_bf16 v[6:9], v[150:153], v[208:211], v[6:9]
	s_barrier
	v_mfma_f32_16x16x32_bf16 v[2:5], v[158:161], v[208:211], v[2:5]
	s_setprio 2
	s_add_i32 s39, 0, 0x18000
	s_add_i32 s62, 0, 0x1c000
	ds_read_b128 v[130:133], v250
	ds_read_b128 v[134:137], v250 offset:1024
	ds_read_b128 v[138:141], v250 offset:2048
	ds_read_b128 v[142:145], v250 offset:3072
	ds_read_b128 v[146:149], v250 offset:16384
	ds_read_b128 v[150:153], v250 offset:17408
	ds_read_b128 v[154:157], v250 offset:18432
	ds_read_b128 v[158:161], v250 offset:19456
	s_add_u32 s36, s36, 0x160000
	s_addc_u32 s37, s37, 0
	s_mov_b32 m0, s42
	v_lshl_add_u64 v[224:225], s[36:37], 0, v[178:179]
	ds_read_b128 v[162:165], v217 offset:32768
	ds_read_b128 v[166:169], v217 offset:33792
	ds_read_b128 v[170:173], v217 offset:34816
	ds_read_b128 v[174:177], v217 offset:35840
	ds_read_b128 v[196:199], v217 offset:36864
	ds_read_b128 v[200:203], v217 offset:37888
	ds_read_b128 v[204:207], v217 offset:38912
	ds_read_b128 v[208:211], v217 offset:39936
	global_load_lds_dwordx4 v[224:225], off
	v_lshl_add_u64 v[224:225], s[36:37], 0, v[182:183]
	s_mov_b32 m0, s43
	s_nop 0
	global_load_lds_dwordx4 v[224:225], off
	s_waitcnt vmcnt(8)
	s_waitcnt lgkmcnt(0)
	s_barrier
	s_setprio 1
	s_waitcnt lgkmcnt(0)
	v_mfma_f32_16x16x32_bf16 v[126:129], v[130:133], v[162:165], v[126:129]
	v_mfma_f32_16x16x32_bf16 v[122:125], v[138:141], v[162:165], v[122:125]
	v_mfma_f32_16x16x32_bf16 v[118:121], v[130:133], v[170:173], v[118:121]
	v_mfma_f32_16x16x32_bf16 v[114:117], v[138:141], v[170:173], v[114:117]
	v_mfma_f32_16x16x32_bf16 v[94:97], v[130:133], v[196:199], v[94:97]
	v_mfma_f32_16x16x32_bf16 v[90:93], v[138:141], v[196:199], v[90:93]
	v_mfma_f32_16x16x32_bf16 v[86:89], v[130:133], v[204:207], v[86:89]
	v_mfma_f32_16x16x32_bf16 v[82:85], v[138:141], v[204:207], v[82:85]
	v_mfma_f32_16x16x32_bf16 v[126:129], v[134:137], v[166:169], v[126:129]
	v_mfma_f32_16x16x32_bf16 v[122:125], v[142:145], v[166:169], v[122:125]
	v_mfma_f32_16x16x32_bf16 v[118:121], v[134:137], v[174:177], v[118:121]
	v_mfma_f32_16x16x32_bf16 v[114:117], v[142:145], v[174:177], v[114:117]
	v_mfma_f32_16x16x32_bf16 v[94:97], v[134:137], v[200:203], v[94:97]
	v_mfma_f32_16x16x32_bf16 v[90:93], v[142:145], v[200:203], v[90:93]
	v_mfma_f32_16x16x32_bf16 v[86:89], v[134:137], v[208:211], v[86:89]
	v_mfma_f32_16x16x32_bf16 v[82:85], v[142:145], v[208:211], v[82:85]
	v_mfma_f32_16x16x32_bf16 v[110:113], v[146:149], v[162:165], v[110:113]
	v_mfma_f32_16x16x32_bf16 v[106:109], v[154:157], v[162:165], v[106:109]
	v_mfma_f32_16x16x32_bf16 v[102:105], v[146:149], v[170:173], v[102:105]
	v_mfma_f32_16x16x32_bf16 v[98:101], v[154:157], v[170:173], v[98:101]
	v_mfma_f32_16x16x32_bf16 v[78:81], v[146:149], v[196:199], v[78:81]
	v_mfma_f32_16x16x32_bf16 v[74:77], v[154:157], v[196:199], v[74:77]
	v_mfma_f32_16x16x32_bf16 v[70:73], v[146:149], v[204:207], v[70:73]
	v_mfma_f32_16x16x32_bf16 v[66:69], v[154:157], v[204:207], v[66:69]
	v_mfma_f32_16x16x32_bf16 v[110:113], v[150:153], v[166:169], v[110:113]
	v_mfma_f32_16x16x32_bf16 v[106:109], v[158:161], v[166:169], v[106:109]
	v_mfma_f32_16x16x32_bf16 v[102:105], v[150:153], v[174:177], v[102:105]
	v_mfma_f32_16x16x32_bf16 v[98:101], v[158:161], v[174:177], v[98:101]
	v_mfma_f32_16x16x32_bf16 v[78:81], v[150:153], v[200:203], v[78:81]
	v_mfma_f32_16x16x32_bf16 v[74:77], v[158:161], v[200:203], v[74:77]
	v_mfma_f32_16x16x32_bf16 v[70:73], v[150:153], v[208:211], v[70:73]
	s_barrier
	v_mfma_f32_16x16x32_bf16 v[66:69], v[158:161], v[208:211], v[66:69]
	s_setprio 2
	s_add_i32 s36, s39, s33
	v_lshl_add_u64 v[192:193], v[192:193], 0, s[18:19]
	s_mov_b32 m0, s36
	ds_read_b128 v[162:165], v217 offset:49152
	ds_read_b128 v[166:169], v217 offset:50176
	ds_read_b128 v[170:173], v217 offset:51200
	ds_read_b128 v[174:177], v217 offset:52224
	ds_read_b128 v[196:199], v217 offset:53248
	ds_read_b128 v[200:203], v217 offset:54272
	ds_read_b128 v[204:207], v217 offset:55296
	ds_read_b128 v[208:211], v217 offset:56320
	global_load_lds_dwordx4 v[192:193], off
	s_add_i32 m0, s36, 0x2000
	s_add_u32 s34, s34, 0x160080
	v_lshl_add_u64 v[192:193], v[218:219], 0, s[18:19]
	s_addc_u32 s35, s35, 0
	s_add_i32 s36, s62, s33
	global_load_lds_dwordx4 v[192:193], off
	v_lshl_add_u64 v[192:193], s[34:35], 0, v[180:181]
	s_mov_b32 m0, s36
	s_nop 0
	global_load_lds_dwordx4 v[192:193], off
	v_lshl_add_u64 v[192:193], s[34:35], 0, v[184:185]
	s_add_i32 m0, s36, 0x2000
	s_nop 0
	global_load_lds_dwordx4 v[192:193], off
	v_lshl_add_u64 v[192:193], v[220:221], 0, s[18:19]
	s_mov_b32 m0, s46
	s_nop 0
	global_load_lds_dwordx4 v[192:193], off
	v_lshl_add_u64 v[192:193], v[222:223], 0, s[18:19]
	s_mov_b32 m0, s47
	s_nop 0
	global_load_lds_dwordx4 v[192:193], off
	s_waitcnt vmcnt(8)
	s_waitcnt lgkmcnt(0)
	s_barrier
	s_setprio 1
	s_waitcnt lgkmcnt(0)
	v_mfma_f32_16x16x32_bf16 v[62:65], v[130:133], v[162:165], v[62:65]
	v_mfma_f32_16x16x32_bf16 v[58:61], v[138:141], v[162:165], v[58:61]
	v_mfma_f32_16x16x32_bf16 v[54:57], v[130:133], v[170:173], v[54:57]
	v_mfma_f32_16x16x32_bf16 v[50:53], v[138:141], v[170:173], v[50:53]
	v_mfma_f32_16x16x32_bf16 v[30:33], v[130:133], v[196:199], v[30:33]
	v_mfma_f32_16x16x32_bf16 v[26:29], v[138:141], v[196:199], v[26:29]
	v_mfma_f32_16x16x32_bf16 v[22:25], v[130:133], v[204:207], v[22:25]
	v_mfma_f32_16x16x32_bf16 v[18:21], v[138:141], v[204:207], v[18:21]
	v_mfma_f32_16x16x32_bf16 v[62:65], v[134:137], v[166:169], v[62:65]
	v_mfma_f32_16x16x32_bf16 v[58:61], v[142:145], v[166:169], v[58:61]
	v_mfma_f32_16x16x32_bf16 v[54:57], v[134:137], v[174:177], v[54:57]
	v_mfma_f32_16x16x32_bf16 v[50:53], v[142:145], v[174:177], v[50:53]
	v_mfma_f32_16x16x32_bf16 v[30:33], v[134:137], v[200:203], v[30:33]
	v_mfma_f32_16x16x32_bf16 v[26:29], v[142:145], v[200:203], v[26:29]
	v_mfma_f32_16x16x32_bf16 v[22:25], v[134:137], v[208:211], v[22:25]
	v_mfma_f32_16x16x32_bf16 v[18:21], v[142:145], v[208:211], v[18:21]
	v_mfma_f32_16x16x32_bf16 v[46:49], v[146:149], v[162:165], v[46:49]
	v_mfma_f32_16x16x32_bf16 v[42:45], v[154:157], v[162:165], v[42:45]
	v_mfma_f32_16x16x32_bf16 v[38:41], v[146:149], v[170:173], v[38:41]
	v_mfma_f32_16x16x32_bf16 v[34:37], v[154:157], v[170:173], v[34:37]
	v_mfma_f32_16x16x32_bf16 v[14:17], v[146:149], v[196:199], v[14:17]
	v_mfma_f32_16x16x32_bf16 v[10:13], v[154:157], v[196:199], v[10:13]
	v_mfma_f32_16x16x32_bf16 v[6:9], v[146:149], v[204:207], v[6:9]
	v_mfma_f32_16x16x32_bf16 v[2:5], v[154:157], v[204:207], v[2:5]
	v_mfma_f32_16x16x32_bf16 v[46:49], v[150:153], v[166:169], v[46:49]
	v_mfma_f32_16x16x32_bf16 v[42:45], v[158:161], v[166:169], v[42:45]
	v_mfma_f32_16x16x32_bf16 v[38:41], v[150:153], v[174:177], v[38:41]
	v_mfma_f32_16x16x32_bf16 v[34:37], v[158:161], v[174:177], v[34:37]
	v_mfma_f32_16x16x32_bf16 v[14:17], v[150:153], v[200:203], v[14:17]
	v_mfma_f32_16x16x32_bf16 v[10:13], v[158:161], v[200:203], v[10:13]
	v_mfma_f32_16x16x32_bf16 v[6:9], v[150:153], v[208:211], v[6:9]
	s_barrier
	v_mfma_f32_16x16x32_bf16 v[2:5], v[158:161], v[208:211], v[2:5]
	s_setprio 2
	s_add_u32 s30, s30, 0x100
	s_addc_u32 s31, s31, 0
	s_add_u32 s23, s23, 0x100
	s_addc_u32 s29, s29, 0
	s_cmp_ge_i32 s38, s61
	s_mov_b32 s34, s38
	s_cbranch_scc0 .LBB0_357

.Lpeel_11:
	v_add_u32_e32 v250, 0x18000, v143
	ds_read_b128 v[148:151], v145
	ds_read_b128 v[152:155], v145 offset:1024
	s_add_u32 s36, s34, 0xfff80080
	s_addc_u32 s37, s35, -1
	s_cmp_eq_u32 s58, 28
	s_cselect_b32 s39, s21, s37
	s_cselect_b32 s38, s54, s36
	s_cselect_b32 s37, s23, s57
	s_cselect_b32 s36, s55, s56
	v_lshl_add_u64 v[192:193], s[34:35], 0, v[138:139]
	s_add_i32 m0, s27, 0xc000
	global_load_lds_dwordx4 v[192:193], off
	v_lshl_add_u64 v[192:193], s[34:35], 0, v[140:141]
	s_add_i32 m0, s27, 0xe000
	s_nop 0
	global_load_lds_dwordx4 v[192:193], off
	s_waitcnt vmcnt(8)
	s_waitcnt lgkmcnt(0)
	s_barrier
	s_setprio 1
	s_waitcnt lgkmcnt(0)
	v_mfma_f32_16x16x32_bf16 v[126:129], v[148:151], v[180:183], 0
	v_mfma_f32_16x16x32_bf16 v[122:125], v[156:159], v[180:183], 0
	v_mfma_f32_16x16x32_bf16 v[118:121], v[148:151], v[188:191], 0
	v_mfma_f32_16x16x32_bf16 v[114:117], v[156:159], v[188:191], 0
	v_mfma_f32_16x16x32_bf16 v[102:105], v[148:151], v[200:203], 0
	v_mfma_f32_16x16x32_bf16 v[98:101], v[156:159], v[200:203], 0
	v_mfma_f32_16x16x32_bf16 v[86:89], v[148:151], v[208:211], 0
	v_mfma_f32_16x16x32_bf16 v[82:85], v[156:159], v[208:211], 0
	v_mfma_f32_16x16x32_bf16 v[126:129], v[152:155], v[184:187], v[126:129]
	v_mfma_f32_16x16x32_bf16 v[122:125], v[160:163], v[184:187], v[122:125]
	v_mfma_f32_16x16x32_bf16 v[118:121], v[152:155], v[196:199], v[118:121]
	v_mfma_f32_16x16x32_bf16 v[114:117], v[160:163], v[196:199], v[114:117]
	v_mfma_f32_16x16x32_bf16 v[102:105], v[152:155], v[204:207], v[102:105]
	v_mfma_f32_16x16x32_bf16 v[98:101], v[160:163], v[204:207], v[98:101]
	v_mfma_f32_16x16x32_bf16 v[86:89], v[152:155], v[212:215], v[86:89]
	v_mfma_f32_16x16x32_bf16 v[82:85], v[160:163], v[212:215], v[82:85]
	v_mfma_f32_16x16x32_bf16 v[110:113], v[164:167], v[180:183], 0
	v_mfma_f32_16x16x32_bf16 v[106:109], v[172:175], v[180:183], 0
	v_mfma_f32_16x16x32_bf16 v[94:97], v[164:167], v[188:191], 0
	v_mfma_f32_16x16x32_bf16 v[90:93], v[172:175], v[188:191], 0
	v_mfma_f32_16x16x32_bf16 v[78:81], v[164:167], v[200:203], 0
	v_mfma_f32_16x16x32_bf16 v[74:77], v[172:175], v[200:203], 0
	v_mfma_f32_16x16x32_bf16 v[70:73], v[164:167], v[208:211], 0
	v_mfma_f32_16x16x32_bf16 v[66:69], v[172:175], v[208:211], 0
	v_mfma_f32_16x16x32_bf16 v[110:113], v[168:171], v[184:187], v[110:113]
	v_mfma_f32_16x16x32_bf16 v[106:109], v[176:179], v[184:187], v[106:109]
	v_mfma_f32_16x16x32_bf16 v[94:97], v[168:171], v[196:199], v[94:97]
	v_mfma_f32_16x16x32_bf16 v[90:93], v[176:179], v[196:199], v[90:93]
	v_mfma_f32_16x16x32_bf16 v[78:81], v[168:171], v[204:207], v[78:81]
	v_mfma_f32_16x16x32_bf16 v[74:77], v[176:179], v[204:207], v[74:77]
	v_mfma_f32_16x16x32_bf16 v[70:73], v[168:171], v[212:215], v[70:73]
	s_barrier
	v_mfma_f32_16x16x32_bf16 v[66:69], v[176:179], v[212:215], v[66:69]
	s_setprio 2
	s_add_i32 s59, s47, s33
	v_lshl_add_u64 v[192:193], s[36:37], 0, v[134:135]
	s_mov_b32 m0, s59
	ds_read_b128 v[180:183], v147 offset:16384
	ds_read_b128 v[184:187], v147 offset:17408
	ds_read_b128 v[188:191], v147 offset:18432
	ds_read_b128 v[196:199], v147 offset:19456
	ds_read_b128 v[200:203], v147 offset:20480
	ds_read_b128 v[204:207], v147 offset:21504
	ds_read_b128 v[208:211], v147 offset:22528
	ds_read_b128 v[212:215], v147 offset:23552
	global_load_lds_dwordx4 v[192:193], off
	s_add_i32 m0, s59, 0x2000
	s_add_u32 s60, s36, 0x80000
	v_lshl_add_u64 v[216:217], s[36:37], 0, v[130:131]
	s_addc_u32 s61, s37, 0
	s_add_i32 s59, s48, s33
	global_load_lds_dwordx4 v[216:217], off
	v_lshl_add_u64 v[218:219], s[60:61], 0, v[134:135]
	s_mov_b32 m0, s59
	v_lshl_add_u64 v[220:221], s[38:39], 0, v[132:133]
	global_load_lds_dwordx4 v[218:219], off
	v_lshl_add_u64 v[218:219], s[60:61], 0, v[130:131]
	s_add_i32 m0, s59, 0x2000
	s_nop 0
	global_load_lds_dwordx4 v[218:219], off
	v_lshl_add_u64 v[218:219], s[38:39], 0, v[136:137]
	s_mov_b32 m0, s27
	s_nop 0
	global_load_lds_dwordx4 v[218:219], off
	s_mov_b32 m0, s41
	s_nop 0
	global_load_lds_dwordx4 v[220:221], off
	s_waitcnt vmcnt(8)
	s_waitcnt lgkmcnt(0)
	s_barrier
	s_setprio 1
	s_waitcnt lgkmcnt(0)
	v_mfma_f32_16x16x32_bf16 v[62:65], v[148:151], v[180:183], 0
	v_mfma_f32_16x16x32_bf16 v[58:61], v[156:159], v[180:183], 0
	v_mfma_f32_16x16x32_bf16 v[54:57], v[148:151], v[188:191], 0
	v_mfma_f32_16x16x32_bf16 v[50:53], v[156:159], v[188:191], 0
	v_mfma_f32_16x16x32_bf16 v[38:41], v[148:151], v[200:203], 0
	v_mfma_f32_16x16x32_bf16 v[34:37], v[156:159], v[200:203], 0
	v_mfma_f32_16x16x32_bf16 v[22:25], v[148:151], v[208:211], 0
	v_mfma_f32_16x16x32_bf16 v[18:21], v[156:159], v[208:211], 0
	v_mfma_f32_16x16x32_bf16 v[62:65], v[152:155], v[184:187], v[62:65]
	v_mfma_f32_16x16x32_bf16 v[58:61], v[160:163], v[184:187], v[58:61]
	v_mfma_f32_16x16x32_bf16 v[54:57], v[152:155], v[196:199], v[54:57]
	v_mfma_f32_16x16x32_bf16 v[50:53], v[160:163], v[196:199], v[50:53]
	v_mfma_f32_16x16x32_bf16 v[38:41], v[152:155], v[204:207], v[38:41]
	v_mfma_f32_16x16x32_bf16 v[34:37], v[160:163], v[204:207], v[34:37]
	v_mfma_f32_16x16x32_bf16 v[22:25], v[152:155], v[212:215], v[22:25]
	v_mfma_f32_16x16x32_bf16 v[18:21], v[160:163], v[212:215], v[18:21]
	v_mfma_f32_16x16x32_bf16 v[46:49], v[164:167], v[180:183], 0
	v_mfma_f32_16x16x32_bf16 v[42:45], v[172:175], v[180:183], 0
	v_mfma_f32_16x16x32_bf16 v[30:33], v[164:167], v[188:191], 0
	v_mfma_f32_16x16x32_bf16 v[26:29], v[172:175], v[188:191], 0
	v_mfma_f32_16x16x32_bf16 v[14:17], v[164:167], v[200:203], 0
	v_mfma_f32_16x16x32_bf16 v[10:13], v[172:175], v[200:203], 0
	v_mfma_f32_16x16x32_bf16 v[6:9], v[164:167], v[208:211], 0
	v_mfma_f32_16x16x32_bf16 v[2:5], v[172:175], v[208:211], 0
	v_mfma_f32_16x16x32_bf16 v[46:49], v[168:171], v[184:187], v[46:49]
	v_mfma_f32_16x16x32_bf16 v[42:45], v[176:179], v[184:187], v[42:45]
	v_mfma_f32_16x16x32_bf16 v[30:33], v[168:171], v[196:199], v[30:33]
	v_mfma_f32_16x16x32_bf16 v[26:29], v[176:179], v[196:199], v[26:29]
	v_mfma_f32_16x16x32_bf16 v[14:17], v[168:171], v[204:207], v[14:17]
	v_mfma_f32_16x16x32_bf16 v[10:13], v[176:179], v[204:207], v[10:13]
	v_mfma_f32_16x16x32_bf16 v[6:9], v[168:171], v[212:215], v[6:9]
	s_barrier
	v_mfma_f32_16x16x32_bf16 v[2:5], v[176:179], v[212:215], v[2:5]
	s_setprio 2
	s_add_i32 s59, 0, 0x18000
	s_add_i32 s60, 0, 0x1c000
	ds_read_b128 v[148:151], v250
	ds_read_b128 v[152:155], v250 offset:1024
	ds_read_b128 v[156:159], v250 offset:2048
	ds_read_b128 v[160:163], v250 offset:3072
	ds_read_b128 v[164:167], v250 offset:16384
	ds_read_b128 v[168:171], v250 offset:17408
	ds_read_b128 v[172:175], v250 offset:18432
	ds_read_b128 v[176:179], v250 offset:19456
	s_add_u32 s38, s38, 0x80000
	s_addc_u32 s39, s39, 0
	s_mov_b32 m0, s42
	v_lshl_add_u64 v[222:223], s[38:39], 0, v[136:137]
	ds_read_b128 v[180:183], v147 offset:32768
	ds_read_b128 v[184:187], v147 offset:33792
	ds_read_b128 v[188:191], v147 offset:34816
	ds_read_b128 v[196:199], v147 offset:35840
	ds_read_b128 v[200:203], v147 offset:36864
	ds_read_b128 v[204:207], v147 offset:37888
	ds_read_b128 v[208:211], v147 offset:38912
	ds_read_b128 v[212:215], v147 offset:39936
	global_load_lds_dwordx4 v[222:223], off
	v_lshl_add_u64 v[222:223], s[38:39], 0, v[132:133]
	s_mov_b32 m0, s43
	s_nop 0
	global_load_lds_dwordx4 v[222:223], off
	s_waitcnt vmcnt(8)
	s_waitcnt lgkmcnt(0)
	s_barrier
	s_setprio 1
	s_waitcnt lgkmcnt(0)
	v_mfma_f32_16x16x32_bf16 v[126:129], v[148:151], v[180:183], v[126:129]
	v_mfma_f32_16x16x32_bf16 v[122:125], v[156:159], v[180:183], v[122:125]
	v_mfma_f32_16x16x32_bf16 v[118:121], v[148:151], v[188:191], v[118:121]
	v_mfma_f32_16x16x32_bf16 v[114:117], v[156:159], v[188:191], v[114:117]
	v_mfma_f32_16x16x32_bf16 v[102:105], v[148:151], v[200:203], v[102:105]
	v_mfma_f32_16x16x32_bf16 v[98:101], v[156:159], v[200:203], v[98:101]
	v_mfma_f32_16x16x32_bf16 v[86:89], v[148:151], v[208:211], v[86:89]
	v_mfma_f32_16x16x32_bf16 v[82:85], v[156:159], v[208:211], v[82:85]
	v_mfma_f32_16x16x32_bf16 v[126:129], v[152:155], v[184:187], v[126:129]
	v_mfma_f32_16x16x32_bf16 v[122:125], v[160:163], v[184:187], v[122:125]
	v_mfma_f32_16x16x32_bf16 v[118:121], v[152:155], v[196:199], v[118:121]
	v_mfma_f32_16x16x32_bf16 v[114:117], v[160:163], v[196:199], v[114:117]
	v_mfma_f32_16x16x32_bf16 v[102:105], v[152:155], v[204:207], v[102:105]
	v_mfma_f32_16x16x32_bf16 v[98:101], v[160:163], v[204:207], v[98:101]
	v_mfma_f32_16x16x32_bf16 v[86:89], v[152:155], v[212:215], v[86:89]
	v_mfma_f32_16x16x32_bf16 v[82:85], v[160:163], v[212:215], v[82:85]
	v_mfma_f32_16x16x32_bf16 v[110:113], v[164:167], v[180:183], v[110:113]
	v_mfma_f32_16x16x32_bf16 v[106:109], v[172:175], v[180:183], v[106:109]
	v_mfma_f32_16x16x32_bf16 v[94:97], v[164:167], v[188:191], v[94:97]
	v_mfma_f32_16x16x32_bf16 v[90:93], v[172:175], v[188:191], v[90:93]
	v_mfma_f32_16x16x32_bf16 v[78:81], v[164:167], v[200:203], v[78:81]
	v_mfma_f32_16x16x32_bf16 v[74:77], v[172:175], v[200:203], v[74:77]
	v_mfma_f32_16x16x32_bf16 v[70:73], v[164:167], v[208:211], v[70:73]
	v_mfma_f32_16x16x32_bf16 v[66:69], v[172:175], v[208:211], v[66:69]
	v_mfma_f32_16x16x32_bf16 v[110:113], v[168:171], v[184:187], v[110:113]
	v_mfma_f32_16x16x32_bf16 v[106:109], v[176:179], v[184:187], v[106:109]
	v_mfma_f32_16x16x32_bf16 v[94:97], v[168:171], v[196:199], v[94:97]
	v_mfma_f32_16x16x32_bf16 v[90:93], v[176:179], v[196:199], v[90:93]
	v_mfma_f32_16x16x32_bf16 v[78:81], v[168:171], v[204:207], v[78:81]
	v_mfma_f32_16x16x32_bf16 v[74:77], v[176:179], v[204:207], v[74:77]
	v_mfma_f32_16x16x32_bf16 v[70:73], v[168:171], v[212:215], v[70:73]
	s_barrier
	v_mfma_f32_16x16x32_bf16 v[66:69], v[176:179], v[212:215], v[66:69]
	s_setprio 2
	s_add_i32 s38, s59, s33
	v_lshl_add_u64 v[192:193], v[192:193], 0, s[6:7]
	s_mov_b32 m0, s38
	ds_read_b128 v[180:183], v147 offset:49152
	ds_read_b128 v[184:187], v147 offset:50176
	ds_read_b128 v[188:191], v147 offset:51200
	ds_read_b128 v[196:199], v147 offset:52224
	ds_read_b128 v[200:203], v147 offset:53248
	ds_read_b128 v[204:207], v147 offset:54272
	ds_read_b128 v[208:211], v147 offset:55296
	ds_read_b128 v[212:215], v147 offset:56320
	global_load_lds_dwordx4 v[192:193], off
	s_add_i32 m0, s38, 0x2000
	s_add_u32 s36, s36, 0x80080
	v_lshl_add_u64 v[192:193], v[216:217], 0, s[6:7]
	s_addc_u32 s37, s37, 0
	s_add_i32 s38, s60, s33
	global_load_lds_dwordx4 v[192:193], off
	v_lshl_add_u64 v[192:193], s[36:37], 0, v[134:135]
	s_mov_b32 m0, s38
	s_nop 0
	global_load_lds_dwordx4 v[192:193], off
	v_lshl_add_u64 v[192:193], s[36:37], 0, v[130:131]
	s_add_i32 m0, s38, 0x2000
	s_nop 0
	global_load_lds_dwordx4 v[192:193], off
	v_lshl_add_u64 v[192:193], v[218:219], 0, s[6:7]
	s_mov_b32 m0, s45
	s_nop 0
	global_load_lds_dwordx4 v[192:193], off
	v_lshl_add_u64 v[192:193], v[220:221], 0, s[6:7]
	s_mov_b32 m0, s46
	s_nop 0
	global_load_lds_dwordx4 v[192:193], off
	s_waitcnt vmcnt(8)
	s_waitcnt lgkmcnt(0)
	s_barrier
	s_setprio 1
	s_waitcnt lgkmcnt(0)
	v_mfma_f32_16x16x32_bf16 v[62:65], v[148:151], v[180:183], v[62:65]
	v_mfma_f32_16x16x32_bf16 v[58:61], v[156:159], v[180:183], v[58:61]
	v_mfma_f32_16x16x32_bf16 v[54:57], v[148:151], v[188:191], v[54:57]
	v_mfma_f32_16x16x32_bf16 v[50:53], v[156:159], v[188:191], v[50:53]
	v_mfma_f32_16x16x32_bf16 v[38:41], v[148:151], v[200:203], v[38:41]
	v_mfma_f32_16x16x32_bf16 v[34:37], v[156:159], v[200:203], v[34:37]
	v_mfma_f32_16x16x32_bf16 v[22:25], v[148:151], v[208:211], v[22:25]
	v_mfma_f32_16x16x32_bf16 v[18:21], v[156:159], v[208:211], v[18:21]
	v_mfma_f32_16x16x32_bf16 v[62:65], v[152:155], v[184:187], v[62:65]
	v_mfma_f32_16x16x32_bf16 v[58:61], v[160:163], v[184:187], v[58:61]
	v_mfma_f32_16x16x32_bf16 v[54:57], v[152:155], v[196:199], v[54:57]
	v_mfma_f32_16x16x32_bf16 v[50:53], v[160:163], v[196:199], v[50:53]
	v_mfma_f32_16x16x32_bf16 v[38:41], v[152:155], v[204:207], v[38:41]
	v_mfma_f32_16x16x32_bf16 v[34:37], v[160:163], v[204:207], v[34:37]
	v_mfma_f32_16x16x32_bf16 v[22:25], v[152:155], v[212:215], v[22:25]
	v_mfma_f32_16x16x32_bf16 v[18:21], v[160:163], v[212:215], v[18:21]
	v_mfma_f32_16x16x32_bf16 v[46:49], v[164:167], v[180:183], v[46:49]
	v_mfma_f32_16x16x32_bf16 v[42:45], v[172:175], v[180:183], v[42:45]
	v_mfma_f32_16x16x32_bf16 v[30:33], v[164:167], v[188:191], v[30:33]
	v_mfma_f32_16x16x32_bf16 v[26:29], v[172:175], v[188:191], v[26:29]
	v_mfma_f32_16x16x32_bf16 v[14:17], v[164:167], v[200:203], v[14:17]
	v_mfma_f32_16x16x32_bf16 v[10:13], v[172:175], v[200:203], v[10:13]
	v_mfma_f32_16x16x32_bf16 v[6:9], v[164:167], v[208:211], v[6:9]
	v_mfma_f32_16x16x32_bf16 v[2:5], v[172:175], v[208:211], v[2:5]
	v_mfma_f32_16x16x32_bf16 v[46:49], v[168:171], v[184:187], v[46:49]
	v_mfma_f32_16x16x32_bf16 v[42:45], v[176:179], v[184:187], v[42:45]
	v_mfma_f32_16x16x32_bf16 v[30:33], v[168:171], v[196:199], v[30:33]
	v_mfma_f32_16x16x32_bf16 v[26:29], v[176:179], v[196:199], v[26:29]
	v_mfma_f32_16x16x32_bf16 v[14:17], v[168:171], v[204:207], v[14:17]
	v_mfma_f32_16x16x32_bf16 v[10:13], v[176:179], v[204:207], v[10:13]
	v_mfma_f32_16x16x32_bf16 v[6:9], v[168:171], v[212:215], v[6:9]
	s_barrier
	v_mfma_f32_16x16x32_bf16 v[2:5], v[176:179], v[212:215], v[2:5]
	s_setprio 2
	s_add_i32 s58, s58, 2
	s_add_u32 s34, s34, 0x100
	s_addc_u32 s35, s35, 0
	s_add_u32 s56, s56, 0x100
	s_addc_u32 s57, s57, 0
	s_cmp_gt_u32 s58, 29
	s_cbranch_scc0 .LBB0_541
	s_branch .Lpeeldone_11
.LBB0_541:
	ds_read_b128 v[148:151], v145
	ds_read_b128 v[152:155], v145 offset:1024
	ds_read_b128 v[156:159], v145 offset:2048
	ds_read_b128 v[160:163], v145 offset:3072
	ds_read_b128 v[164:167], v146
	ds_read_b128 v[168:171], v146 offset:1024
	ds_read_b128 v[172:175], v146 offset:2048
	ds_read_b128 v[176:179], v146 offset:3072
	s_add_u32 s36, s34, 0xfff80080
	s_addc_u32 s37, s35, -1
	s_cmp_eq_u32 s58, 28
	s_cselect_b32 s39, s21, s37
	s_cselect_b32 s38, s54, s36
	s_cselect_b32 s37, s23, s57
	s_cselect_b32 s36, s55, s56
	v_lshl_add_u64 v[192:193], s[34:35], 0, v[138:139]
	s_add_i32 m0, s27, 0xc000
	ds_read_b128 v[180:183], v147
	ds_read_b128 v[184:187], v147 offset:1024
	ds_read_b128 v[188:191], v147 offset:2048
	ds_read_b128 v[196:199], v147 offset:3072
	ds_read_b128 v[200:203], v147 offset:4096
	ds_read_b128 v[204:207], v147 offset:5120
	ds_read_b128 v[208:211], v147 offset:6144
	ds_read_b128 v[212:215], v147 offset:7168
	global_load_lds_dwordx4 v[192:193], off
	v_lshl_add_u64 v[192:193], s[34:35], 0, v[140:141]
	s_add_i32 m0, s27, 0xe000
	s_nop 0
	global_load_lds_dwordx4 v[192:193], off
	s_waitcnt vmcnt(8)
	s_waitcnt lgkmcnt(0)
	s_barrier
	s_setprio 1
	s_waitcnt lgkmcnt(0)
	v_mfma_f32_16x16x32_bf16 v[126:129], v[148:151], v[180:183], v[126:129]
	v_mfma_f32_16x16x32_bf16 v[122:125], v[156:159], v[180:183], v[122:125]
	v_mfma_f32_16x16x32_bf16 v[118:121], v[148:151], v[188:191], v[118:121]
	v_mfma_f32_16x16x32_bf16 v[114:117], v[156:159], v[188:191], v[114:117]
	v_mfma_f32_16x16x32_bf16 v[102:105], v[148:151], v[200:203], v[102:105]
	v_mfma_f32_16x16x32_bf16 v[98:101], v[156:159], v[200:203], v[98:101]
	v_mfma_f32_16x16x32_bf16 v[86:89], v[148:151], v[208:211], v[86:89]
	v_mfma_f32_16x16x32_bf16 v[82:85], v[156:159], v[208:211], v[82:85]
	v_mfma_f32_16x16x32_bf16 v[126:129], v[152:155], v[184:187], v[126:129]
	v_mfma_f32_16x16x32_bf16 v[122:125], v[160:163], v[184:187], v[122:125]
	v_mfma_f32_16x16x32_bf16 v[118:121], v[152:155], v[196:199], v[118:121]
	v_mfma_f32_16x16x32_bf16 v[114:117], v[160:163], v[196:199], v[114:117]
	v_mfma_f32_16x16x32_bf16 v[102:105], v[152:155], v[204:207], v[102:105]
	v_mfma_f32_16x16x32_bf16 v[98:101], v[160:163], v[204:207], v[98:101]
	v_mfma_f32_16x16x32_bf16 v[86:89], v[152:155], v[212:215], v[86:89]
	v_mfma_f32_16x16x32_bf16 v[82:85], v[160:163], v[212:215], v[82:85]
	v_mfma_f32_16x16x32_bf16 v[110:113], v[164:167], v[180:183], v[110:113]
	v_mfma_f32_16x16x32_bf16 v[106:109], v[172:175], v[180:183], v[106:109]
	v_mfma_f32_16x16x32_bf16 v[94:97], v[164:167], v[188:191], v[94:97]
	v_mfma_f32_16x16x32_bf16 v[90:93], v[172:175], v[188:191], v[90:93]
	v_mfma_f32_16x16x32_bf16 v[78:81], v[164:167], v[200:203], v[78:81]
	v_mfma_f32_16x16x32_bf16 v[74:77], v[172:175], v[200:203], v[74:77]
	v_mfma_f32_16x16x32_bf16 v[70:73], v[164:167], v[208:211], v[70:73]
	v_mfma_f32_16x16x32_bf16 v[66:69], v[172:175], v[208:211], v[66:69]
	v_mfma_f32_16x16x32_bf16 v[110:113], v[168:171], v[184:187], v[110:113]
	v_mfma_f32_16x16x32_bf16 v[106:109], v[176:179], v[184:187], v[106:109]
	v_mfma_f32_16x16x32_bf16 v[94:97], v[168:171], v[196:199], v[94:97]
	v_mfma_f32_16x16x32_bf16 v[90:93], v[176:179], v[196:199], v[90:93]
	v_mfma_f32_16x16x32_bf16 v[78:81], v[168:171], v[204:207], v[78:81]
	v_mfma_f32_16x16x32_bf16 v[74:77], v[176:179], v[204:207], v[74:77]
	v_mfma_f32_16x16x32_bf16 v[70:73], v[168:171], v[212:215], v[70:73]
	s_barrier
	v_mfma_f32_16x16x32_bf16 v[66:69], v[176:179], v[212:215], v[66:69]
	s_setprio 2
	s_add_i32 s59, s47, s33
	v_lshl_add_u64 v[192:193], s[36:37], 0, v[134:135]
	s_mov_b32 m0, s59
	ds_read_b128 v[180:183], v147 offset:16384
	ds_read_b128 v[184:187], v147 offset:17408
	ds_read_b128 v[188:191], v147 offset:18432
	ds_read_b128 v[196:199], v147 offset:19456
	ds_read_b128 v[200:203], v147 offset:20480
	ds_read_b128 v[204:207], v147 offset:21504
	ds_read_b128 v[208:211], v147 offset:22528
	ds_read_b128 v[212:215], v147 offset:23552
	global_load_lds_dwordx4 v[192:193], off
	s_add_i32 m0, s59, 0x2000
	s_add_u32 s60, s36, 0x80000
	v_lshl_add_u64 v[216:217], s[36:37], 0, v[130:131]
	s_addc_u32 s61, s37, 0
	s_add_i32 s59, s48, s33
	global_load_lds_dwordx4 v[216:217], off
	v_lshl_add_u64 v[218:219], s[60:61], 0, v[134:135]
	s_mov_b32 m0, s59
	v_lshl_add_u64 v[220:221], s[38:39], 0, v[132:133]
	global_load_lds_dwordx4 v[218:219], off
	v_lshl_add_u64 v[218:219], s[60:61], 0, v[130:131]
	s_add_i32 m0, s59, 0x2000
	s_nop 0
	global_load_lds_dwordx4 v[218:219], off
	v_lshl_add_u64 v[218:219], s[38:39], 0, v[136:137]
	s_mov_b32 m0, s27
	s_nop 0
	global_load_lds_dwordx4 v[218:219], off
	s_mov_b32 m0, s41
	s_nop 0
	global_load_lds_dwordx4 v[220:221], off
	s_waitcnt vmcnt(8)
	s_waitcnt lgkmcnt(0)
	s_barrier
	s_setprio 1
	s_waitcnt lgkmcnt(0)
	v_mfma_f32_16x16x32_bf16 v[62:65], v[148:151], v[180:183], v[62:65]
	v_mfma_f32_16x16x32_bf16 v[58:61], v[156:159], v[180:183], v[58:61]
	v_mfma_f32_16x16x32_bf16 v[54:57], v[148:151], v[188:191], v[54:57]
	v_mfma_f32_16x16x32_bf16 v[50:53], v[156:159], v[188:191], v[50:53]
	v_mfma_f32_16x16x32_bf16 v[38:41], v[148:151], v[200:203], v[38:41]
	v_mfma_f32_16x16x32_bf16 v[34:37], v[156:159], v[200:203], v[34:37]
	v_mfma_f32_16x16x32_bf16 v[22:25], v[148:151], v[208:211], v[22:25]
	v_mfma_f32_16x16x32_bf16 v[18:21], v[156:159], v[208:211], v[18:21]
	v_mfma_f32_16x16x32_bf16 v[62:65], v[152:155], v[184:187], v[62:65]
	v_mfma_f32_16x16x32_bf16 v[58:61], v[160:163], v[184:187], v[58:61]
	v_mfma_f32_16x16x32_bf16 v[54:57], v[152:155], v[196:199], v[54:57]
	v_mfma_f32_16x16x32_bf16 v[50:53], v[160:163], v[196:199], v[50:53]
	v_mfma_f32_16x16x32_bf16 v[38:41], v[152:155], v[204:207], v[38:41]
	v_mfma_f32_16x16x32_bf16 v[34:37], v[160:163], v[204:207], v[34:37]
	v_mfma_f32_16x16x32_bf16 v[22:25], v[152:155], v[212:215], v[22:25]
	v_mfma_f32_16x16x32_bf16 v[18:21], v[160:163], v[212:215], v[18:21]
	v_mfma_f32_16x16x32_bf16 v[46:49], v[164:167], v[180:183], v[46:49]
	v_mfma_f32_16x16x32_bf16 v[42:45], v[172:175], v[180:183], v[42:45]
	v_mfma_f32_16x16x32_bf16 v[30:33], v[164:167], v[188:191], v[30:33]
	v_mfma_f32_16x16x32_bf16 v[26:29], v[172:175], v[188:191], v[26:29]
	v_mfma_f32_16x16x32_bf16 v[14:17], v[164:167], v[200:203], v[14:17]
	v_mfma_f32_16x16x32_bf16 v[10:13], v[172:175], v[200:203], v[10:13]
	v_mfma_f32_16x16x32_bf16 v[6:9], v[164:167], v[208:211], v[6:9]
	v_mfma_f32_16x16x32_bf16 v[2:5], v[172:175], v[208:211], v[2:5]
	v_mfma_f32_16x16x32_bf16 v[46:49], v[168:171], v[184:187], v[46:49]
	v_mfma_f32_16x16x32_bf16 v[42:45], v[176:179], v[184:187], v[42:45]
	v_mfma_f32_16x16x32_bf16 v[30:33], v[168:171], v[196:199], v[30:33]
	v_mfma_f32_16x16x32_bf16 v[26:29], v[176:179], v[196:199], v[26:29]
	v_mfma_f32_16x16x32_bf16 v[14:17], v[168:171], v[204:207], v[14:17]
	v_mfma_f32_16x16x32_bf16 v[10:13], v[176:179], v[204:207], v[10:13]
	v_mfma_f32_16x16x32_bf16 v[6:9], v[168:171], v[212:215], v[6:9]
	s_barrier
	v_mfma_f32_16x16x32_bf16 v[2:5], v[176:179], v[212:215], v[2:5]
	s_setprio 2
	s_add_i32 s59, 0, 0x18000
	s_add_i32 s60, 0, 0x1c000
	ds_read_b128 v[148:151], v250
	ds_read_b128 v[152:155], v250 offset:1024
	ds_read_b128 v[156:159], v250 offset:2048
	ds_read_b128 v[160:163], v250 offset:3072
	ds_read_b128 v[164:167], v250 offset:16384
	ds_read_b128 v[168:171], v250 offset:17408
	ds_read_b128 v[172:175], v250 offset:18432
	ds_read_b128 v[176:179], v250 offset:19456
	s_add_u32 s38, s38, 0x80000
	s_addc_u32 s39, s39, 0
	s_mov_b32 m0, s42
	v_lshl_add_u64 v[222:223], s[38:39], 0, v[136:137]
	ds_read_b128 v[180:183], v147 offset:32768
	ds_read_b128 v[184:187], v147 offset:33792
	ds_read_b128 v[188:191], v147 offset:34816
	ds_read_b128 v[196:199], v147 offset:35840
	ds_read_b128 v[200:203], v147 offset:36864
	ds_read_b128 v[204:207], v147 offset:37888
	ds_read_b128 v[208:211], v147 offset:38912
	ds_read_b128 v[212:215], v147 offset:39936
	global_load_lds_dwordx4 v[222:223], off
	v_lshl_add_u64 v[222:223], s[38:39], 0, v[132:133]
	s_mov_b32 m0, s43
	s_nop 0
	global_load_lds_dwordx4 v[222:223], off
	s_waitcnt vmcnt(8)
	s_waitcnt lgkmcnt(0)
	s_barrier
	s_setprio 1
	s_waitcnt lgkmcnt(0)
	v_mfma_f32_16x16x32_bf16 v[126:129], v[148:151], v[180:183], v[126:129]
	v_mfma_f32_16x16x32_bf16 v[122:125], v[156:159], v[180:183], v[122:125]
	v_mfma_f32_16x16x32_bf16 v[118:121], v[148:151], v[188:191], v[118:121]
	v_mfma_f32_16x16x32_bf16 v[114:117], v[156:159], v[188:191], v[114:117]
	v_mfma_f32_16x16x32_bf16 v[102:105], v[148:151], v[200:203], v[102:105]
	v_mfma_f32_16x16x32_bf16 v[98:101], v[156:159], v[200:203], v[98:101]
	v_mfma_f32_16x16x32_bf16 v[86:89], v[148:151], v[208:211], v[86:89]
	v_mfma_f32_16x16x32_bf16 v[82:85], v[156:159], v[208:211], v[82:85]
	v_mfma_f32_16x16x32_bf16 v[126:129], v[152:155], v[184:187], v[126:129]
	v_mfma_f32_16x16x32_bf16 v[122:125], v[160:163], v[184:187], v[122:125]
	v_mfma_f32_16x16x32_bf16 v[118:121], v[152:155], v[196:199], v[118:121]
	v_mfma_f32_16x16x32_bf16 v[114:117], v[160:163], v[196:199], v[114:117]
	v_mfma_f32_16x16x32_bf16 v[102:105], v[152:155], v[204:207], v[102:105]
	v_mfma_f32_16x16x32_bf16 v[98:101], v[160:163], v[204:207], v[98:101]
	v_mfma_f32_16x16x32_bf16 v[86:89], v[152:155], v[212:215], v[86:89]
	v_mfma_f32_16x16x32_bf16 v[82:85], v[160:163], v[212:215], v[82:85]
	v_mfma_f32_16x16x32_bf16 v[110:113], v[164:167], v[180:183], v[110:113]
	v_mfma_f32_16x16x32_bf16 v[106:109], v[172:175], v[180:183], v[106:109]
	v_mfma_f32_16x16x32_bf16 v[94:97], v[164:167], v[188:191], v[94:97]
	v_mfma_f32_16x16x32_bf16 v[90:93], v[172:175], v[188:191], v[90:93]
	v_mfma_f32_16x16x32_bf16 v[78:81], v[164:167], v[200:203], v[78:81]
	v_mfma_f32_16x16x32_bf16 v[74:77], v[172:175], v[200:203], v[74:77]
	v_mfma_f32_16x16x32_bf16 v[70:73], v[164:167], v[208:211], v[70:73]
	v_mfma_f32_16x16x32_bf16 v[66:69], v[172:175], v[208:211], v[66:69]
	v_mfma_f32_16x16x32_bf16 v[110:113], v[168:171], v[184:187], v[110:113]
	v_mfma_f32_16x16x32_bf16 v[106:109], v[176:179], v[184:187], v[106:109]
	v_mfma_f32_16x16x32_bf16 v[94:97], v[168:171], v[196:199], v[94:97]
	v_mfma_f32_16x16x32_bf16 v[90:93], v[176:179], v[196:199], v[90:93]
	v_mfma_f32_16x16x32_bf16 v[78:81], v[168:171], v[204:207], v[78:81]
	v_mfma_f32_16x16x32_bf16 v[74:77], v[176:179], v[204:207], v[74:77]
	v_mfma_f32_16x16x32_bf16 v[70:73], v[168:171], v[212:215], v[70:73]
	s_barrier
	v_mfma_f32_16x16x32_bf16 v[66:69], v[176:179], v[212:215], v[66:69]
	s_setprio 2
	s_add_i32 s38, s59, s33
	v_lshl_add_u64 v[192:193], v[192:193], 0, s[6:7]
	s_mov_b32 m0, s38
	ds_read_b128 v[180:183], v147 offset:49152
	ds_read_b128 v[184:187], v147 offset:50176
	ds_read_b128 v[188:191], v147 offset:51200
	ds_read_b128 v[196:199], v147 offset:52224
	ds_read_b128 v[200:203], v147 offset:53248
	ds_read_b128 v[204:207], v147 offset:54272
	ds_read_b128 v[208:211], v147 offset:55296
	ds_read_b128 v[212:215], v147 offset:56320
	global_load_lds_dwordx4 v[192:193], off
	s_add_i32 m0, s38, 0x2000
	s_add_u32 s36, s36, 0x80080
	v_lshl_add_u64 v[192:193], v[216:217], 0, s[6:7]
	s_addc_u32 s37, s37, 0
	s_add_i32 s38, s60, s33
	global_load_lds_dwordx4 v[192:193], off
	v_lshl_add_u64 v[192:193], s[36:37], 0, v[134:135]
	s_mov_b32 m0, s38
	s_nop 0
	global_load_lds_dwordx4 v[192:193], off
	v_lshl_add_u64 v[192:193], s[36:37], 0, v[130:131]
	s_add_i32 m0, s38, 0x2000
	s_nop 0
	global_load_lds_dwordx4 v[192:193], off
	v_lshl_add_u64 v[192:193], v[218:219], 0, s[6:7]
	s_mov_b32 m0, s45
	s_nop 0
	global_load_lds_dwordx4 v[192:193], off
	v_lshl_add_u64 v[192:193], v[220:221], 0, s[6:7]
	s_mov_b32 m0, s46
	s_nop 0
	global_load_lds_dwordx4 v[192:193], off
	s_waitcnt vmcnt(8)
	s_waitcnt lgkmcnt(0)
	s_barrier
	s_setprio 1
	s_waitcnt lgkmcnt(0)
	v_mfma_f32_16x16x32_bf16 v[62:65], v[148:151], v[180:183], v[62:65]
	v_mfma_f32_16x16x32_bf16 v[58:61], v[156:159], v[180:183], v[58:61]
	v_mfma_f32_16x16x32_bf16 v[54:57], v[148:151], v[188:191], v[54:57]
	v_mfma_f32_16x16x32_bf16 v[50:53], v[156:159], v[188:191], v[50:53]
	v_mfma_f32_16x16x32_bf16 v[38:41], v[148:151], v[200:203], v[38:41]
	v_mfma_f32_16x16x32_bf16 v[34:37], v[156:159], v[200:203], v[34:37]
	v_mfma_f32_16x16x32_bf16 v[22:25], v[148:151], v[208:211], v[22:25]
	v_mfma_f32_16x16x32_bf16 v[18:21], v[156:159], v[208:211], v[18:21]
	v_mfma_f32_16x16x32_bf16 v[62:65], v[152:155], v[184:187], v[62:65]
	v_mfma_f32_16x16x32_bf16 v[58:61], v[160:163], v[184:187], v[58:61]
	v_mfma_f32_16x16x32_bf16 v[54:57], v[152:155], v[196:199], v[54:57]
	v_mfma_f32_16x16x32_bf16 v[50:53], v[160:163], v[196:199], v[50:53]
	v_mfma_f32_16x16x32_bf16 v[38:41], v[152:155], v[204:207], v[38:41]
	v_mfma_f32_16x16x32_bf16 v[34:37], v[160:163], v[204:207], v[34:37]
	v_mfma_f32_16x16x32_bf16 v[22:25], v[152:155], v[212:215], v[22:25]
	v_mfma_f32_16x16x32_bf16 v[18:21], v[160:163], v[212:215], v[18:21]
	v_mfma_f32_16x16x32_bf16 v[46:49], v[164:167], v[180:183], v[46:49]
	v_mfma_f32_16x16x32_bf16 v[42:45], v[172:175], v[180:183], v[42:45]
	v_mfma_f32_16x16x32_bf16 v[30:33], v[164:167], v[188:191], v[30:33]
	v_mfma_f32_16x16x32_bf16 v[26:29], v[172:175], v[188:191], v[26:29]
	v_mfma_f32_16x16x32_bf16 v[14:17], v[164:167], v[200:203], v[14:17]
	v_mfma_f32_16x16x32_bf16 v[10:13], v[172:175], v[200:203], v[10:13]
	v_mfma_f32_16x16x32_bf16 v[6:9], v[164:167], v[208:211], v[6:9]
	v_mfma_f32_16x16x32_bf16 v[2:5], v[172:175], v[208:211], v[2:5]
	v_mfma_f32_16x16x32_bf16 v[46:49], v[168:171], v[184:187], v[46:49]
	v_mfma_f32_16x16x32_bf16 v[42:45], v[176:179], v[184:187], v[42:45]
	v_mfma_f32_16x16x32_bf16 v[30:33], v[168:171], v[196:199], v[30:33]
	v_mfma_f32_16x16x32_bf16 v[26:29], v[176:179], v[196:199], v[26:29]
	v_mfma_f32_16x16x32_bf16 v[14:17], v[168:171], v[204:207], v[14:17]
	v_mfma_f32_16x16x32_bf16 v[10:13], v[176:179], v[204:207], v[10:13]
	v_mfma_f32_16x16x32_bf16 v[6:9], v[168:171], v[212:215], v[6:9]
	s_barrier
	v_mfma_f32_16x16x32_bf16 v[2:5], v[176:179], v[212:215], v[2:5]
	s_setprio 2
	s_add_i32 s58, s58, 2
	s_add_u32 s34, s34, 0x100
	s_addc_u32 s35, s35, 0
	s_add_u32 s56, s56, 0x100
	s_addc_u32 s57, s57, 0
	s_cmp_gt_u32 s58, 29
	s_cbranch_scc0 .LBB0_541

.Lpeel_10:
	v_add_u32_e32 v250, 0x18000, v145
	ds_read_b128 v[150:153], v147
	ds_read_b128 v[154:157], v147 offset:1024
	s_add_u32 s28, s26, 0xfffe0080
	s_addc_u32 s29, s27, -1
	s_cmp_eq_u32 s50, 4
	s_cselect_b32 s31, s13, s29
	s_cselect_b32 s30, s46, s28
	s_cselect_b32 s29, s17, s49
	s_cselect_b32 s28, s47, s48
	v_lshl_add_u64 v[202:203], s[26:27], 0, v[138:139]
	s_add_i32 m0, s36, 0xc000
	global_load_lds_dwordx4 v[202:203], off
	v_lshl_add_u64 v[202:203], s[26:27], 0, v[140:141]
	s_add_i32 m0, s36, 0xe000
	s_nop 0
	global_load_lds_dwordx4 v[202:203], off
	s_waitcnt vmcnt(8)
	s_waitcnt lgkmcnt(0)
	s_barrier
	s_setprio 1
	s_waitcnt lgkmcnt(0)
	v_mfma_f32_16x16x32_bf16 v[126:129], v[150:153], v[182:185], 0
	v_mfma_f32_16x16x32_bf16 v[122:125], v[158:161], v[182:185], 0
	v_mfma_f32_16x16x32_bf16 v[118:121], v[150:153], v[190:193], 0
	v_mfma_f32_16x16x32_bf16 v[114:117], v[158:161], v[190:193], 0
	v_mfma_f32_16x16x32_bf16 v[102:105], v[150:153], v[210:213], 0
	v_mfma_f32_16x16x32_bf16 v[98:101], v[158:161], v[210:213], 0
	v_mfma_f32_16x16x32_bf16 v[86:89], v[150:153], v[218:221], 0
	v_mfma_f32_16x16x32_bf16 v[82:85], v[158:161], v[218:221], 0
	v_mfma_f32_16x16x32_bf16 v[126:129], v[154:157], v[186:189], v[126:129]
	v_mfma_f32_16x16x32_bf16 v[122:125], v[162:165], v[186:189], v[122:125]
	v_mfma_f32_16x16x32_bf16 v[118:121], v[154:157], v[198:201], v[118:121]
	v_mfma_f32_16x16x32_bf16 v[114:117], v[162:165], v[198:201], v[114:117]
	v_mfma_f32_16x16x32_bf16 v[102:105], v[154:157], v[214:217], v[102:105]
	v_mfma_f32_16x16x32_bf16 v[98:101], v[162:165], v[214:217], v[98:101]
	v_mfma_f32_16x16x32_bf16 v[86:89], v[154:157], v[222:225], v[86:89]
	v_mfma_f32_16x16x32_bf16 v[82:85], v[162:165], v[222:225], v[82:85]
	v_mfma_f32_16x16x32_bf16 v[110:113], v[166:169], v[182:185], 0
	v_mfma_f32_16x16x32_bf16 v[106:109], v[174:177], v[182:185], 0
	v_mfma_f32_16x16x32_bf16 v[94:97], v[166:169], v[190:193], 0
	v_mfma_f32_16x16x32_bf16 v[90:93], v[174:177], v[190:193], 0
	v_mfma_f32_16x16x32_bf16 v[78:81], v[166:169], v[210:213], 0
	v_mfma_f32_16x16x32_bf16 v[74:77], v[174:177], v[210:213], 0
	v_mfma_f32_16x16x32_bf16 v[70:73], v[166:169], v[218:221], 0
	v_mfma_f32_16x16x32_bf16 v[66:69], v[174:177], v[218:221], 0
	v_mfma_f32_16x16x32_bf16 v[110:113], v[170:173], v[186:189], v[110:113]
	v_mfma_f32_16x16x32_bf16 v[106:109], v[178:181], v[186:189], v[106:109]
	v_mfma_f32_16x16x32_bf16 v[94:97], v[170:173], v[198:201], v[94:97]
	v_mfma_f32_16x16x32_bf16 v[90:93], v[178:181], v[198:201], v[90:93]
	v_mfma_f32_16x16x32_bf16 v[78:81], v[170:173], v[214:217], v[78:81]
	v_mfma_f32_16x16x32_bf16 v[74:77], v[178:181], v[214:217], v[74:77]
	v_mfma_f32_16x16x32_bf16 v[70:73], v[170:173], v[222:225], v[70:73]
	s_barrier
	v_mfma_f32_16x16x32_bf16 v[66:69], v[178:181], v[222:225], v[66:69]
	s_setprio 2
	s_add_i32 s51, s43, s35
	v_lshl_add_u64 v[202:203], s[28:29], 0, v[132:133]
	s_mov_b32 m0, s51
	ds_read_b128 v[182:185], v149 offset:16384
	ds_read_b128 v[186:189], v149 offset:17408
	ds_read_b128 v[190:193], v149 offset:18432
	ds_read_b128 v[198:201], v149 offset:19456
	ds_read_b128 v[210:213], v149 offset:20480
	ds_read_b128 v[214:217], v149 offset:21504
	ds_read_b128 v[218:221], v149 offset:22528
	ds_read_b128 v[222:225], v149 offset:23552
	global_load_lds_dwordx4 v[202:203], off
	s_add_i32 m0, s51, 0x2000
	s_add_u32 s52, s28, 0x20000
	v_lshl_add_u64 v[206:207], s[28:29], 0, v[134:135]
	s_addc_u32 s53, s29, 0
	s_add_i32 s51, s44, s35
	global_load_lds_dwordx4 v[206:207], off
	v_lshl_add_u64 v[226:227], s[52:53], 0, v[132:133]
	s_mov_b32 m0, s51
	v_lshl_add_u64 v[228:229], s[30:31], 0, v[136:137]
	global_load_lds_dwordx4 v[226:227], off
	v_lshl_add_u64 v[226:227], s[52:53], 0, v[134:135]
	s_add_i32 m0, s51, 0x2000
	s_nop 0
	global_load_lds_dwordx4 v[226:227], off
	v_lshl_add_u64 v[226:227], s[30:31], 0, v[130:131]
	s_mov_b32 m0, s36
	s_nop 0
	global_load_lds_dwordx4 v[226:227], off
	s_mov_b32 m0, s37
	s_nop 0
	global_load_lds_dwordx4 v[228:229], off
	s_waitcnt vmcnt(8)
	s_waitcnt lgkmcnt(0)
	s_barrier
	s_setprio 1
	s_waitcnt lgkmcnt(0)
	v_mfma_f32_16x16x32_bf16 v[62:65], v[150:153], v[182:185], 0
	v_mfma_f32_16x16x32_bf16 v[58:61], v[158:161], v[182:185], 0
	v_mfma_f32_16x16x32_bf16 v[54:57], v[150:153], v[190:193], 0
	v_mfma_f32_16x16x32_bf16 v[50:53], v[158:161], v[190:193], 0
	v_mfma_f32_16x16x32_bf16 v[38:41], v[150:153], v[210:213], 0
	v_mfma_f32_16x16x32_bf16 v[34:37], v[158:161], v[210:213], 0
	v_mfma_f32_16x16x32_bf16 v[22:25], v[150:153], v[218:221], 0
	v_mfma_f32_16x16x32_bf16 v[18:21], v[158:161], v[218:221], 0
	v_mfma_f32_16x16x32_bf16 v[62:65], v[154:157], v[186:189], v[62:65]
	v_mfma_f32_16x16x32_bf16 v[58:61], v[162:165], v[186:189], v[58:61]
	v_mfma_f32_16x16x32_bf16 v[54:57], v[154:157], v[198:201], v[54:57]
	v_mfma_f32_16x16x32_bf16 v[50:53], v[162:165], v[198:201], v[50:53]
	v_mfma_f32_16x16x32_bf16 v[38:41], v[154:157], v[214:217], v[38:41]
	v_mfma_f32_16x16x32_bf16 v[34:37], v[162:165], v[214:217], v[34:37]
	v_mfma_f32_16x16x32_bf16 v[22:25], v[154:157], v[222:225], v[22:25]
	v_mfma_f32_16x16x32_bf16 v[18:21], v[162:165], v[222:225], v[18:21]
	v_mfma_f32_16x16x32_bf16 v[46:49], v[166:169], v[182:185], 0
	v_mfma_f32_16x16x32_bf16 v[42:45], v[174:177], v[182:185], 0
	v_mfma_f32_16x16x32_bf16 v[30:33], v[166:169], v[190:193], 0
	v_mfma_f32_16x16x32_bf16 v[26:29], v[174:177], v[190:193], 0
	v_mfma_f32_16x16x32_bf16 v[14:17], v[166:169], v[210:213], 0
	v_mfma_f32_16x16x32_bf16 v[10:13], v[174:177], v[210:213], 0
	v_mfma_f32_16x16x32_bf16 v[6:9], v[166:169], v[218:221], 0
	v_mfma_f32_16x16x32_bf16 v[2:5], v[174:177], v[218:221], 0
	v_mfma_f32_16x16x32_bf16 v[46:49], v[170:173], v[186:189], v[46:49]
	v_mfma_f32_16x16x32_bf16 v[42:45], v[178:181], v[186:189], v[42:45]
	v_mfma_f32_16x16x32_bf16 v[30:33], v[170:173], v[198:201], v[30:33]
	v_mfma_f32_16x16x32_bf16 v[26:29], v[178:181], v[198:201], v[26:29]
	v_mfma_f32_16x16x32_bf16 v[14:17], v[170:173], v[214:217], v[14:17]
	v_mfma_f32_16x16x32_bf16 v[10:13], v[178:181], v[214:217], v[10:13]
	v_mfma_f32_16x16x32_bf16 v[6:9], v[170:173], v[222:225], v[6:9]
	s_barrier
	v_mfma_f32_16x16x32_bf16 v[2:5], v[178:181], v[222:225], v[2:5]
	s_setprio 2
	s_add_i32 s51, 0, 0x18000
	s_add_i32 s52, 0, 0x1c000
	ds_read_b128 v[150:153], v250
	ds_read_b128 v[154:157], v250 offset:1024
	ds_read_b128 v[158:161], v250 offset:2048
	ds_read_b128 v[162:165], v250 offset:3072
	ds_read_b128 v[166:169], v250 offset:16384
	ds_read_b128 v[170:173], v250 offset:17408
	ds_read_b128 v[174:177], v250 offset:18432
	ds_read_b128 v[178:181], v250 offset:19456
	s_add_u32 s30, s30, 0x20000
	s_addc_u32 s31, s31, 0
	s_mov_b32 m0, s38
	v_lshl_add_u64 v[230:231], s[30:31], 0, v[130:131]
	ds_read_b128 v[182:185], v149 offset:32768
	ds_read_b128 v[186:189], v149 offset:33792
	ds_read_b128 v[190:193], v149 offset:34816
	ds_read_b128 v[198:201], v149 offset:35840
	ds_read_b128 v[210:213], v149 offset:36864
	ds_read_b128 v[214:217], v149 offset:37888
	ds_read_b128 v[218:221], v149 offset:38912
	ds_read_b128 v[222:225], v149 offset:39936
	global_load_lds_dwordx4 v[230:231], off
	v_lshl_add_u64 v[230:231], s[30:31], 0, v[136:137]
	s_mov_b32 m0, s39
	s_nop 0
	global_load_lds_dwordx4 v[230:231], off
	s_waitcnt vmcnt(8)
	s_waitcnt lgkmcnt(0)
	s_barrier
	s_setprio 1
	s_waitcnt lgkmcnt(0)
	v_mfma_f32_16x16x32_bf16 v[126:129], v[150:153], v[182:185], v[126:129]
	v_mfma_f32_16x16x32_bf16 v[122:125], v[158:161], v[182:185], v[122:125]
	v_mfma_f32_16x16x32_bf16 v[118:121], v[150:153], v[190:193], v[118:121]
	v_mfma_f32_16x16x32_bf16 v[114:117], v[158:161], v[190:193], v[114:117]
	v_mfma_f32_16x16x32_bf16 v[102:105], v[150:153], v[210:213], v[102:105]
	v_mfma_f32_16x16x32_bf16 v[98:101], v[158:161], v[210:213], v[98:101]
	v_mfma_f32_16x16x32_bf16 v[86:89], v[150:153], v[218:221], v[86:89]
	v_mfma_f32_16x16x32_bf16 v[82:85], v[158:161], v[218:221], v[82:85]
	v_mfma_f32_16x16x32_bf16 v[126:129], v[154:157], v[186:189], v[126:129]
	v_mfma_f32_16x16x32_bf16 v[122:125], v[162:165], v[186:189], v[122:125]
	v_mfma_f32_16x16x32_bf16 v[118:121], v[154:157], v[198:201], v[118:121]
	v_mfma_f32_16x16x32_bf16 v[114:117], v[162:165], v[198:201], v[114:117]
	v_mfma_f32_16x16x32_bf16 v[102:105], v[154:157], v[214:217], v[102:105]
	v_mfma_f32_16x16x32_bf16 v[98:101], v[162:165], v[214:217], v[98:101]
	v_mfma_f32_16x16x32_bf16 v[86:89], v[154:157], v[222:225], v[86:89]
	v_mfma_f32_16x16x32_bf16 v[82:85], v[162:165], v[222:225], v[82:85]
	v_mfma_f32_16x16x32_bf16 v[110:113], v[166:169], v[182:185], v[110:113]
	v_mfma_f32_16x16x32_bf16 v[106:109], v[174:177], v[182:185], v[106:109]
	v_mfma_f32_16x16x32_bf16 v[94:97], v[166:169], v[190:193], v[94:97]
	v_mfma_f32_16x16x32_bf16 v[90:93], v[174:177], v[190:193], v[90:93]
	v_mfma_f32_16x16x32_bf16 v[78:81], v[166:169], v[210:213], v[78:81]
	v_mfma_f32_16x16x32_bf16 v[74:77], v[174:177], v[210:213], v[74:77]
	v_mfma_f32_16x16x32_bf16 v[70:73], v[166:169], v[218:221], v[70:73]
	v_mfma_f32_16x16x32_bf16 v[66:69], v[174:177], v[218:221], v[66:69]
	v_mfma_f32_16x16x32_bf16 v[110:113], v[170:173], v[186:189], v[110:113]
	v_mfma_f32_16x16x32_bf16 v[106:109], v[178:181], v[186:189], v[106:109]
	v_mfma_f32_16x16x32_bf16 v[94:97], v[170:173], v[198:201], v[94:97]
	v_mfma_f32_16x16x32_bf16 v[90:93], v[178:181], v[198:201], v[90:93]
	v_mfma_f32_16x16x32_bf16 v[78:81], v[170:173], v[214:217], v[78:81]
	v_mfma_f32_16x16x32_bf16 v[74:77], v[178:181], v[214:217], v[74:77]
	v_mfma_f32_16x16x32_bf16 v[70:73], v[170:173], v[222:225], v[70:73]
	s_barrier
	v_mfma_f32_16x16x32_bf16 v[66:69], v[178:181], v[222:225], v[66:69]
	s_setprio 2
	s_add_i32 s30, s51, s35
	v_lshl_add_u64 v[202:203], v[202:203], 0, s[8:9]
	s_mov_b32 m0, s30
	ds_read_b128 v[182:185], v149 offset:49152
	ds_read_b128 v[186:189], v149 offset:50176
	ds_read_b128 v[190:193], v149 offset:51200
	ds_read_b128 v[198:201], v149 offset:52224
	ds_read_b128 v[210:213], v149 offset:53248
	ds_read_b128 v[214:217], v149 offset:54272
	ds_read_b128 v[218:221], v149 offset:55296
	ds_read_b128 v[222:225], v149 offset:56320
	global_load_lds_dwordx4 v[202:203], off
	s_add_i32 m0, s30, 0x2000
	s_add_u32 s28, s28, 0x20080
	v_lshl_add_u64 v[202:203], v[206:207], 0, s[8:9]
	s_addc_u32 s29, s29, 0
	s_add_i32 s30, s52, s35
	global_load_lds_dwordx4 v[202:203], off
	v_lshl_add_u64 v[202:203], s[28:29], 0, v[132:133]
	s_mov_b32 m0, s30
	s_nop 0
	global_load_lds_dwordx4 v[202:203], off
	v_lshl_add_u64 v[202:203], s[28:29], 0, v[134:135]
	s_add_i32 m0, s30, 0x2000
	s_nop 0
	global_load_lds_dwordx4 v[202:203], off
	v_lshl_add_u64 v[202:203], v[226:227], 0, s[8:9]
	s_mov_b32 m0, s41
	s_nop 0
	global_load_lds_dwordx4 v[202:203], off
	v_lshl_add_u64 v[202:203], v[228:229], 0, s[8:9]
	s_mov_b32 m0, s42
	s_nop 0
	global_load_lds_dwordx4 v[202:203], off
	s_waitcnt vmcnt(8)
	s_waitcnt lgkmcnt(0)
	s_barrier
	s_setprio 1
	s_waitcnt lgkmcnt(0)
	v_mfma_f32_16x16x32_bf16 v[62:65], v[150:153], v[182:185], v[62:65]
	v_mfma_f32_16x16x32_bf16 v[58:61], v[158:161], v[182:185], v[58:61]
	v_mfma_f32_16x16x32_bf16 v[54:57], v[150:153], v[190:193], v[54:57]
	v_mfma_f32_16x16x32_bf16 v[50:53], v[158:161], v[190:193], v[50:53]
	v_mfma_f32_16x16x32_bf16 v[38:41], v[150:153], v[210:213], v[38:41]
	v_mfma_f32_16x16x32_bf16 v[34:37], v[158:161], v[210:213], v[34:37]
	v_mfma_f32_16x16x32_bf16 v[22:25], v[150:153], v[218:221], v[22:25]
	v_mfma_f32_16x16x32_bf16 v[18:21], v[158:161], v[218:221], v[18:21]
	v_mfma_f32_16x16x32_bf16 v[62:65], v[154:157], v[186:189], v[62:65]
	v_mfma_f32_16x16x32_bf16 v[58:61], v[162:165], v[186:189], v[58:61]
	v_mfma_f32_16x16x32_bf16 v[54:57], v[154:157], v[198:201], v[54:57]
	v_mfma_f32_16x16x32_bf16 v[50:53], v[162:165], v[198:201], v[50:53]
	v_mfma_f32_16x16x32_bf16 v[38:41], v[154:157], v[214:217], v[38:41]
	v_mfma_f32_16x16x32_bf16 v[34:37], v[162:165], v[214:217], v[34:37]
	v_mfma_f32_16x16x32_bf16 v[22:25], v[154:157], v[222:225], v[22:25]
	v_mfma_f32_16x16x32_bf16 v[18:21], v[162:165], v[222:225], v[18:21]
	v_mfma_f32_16x16x32_bf16 v[46:49], v[166:169], v[182:185], v[46:49]
	v_mfma_f32_16x16x32_bf16 v[42:45], v[174:177], v[182:185], v[42:45]
	v_mfma_f32_16x16x32_bf16 v[30:33], v[166:169], v[190:193], v[30:33]
	v_mfma_f32_16x16x32_bf16 v[26:29], v[174:177], v[190:193], v[26:29]
	v_mfma_f32_16x16x32_bf16 v[14:17], v[166:169], v[210:213], v[14:17]
	v_mfma_f32_16x16x32_bf16 v[10:13], v[174:177], v[210:213], v[10:13]
	v_mfma_f32_16x16x32_bf16 v[6:9], v[166:169], v[218:221], v[6:9]
	v_mfma_f32_16x16x32_bf16 v[2:5], v[174:177], v[218:221], v[2:5]
	v_mfma_f32_16x16x32_bf16 v[46:49], v[170:173], v[186:189], v[46:49]
	v_mfma_f32_16x16x32_bf16 v[42:45], v[178:181], v[186:189], v[42:45]
	v_mfma_f32_16x16x32_bf16 v[30:33], v[170:173], v[198:201], v[30:33]
	v_mfma_f32_16x16x32_bf16 v[26:29], v[178:181], v[198:201], v[26:29]
	v_mfma_f32_16x16x32_bf16 v[14:17], v[170:173], v[214:217], v[14:17]
	v_mfma_f32_16x16x32_bf16 v[10:13], v[178:181], v[214:217], v[10:13]
	v_mfma_f32_16x16x32_bf16 v[6:9], v[170:173], v[222:225], v[6:9]
	s_barrier
	v_mfma_f32_16x16x32_bf16 v[2:5], v[178:181], v[222:225], v[2:5]
	s_setprio 2
	s_add_i32 s50, s50, 2
	s_add_u32 s26, s26, 0x100
	s_addc_u32 s27, s27, 0
	s_add_u32 s48, s48, 0x100
	s_addc_u32 s49, s49, 0
	s_cmp_gt_u32 s50, 5
	s_cbranch_scc0 .LBB0_690
	s_branch .Lpeeldone_10
.LBB0_690:
	ds_read_b128 v[150:153], v147
	ds_read_b128 v[154:157], v147 offset:1024
	ds_read_b128 v[158:161], v147 offset:2048
	ds_read_b128 v[162:165], v147 offset:3072
	ds_read_b128 v[166:169], v148
	ds_read_b128 v[170:173], v148 offset:1024
	ds_read_b128 v[174:177], v148 offset:2048
	ds_read_b128 v[178:181], v148 offset:3072
	s_add_u32 s28, s26, 0xfffe0080
	s_addc_u32 s29, s27, -1
	s_cmp_eq_u32 s50, 4
	s_cselect_b32 s31, s13, s29
	s_cselect_b32 s30, s46, s28
	s_cselect_b32 s29, s17, s49
	s_cselect_b32 s28, s47, s48
	v_lshl_add_u64 v[202:203], s[26:27], 0, v[138:139]
	s_add_i32 m0, s36, 0xc000
	ds_read_b128 v[182:185], v149
	ds_read_b128 v[186:189], v149 offset:1024
	ds_read_b128 v[190:193], v149 offset:2048
	ds_read_b128 v[198:201], v149 offset:3072
	ds_read_b128 v[210:213], v149 offset:4096
	ds_read_b128 v[214:217], v149 offset:5120
	ds_read_b128 v[218:221], v149 offset:6144
	ds_read_b128 v[222:225], v149 offset:7168
	global_load_lds_dwordx4 v[202:203], off
	v_lshl_add_u64 v[202:203], s[26:27], 0, v[140:141]
	s_add_i32 m0, s36, 0xe000
	s_nop 0
	global_load_lds_dwordx4 v[202:203], off
	s_waitcnt vmcnt(8)
	s_waitcnt lgkmcnt(0)
	s_barrier
	s_setprio 1
	s_waitcnt lgkmcnt(0)
	v_mfma_f32_16x16x32_bf16 v[126:129], v[150:153], v[182:185], v[126:129]
	v_mfma_f32_16x16x32_bf16 v[122:125], v[158:161], v[182:185], v[122:125]
	v_mfma_f32_16x16x32_bf16 v[118:121], v[150:153], v[190:193], v[118:121]
	v_mfma_f32_16x16x32_bf16 v[114:117], v[158:161], v[190:193], v[114:117]
	v_mfma_f32_16x16x32_bf16 v[102:105], v[150:153], v[210:213], v[102:105]
	v_mfma_f32_16x16x32_bf16 v[98:101], v[158:161], v[210:213], v[98:101]
	v_mfma_f32_16x16x32_bf16 v[86:89], v[150:153], v[218:221], v[86:89]
	v_mfma_f32_16x16x32_bf16 v[82:85], v[158:161], v[218:221], v[82:85]
	v_mfma_f32_16x16x32_bf16 v[126:129], v[154:157], v[186:189], v[126:129]
	v_mfma_f32_16x16x32_bf16 v[122:125], v[162:165], v[186:189], v[122:125]
	v_mfma_f32_16x16x32_bf16 v[118:121], v[154:157], v[198:201], v[118:121]
	v_mfma_f32_16x16x32_bf16 v[114:117], v[162:165], v[198:201], v[114:117]
	v_mfma_f32_16x16x32_bf16 v[102:105], v[154:157], v[214:217], v[102:105]
	v_mfma_f32_16x16x32_bf16 v[98:101], v[162:165], v[214:217], v[98:101]
	v_mfma_f32_16x16x32_bf16 v[86:89], v[154:157], v[222:225], v[86:89]
	v_mfma_f32_16x16x32_bf16 v[82:85], v[162:165], v[222:225], v[82:85]
	v_mfma_f32_16x16x32_bf16 v[110:113], v[166:169], v[182:185], v[110:113]
	v_mfma_f32_16x16x32_bf16 v[106:109], v[174:177], v[182:185], v[106:109]
	v_mfma_f32_16x16x32_bf16 v[94:97], v[166:169], v[190:193], v[94:97]
	v_mfma_f32_16x16x32_bf16 v[90:93], v[174:177], v[190:193], v[90:93]
	v_mfma_f32_16x16x32_bf16 v[78:81], v[166:169], v[210:213], v[78:81]
	v_mfma_f32_16x16x32_bf16 v[74:77], v[174:177], v[210:213], v[74:77]
	v_mfma_f32_16x16x32_bf16 v[70:73], v[166:169], v[218:221], v[70:73]
	v_mfma_f32_16x16x32_bf16 v[66:69], v[174:177], v[218:221], v[66:69]
	v_mfma_f32_16x16x32_bf16 v[110:113], v[170:173], v[186:189], v[110:113]
	v_mfma_f32_16x16x32_bf16 v[106:109], v[178:181], v[186:189], v[106:109]
	v_mfma_f32_16x16x32_bf16 v[94:97], v[170:173], v[198:201], v[94:97]
	v_mfma_f32_16x16x32_bf16 v[90:93], v[178:181], v[198:201], v[90:93]
	v_mfma_f32_16x16x32_bf16 v[78:81], v[170:173], v[214:217], v[78:81]
	v_mfma_f32_16x16x32_bf16 v[74:77], v[178:181], v[214:217], v[74:77]
	v_mfma_f32_16x16x32_bf16 v[70:73], v[170:173], v[222:225], v[70:73]
	s_barrier
	v_mfma_f32_16x16x32_bf16 v[66:69], v[178:181], v[222:225], v[66:69]
	s_setprio 2
	s_add_i32 s51, s43, s35
	v_lshl_add_u64 v[202:203], s[28:29], 0, v[132:133]
	s_mov_b32 m0, s51
	ds_read_b128 v[182:185], v149 offset:16384
	ds_read_b128 v[186:189], v149 offset:17408
	ds_read_b128 v[190:193], v149 offset:18432
	ds_read_b128 v[198:201], v149 offset:19456
	ds_read_b128 v[210:213], v149 offset:20480
	ds_read_b128 v[214:217], v149 offset:21504
	ds_read_b128 v[218:221], v149 offset:22528
	ds_read_b128 v[222:225], v149 offset:23552
	global_load_lds_dwordx4 v[202:203], off
	s_add_i32 m0, s51, 0x2000
	s_add_u32 s52, s28, 0x20000
	v_lshl_add_u64 v[206:207], s[28:29], 0, v[134:135]
	s_addc_u32 s53, s29, 0
	s_add_i32 s51, s44, s35
	global_load_lds_dwordx4 v[206:207], off
	v_lshl_add_u64 v[226:227], s[52:53], 0, v[132:133]
	s_mov_b32 m0, s51
	v_lshl_add_u64 v[228:229], s[30:31], 0, v[136:137]
	global_load_lds_dwordx4 v[226:227], off
	v_lshl_add_u64 v[226:227], s[52:53], 0, v[134:135]
	s_add_i32 m0, s51, 0x2000
	s_nop 0
	global_load_lds_dwordx4 v[226:227], off
	v_lshl_add_u64 v[226:227], s[30:31], 0, v[130:131]
	s_mov_b32 m0, s36
	s_nop 0
	global_load_lds_dwordx4 v[226:227], off
	s_mov_b32 m0, s37
	s_nop 0
	global_load_lds_dwordx4 v[228:229], off
	s_waitcnt vmcnt(8)
	s_waitcnt lgkmcnt(0)
	s_barrier
	s_setprio 1
	s_waitcnt lgkmcnt(0)
	v_mfma_f32_16x16x32_bf16 v[62:65], v[150:153], v[182:185], v[62:65]
	v_mfma_f32_16x16x32_bf16 v[58:61], v[158:161], v[182:185], v[58:61]
	v_mfma_f32_16x16x32_bf16 v[54:57], v[150:153], v[190:193], v[54:57]
	v_mfma_f32_16x16x32_bf16 v[50:53], v[158:161], v[190:193], v[50:53]
	v_mfma_f32_16x16x32_bf16 v[38:41], v[150:153], v[210:213], v[38:41]
	v_mfma_f32_16x16x32_bf16 v[34:37], v[158:161], v[210:213], v[34:37]
	v_mfma_f32_16x16x32_bf16 v[22:25], v[150:153], v[218:221], v[22:25]
	v_mfma_f32_16x16x32_bf16 v[18:21], v[158:161], v[218:221], v[18:21]
	v_mfma_f32_16x16x32_bf16 v[62:65], v[154:157], v[186:189], v[62:65]
	v_mfma_f32_16x16x32_bf16 v[58:61], v[162:165], v[186:189], v[58:61]
	v_mfma_f32_16x16x32_bf16 v[54:57], v[154:157], v[198:201], v[54:57]
	v_mfma_f32_16x16x32_bf16 v[50:53], v[162:165], v[198:201], v[50:53]
	v_mfma_f32_16x16x32_bf16 v[38:41], v[154:157], v[214:217], v[38:41]
	v_mfma_f32_16x16x32_bf16 v[34:37], v[162:165], v[214:217], v[34:37]
	v_mfma_f32_16x16x32_bf16 v[22:25], v[154:157], v[222:225], v[22:25]
	v_mfma_f32_16x16x32_bf16 v[18:21], v[162:165], v[222:225], v[18:21]
	v_mfma_f32_16x16x32_bf16 v[46:49], v[166:169], v[182:185], v[46:49]
	v_mfma_f32_16x16x32_bf16 v[42:45], v[174:177], v[182:185], v[42:45]
	v_mfma_f32_16x16x32_bf16 v[30:33], v[166:169], v[190:193], v[30:33]
	v_mfma_f32_16x16x32_bf16 v[26:29], v[174:177], v[190:193], v[26:29]
	v_mfma_f32_16x16x32_bf16 v[14:17], v[166:169], v[210:213], v[14:17]
	v_mfma_f32_16x16x32_bf16 v[10:13], v[174:177], v[210:213], v[10:13]
	v_mfma_f32_16x16x32_bf16 v[6:9], v[166:169], v[218:221], v[6:9]
	v_mfma_f32_16x16x32_bf16 v[2:5], v[174:177], v[218:221], v[2:5]
	v_mfma_f32_16x16x32_bf16 v[46:49], v[170:173], v[186:189], v[46:49]
	v_mfma_f32_16x16x32_bf16 v[42:45], v[178:181], v[186:189], v[42:45]
	v_mfma_f32_16x16x32_bf16 v[30:33], v[170:173], v[198:201], v[30:33]
	v_mfma_f32_16x16x32_bf16 v[26:29], v[178:181], v[198:201], v[26:29]
	v_mfma_f32_16x16x32_bf16 v[14:17], v[170:173], v[214:217], v[14:17]
	v_mfma_f32_16x16x32_bf16 v[10:13], v[178:181], v[214:217], v[10:13]
	v_mfma_f32_16x16x32_bf16 v[6:9], v[170:173], v[222:225], v[6:9]
	s_barrier
	v_mfma_f32_16x16x32_bf16 v[2:5], v[178:181], v[222:225], v[2:5]
	s_setprio 2
	s_add_i32 s51, 0, 0x18000
	s_add_i32 s52, 0, 0x1c000
	ds_read_b128 v[150:153], v250
	ds_read_b128 v[154:157], v250 offset:1024
	ds_read_b128 v[158:161], v250 offset:2048
	ds_read_b128 v[162:165], v250 offset:3072
	ds_read_b128 v[166:169], v250 offset:16384
	ds_read_b128 v[170:173], v250 offset:17408
	ds_read_b128 v[174:177], v250 offset:18432
	ds_read_b128 v[178:181], v250 offset:19456
	s_add_u32 s30, s30, 0x20000
	s_addc_u32 s31, s31, 0
	s_mov_b32 m0, s38
	v_lshl_add_u64 v[230:231], s[30:31], 0, v[130:131]
	ds_read_b128 v[182:185], v149 offset:32768
	ds_read_b128 v[186:189], v149 offset:33792
	ds_read_b128 v[190:193], v149 offset:34816
	ds_read_b128 v[198:201], v149 offset:35840
	ds_read_b128 v[210:213], v149 offset:36864
	ds_read_b128 v[214:217], v149 offset:37888
	ds_read_b128 v[218:221], v149 offset:38912
	ds_read_b128 v[222:225], v149 offset:39936
	global_load_lds_dwordx4 v[230:231], off
	v_lshl_add_u64 v[230:231], s[30:31], 0, v[136:137]
	s_mov_b32 m0, s39
	s_nop 0
	global_load_lds_dwordx4 v[230:231], off
	s_waitcnt vmcnt(8)
	s_waitcnt lgkmcnt(0)
	s_barrier
	s_setprio 1
	s_waitcnt lgkmcnt(0)
	v_mfma_f32_16x16x32_bf16 v[126:129], v[150:153], v[182:185], v[126:129]
	v_mfma_f32_16x16x32_bf16 v[122:125], v[158:161], v[182:185], v[122:125]
	v_mfma_f32_16x16x32_bf16 v[118:121], v[150:153], v[190:193], v[118:121]
	v_mfma_f32_16x16x32_bf16 v[114:117], v[158:161], v[190:193], v[114:117]
	v_mfma_f32_16x16x32_bf16 v[102:105], v[150:153], v[210:213], v[102:105]
	v_mfma_f32_16x16x32_bf16 v[98:101], v[158:161], v[210:213], v[98:101]
	v_mfma_f32_16x16x32_bf16 v[86:89], v[150:153], v[218:221], v[86:89]
	v_mfma_f32_16x16x32_bf16 v[82:85], v[158:161], v[218:221], v[82:85]
	v_mfma_f32_16x16x32_bf16 v[126:129], v[154:157], v[186:189], v[126:129]
	v_mfma_f32_16x16x32_bf16 v[122:125], v[162:165], v[186:189], v[122:125]
	v_mfma_f32_16x16x32_bf16 v[118:121], v[154:157], v[198:201], v[118:121]
	v_mfma_f32_16x16x32_bf16 v[114:117], v[162:165], v[198:201], v[114:117]
	v_mfma_f32_16x16x32_bf16 v[102:105], v[154:157], v[214:217], v[102:105]
	v_mfma_f32_16x16x32_bf16 v[98:101], v[162:165], v[214:217], v[98:101]
	v_mfma_f32_16x16x32_bf16 v[86:89], v[154:157], v[222:225], v[86:89]
	v_mfma_f32_16x16x32_bf16 v[82:85], v[162:165], v[222:225], v[82:85]
	v_mfma_f32_16x16x32_bf16 v[110:113], v[166:169], v[182:185], v[110:113]
	v_mfma_f32_16x16x32_bf16 v[106:109], v[174:177], v[182:185], v[106:109]
	v_mfma_f32_16x16x32_bf16 v[94:97], v[166:169], v[190:193], v[94:97]
	v_mfma_f32_16x16x32_bf16 v[90:93], v[174:177], v[190:193], v[90:93]
	v_mfma_f32_16x16x32_bf16 v[78:81], v[166:169], v[210:213], v[78:81]
	v_mfma_f32_16x16x32_bf16 v[74:77], v[174:177], v[210:213], v[74:77]
	v_mfma_f32_16x16x32_bf16 v[70:73], v[166:169], v[218:221], v[70:73]
	v_mfma_f32_16x16x32_bf16 v[66:69], v[174:177], v[218:221], v[66:69]
	v_mfma_f32_16x16x32_bf16 v[110:113], v[170:173], v[186:189], v[110:113]
	v_mfma_f32_16x16x32_bf16 v[106:109], v[178:181], v[186:189], v[106:109]
	v_mfma_f32_16x16x32_bf16 v[94:97], v[170:173], v[198:201], v[94:97]
	v_mfma_f32_16x16x32_bf16 v[90:93], v[178:181], v[198:201], v[90:93]
	v_mfma_f32_16x16x32_bf16 v[78:81], v[170:173], v[214:217], v[78:81]
	v_mfma_f32_16x16x32_bf16 v[74:77], v[178:181], v[214:217], v[74:77]
	v_mfma_f32_16x16x32_bf16 v[70:73], v[170:173], v[222:225], v[70:73]
	s_barrier
	v_mfma_f32_16x16x32_bf16 v[66:69], v[178:181], v[222:225], v[66:69]
	s_setprio 2
	s_add_i32 s30, s51, s35
	v_lshl_add_u64 v[202:203], v[202:203], 0, s[8:9]
	s_mov_b32 m0, s30
	ds_read_b128 v[182:185], v149 offset:49152
	ds_read_b128 v[186:189], v149 offset:50176
	ds_read_b128 v[190:193], v149 offset:51200
	ds_read_b128 v[198:201], v149 offset:52224
	ds_read_b128 v[210:213], v149 offset:53248
	ds_read_b128 v[214:217], v149 offset:54272
	ds_read_b128 v[218:221], v149 offset:55296
	ds_read_b128 v[222:225], v149 offset:56320
	global_load_lds_dwordx4 v[202:203], off
	s_add_i32 m0, s30, 0x2000
	s_add_u32 s28, s28, 0x20080
	v_lshl_add_u64 v[202:203], v[206:207], 0, s[8:9]
	s_addc_u32 s29, s29, 0
	s_add_i32 s30, s52, s35
	global_load_lds_dwordx4 v[202:203], off
	v_lshl_add_u64 v[202:203], s[28:29], 0, v[132:133]
	s_mov_b32 m0, s30
	s_nop 0
	global_load_lds_dwordx4 v[202:203], off
	v_lshl_add_u64 v[202:203], s[28:29], 0, v[134:135]
	s_add_i32 m0, s30, 0x2000
	s_nop 0
	global_load_lds_dwordx4 v[202:203], off
	v_lshl_add_u64 v[202:203], v[226:227], 0, s[8:9]
	s_mov_b32 m0, s41
	s_nop 0
	global_load_lds_dwordx4 v[202:203], off
	v_lshl_add_u64 v[202:203], v[228:229], 0, s[8:9]
	s_mov_b32 m0, s42
	s_nop 0
	global_load_lds_dwordx4 v[202:203], off
	s_waitcnt vmcnt(8)
	s_waitcnt lgkmcnt(0)
	s_barrier
	s_setprio 1
	s_waitcnt lgkmcnt(0)
	v_mfma_f32_16x16x32_bf16 v[62:65], v[150:153], v[182:185], v[62:65]
	v_mfma_f32_16x16x32_bf16 v[58:61], v[158:161], v[182:185], v[58:61]
	v_mfma_f32_16x16x32_bf16 v[54:57], v[150:153], v[190:193], v[54:57]
	v_mfma_f32_16x16x32_bf16 v[50:53], v[158:161], v[190:193], v[50:53]
	v_mfma_f32_16x16x32_bf16 v[38:41], v[150:153], v[210:213], v[38:41]
	v_mfma_f32_16x16x32_bf16 v[34:37], v[158:161], v[210:213], v[34:37]
	v_mfma_f32_16x16x32_bf16 v[22:25], v[150:153], v[218:221], v[22:25]
	v_mfma_f32_16x16x32_bf16 v[18:21], v[158:161], v[218:221], v[18:21]
	v_mfma_f32_16x16x32_bf16 v[62:65], v[154:157], v[186:189], v[62:65]
	v_mfma_f32_16x16x32_bf16 v[58:61], v[162:165], v[186:189], v[58:61]
	v_mfma_f32_16x16x32_bf16 v[54:57], v[154:157], v[198:201], v[54:57]
	v_mfma_f32_16x16x32_bf16 v[50:53], v[162:165], v[198:201], v[50:53]
	v_mfma_f32_16x16x32_bf16 v[38:41], v[154:157], v[214:217], v[38:41]
	v_mfma_f32_16x16x32_bf16 v[34:37], v[162:165], v[214:217], v[34:37]
	v_mfma_f32_16x16x32_bf16 v[22:25], v[154:157], v[222:225], v[22:25]
	v_mfma_f32_16x16x32_bf16 v[18:21], v[162:165], v[222:225], v[18:21]
	v_mfma_f32_16x16x32_bf16 v[46:49], v[166:169], v[182:185], v[46:49]
	v_mfma_f32_16x16x32_bf16 v[42:45], v[174:177], v[182:185], v[42:45]
	v_mfma_f32_16x16x32_bf16 v[30:33], v[166:169], v[190:193], v[30:33]
	v_mfma_f32_16x16x32_bf16 v[26:29], v[174:177], v[190:193], v[26:29]
	v_mfma_f32_16x16x32_bf16 v[14:17], v[166:169], v[210:213], v[14:17]
	v_mfma_f32_16x16x32_bf16 v[10:13], v[174:177], v[210:213], v[10:13]
	v_mfma_f32_16x16x32_bf16 v[6:9], v[166:169], v[218:221], v[6:9]
	v_mfma_f32_16x16x32_bf16 v[2:5], v[174:177], v[218:221], v[2:5]
	v_mfma_f32_16x16x32_bf16 v[46:49], v[170:173], v[186:189], v[46:49]
	v_mfma_f32_16x16x32_bf16 v[42:45], v[178:181], v[186:189], v[42:45]
	v_mfma_f32_16x16x32_bf16 v[30:33], v[170:173], v[198:201], v[30:33]
	v_mfma_f32_16x16x32_bf16 v[26:29], v[178:181], v[198:201], v[26:29]
	v_mfma_f32_16x16x32_bf16 v[14:17], v[170:173], v[214:217], v[14:17]
	v_mfma_f32_16x16x32_bf16 v[10:13], v[178:181], v[214:217], v[10:13]
	v_mfma_f32_16x16x32_bf16 v[6:9], v[170:173], v[222:225], v[6:9]
	s_barrier
	v_mfma_f32_16x16x32_bf16 v[2:5], v[178:181], v[222:225], v[2:5]
	s_setprio 2
	s_add_i32 s50, s50, 2
	s_add_u32 s26, s26, 0x100
	s_addc_u32 s27, s27, 0
	s_add_u32 s48, s48, 0x100
	s_addc_u32 s49, s49, 0
	s_cmp_gt_u32 s50, 5
	s_cbranch_scc0 .LBB0_690

.Lpeel_9:
	v_add_u32_e32 v250, 0x18000, v139
	ds_read_b128 v[144:147], v140
	ds_read_b128 v[148:151], v140 offset:1024
	s_add_u32 s36, s34, 0xfffe0080
	s_addc_u32 s37, s35, -1
	s_cmp_eq_u32 s59, 4
	s_cselect_b32 s39, s21, s37
	s_cselect_b32 s38, s55, s36
	s_cselect_b32 s37, s25, s58
	s_cselect_b32 s36, s56, s57
	v_lshl_add_u64 v[192:193], s[34:35], 0, v[130:131]
	s_add_i32 m0, s27, 0xc000
	global_load_lds_dwordx4 v[192:193], off
	v_lshl_add_u64 v[192:193], s[34:35], 0, v[136:137]
	s_add_i32 m0, s27, 0xe000
	s_nop 0
	global_load_lds_dwordx4 v[192:193], off
	s_waitcnt vmcnt(8)
	s_waitcnt lgkmcnt(0)
	s_barrier
	s_setprio 1
	s_waitcnt lgkmcnt(0)
	v_mfma_f32_16x16x32_bf16 v[126:129], v[144:147], v[176:179], 0
	v_mfma_f32_16x16x32_bf16 v[122:125], v[152:155], v[176:179], 0
	v_mfma_f32_16x16x32_bf16 v[118:121], v[144:147], v[184:187], 0
	v_mfma_f32_16x16x32_bf16 v[114:117], v[152:155], v[184:187], 0
	v_mfma_f32_16x16x32_bf16 v[102:105], v[144:147], v[198:201], 0
	v_mfma_f32_16x16x32_bf16 v[98:101], v[152:155], v[198:201], 0
	v_mfma_f32_16x16x32_bf16 v[86:89], v[144:147], v[214:217], 0
	v_mfma_f32_16x16x32_bf16 v[82:85], v[152:155], v[214:217], 0
	v_mfma_f32_16x16x32_bf16 v[126:129], v[148:151], v[180:183], v[126:129]
	v_mfma_f32_16x16x32_bf16 v[122:125], v[156:159], v[180:183], v[122:125]
	v_mfma_f32_16x16x32_bf16 v[118:121], v[148:151], v[188:191], v[118:121]
	v_mfma_f32_16x16x32_bf16 v[114:117], v[156:159], v[188:191], v[114:117]
	v_mfma_f32_16x16x32_bf16 v[102:105], v[148:151], v[210:213], v[102:105]
	v_mfma_f32_16x16x32_bf16 v[98:101], v[156:159], v[210:213], v[98:101]
	v_mfma_f32_16x16x32_bf16 v[86:89], v[148:151], v[218:221], v[86:89]
	v_mfma_f32_16x16x32_bf16 v[82:85], v[156:159], v[218:221], v[82:85]
	v_mfma_f32_16x16x32_bf16 v[110:113], v[160:163], v[176:179], 0
	v_mfma_f32_16x16x32_bf16 v[106:109], v[168:171], v[176:179], 0
	v_mfma_f32_16x16x32_bf16 v[94:97], v[160:163], v[184:187], 0
	v_mfma_f32_16x16x32_bf16 v[90:93], v[168:171], v[184:187], 0
	v_mfma_f32_16x16x32_bf16 v[78:81], v[160:163], v[198:201], 0
	v_mfma_f32_16x16x32_bf16 v[74:77], v[168:171], v[198:201], 0
	v_mfma_f32_16x16x32_bf16 v[70:73], v[160:163], v[214:217], 0
	v_mfma_f32_16x16x32_bf16 v[66:69], v[168:171], v[214:217], 0
	v_mfma_f32_16x16x32_bf16 v[110:113], v[164:167], v[180:183], v[110:113]
	v_mfma_f32_16x16x32_bf16 v[106:109], v[172:175], v[180:183], v[106:109]
	v_mfma_f32_16x16x32_bf16 v[94:97], v[164:167], v[188:191], v[94:97]
	v_mfma_f32_16x16x32_bf16 v[90:93], v[172:175], v[188:191], v[90:93]
	v_mfma_f32_16x16x32_bf16 v[78:81], v[164:167], v[210:213], v[78:81]
	v_mfma_f32_16x16x32_bf16 v[74:77], v[172:175], v[210:213], v[74:77]
	v_mfma_f32_16x16x32_bf16 v[70:73], v[164:167], v[218:221], v[70:73]
	s_barrier
	v_mfma_f32_16x16x32_bf16 v[66:69], v[172:175], v[218:221], v[66:69]
	s_setprio 2
	s_add_i32 s60, s48, s41
	v_lshl_add_u64 v[192:193], s[36:37], 0, v[132:133]
	s_mov_b32 m0, s60
	ds_read_b128 v[176:179], v142 offset:16384
	ds_read_b128 v[180:183], v142 offset:17408
	ds_read_b128 v[184:187], v142 offset:18432
	ds_read_b128 v[188:191], v142 offset:19456
	ds_read_b128 v[198:201], v142 offset:20480
	ds_read_b128 v[210:213], v142 offset:21504
	ds_read_b128 v[214:217], v142 offset:22528
	ds_read_b128 v[218:221], v142 offset:23552
	global_load_lds_dwordx4 v[192:193], off
	s_add_i32 m0, s60, 0x2000
	s_add_u32 s60, s36, 0x20000
	v_lshl_add_u64 v[202:203], s[36:37], 0, v[134:135]
	s_addc_u32 s61, s37, 0
	s_add_i32 s62, s49, s41
	global_load_lds_dwordx4 v[202:203], off
	v_lshl_add_u64 v[206:207], s[60:61], 0, v[132:133]
	s_mov_b32 m0, s62
	v_lshl_add_u64 v[222:223], s[38:39], 0, v[136:137]
	global_load_lds_dwordx4 v[206:207], off
	v_lshl_add_u64 v[206:207], s[60:61], 0, v[134:135]
	s_add_i32 m0, s62, 0x2000
	s_nop 0
	global_load_lds_dwordx4 v[206:207], off
	v_lshl_add_u64 v[206:207], s[38:39], 0, v[130:131]
	s_mov_b32 m0, s27
	s_nop 0
	global_load_lds_dwordx4 v[206:207], off
	s_mov_b32 m0, s42
	s_nop 0
	global_load_lds_dwordx4 v[222:223], off
	s_waitcnt vmcnt(8)
	s_waitcnt lgkmcnt(0)
	s_barrier
	s_setprio 1
	s_waitcnt lgkmcnt(0)
	v_mfma_f32_16x16x32_bf16 v[62:65], v[144:147], v[176:179], 0
	v_mfma_f32_16x16x32_bf16 v[58:61], v[152:155], v[176:179], 0
	v_mfma_f32_16x16x32_bf16 v[54:57], v[144:147], v[184:187], 0
	v_mfma_f32_16x16x32_bf16 v[50:53], v[152:155], v[184:187], 0
	v_mfma_f32_16x16x32_bf16 v[38:41], v[144:147], v[198:201], 0
	v_mfma_f32_16x16x32_bf16 v[34:37], v[152:155], v[198:201], 0
	v_mfma_f32_16x16x32_bf16 v[22:25], v[144:147], v[214:217], 0
	v_mfma_f32_16x16x32_bf16 v[18:21], v[152:155], v[214:217], 0
	v_mfma_f32_16x16x32_bf16 v[62:65], v[148:151], v[180:183], v[62:65]
	v_mfma_f32_16x16x32_bf16 v[58:61], v[156:159], v[180:183], v[58:61]
	v_mfma_f32_16x16x32_bf16 v[54:57], v[148:151], v[188:191], v[54:57]
	v_mfma_f32_16x16x32_bf16 v[50:53], v[156:159], v[188:191], v[50:53]
	v_mfma_f32_16x16x32_bf16 v[38:41], v[148:151], v[210:213], v[38:41]
	v_mfma_f32_16x16x32_bf16 v[34:37], v[156:159], v[210:213], v[34:37]
	v_mfma_f32_16x16x32_bf16 v[22:25], v[148:151], v[218:221], v[22:25]
	v_mfma_f32_16x16x32_bf16 v[18:21], v[156:159], v[218:221], v[18:21]
	v_mfma_f32_16x16x32_bf16 v[46:49], v[160:163], v[176:179], 0
	v_mfma_f32_16x16x32_bf16 v[42:45], v[168:171], v[176:179], 0
	v_mfma_f32_16x16x32_bf16 v[30:33], v[160:163], v[184:187], 0
	v_mfma_f32_16x16x32_bf16 v[26:29], v[168:171], v[184:187], 0
	v_mfma_f32_16x16x32_bf16 v[14:17], v[160:163], v[198:201], 0
	v_mfma_f32_16x16x32_bf16 v[10:13], v[168:171], v[198:201], 0
	v_mfma_f32_16x16x32_bf16 v[6:9], v[160:163], v[214:217], 0
	v_mfma_f32_16x16x32_bf16 v[2:5], v[168:171], v[214:217], 0
	v_mfma_f32_16x16x32_bf16 v[46:49], v[164:167], v[180:183], v[46:49]
	v_mfma_f32_16x16x32_bf16 v[42:45], v[172:175], v[180:183], v[42:45]
	v_mfma_f32_16x16x32_bf16 v[30:33], v[164:167], v[188:191], v[30:33]
	v_mfma_f32_16x16x32_bf16 v[26:29], v[172:175], v[188:191], v[26:29]
	v_mfma_f32_16x16x32_bf16 v[14:17], v[164:167], v[210:213], v[14:17]
	v_mfma_f32_16x16x32_bf16 v[10:13], v[172:175], v[210:213], v[10:13]
	v_mfma_f32_16x16x32_bf16 v[6:9], v[164:167], v[218:221], v[6:9]
	s_barrier
	v_mfma_f32_16x16x32_bf16 v[2:5], v[172:175], v[218:221], v[2:5]
	s_setprio 2
	s_add_i32 s60, 0, 0x18000
	s_add_i32 s61, 0, 0x1c000
	ds_read_b128 v[144:147], v250
	ds_read_b128 v[148:151], v250 offset:1024
	ds_read_b128 v[152:155], v250 offset:2048
	ds_read_b128 v[156:159], v250 offset:3072
	ds_read_b128 v[160:163], v250 offset:16384
	ds_read_b128 v[164:167], v250 offset:17408
	ds_read_b128 v[168:171], v250 offset:18432
	ds_read_b128 v[172:175], v250 offset:19456
	v_add_u32_e32 v143, s61, v139
	s_add_u32 s38, s38, 0x20000
	s_addc_u32 s39, s39, 0
	s_mov_b32 m0, s43
	v_lshl_add_u64 v[224:225], s[38:39], 0, v[130:131]
	ds_read_b128 v[176:179], v142 offset:32768
	ds_read_b128 v[180:183], v142 offset:33792
	ds_read_b128 v[184:187], v142 offset:34816
	ds_read_b128 v[188:191], v142 offset:35840
	ds_read_b128 v[198:201], v142 offset:36864
	ds_read_b128 v[210:213], v142 offset:37888
	ds_read_b128 v[214:217], v142 offset:38912
	ds_read_b128 v[218:221], v142 offset:39936
	global_load_lds_dwordx4 v[224:225], off
	v_lshl_add_u64 v[224:225], s[38:39], 0, v[136:137]
	s_mov_b32 m0, s44
	s_nop 0
	global_load_lds_dwordx4 v[224:225], off
	s_waitcnt vmcnt(8)
	s_waitcnt lgkmcnt(0)
	s_barrier
	s_setprio 1
	s_waitcnt lgkmcnt(0)
	v_mfma_f32_16x16x32_bf16 v[126:129], v[144:147], v[176:179], v[126:129]
	v_mfma_f32_16x16x32_bf16 v[122:125], v[152:155], v[176:179], v[122:125]
	v_mfma_f32_16x16x32_bf16 v[118:121], v[144:147], v[184:187], v[118:121]
	v_mfma_f32_16x16x32_bf16 v[114:117], v[152:155], v[184:187], v[114:117]
	v_mfma_f32_16x16x32_bf16 v[102:105], v[144:147], v[198:201], v[102:105]
	v_mfma_f32_16x16x32_bf16 v[98:101], v[152:155], v[198:201], v[98:101]
	v_mfma_f32_16x16x32_bf16 v[86:89], v[144:147], v[214:217], v[86:89]
	v_mfma_f32_16x16x32_bf16 v[82:85], v[152:155], v[214:217], v[82:85]
	v_mfma_f32_16x16x32_bf16 v[126:129], v[148:151], v[180:183], v[126:129]
	v_mfma_f32_16x16x32_bf16 v[122:125], v[156:159], v[180:183], v[122:125]
	v_mfma_f32_16x16x32_bf16 v[118:121], v[148:151], v[188:191], v[118:121]
	v_mfma_f32_16x16x32_bf16 v[114:117], v[156:159], v[188:191], v[114:117]
	v_mfma_f32_16x16x32_bf16 v[102:105], v[148:151], v[210:213], v[102:105]
	v_mfma_f32_16x16x32_bf16 v[98:101], v[156:159], v[210:213], v[98:101]
	v_mfma_f32_16x16x32_bf16 v[86:89], v[148:151], v[218:221], v[86:89]
	v_mfma_f32_16x16x32_bf16 v[82:85], v[156:159], v[218:221], v[82:85]
	v_mfma_f32_16x16x32_bf16 v[110:113], v[160:163], v[176:179], v[110:113]
	v_mfma_f32_16x16x32_bf16 v[106:109], v[168:171], v[176:179], v[106:109]
	v_mfma_f32_16x16x32_bf16 v[94:97], v[160:163], v[184:187], v[94:97]
	v_mfma_f32_16x16x32_bf16 v[90:93], v[168:171], v[184:187], v[90:93]
	v_mfma_f32_16x16x32_bf16 v[78:81], v[160:163], v[198:201], v[78:81]
	v_mfma_f32_16x16x32_bf16 v[74:77], v[168:171], v[198:201], v[74:77]
	v_mfma_f32_16x16x32_bf16 v[70:73], v[160:163], v[214:217], v[70:73]
	v_mfma_f32_16x16x32_bf16 v[66:69], v[168:171], v[214:217], v[66:69]
	v_mfma_f32_16x16x32_bf16 v[110:113], v[164:167], v[180:183], v[110:113]
	v_mfma_f32_16x16x32_bf16 v[106:109], v[172:175], v[180:183], v[106:109]
	v_mfma_f32_16x16x32_bf16 v[94:97], v[164:167], v[188:191], v[94:97]
	v_mfma_f32_16x16x32_bf16 v[90:93], v[172:175], v[188:191], v[90:93]
	v_mfma_f32_16x16x32_bf16 v[78:81], v[164:167], v[210:213], v[78:81]
	v_mfma_f32_16x16x32_bf16 v[74:77], v[172:175], v[210:213], v[74:77]
	v_mfma_f32_16x16x32_bf16 v[70:73], v[164:167], v[218:221], v[70:73]
	s_barrier
	v_mfma_f32_16x16x32_bf16 v[66:69], v[172:175], v[218:221], v[66:69]
	s_setprio 2
	s_add_i32 s38, s60, s41
	v_lshl_add_u64 v[192:193], v[192:193], 0, s[6:7]
	s_mov_b32 m0, s38
	ds_read_b128 v[176:179], v142 offset:49152
	ds_read_b128 v[180:183], v142 offset:50176
	ds_read_b128 v[184:187], v142 offset:51200
	ds_read_b128 v[188:191], v142 offset:52224
	ds_read_b128 v[198:201], v142 offset:53248
	ds_read_b128 v[210:213], v142 offset:54272
	ds_read_b128 v[214:217], v142 offset:55296
	ds_read_b128 v[218:221], v142 offset:56320
	global_load_lds_dwordx4 v[192:193], off
	s_add_i32 m0, s38, 0x2000
	s_add_u32 s36, s36, 0x20080
	v_lshl_add_u64 v[192:193], v[202:203], 0, s[6:7]
	s_addc_u32 s37, s37, 0
	s_add_i32 s38, s61, s41
	global_load_lds_dwordx4 v[192:193], off
	v_lshl_add_u64 v[192:193], s[36:37], 0, v[132:133]
	s_mov_b32 m0, s38
	s_nop 0
	global_load_lds_dwordx4 v[192:193], off
	v_lshl_add_u64 v[192:193], s[36:37], 0, v[134:135]
	s_add_i32 m0, s38, 0x2000
	s_nop 0
	global_load_lds_dwordx4 v[192:193], off
	v_lshl_add_u64 v[192:193], v[206:207], 0, s[6:7]
	s_mov_b32 m0, s46
	s_nop 0
	global_load_lds_dwordx4 v[192:193], off
	v_lshl_add_u64 v[192:193], v[222:223], 0, s[6:7]
	s_mov_b32 m0, s47
	s_nop 0
	global_load_lds_dwordx4 v[192:193], off
	s_waitcnt vmcnt(8)
	s_waitcnt lgkmcnt(0)
	s_barrier
	s_setprio 1
	s_waitcnt lgkmcnt(0)
	v_mfma_f32_16x16x32_bf16 v[62:65], v[144:147], v[176:179], v[62:65]
	v_mfma_f32_16x16x32_bf16 v[58:61], v[152:155], v[176:179], v[58:61]
	v_mfma_f32_16x16x32_bf16 v[54:57], v[144:147], v[184:187], v[54:57]
	v_mfma_f32_16x16x32_bf16 v[50:53], v[152:155], v[184:187], v[50:53]
	v_mfma_f32_16x16x32_bf16 v[38:41], v[144:147], v[198:201], v[38:41]
	v_mfma_f32_16x16x32_bf16 v[34:37], v[152:155], v[198:201], v[34:37]
	v_mfma_f32_16x16x32_bf16 v[22:25], v[144:147], v[214:217], v[22:25]
	v_mfma_f32_16x16x32_bf16 v[18:21], v[152:155], v[214:217], v[18:21]
	v_mfma_f32_16x16x32_bf16 v[62:65], v[148:151], v[180:183], v[62:65]
	v_mfma_f32_16x16x32_bf16 v[58:61], v[156:159], v[180:183], v[58:61]
	v_mfma_f32_16x16x32_bf16 v[54:57], v[148:151], v[188:191], v[54:57]
	v_mfma_f32_16x16x32_bf16 v[50:53], v[156:159], v[188:191], v[50:53]
	v_mfma_f32_16x16x32_bf16 v[38:41], v[148:151], v[210:213], v[38:41]
	v_mfma_f32_16x16x32_bf16 v[34:37], v[156:159], v[210:213], v[34:37]
	v_mfma_f32_16x16x32_bf16 v[22:25], v[148:151], v[218:221], v[22:25]
	v_mfma_f32_16x16x32_bf16 v[18:21], v[156:159], v[218:221], v[18:21]
	v_mfma_f32_16x16x32_bf16 v[46:49], v[160:163], v[176:179], v[46:49]
	v_mfma_f32_16x16x32_bf16 v[42:45], v[168:171], v[176:179], v[42:45]
	v_mfma_f32_16x16x32_bf16 v[30:33], v[160:163], v[184:187], v[30:33]
	v_mfma_f32_16x16x32_bf16 v[26:29], v[168:171], v[184:187], v[26:29]
	v_mfma_f32_16x16x32_bf16 v[14:17], v[160:163], v[198:201], v[14:17]
	v_mfma_f32_16x16x32_bf16 v[10:13], v[168:171], v[198:201], v[10:13]
	v_mfma_f32_16x16x32_bf16 v[6:9], v[160:163], v[214:217], v[6:9]
	v_mfma_f32_16x16x32_bf16 v[2:5], v[168:171], v[214:217], v[2:5]
	v_mfma_f32_16x16x32_bf16 v[46:49], v[164:167], v[180:183], v[46:49]
	v_mfma_f32_16x16x32_bf16 v[42:45], v[172:175], v[180:183], v[42:45]
	v_mfma_f32_16x16x32_bf16 v[30:33], v[164:167], v[188:191], v[30:33]
	v_mfma_f32_16x16x32_bf16 v[26:29], v[172:175], v[188:191], v[26:29]
	v_mfma_f32_16x16x32_bf16 v[14:17], v[164:167], v[210:213], v[14:17]
	v_mfma_f32_16x16x32_bf16 v[10:13], v[172:175], v[210:213], v[10:13]
	v_mfma_f32_16x16x32_bf16 v[6:9], v[164:167], v[218:221], v[6:9]
	s_barrier
	v_mfma_f32_16x16x32_bf16 v[2:5], v[172:175], v[218:221], v[2:5]
	s_setprio 2
	s_add_i32 s59, s59, 2
	s_add_u32 s34, s34, 0x100
	s_addc_u32 s35, s35, 0
	s_add_u32 s57, s57, 0x100
	s_addc_u32 s58, s58, 0
	s_cmp_gt_u32 s59, 5
	s_cbranch_scc0 .LBB0_714
	s_branch .Lpeeldone_9
.LBB0_714:
	ds_read_b128 v[144:147], v140
	ds_read_b128 v[148:151], v140 offset:1024
	ds_read_b128 v[152:155], v140 offset:2048
	ds_read_b128 v[156:159], v140 offset:3072
	ds_read_b128 v[160:163], v141
	ds_read_b128 v[164:167], v141 offset:1024
	ds_read_b128 v[168:171], v141 offset:2048
	ds_read_b128 v[172:175], v141 offset:3072
	s_add_u32 s36, s34, 0xfffe0080
	s_addc_u32 s37, s35, -1
	s_cmp_eq_u32 s59, 4
	s_cselect_b32 s39, s21, s37
	s_cselect_b32 s38, s55, s36
	s_cselect_b32 s37, s25, s58
	s_cselect_b32 s36, s56, s57
	v_lshl_add_u64 v[192:193], s[34:35], 0, v[130:131]
	s_add_i32 m0, s27, 0xc000
	ds_read_b128 v[176:179], v142
	ds_read_b128 v[180:183], v142 offset:1024
	ds_read_b128 v[184:187], v142 offset:2048
	ds_read_b128 v[188:191], v142 offset:3072
	ds_read_b128 v[198:201], v142 offset:4096
	ds_read_b128 v[210:213], v142 offset:5120
	ds_read_b128 v[214:217], v142 offset:6144
	ds_read_b128 v[218:221], v142 offset:7168
	global_load_lds_dwordx4 v[192:193], off
	v_lshl_add_u64 v[192:193], s[34:35], 0, v[136:137]
	s_add_i32 m0, s27, 0xe000
	s_nop 0
	global_load_lds_dwordx4 v[192:193], off
	s_waitcnt vmcnt(8)
	s_waitcnt lgkmcnt(0)
	s_barrier
	s_setprio 1
	s_waitcnt lgkmcnt(0)
	v_mfma_f32_16x16x32_bf16 v[126:129], v[144:147], v[176:179], v[126:129]
	v_mfma_f32_16x16x32_bf16 v[122:125], v[152:155], v[176:179], v[122:125]
	v_mfma_f32_16x16x32_bf16 v[118:121], v[144:147], v[184:187], v[118:121]
	v_mfma_f32_16x16x32_bf16 v[114:117], v[152:155], v[184:187], v[114:117]
	v_mfma_f32_16x16x32_bf16 v[102:105], v[144:147], v[198:201], v[102:105]
	v_mfma_f32_16x16x32_bf16 v[98:101], v[152:155], v[198:201], v[98:101]
	v_mfma_f32_16x16x32_bf16 v[86:89], v[144:147], v[214:217], v[86:89]
	v_mfma_f32_16x16x32_bf16 v[82:85], v[152:155], v[214:217], v[82:85]
	v_mfma_f32_16x16x32_bf16 v[126:129], v[148:151], v[180:183], v[126:129]
	v_mfma_f32_16x16x32_bf16 v[122:125], v[156:159], v[180:183], v[122:125]
	v_mfma_f32_16x16x32_bf16 v[118:121], v[148:151], v[188:191], v[118:121]
	v_mfma_f32_16x16x32_bf16 v[114:117], v[156:159], v[188:191], v[114:117]
	v_mfma_f32_16x16x32_bf16 v[102:105], v[148:151], v[210:213], v[102:105]
	v_mfma_f32_16x16x32_bf16 v[98:101], v[156:159], v[210:213], v[98:101]
	v_mfma_f32_16x16x32_bf16 v[86:89], v[148:151], v[218:221], v[86:89]
	v_mfma_f32_16x16x32_bf16 v[82:85], v[156:159], v[218:221], v[82:85]
	v_mfma_f32_16x16x32_bf16 v[110:113], v[160:163], v[176:179], v[110:113]
	v_mfma_f32_16x16x32_bf16 v[106:109], v[168:171], v[176:179], v[106:109]
	v_mfma_f32_16x16x32_bf16 v[94:97], v[160:163], v[184:187], v[94:97]
	v_mfma_f32_16x16x32_bf16 v[90:93], v[168:171], v[184:187], v[90:93]
	v_mfma_f32_16x16x32_bf16 v[78:81], v[160:163], v[198:201], v[78:81]
	v_mfma_f32_16x16x32_bf16 v[74:77], v[168:171], v[198:201], v[74:77]
	v_mfma_f32_16x16x32_bf16 v[70:73], v[160:163], v[214:217], v[70:73]
	v_mfma_f32_16x16x32_bf16 v[66:69], v[168:171], v[214:217], v[66:69]
	v_mfma_f32_16x16x32_bf16 v[110:113], v[164:167], v[180:183], v[110:113]
	v_mfma_f32_16x16x32_bf16 v[106:109], v[172:175], v[180:183], v[106:109]
	v_mfma_f32_16x16x32_bf16 v[94:97], v[164:167], v[188:191], v[94:97]
	v_mfma_f32_16x16x32_bf16 v[90:93], v[172:175], v[188:191], v[90:93]
	v_mfma_f32_16x16x32_bf16 v[78:81], v[164:167], v[210:213], v[78:81]
	v_mfma_f32_16x16x32_bf16 v[74:77], v[172:175], v[210:213], v[74:77]
	v_mfma_f32_16x16x32_bf16 v[70:73], v[164:167], v[218:221], v[70:73]
	s_barrier
	v_mfma_f32_16x16x32_bf16 v[66:69], v[172:175], v[218:221], v[66:69]
	s_setprio 2
	s_add_i32 s60, s48, s41
	v_lshl_add_u64 v[192:193], s[36:37], 0, v[132:133]
	s_mov_b32 m0, s60
	ds_read_b128 v[176:179], v142 offset:16384
	ds_read_b128 v[180:183], v142 offset:17408
	ds_read_b128 v[184:187], v142 offset:18432
	ds_read_b128 v[188:191], v142 offset:19456
	ds_read_b128 v[198:201], v142 offset:20480
	ds_read_b128 v[210:213], v142 offset:21504
	ds_read_b128 v[214:217], v142 offset:22528
	ds_read_b128 v[218:221], v142 offset:23552
	global_load_lds_dwordx4 v[192:193], off
	s_add_i32 m0, s60, 0x2000
	s_add_u32 s60, s36, 0x20000
	v_lshl_add_u64 v[202:203], s[36:37], 0, v[134:135]
	s_addc_u32 s61, s37, 0
	s_add_i32 s62, s49, s41
	global_load_lds_dwordx4 v[202:203], off
	v_lshl_add_u64 v[206:207], s[60:61], 0, v[132:133]
	s_mov_b32 m0, s62
	v_lshl_add_u64 v[222:223], s[38:39], 0, v[136:137]
	global_load_lds_dwordx4 v[206:207], off
	v_lshl_add_u64 v[206:207], s[60:61], 0, v[134:135]
	s_add_i32 m0, s62, 0x2000
	s_nop 0
	global_load_lds_dwordx4 v[206:207], off
	v_lshl_add_u64 v[206:207], s[38:39], 0, v[130:131]
	s_mov_b32 m0, s27
	s_nop 0
	global_load_lds_dwordx4 v[206:207], off
	s_mov_b32 m0, s42
	s_nop 0
	global_load_lds_dwordx4 v[222:223], off
	s_waitcnt vmcnt(8)
	s_waitcnt lgkmcnt(0)
	s_barrier
	s_setprio 1
	s_waitcnt lgkmcnt(0)
	v_mfma_f32_16x16x32_bf16 v[62:65], v[144:147], v[176:179], v[62:65]
	v_mfma_f32_16x16x32_bf16 v[58:61], v[152:155], v[176:179], v[58:61]
	v_mfma_f32_16x16x32_bf16 v[54:57], v[144:147], v[184:187], v[54:57]
	v_mfma_f32_16x16x32_bf16 v[50:53], v[152:155], v[184:187], v[50:53]
	v_mfma_f32_16x16x32_bf16 v[38:41], v[144:147], v[198:201], v[38:41]
	v_mfma_f32_16x16x32_bf16 v[34:37], v[152:155], v[198:201], v[34:37]
	v_mfma_f32_16x16x32_bf16 v[22:25], v[144:147], v[214:217], v[22:25]
	v_mfma_f32_16x16x32_bf16 v[18:21], v[152:155], v[214:217], v[18:21]
	v_mfma_f32_16x16x32_bf16 v[62:65], v[148:151], v[180:183], v[62:65]
	v_mfma_f32_16x16x32_bf16 v[58:61], v[156:159], v[180:183], v[58:61]
	v_mfma_f32_16x16x32_bf16 v[54:57], v[148:151], v[188:191], v[54:57]
	v_mfma_f32_16x16x32_bf16 v[50:53], v[156:159], v[188:191], v[50:53]
	v_mfma_f32_16x16x32_bf16 v[38:41], v[148:151], v[210:213], v[38:41]
	v_mfma_f32_16x16x32_bf16 v[34:37], v[156:159], v[210:213], v[34:37]
	v_mfma_f32_16x16x32_bf16 v[22:25], v[148:151], v[218:221], v[22:25]
	v_mfma_f32_16x16x32_bf16 v[18:21], v[156:159], v[218:221], v[18:21]
	v_mfma_f32_16x16x32_bf16 v[46:49], v[160:163], v[176:179], v[46:49]
	v_mfma_f32_16x16x32_bf16 v[42:45], v[168:171], v[176:179], v[42:45]
	v_mfma_f32_16x16x32_bf16 v[30:33], v[160:163], v[184:187], v[30:33]
	v_mfma_f32_16x16x32_bf16 v[26:29], v[168:171], v[184:187], v[26:29]
	v_mfma_f32_16x16x32_bf16 v[14:17], v[160:163], v[198:201], v[14:17]
	v_mfma_f32_16x16x32_bf16 v[10:13], v[168:171], v[198:201], v[10:13]
	v_mfma_f32_16x16x32_bf16 v[6:9], v[160:163], v[214:217], v[6:9]
	v_mfma_f32_16x16x32_bf16 v[2:5], v[168:171], v[214:217], v[2:5]
	v_mfma_f32_16x16x32_bf16 v[46:49], v[164:167], v[180:183], v[46:49]
	v_mfma_f32_16x16x32_bf16 v[42:45], v[172:175], v[180:183], v[42:45]
	v_mfma_f32_16x16x32_bf16 v[30:33], v[164:167], v[188:191], v[30:33]
	v_mfma_f32_16x16x32_bf16 v[26:29], v[172:175], v[188:191], v[26:29]
	v_mfma_f32_16x16x32_bf16 v[14:17], v[164:167], v[210:213], v[14:17]
	v_mfma_f32_16x16x32_bf16 v[10:13], v[172:175], v[210:213], v[10:13]
	v_mfma_f32_16x16x32_bf16 v[6:9], v[164:167], v[218:221], v[6:9]
	s_barrier
	v_mfma_f32_16x16x32_bf16 v[2:5], v[172:175], v[218:221], v[2:5]
	s_setprio 2
	s_add_i32 s60, 0, 0x18000
	s_add_i32 s61, 0, 0x1c000
	ds_read_b128 v[144:147], v250
	ds_read_b128 v[148:151], v250 offset:1024
	ds_read_b128 v[152:155], v250 offset:2048
	ds_read_b128 v[156:159], v250 offset:3072
	ds_read_b128 v[160:163], v250 offset:16384
	ds_read_b128 v[164:167], v250 offset:17408
	ds_read_b128 v[168:171], v250 offset:18432
	ds_read_b128 v[172:175], v250 offset:19456
	v_add_u32_e32 v143, s61, v139
	s_add_u32 s38, s38, 0x20000
	s_addc_u32 s39, s39, 0
	s_mov_b32 m0, s43
	v_lshl_add_u64 v[224:225], s[38:39], 0, v[130:131]
	ds_read_b128 v[176:179], v142 offset:32768
	ds_read_b128 v[180:183], v142 offset:33792
	ds_read_b128 v[184:187], v142 offset:34816
	ds_read_b128 v[188:191], v142 offset:35840
	ds_read_b128 v[198:201], v142 offset:36864
	ds_read_b128 v[210:213], v142 offset:37888
	ds_read_b128 v[214:217], v142 offset:38912
	ds_read_b128 v[218:221], v142 offset:39936
	global_load_lds_dwordx4 v[224:225], off
	v_lshl_add_u64 v[224:225], s[38:39], 0, v[136:137]
	s_mov_b32 m0, s44
	s_nop 0
	global_load_lds_dwordx4 v[224:225], off
	s_waitcnt vmcnt(8)
	s_waitcnt lgkmcnt(0)
	s_barrier
	s_setprio 1
	s_waitcnt lgkmcnt(0)
	v_mfma_f32_16x16x32_bf16 v[126:129], v[144:147], v[176:179], v[126:129]
	v_mfma_f32_16x16x32_bf16 v[122:125], v[152:155], v[176:179], v[122:125]
	v_mfma_f32_16x16x32_bf16 v[118:121], v[144:147], v[184:187], v[118:121]
	v_mfma_f32_16x16x32_bf16 v[114:117], v[152:155], v[184:187], v[114:117]
	v_mfma_f32_16x16x32_bf16 v[102:105], v[144:147], v[198:201], v[102:105]
	v_mfma_f32_16x16x32_bf16 v[98:101], v[152:155], v[198:201], v[98:101]
	v_mfma_f32_16x16x32_bf16 v[86:89], v[144:147], v[214:217], v[86:89]
	v_mfma_f32_16x16x32_bf16 v[82:85], v[152:155], v[214:217], v[82:85]
	v_mfma_f32_16x16x32_bf16 v[126:129], v[148:151], v[180:183], v[126:129]
	v_mfma_f32_16x16x32_bf16 v[122:125], v[156:159], v[180:183], v[122:125]
	v_mfma_f32_16x16x32_bf16 v[118:121], v[148:151], v[188:191], v[118:121]
	v_mfma_f32_16x16x32_bf16 v[114:117], v[156:159], v[188:191], v[114:117]
	v_mfma_f32_16x16x32_bf16 v[102:105], v[148:151], v[210:213], v[102:105]
	v_mfma_f32_16x16x32_bf16 v[98:101], v[156:159], v[210:213], v[98:101]
	v_mfma_f32_16x16x32_bf16 v[86:89], v[148:151], v[218:221], v[86:89]
	v_mfma_f32_16x16x32_bf16 v[82:85], v[156:159], v[218:221], v[82:85]
	v_mfma_f32_16x16x32_bf16 v[110:113], v[160:163], v[176:179], v[110:113]
	v_mfma_f32_16x16x32_bf16 v[106:109], v[168:171], v[176:179], v[106:109]
	v_mfma_f32_16x16x32_bf16 v[94:97], v[160:163], v[184:187], v[94:97]
	v_mfma_f32_16x16x32_bf16 v[90:93], v[168:171], v[184:187], v[90:93]
	v_mfma_f32_16x16x32_bf16 v[78:81], v[160:163], v[198:201], v[78:81]
	v_mfma_f32_16x16x32_bf16 v[74:77], v[168:171], v[198:201], v[74:77]
	v_mfma_f32_16x16x32_bf16 v[70:73], v[160:163], v[214:217], v[70:73]
	v_mfma_f32_16x16x32_bf16 v[66:69], v[168:171], v[214:217], v[66:69]
	v_mfma_f32_16x16x32_bf16 v[110:113], v[164:167], v[180:183], v[110:113]
	v_mfma_f32_16x16x32_bf16 v[106:109], v[172:175], v[180:183], v[106:109]
	v_mfma_f32_16x16x32_bf16 v[94:97], v[164:167], v[188:191], v[94:97]
	v_mfma_f32_16x16x32_bf16 v[90:93], v[172:175], v[188:191], v[90:93]
	v_mfma_f32_16x16x32_bf16 v[78:81], v[164:167], v[210:213], v[78:81]
	v_mfma_f32_16x16x32_bf16 v[74:77], v[172:175], v[210:213], v[74:77]
	v_mfma_f32_16x16x32_bf16 v[70:73], v[164:167], v[218:221], v[70:73]
	s_barrier
	v_mfma_f32_16x16x32_bf16 v[66:69], v[172:175], v[218:221], v[66:69]
	s_setprio 2
	s_add_i32 s38, s60, s41
	v_lshl_add_u64 v[192:193], v[192:193], 0, s[6:7]
	s_mov_b32 m0, s38
	ds_read_b128 v[176:179], v142 offset:49152
	ds_read_b128 v[180:183], v142 offset:50176
	ds_read_b128 v[184:187], v142 offset:51200
	ds_read_b128 v[188:191], v142 offset:52224
	ds_read_b128 v[198:201], v142 offset:53248
	ds_read_b128 v[210:213], v142 offset:54272
	ds_read_b128 v[214:217], v142 offset:55296
	ds_read_b128 v[218:221], v142 offset:56320
	global_load_lds_dwordx4 v[192:193], off
	s_add_i32 m0, s38, 0x2000
	s_add_u32 s36, s36, 0x20080
	v_lshl_add_u64 v[192:193], v[202:203], 0, s[6:7]
	s_addc_u32 s37, s37, 0
	s_add_i32 s38, s61, s41
	global_load_lds_dwordx4 v[192:193], off
	v_lshl_add_u64 v[192:193], s[36:37], 0, v[132:133]
	s_mov_b32 m0, s38
	s_nop 0
	global_load_lds_dwordx4 v[192:193], off
	v_lshl_add_u64 v[192:193], s[36:37], 0, v[134:135]
	s_add_i32 m0, s38, 0x2000
	s_nop 0
	global_load_lds_dwordx4 v[192:193], off
	v_lshl_add_u64 v[192:193], v[206:207], 0, s[6:7]
	s_mov_b32 m0, s46
	s_nop 0
	global_load_lds_dwordx4 v[192:193], off
	v_lshl_add_u64 v[192:193], v[222:223], 0, s[6:7]
	s_mov_b32 m0, s47
	s_nop 0
	global_load_lds_dwordx4 v[192:193], off
	s_waitcnt vmcnt(8)
	s_waitcnt lgkmcnt(0)
	s_barrier
	s_setprio 1
	s_waitcnt lgkmcnt(0)
	v_mfma_f32_16x16x32_bf16 v[62:65], v[144:147], v[176:179], v[62:65]
	v_mfma_f32_16x16x32_bf16 v[58:61], v[152:155], v[176:179], v[58:61]
	v_mfma_f32_16x16x32_bf16 v[54:57], v[144:147], v[184:187], v[54:57]
	v_mfma_f32_16x16x32_bf16 v[50:53], v[152:155], v[184:187], v[50:53]
	v_mfma_f32_16x16x32_bf16 v[38:41], v[144:147], v[198:201], v[38:41]
	v_mfma_f32_16x16x32_bf16 v[34:37], v[152:155], v[198:201], v[34:37]
	v_mfma_f32_16x16x32_bf16 v[22:25], v[144:147], v[214:217], v[22:25]
	v_mfma_f32_16x16x32_bf16 v[18:21], v[152:155], v[214:217], v[18:21]
	v_mfma_f32_16x16x32_bf16 v[62:65], v[148:151], v[180:183], v[62:65]
	v_mfma_f32_16x16x32_bf16 v[58:61], v[156:159], v[180:183], v[58:61]
	v_mfma_f32_16x16x32_bf16 v[54:57], v[148:151], v[188:191], v[54:57]
	v_mfma_f32_16x16x32_bf16 v[50:53], v[156:159], v[188:191], v[50:53]
	v_mfma_f32_16x16x32_bf16 v[38:41], v[148:151], v[210:213], v[38:41]
	v_mfma_f32_16x16x32_bf16 v[34:37], v[156:159], v[210:213], v[34:37]
	v_mfma_f32_16x16x32_bf16 v[22:25], v[148:151], v[218:221], v[22:25]
	v_mfma_f32_16x16x32_bf16 v[18:21], v[156:159], v[218:221], v[18:21]
	v_mfma_f32_16x16x32_bf16 v[46:49], v[160:163], v[176:179], v[46:49]
	v_mfma_f32_16x16x32_bf16 v[42:45], v[168:171], v[176:179], v[42:45]
	v_mfma_f32_16x16x32_bf16 v[30:33], v[160:163], v[184:187], v[30:33]
	v_mfma_f32_16x16x32_bf16 v[26:29], v[168:171], v[184:187], v[26:29]
	v_mfma_f32_16x16x32_bf16 v[14:17], v[160:163], v[198:201], v[14:17]
	v_mfma_f32_16x16x32_bf16 v[10:13], v[168:171], v[198:201], v[10:13]
	v_mfma_f32_16x16x32_bf16 v[6:9], v[160:163], v[214:217], v[6:9]
	v_mfma_f32_16x16x32_bf16 v[2:5], v[168:171], v[214:217], v[2:5]
	v_mfma_f32_16x16x32_bf16 v[46:49], v[164:167], v[180:183], v[46:49]
	v_mfma_f32_16x16x32_bf16 v[42:45], v[172:175], v[180:183], v[42:45]
	v_mfma_f32_16x16x32_bf16 v[30:33], v[164:167], v[188:191], v[30:33]
	v_mfma_f32_16x16x32_bf16 v[26:29], v[172:175], v[188:191], v[26:29]
	v_mfma_f32_16x16x32_bf16 v[14:17], v[164:167], v[210:213], v[14:17]
	v_mfma_f32_16x16x32_bf16 v[10:13], v[172:175], v[210:213], v[10:13]
	v_mfma_f32_16x16x32_bf16 v[6:9], v[164:167], v[218:221], v[6:9]
	s_barrier
	v_mfma_f32_16x16x32_bf16 v[2:5], v[172:175], v[218:221], v[2:5]
	s_setprio 2
	s_add_i32 s59, s59, 2
	s_add_u32 s34, s34, 0x100
	s_addc_u32 s35, s35, 0
	s_add_u32 s57, s57, 0x100
	s_addc_u32 s58, s58, 0
	s_cmp_gt_u32 s59, 5
	s_cbranch_scc0 .LBB0_714

.Lpeel_8:
	v_add_u32_e32 v250, 0x18000, v168
	ds_read_b128 v[130:133], v170
	ds_read_b128 v[134:137], v170 offset:1024
	ds_read_b128 v[138:141], v170 offset:2048
	ds_read_b128 v[142:145], v170 offset:3072
	ds_read_b128 v[160:163], v171
	ds_read_b128 v[164:167], v171 offset:1024
	ds_read_b128 v[174:177], v171 offset:2048
	ds_read_b128 v[178:181], v171 offset:3072
	s_add_i32 s31, s21, 2
	s_add_u32 s36, s34, 0xfff80080
	s_addc_u32 s37, s35, -1
	s_cmp_eq_u32 s30, s21
	s_cselect_b32 s39, s23, s37
	s_cselect_b32 s38, s22, s36
	s_cselect_b32 s37, s25, s19
	s_cselect_b32 s36, s24, s17
	v_lshl_add_u64 v[202:203], s[34:35], 0, v[156:157]
	s_add_i32 m0, s27, 0xc000
	ds_read_b128 v[182:185], v172
	ds_read_b128 v[186:189], v172 offset:1024
	ds_read_b128 v[190:193], v172 offset:2048
	ds_read_b128 v[198:201], v172 offset:3072
	ds_read_b128 v[210:213], v172 offset:4096
	ds_read_b128 v[214:217], v172 offset:5120
	global_load_lds_dwordx4 v[202:203], off
	v_lshl_add_u64 v[202:203], s[34:35], 0, v[158:159]
	s_add_i32 m0, s27, 0xe000
	s_nop 0
	global_load_lds_dwordx4 v[202:203], off
	s_waitcnt vmcnt(8)
	s_waitcnt lgkmcnt(0)
	s_barrier
	s_setprio 1
	s_waitcnt lgkmcnt(0)
	v_mfma_f32_16x16x32_bf16 v[126:129], v[130:133], v[182:185], 0
	v_mfma_f32_16x16x32_bf16 v[122:125], v[138:141], v[182:185], 0
	v_mfma_f32_16x16x32_bf16 v[118:121], v[130:133], v[190:193], 0
	v_mfma_f32_16x16x32_bf16 v[110:113], v[138:141], v[190:193], 0
	v_mfma_f32_16x16x32_bf16 v[94:97], v[130:133], v[210:213], 0
	v_mfma_f32_16x16x32_bf16 v[90:93], v[138:141], v[210:213], 0
	v_mfma_f32_16x16x32_bf16 v[78:81], v[130:133], v[218:221], 0
	v_mfma_f32_16x16x32_bf16 v[74:77], v[138:141], v[218:221], 0
	v_mfma_f32_16x16x32_bf16 v[126:129], v[134:137], v[186:189], v[126:129]
	v_mfma_f32_16x16x32_bf16 v[122:125], v[142:145], v[186:189], v[122:125]
	v_mfma_f32_16x16x32_bf16 v[118:121], v[134:137], v[198:201], v[118:121]
	v_mfma_f32_16x16x32_bf16 v[110:113], v[142:145], v[198:201], v[110:113]
	v_mfma_f32_16x16x32_bf16 v[94:97], v[134:137], v[214:217], v[94:97]
	v_mfma_f32_16x16x32_bf16 v[90:93], v[142:145], v[214:217], v[90:93]
	v_mfma_f32_16x16x32_bf16 v[78:81], v[134:137], v[222:225], v[78:81]
	v_mfma_f32_16x16x32_bf16 v[74:77], v[142:145], v[222:225], v[74:77]
	v_mfma_f32_16x16x32_bf16 v[114:117], v[160:163], v[182:185], 0
	v_mfma_f32_16x16x32_bf16 v[106:109], v[174:177], v[182:185], 0
	v_mfma_f32_16x16x32_bf16 v[102:105], v[160:163], v[190:193], 0
	v_mfma_f32_16x16x32_bf16 v[98:101], v[174:177], v[190:193], 0
	v_mfma_f32_16x16x32_bf16 v[86:89], v[160:163], v[210:213], 0
	v_mfma_f32_16x16x32_bf16 v[82:85], v[174:177], v[210:213], 0
	v_mfma_f32_16x16x32_bf16 v[70:73], v[160:163], v[218:221], 0
	v_mfma_f32_16x16x32_bf16 v[66:69], v[174:177], v[218:221], 0
	v_mfma_f32_16x16x32_bf16 v[114:117], v[164:167], v[186:189], v[114:117]
	v_mfma_f32_16x16x32_bf16 v[106:109], v[178:181], v[186:189], v[106:109]
	v_mfma_f32_16x16x32_bf16 v[102:105], v[164:167], v[198:201], v[102:105]
	v_mfma_f32_16x16x32_bf16 v[98:101], v[178:181], v[198:201], v[98:101]
	v_mfma_f32_16x16x32_bf16 v[86:89], v[164:167], v[214:217], v[86:89]
	v_mfma_f32_16x16x32_bf16 v[82:85], v[178:181], v[214:217], v[82:85]
	v_mfma_f32_16x16x32_bf16 v[70:73], v[164:167], v[222:225], v[70:73]
	s_barrier
	v_mfma_f32_16x16x32_bf16 v[66:69], v[178:181], v[222:225], v[66:69]
	s_setprio 2
	s_add_i32 s21, s63, s33
	v_lshl_add_u64 v[202:203], s[36:37], 0, v[148:149]
	s_mov_b32 m0, s21
	ds_read_b128 v[182:185], v172 offset:16384
	ds_read_b128 v[186:189], v172 offset:17408
	ds_read_b128 v[190:193], v172 offset:18432
	ds_read_b128 v[198:201], v172 offset:19456
	ds_read_b128 v[210:213], v172 offset:20480
	ds_read_b128 v[214:217], v172 offset:21504
	ds_read_b128 v[218:221], v172 offset:22528
	ds_read_b128 v[222:225], v172 offset:23552
	global_load_lds_dwordx4 v[202:203], off
	s_add_i32 m0, s21, 0x2000
	s_add_u32 s40, s36, 0x80000
	v_lshl_add_u64 v[206:207], s[36:37], 0, v[152:153]
	s_addc_u32 s41, s37, 0
	s_add_i32 s21, s64, s33
	global_load_lds_dwordx4 v[206:207], off
	v_lshl_add_u64 v[226:227], s[40:41], 0, v[148:149]
	s_mov_b32 m0, s21
	v_lshl_add_u64 v[228:229], s[38:39], 0, v[150:151]
	global_load_lds_dwordx4 v[226:227], off
	v_lshl_add_u64 v[226:227], s[40:41], 0, v[152:153]
	s_add_i32 m0, s21, 0x2000
	s_nop 0
	global_load_lds_dwordx4 v[226:227], off
	v_lshl_add_u64 v[226:227], s[38:39], 0, v[146:147]
	s_mov_b32 m0, s27
	s_nop 0
	global_load_lds_dwordx4 v[226:227], off
	s_mov_b32 m0, s29
	s_nop 0
	global_load_lds_dwordx4 v[228:229], off
	s_waitcnt vmcnt(8)
	s_waitcnt lgkmcnt(0)
	s_barrier
	s_setprio 1
	s_waitcnt lgkmcnt(0)
	v_mfma_f32_16x16x32_bf16 v[62:65], v[130:133], v[182:185], 0
	v_mfma_f32_16x16x32_bf16 v[58:61], v[138:141], v[182:185], 0
	v_mfma_f32_16x16x32_bf16 v[46:49], v[130:133], v[190:193], 0
	v_mfma_f32_16x16x32_bf16 v[42:45], v[138:141], v[190:193], 0
	v_mfma_f32_16x16x32_bf16 v[30:33], v[130:133], v[210:213], 0
	v_mfma_f32_16x16x32_bf16 v[26:29], v[138:141], v[210:213], 0
	v_mfma_f32_16x16x32_bf16 v[14:17], v[130:133], v[218:221], 0
	v_mfma_f32_16x16x32_bf16 v[10:13], v[138:141], v[218:221], 0
	v_mfma_f32_16x16x32_bf16 v[62:65], v[134:137], v[186:189], v[62:65]
	v_mfma_f32_16x16x32_bf16 v[58:61], v[142:145], v[186:189], v[58:61]
	v_mfma_f32_16x16x32_bf16 v[46:49], v[134:137], v[198:201], v[46:49]
	v_mfma_f32_16x16x32_bf16 v[42:45], v[142:145], v[198:201], v[42:45]
	v_mfma_f32_16x16x32_bf16 v[30:33], v[134:137], v[214:217], v[30:33]
	v_mfma_f32_16x16x32_bf16 v[26:29], v[142:145], v[214:217], v[26:29]
	v_mfma_f32_16x16x32_bf16 v[14:17], v[134:137], v[222:225], v[14:17]
	v_mfma_f32_16x16x32_bf16 v[10:13], v[142:145], v[222:225], v[10:13]
	v_mfma_f32_16x16x32_bf16 v[54:57], v[160:163], v[182:185], 0
	v_mfma_f32_16x16x32_bf16 v[50:53], v[174:177], v[182:185], 0
	v_mfma_f32_16x16x32_bf16 v[38:41], v[160:163], v[190:193], 0
	v_mfma_f32_16x16x32_bf16 v[34:37], v[174:177], v[190:193], 0
	v_mfma_f32_16x16x32_bf16 v[22:25], v[160:163], v[210:213], 0
	v_mfma_f32_16x16x32_bf16 v[18:21], v[174:177], v[210:213], 0
	v_mfma_f32_16x16x32_bf16 v[6:9], v[160:163], v[218:221], 0
	v_mfma_f32_16x16x32_bf16 v[2:5], v[174:177], v[218:221], 0
	v_mfma_f32_16x16x32_bf16 v[54:57], v[164:167], v[186:189], v[54:57]
	v_mfma_f32_16x16x32_bf16 v[50:53], v[178:181], v[186:189], v[50:53]
	v_mfma_f32_16x16x32_bf16 v[38:41], v[164:167], v[198:201], v[38:41]
	v_mfma_f32_16x16x32_bf16 v[34:37], v[178:181], v[198:201], v[34:37]
	v_mfma_f32_16x16x32_bf16 v[22:25], v[164:167], v[214:217], v[22:25]
	v_mfma_f32_16x16x32_bf16 v[18:21], v[178:181], v[214:217], v[18:21]
	v_mfma_f32_16x16x32_bf16 v[6:9], v[164:167], v[222:225], v[6:9]
	s_barrier
	v_mfma_f32_16x16x32_bf16 v[2:5], v[178:181], v[222:225], v[2:5]
	s_setprio 2
	s_add_i32 s21, 0, 0x18000
	s_add_i32 s40, 0, 0x1c000
	ds_read_b128 v[130:133], v250
	ds_read_b128 v[134:137], v250 offset:1024
	ds_read_b128 v[138:141], v250 offset:2048
	ds_read_b128 v[142:145], v250 offset:3072
	ds_read_b128 v[160:163], v250 offset:16384
	ds_read_b128 v[164:167], v250 offset:17408
	ds_read_b128 v[174:177], v250 offset:18432
	ds_read_b128 v[178:181], v250 offset:19456
	v_add_u32_e32 v173, s40, v168
	s_add_u32 s38, s38, 0x80000
	s_addc_u32 s39, s39, 0
	s_mov_b32 m0, s42
	v_lshl_add_u64 v[230:231], s[38:39], 0, v[146:147]
	ds_read_b128 v[182:185], v172 offset:32768
	ds_read_b128 v[186:189], v172 offset:33792
	ds_read_b128 v[190:193], v172 offset:34816
	ds_read_b128 v[198:201], v172 offset:35840
	ds_read_b128 v[210:213], v172 offset:36864
	ds_read_b128 v[214:217], v172 offset:37888
	ds_read_b128 v[218:221], v172 offset:38912
	ds_read_b128 v[222:225], v172 offset:39936
	global_load_lds_dwordx4 v[230:231], off
	v_lshl_add_u64 v[230:231], s[38:39], 0, v[150:151]
	s_mov_b32 m0, s43
	s_nop 0
	global_load_lds_dwordx4 v[230:231], off
	s_waitcnt vmcnt(8)
	s_waitcnt lgkmcnt(0)
	s_barrier
	s_setprio 1
	s_waitcnt lgkmcnt(0)
	v_mfma_f32_16x16x32_bf16 v[126:129], v[130:133], v[182:185], v[126:129]
	v_mfma_f32_16x16x32_bf16 v[122:125], v[138:141], v[182:185], v[122:125]
	v_mfma_f32_16x16x32_bf16 v[118:121], v[130:133], v[190:193], v[118:121]
	v_mfma_f32_16x16x32_bf16 v[110:113], v[138:141], v[190:193], v[110:113]
	v_mfma_f32_16x16x32_bf16 v[94:97], v[130:133], v[210:213], v[94:97]
	v_mfma_f32_16x16x32_bf16 v[90:93], v[138:141], v[210:213], v[90:93]
	v_mfma_f32_16x16x32_bf16 v[78:81], v[130:133], v[218:221], v[78:81]
	v_mfma_f32_16x16x32_bf16 v[74:77], v[138:141], v[218:221], v[74:77]
	v_mfma_f32_16x16x32_bf16 v[126:129], v[134:137], v[186:189], v[126:129]
	v_mfma_f32_16x16x32_bf16 v[122:125], v[142:145], v[186:189], v[122:125]
	v_mfma_f32_16x16x32_bf16 v[118:121], v[134:137], v[198:201], v[118:121]
	v_mfma_f32_16x16x32_bf16 v[110:113], v[142:145], v[198:201], v[110:113]
	v_mfma_f32_16x16x32_bf16 v[94:97], v[134:137], v[214:217], v[94:97]
	v_mfma_f32_16x16x32_bf16 v[90:93], v[142:145], v[214:217], v[90:93]
	v_mfma_f32_16x16x32_bf16 v[78:81], v[134:137], v[222:225], v[78:81]
	v_mfma_f32_16x16x32_bf16 v[74:77], v[142:145], v[222:225], v[74:77]
	v_mfma_f32_16x16x32_bf16 v[114:117], v[160:163], v[182:185], v[114:117]
	v_mfma_f32_16x16x32_bf16 v[106:109], v[174:177], v[182:185], v[106:109]
	v_mfma_f32_16x16x32_bf16 v[102:105], v[160:163], v[190:193], v[102:105]
	v_mfma_f32_16x16x32_bf16 v[98:101], v[174:177], v[190:193], v[98:101]
	v_mfma_f32_16x16x32_bf16 v[86:89], v[160:163], v[210:213], v[86:89]
	v_mfma_f32_16x16x32_bf16 v[82:85], v[174:177], v[210:213], v[82:85]
	v_mfma_f32_16x16x32_bf16 v[70:73], v[160:163], v[218:221], v[70:73]
	v_mfma_f32_16x16x32_bf16 v[66:69], v[174:177], v[218:221], v[66:69]
	v_mfma_f32_16x16x32_bf16 v[114:117], v[164:167], v[186:189], v[114:117]
	v_mfma_f32_16x16x32_bf16 v[106:109], v[178:181], v[186:189], v[106:109]
	v_mfma_f32_16x16x32_bf16 v[102:105], v[164:167], v[198:201], v[102:105]
	v_mfma_f32_16x16x32_bf16 v[98:101], v[178:181], v[198:201], v[98:101]
	v_mfma_f32_16x16x32_bf16 v[86:89], v[164:167], v[214:217], v[86:89]
	v_mfma_f32_16x16x32_bf16 v[82:85], v[178:181], v[214:217], v[82:85]
	v_mfma_f32_16x16x32_bf16 v[70:73], v[164:167], v[222:225], v[70:73]
	s_barrier
	v_mfma_f32_16x16x32_bf16 v[66:69], v[178:181], v[222:225], v[66:69]
	s_setprio 2
	s_add_i32 s21, s21, s33
	v_lshl_add_u64 v[202:203], v[202:203], 0, s[12:13]
	s_mov_b32 m0, s21
	ds_read_b128 v[182:185], v172 offset:49152
	ds_read_b128 v[186:189], v172 offset:50176
	ds_read_b128 v[190:193], v172 offset:51200
	ds_read_b128 v[198:201], v172 offset:52224
	ds_read_b128 v[210:213], v172 offset:53248
	ds_read_b128 v[214:217], v172 offset:54272
	ds_read_b128 v[218:221], v172 offset:55296
	ds_read_b128 v[222:225], v172 offset:56320
	global_load_lds_dwordx4 v[202:203], off
	s_add_i32 m0, s21, 0x2000
	s_add_u32 s36, s36, 0x80080
	v_lshl_add_u64 v[202:203], v[206:207], 0, s[12:13]
	s_addc_u32 s37, s37, 0
	s_add_i32 s21, s40, s33
	global_load_lds_dwordx4 v[202:203], off
	v_lshl_add_u64 v[202:203], s[36:37], 0, v[148:149]
	s_mov_b32 m0, s21
	s_nop 0
	global_load_lds_dwordx4 v[202:203], off
	v_lshl_add_u64 v[202:203], s[36:37], 0, v[152:153]
	s_add_i32 m0, s21, 0x2000
	s_nop 0
	global_load_lds_dwordx4 v[202:203], off
	v_lshl_add_u64 v[202:203], v[226:227], 0, s[12:13]
	s_mov_b32 m0, s53
	s_nop 0
	global_load_lds_dwordx4 v[202:203], off
	v_lshl_add_u64 v[202:203], v[228:229], 0, s[12:13]
	s_mov_b32 m0, s54
	s_nop 0
	global_load_lds_dwordx4 v[202:203], off
	s_waitcnt vmcnt(8)
	s_waitcnt lgkmcnt(0)
	s_barrier
	s_setprio 1
	s_waitcnt lgkmcnt(0)
	v_mfma_f32_16x16x32_bf16 v[62:65], v[130:133], v[182:185], v[62:65]
	v_mfma_f32_16x16x32_bf16 v[58:61], v[138:141], v[182:185], v[58:61]
	v_mfma_f32_16x16x32_bf16 v[46:49], v[130:133], v[190:193], v[46:49]
	v_mfma_f32_16x16x32_bf16 v[42:45], v[138:141], v[190:193], v[42:45]
	v_mfma_f32_16x16x32_bf16 v[30:33], v[130:133], v[210:213], v[30:33]
	v_mfma_f32_16x16x32_bf16 v[26:29], v[138:141], v[210:213], v[26:29]
	v_mfma_f32_16x16x32_bf16 v[14:17], v[130:133], v[218:221], v[14:17]
	v_mfma_f32_16x16x32_bf16 v[10:13], v[138:141], v[218:221], v[10:13]
	v_mfma_f32_16x16x32_bf16 v[62:65], v[134:137], v[186:189], v[62:65]
	v_mfma_f32_16x16x32_bf16 v[58:61], v[142:145], v[186:189], v[58:61]
	v_mfma_f32_16x16x32_bf16 v[46:49], v[134:137], v[198:201], v[46:49]
	v_mfma_f32_16x16x32_bf16 v[42:45], v[142:145], v[198:201], v[42:45]
	v_mfma_f32_16x16x32_bf16 v[30:33], v[134:137], v[214:217], v[30:33]
	v_mfma_f32_16x16x32_bf16 v[26:29], v[142:145], v[214:217], v[26:29]
	v_mfma_f32_16x16x32_bf16 v[14:17], v[134:137], v[222:225], v[14:17]
	v_mfma_f32_16x16x32_bf16 v[10:13], v[142:145], v[222:225], v[10:13]
	v_mfma_f32_16x16x32_bf16 v[54:57], v[160:163], v[182:185], v[54:57]
	v_mfma_f32_16x16x32_bf16 v[50:53], v[174:177], v[182:185], v[50:53]
	v_mfma_f32_16x16x32_bf16 v[38:41], v[160:163], v[190:193], v[38:41]
	v_mfma_f32_16x16x32_bf16 v[34:37], v[174:177], v[190:193], v[34:37]
	v_mfma_f32_16x16x32_bf16 v[22:25], v[160:163], v[210:213], v[22:25]
	v_mfma_f32_16x16x32_bf16 v[18:21], v[174:177], v[210:213], v[18:21]
	v_mfma_f32_16x16x32_bf16 v[6:9], v[160:163], v[218:221], v[6:9]
	v_mfma_f32_16x16x32_bf16 v[2:5], v[174:177], v[218:221], v[2:5]
	v_mfma_f32_16x16x32_bf16 v[54:57], v[164:167], v[186:189], v[54:57]
	v_mfma_f32_16x16x32_bf16 v[50:53], v[178:181], v[186:189], v[50:53]
	v_mfma_f32_16x16x32_bf16 v[38:41], v[164:167], v[198:201], v[38:41]
	v_mfma_f32_16x16x32_bf16 v[34:37], v[178:181], v[198:201], v[34:37]
	v_mfma_f32_16x16x32_bf16 v[22:25], v[164:167], v[214:217], v[22:25]
	v_mfma_f32_16x16x32_bf16 v[18:21], v[178:181], v[214:217], v[18:21]
	v_mfma_f32_16x16x32_bf16 v[6:9], v[164:167], v[222:225], v[6:9]
	s_barrier
	v_mfma_f32_16x16x32_bf16 v[2:5], v[178:181], v[222:225], v[2:5]
	s_setprio 2
	s_add_u32 s34, s34, 0x100
	s_addc_u32 s35, s35, 0
	s_add_u32 s17, s17, 0x100
	s_addc_u32 s19, s19, 0
	s_cmp_ge_i32 s31, s69
	s_mov_b32 s21, s31
	s_cbranch_scc0 .LBB0_1122
	s_branch .Lpeeldone_8
.LBB0_1122:
	ds_read_b128 v[130:133], v170
	ds_read_b128 v[134:137], v170 offset:1024
	ds_read_b128 v[138:141], v170 offset:2048
	ds_read_b128 v[142:145], v170 offset:3072
	ds_read_b128 v[160:163], v171
	ds_read_b128 v[164:167], v171 offset:1024
	ds_read_b128 v[174:177], v171 offset:2048
	ds_read_b128 v[178:181], v171 offset:3072
	s_add_i32 s31, s21, 2
	s_add_u32 s36, s34, 0xfff80080
	s_addc_u32 s37, s35, -1
	s_cmp_eq_u32 s30, s21
	s_cselect_b32 s39, s23, s37
	s_cselect_b32 s38, s22, s36
	s_cselect_b32 s37, s25, s19
	s_cselect_b32 s36, s24, s17
	v_lshl_add_u64 v[202:203], s[34:35], 0, v[156:157]
	s_add_i32 m0, s27, 0xc000
	ds_read_b128 v[182:185], v172
	ds_read_b128 v[186:189], v172 offset:1024
	ds_read_b128 v[190:193], v172 offset:2048
	ds_read_b128 v[198:201], v172 offset:3072
	ds_read_b128 v[210:213], v172 offset:4096
	ds_read_b128 v[214:217], v172 offset:5120
	ds_read_b128 v[218:221], v172 offset:6144
	ds_read_b128 v[222:225], v172 offset:7168
	global_load_lds_dwordx4 v[202:203], off
	v_lshl_add_u64 v[202:203], s[34:35], 0, v[158:159]
	s_add_i32 m0, s27, 0xe000
	s_nop 0
	global_load_lds_dwordx4 v[202:203], off
	s_waitcnt vmcnt(8)
	s_waitcnt lgkmcnt(0)
	s_barrier
	s_setprio 1
	s_waitcnt lgkmcnt(0)
	v_mfma_f32_16x16x32_bf16 v[126:129], v[130:133], v[182:185], v[126:129]
	v_mfma_f32_16x16x32_bf16 v[122:125], v[138:141], v[182:185], v[122:125]
	v_mfma_f32_16x16x32_bf16 v[118:121], v[130:133], v[190:193], v[118:121]
	v_mfma_f32_16x16x32_bf16 v[110:113], v[138:141], v[190:193], v[110:113]
	v_mfma_f32_16x16x32_bf16 v[94:97], v[130:133], v[210:213], v[94:97]
	v_mfma_f32_16x16x32_bf16 v[90:93], v[138:141], v[210:213], v[90:93]
	v_mfma_f32_16x16x32_bf16 v[78:81], v[130:133], v[218:221], v[78:81]
	v_mfma_f32_16x16x32_bf16 v[74:77], v[138:141], v[218:221], v[74:77]
	v_mfma_f32_16x16x32_bf16 v[126:129], v[134:137], v[186:189], v[126:129]
	v_mfma_f32_16x16x32_bf16 v[122:125], v[142:145], v[186:189], v[122:125]
	v_mfma_f32_16x16x32_bf16 v[118:121], v[134:137], v[198:201], v[118:121]
	v_mfma_f32_16x16x32_bf16 v[110:113], v[142:145], v[198:201], v[110:113]
	v_mfma_f32_16x16x32_bf16 v[94:97], v[134:137], v[214:217], v[94:97]
	v_mfma_f32_16x16x32_bf16 v[90:93], v[142:145], v[214:217], v[90:93]
	v_mfma_f32_16x16x32_bf16 v[78:81], v[134:137], v[222:225], v[78:81]
	v_mfma_f32_16x16x32_bf16 v[74:77], v[142:145], v[222:225], v[74:77]
	v_mfma_f32_16x16x32_bf16 v[114:117], v[160:163], v[182:185], v[114:117]
	v_mfma_f32_16x16x32_bf16 v[106:109], v[174:177], v[182:185], v[106:109]
	v_mfma_f32_16x16x32_bf16 v[102:105], v[160:163], v[190:193], v[102:105]
	v_mfma_f32_16x16x32_bf16 v[98:101], v[174:177], v[190:193], v[98:101]
	v_mfma_f32_16x16x32_bf16 v[86:89], v[160:163], v[210:213], v[86:89]
	v_mfma_f32_16x16x32_bf16 v[82:85], v[174:177], v[210:213], v[82:85]
	v_mfma_f32_16x16x32_bf16 v[70:73], v[160:163], v[218:221], v[70:73]
	v_mfma_f32_16x16x32_bf16 v[66:69], v[174:177], v[218:221], v[66:69]
	v_mfma_f32_16x16x32_bf16 v[114:117], v[164:167], v[186:189], v[114:117]
	v_mfma_f32_16x16x32_bf16 v[106:109], v[178:181], v[186:189], v[106:109]
	v_mfma_f32_16x16x32_bf16 v[102:105], v[164:167], v[198:201], v[102:105]
	v_mfma_f32_16x16x32_bf16 v[98:101], v[178:181], v[198:201], v[98:101]
	v_mfma_f32_16x16x32_bf16 v[86:89], v[164:167], v[214:217], v[86:89]
	v_mfma_f32_16x16x32_bf16 v[82:85], v[178:181], v[214:217], v[82:85]
	v_mfma_f32_16x16x32_bf16 v[70:73], v[164:167], v[222:225], v[70:73]
	s_barrier
	v_mfma_f32_16x16x32_bf16 v[66:69], v[178:181], v[222:225], v[66:69]
	s_setprio 2
	s_add_i32 s21, s63, s33
	v_lshl_add_u64 v[202:203], s[36:37], 0, v[148:149]
	s_mov_b32 m0, s21
	ds_read_b128 v[182:185], v172 offset:16384
	ds_read_b128 v[186:189], v172 offset:17408
	ds_read_b128 v[190:193], v172 offset:18432
	ds_read_b128 v[198:201], v172 offset:19456
	ds_read_b128 v[210:213], v172 offset:20480
	ds_read_b128 v[214:217], v172 offset:21504
	ds_read_b128 v[218:221], v172 offset:22528
	ds_read_b128 v[222:225], v172 offset:23552
	global_load_lds_dwordx4 v[202:203], off
	s_add_i32 m0, s21, 0x2000
	s_add_u32 s40, s36, 0x80000
	v_lshl_add_u64 v[206:207], s[36:37], 0, v[152:153]
	s_addc_u32 s41, s37, 0
	s_add_i32 s21, s64, s33
	global_load_lds_dwordx4 v[206:207], off
	v_lshl_add_u64 v[226:227], s[40:41], 0, v[148:149]
	s_mov_b32 m0, s21
	v_lshl_add_u64 v[228:229], s[38:39], 0, v[150:151]
	global_load_lds_dwordx4 v[226:227], off
	v_lshl_add_u64 v[226:227], s[40:41], 0, v[152:153]
	s_add_i32 m0, s21, 0x2000
	s_nop 0
	global_load_lds_dwordx4 v[226:227], off
	v_lshl_add_u64 v[226:227], s[38:39], 0, v[146:147]
	s_mov_b32 m0, s27
	s_nop 0
	global_load_lds_dwordx4 v[226:227], off
	s_mov_b32 m0, s29
	s_nop 0
	global_load_lds_dwordx4 v[228:229], off
	s_waitcnt vmcnt(8)
	s_waitcnt lgkmcnt(0)
	s_barrier
	s_setprio 1
	s_waitcnt lgkmcnt(0)
	v_mfma_f32_16x16x32_bf16 v[62:65], v[130:133], v[182:185], v[62:65]
	v_mfma_f32_16x16x32_bf16 v[58:61], v[138:141], v[182:185], v[58:61]
	v_mfma_f32_16x16x32_bf16 v[46:49], v[130:133], v[190:193], v[46:49]
	v_mfma_f32_16x16x32_bf16 v[42:45], v[138:141], v[190:193], v[42:45]
	v_mfma_f32_16x16x32_bf16 v[30:33], v[130:133], v[210:213], v[30:33]
	v_mfma_f32_16x16x32_bf16 v[26:29], v[138:141], v[210:213], v[26:29]
	v_mfma_f32_16x16x32_bf16 v[14:17], v[130:133], v[218:221], v[14:17]
	v_mfma_f32_16x16x32_bf16 v[10:13], v[138:141], v[218:221], v[10:13]
	v_mfma_f32_16x16x32_bf16 v[62:65], v[134:137], v[186:189], v[62:65]
	v_mfma_f32_16x16x32_bf16 v[58:61], v[142:145], v[186:189], v[58:61]
	v_mfma_f32_16x16x32_bf16 v[46:49], v[134:137], v[198:201], v[46:49]
	v_mfma_f32_16x16x32_bf16 v[42:45], v[142:145], v[198:201], v[42:45]
	v_mfma_f32_16x16x32_bf16 v[30:33], v[134:137], v[214:217], v[30:33]
	v_mfma_f32_16x16x32_bf16 v[26:29], v[142:145], v[214:217], v[26:29]
	v_mfma_f32_16x16x32_bf16 v[14:17], v[134:137], v[222:225], v[14:17]
	v_mfma_f32_16x16x32_bf16 v[10:13], v[142:145], v[222:225], v[10:13]
	v_mfma_f32_16x16x32_bf16 v[54:57], v[160:163], v[182:185], v[54:57]
	v_mfma_f32_16x16x32_bf16 v[50:53], v[174:177], v[182:185], v[50:53]
	v_mfma_f32_16x16x32_bf16 v[38:41], v[160:163], v[190:193], v[38:41]
	v_mfma_f32_16x16x32_bf16 v[34:37], v[174:177], v[190:193], v[34:37]
	v_mfma_f32_16x16x32_bf16 v[22:25], v[160:163], v[210:213], v[22:25]
	v_mfma_f32_16x16x32_bf16 v[18:21], v[174:177], v[210:213], v[18:21]
	v_mfma_f32_16x16x32_bf16 v[6:9], v[160:163], v[218:221], v[6:9]
	v_mfma_f32_16x16x32_bf16 v[2:5], v[174:177], v[218:221], v[2:5]
	v_mfma_f32_16x16x32_bf16 v[54:57], v[164:167], v[186:189], v[54:57]
	v_mfma_f32_16x16x32_bf16 v[50:53], v[178:181], v[186:189], v[50:53]
	v_mfma_f32_16x16x32_bf16 v[38:41], v[164:167], v[198:201], v[38:41]
	v_mfma_f32_16x16x32_bf16 v[34:37], v[178:181], v[198:201], v[34:37]
	v_mfma_f32_16x16x32_bf16 v[22:25], v[164:167], v[214:217], v[22:25]
	v_mfma_f32_16x16x32_bf16 v[18:21], v[178:181], v[214:217], v[18:21]
	v_mfma_f32_16x16x32_bf16 v[6:9], v[164:167], v[222:225], v[6:9]
	s_barrier
	v_mfma_f32_16x16x32_bf16 v[2:5], v[178:181], v[222:225], v[2:5]
	s_setprio 2
	s_add_i32 s21, 0, 0x18000
	s_add_i32 s40, 0, 0x1c000
	ds_read_b128 v[130:133], v250
	ds_read_b128 v[134:137], v250 offset:1024
	ds_read_b128 v[138:141], v250 offset:2048
	ds_read_b128 v[142:145], v250 offset:3072
	ds_read_b128 v[160:163], v250 offset:16384
	ds_read_b128 v[164:167], v250 offset:17408
	ds_read_b128 v[174:177], v250 offset:18432
	ds_read_b128 v[178:181], v250 offset:19456
	v_add_u32_e32 v173, s40, v168
	s_add_u32 s38, s38, 0x80000
	s_addc_u32 s39, s39, 0
	s_mov_b32 m0, s42
	v_lshl_add_u64 v[230:231], s[38:39], 0, v[146:147]
	ds_read_b128 v[182:185], v172 offset:32768
	ds_read_b128 v[186:189], v172 offset:33792
	ds_read_b128 v[190:193], v172 offset:34816
	ds_read_b128 v[198:201], v172 offset:35840
	ds_read_b128 v[210:213], v172 offset:36864
	ds_read_b128 v[214:217], v172 offset:37888
	ds_read_b128 v[218:221], v172 offset:38912
	ds_read_b128 v[222:225], v172 offset:39936
	global_load_lds_dwordx4 v[230:231], off
	v_lshl_add_u64 v[230:231], s[38:39], 0, v[150:151]
	s_mov_b32 m0, s43
	s_nop 0
	global_load_lds_dwordx4 v[230:231], off
	s_waitcnt vmcnt(8)
	s_waitcnt lgkmcnt(0)
	s_barrier
	s_setprio 1
	s_waitcnt lgkmcnt(0)
	v_mfma_f32_16x16x32_bf16 v[126:129], v[130:133], v[182:185], v[126:129]
	v_mfma_f32_16x16x32_bf16 v[122:125], v[138:141], v[182:185], v[122:125]
	v_mfma_f32_16x16x32_bf16 v[118:121], v[130:133], v[190:193], v[118:121]
	v_mfma_f32_16x16x32_bf16 v[110:113], v[138:141], v[190:193], v[110:113]
	v_mfma_f32_16x16x32_bf16 v[94:97], v[130:133], v[210:213], v[94:97]
	v_mfma_f32_16x16x32_bf16 v[90:93], v[138:141], v[210:213], v[90:93]
	v_mfma_f32_16x16x32_bf16 v[78:81], v[130:133], v[218:221], v[78:81]
	v_mfma_f32_16x16x32_bf16 v[74:77], v[138:141], v[218:221], v[74:77]
	v_mfma_f32_16x16x32_bf16 v[126:129], v[134:137], v[186:189], v[126:129]
	v_mfma_f32_16x16x32_bf16 v[122:125], v[142:145], v[186:189], v[122:125]
	v_mfma_f32_16x16x32_bf16 v[118:121], v[134:137], v[198:201], v[118:121]
	v_mfma_f32_16x16x32_bf16 v[110:113], v[142:145], v[198:201], v[110:113]
	v_mfma_f32_16x16x32_bf16 v[94:97], v[134:137], v[214:217], v[94:97]
	v_mfma_f32_16x16x32_bf16 v[90:93], v[142:145], v[214:217], v[90:93]
	v_mfma_f32_16x16x32_bf16 v[78:81], v[134:137], v[222:225], v[78:81]
	v_mfma_f32_16x16x32_bf16 v[74:77], v[142:145], v[222:225], v[74:77]
	v_mfma_f32_16x16x32_bf16 v[114:117], v[160:163], v[182:185], v[114:117]
	v_mfma_f32_16x16x32_bf16 v[106:109], v[174:177], v[182:185], v[106:109]
	v_mfma_f32_16x16x32_bf16 v[102:105], v[160:163], v[190:193], v[102:105]
	v_mfma_f32_16x16x32_bf16 v[98:101], v[174:177], v[190:193], v[98:101]
	v_mfma_f32_16x16x32_bf16 v[86:89], v[160:163], v[210:213], v[86:89]
	v_mfma_f32_16x16x32_bf16 v[82:85], v[174:177], v[210:213], v[82:85]
	v_mfma_f32_16x16x32_bf16 v[70:73], v[160:163], v[218:221], v[70:73]
	v_mfma_f32_16x16x32_bf16 v[66:69], v[174:177], v[218:221], v[66:69]
	v_mfma_f32_16x16x32_bf16 v[114:117], v[164:167], v[186:189], v[114:117]
	v_mfma_f32_16x16x32_bf16 v[106:109], v[178:181], v[186:189], v[106:109]
	v_mfma_f32_16x16x32_bf16 v[102:105], v[164:167], v[198:201], v[102:105]
	v_mfma_f32_16x16x32_bf16 v[98:101], v[178:181], v[198:201], v[98:101]
	v_mfma_f32_16x16x32_bf16 v[86:89], v[164:167], v[214:217], v[86:89]
	v_mfma_f32_16x16x32_bf16 v[82:85], v[178:181], v[214:217], v[82:85]
	v_mfma_f32_16x16x32_bf16 v[70:73], v[164:167], v[222:225], v[70:73]
	s_barrier
	v_mfma_f32_16x16x32_bf16 v[66:69], v[178:181], v[222:225], v[66:69]
	s_setprio 2
	s_add_i32 s21, s21, s33
	v_lshl_add_u64 v[202:203], v[202:203], 0, s[12:13]
	s_mov_b32 m0, s21
	ds_read_b128 v[182:185], v172 offset:49152
	ds_read_b128 v[186:189], v172 offset:50176
	ds_read_b128 v[190:193], v172 offset:51200
	ds_read_b128 v[198:201], v172 offset:52224
	ds_read_b128 v[210:213], v172 offset:53248
	ds_read_b128 v[214:217], v172 offset:54272
	ds_read_b128 v[218:221], v172 offset:55296
	ds_read_b128 v[222:225], v172 offset:56320
	global_load_lds_dwordx4 v[202:203], off
	s_add_i32 m0, s21, 0x2000
	s_add_u32 s36, s36, 0x80080
	v_lshl_add_u64 v[202:203], v[206:207], 0, s[12:13]
	s_addc_u32 s37, s37, 0
	s_add_i32 s21, s40, s33
	global_load_lds_dwordx4 v[202:203], off
	v_lshl_add_u64 v[202:203], s[36:37], 0, v[148:149]
	s_mov_b32 m0, s21
	s_nop 0
	global_load_lds_dwordx4 v[202:203], off
	v_lshl_add_u64 v[202:203], s[36:37], 0, v[152:153]
	s_add_i32 m0, s21, 0x2000
	s_nop 0
	global_load_lds_dwordx4 v[202:203], off
	v_lshl_add_u64 v[202:203], v[226:227], 0, s[12:13]
	s_mov_b32 m0, s53
	s_nop 0
	global_load_lds_dwordx4 v[202:203], off
	v_lshl_add_u64 v[202:203], v[228:229], 0, s[12:13]
	s_mov_b32 m0, s54
	s_nop 0
	global_load_lds_dwordx4 v[202:203], off
	s_waitcnt vmcnt(8)
	s_waitcnt lgkmcnt(0)
	s_barrier
	s_setprio 1
	s_waitcnt lgkmcnt(0)
	v_mfma_f32_16x16x32_bf16 v[62:65], v[130:133], v[182:185], v[62:65]
	v_mfma_f32_16x16x32_bf16 v[58:61], v[138:141], v[182:185], v[58:61]
	v_mfma_f32_16x16x32_bf16 v[46:49], v[130:133], v[190:193], v[46:49]
	v_mfma_f32_16x16x32_bf16 v[42:45], v[138:141], v[190:193], v[42:45]
	v_mfma_f32_16x16x32_bf16 v[30:33], v[130:133], v[210:213], v[30:33]
	v_mfma_f32_16x16x32_bf16 v[26:29], v[138:141], v[210:213], v[26:29]
	v_mfma_f32_16x16x32_bf16 v[14:17], v[130:133], v[218:221], v[14:17]
	v_mfma_f32_16x16x32_bf16 v[10:13], v[138:141], v[218:221], v[10:13]
	v_mfma_f32_16x16x32_bf16 v[62:65], v[134:137], v[186:189], v[62:65]
	v_mfma_f32_16x16x32_bf16 v[58:61], v[142:145], v[186:189], v[58:61]
	v_mfma_f32_16x16x32_bf16 v[46:49], v[134:137], v[198:201], v[46:49]
	v_mfma_f32_16x16x32_bf16 v[42:45], v[142:145], v[198:201], v[42:45]
	v_mfma_f32_16x16x32_bf16 v[30:33], v[134:137], v[214:217], v[30:33]
	v_mfma_f32_16x16x32_bf16 v[26:29], v[142:145], v[214:217], v[26:29]
	v_mfma_f32_16x16x32_bf16 v[14:17], v[134:137], v[222:225], v[14:17]
	v_mfma_f32_16x16x32_bf16 v[10:13], v[142:145], v[222:225], v[10:13]
	v_mfma_f32_16x16x32_bf16 v[54:57], v[160:163], v[182:185], v[54:57]
	v_mfma_f32_16x16x32_bf16 v[50:53], v[174:177], v[182:185], v[50:53]
	v_mfma_f32_16x16x32_bf16 v[38:41], v[160:163], v[190:193], v[38:41]
	v_mfma_f32_16x16x32_bf16 v[34:37], v[174:177], v[190:193], v[34:37]
	v_mfma_f32_16x16x32_bf16 v[22:25], v[160:163], v[210:213], v[22:25]
	v_mfma_f32_16x16x32_bf16 v[18:21], v[174:177], v[210:213], v[18:21]
	v_mfma_f32_16x16x32_bf16 v[6:9], v[160:163], v[218:221], v[6:9]
	v_mfma_f32_16x16x32_bf16 v[2:5], v[174:177], v[218:221], v[2:5]
	v_mfma_f32_16x16x32_bf16 v[54:57], v[164:167], v[186:189], v[54:57]
	v_mfma_f32_16x16x32_bf16 v[50:53], v[178:181], v[186:189], v[50:53]
	v_mfma_f32_16x16x32_bf16 v[38:41], v[164:167], v[198:201], v[38:41]
	v_mfma_f32_16x16x32_bf16 v[34:37], v[178:181], v[198:201], v[34:37]
	v_mfma_f32_16x16x32_bf16 v[22:25], v[164:167], v[214:217], v[22:25]
	v_mfma_f32_16x16x32_bf16 v[18:21], v[178:181], v[214:217], v[18:21]
	v_mfma_f32_16x16x32_bf16 v[6:9], v[164:167], v[222:225], v[6:9]
	s_barrier
	v_mfma_f32_16x16x32_bf16 v[2:5], v[178:181], v[222:225], v[2:5]
	s_setprio 2
	s_add_u32 s34, s34, 0x100
	s_addc_u32 s35, s35, 0
	s_add_u32 s17, s17, 0x100
	s_addc_u32 s19, s19, 0
	s_cmp_ge_i32 s31, s69
	s_mov_b32 s21, s31
	s_cbranch_scc0 .LBB0_1122

.Lpeel_7:
	v_add_u32_e32 v250, 0x18000, v146
	ds_read_b128 v[152:155], v148
	ds_read_b128 v[156:159], v148 offset:1024
	s_add_i32 s29, s19, 2
	s_add_u32 s34, s30, 0xfff80080
	s_addc_u32 s35, s31, -1
	s_cmp_eq_u32 s28, s19
	s_cselect_b32 s37, s21, s35
	s_cselect_b32 s36, s20, s34
	s_cselect_b32 s35, s23, s17
	s_cselect_b32 s34, s22, s15
	v_lshl_add_u64 v[144:145], s[30:31], 0, v[140:141]
	s_add_i32 m0, s27, 0xc000
	global_load_lds_dwordx4 v[144:145], off
	v_lshl_add_u64 v[144:145], s[30:31], 0, v[142:143]
	s_add_i32 m0, s27, 0xe000
	s_nop 0
	global_load_lds_dwordx4 v[144:145], off
	s_waitcnt vmcnt(8)
	s_waitcnt lgkmcnt(0)
	s_barrier
	s_setprio 1
	s_waitcnt lgkmcnt(0)
	v_mfma_f32_16x16x32_bf16 v[126:129], v[152:155], v[184:187], 0
	v_mfma_f32_16x16x32_bf16 v[122:125], v[160:163], v[184:187], 0
	v_mfma_f32_16x16x32_bf16 v[110:113], v[152:155], v[198:201], 0
	v_mfma_f32_16x16x32_bf16 v[106:109], v[160:163], v[198:201], 0
	v_mfma_f32_16x16x32_bf16 v[94:97], v[152:155], v[214:217], 0
	v_mfma_f32_16x16x32_bf16 v[90:93], v[160:163], v[214:217], 0
	v_mfma_f32_16x16x32_bf16 v[78:81], v[152:155], v[222:225], 0
	v_mfma_f32_16x16x32_bf16 v[74:77], v[160:163], v[222:225], 0
	v_mfma_f32_16x16x32_bf16 v[126:129], v[156:159], v[188:191], v[126:129]
	v_mfma_f32_16x16x32_bf16 v[122:125], v[164:167], v[188:191], v[122:125]
	v_mfma_f32_16x16x32_bf16 v[110:113], v[156:159], v[210:213], v[110:113]
	v_mfma_f32_16x16x32_bf16 v[106:109], v[164:167], v[210:213], v[106:109]
	v_mfma_f32_16x16x32_bf16 v[94:97], v[156:159], v[218:221], v[94:97]
	v_mfma_f32_16x16x32_bf16 v[90:93], v[164:167], v[218:221], v[90:93]
	v_mfma_f32_16x16x32_bf16 v[78:81], v[156:159], v[226:229], v[78:81]
	v_mfma_f32_16x16x32_bf16 v[74:77], v[164:167], v[226:229], v[74:77]
	v_mfma_f32_16x16x32_bf16 v[118:121], v[168:171], v[184:187], 0
	v_mfma_f32_16x16x32_bf16 v[114:117], v[176:179], v[184:187], 0
	v_mfma_f32_16x16x32_bf16 v[102:105], v[168:171], v[198:201], 0
	v_mfma_f32_16x16x32_bf16 v[98:101], v[176:179], v[198:201], 0
	v_mfma_f32_16x16x32_bf16 v[86:89], v[168:171], v[214:217], 0
	v_mfma_f32_16x16x32_bf16 v[82:85], v[176:179], v[214:217], 0
	v_mfma_f32_16x16x32_bf16 v[70:73], v[168:171], v[222:225], 0
	v_mfma_f32_16x16x32_bf16 v[66:69], v[176:179], v[222:225], 0
	v_mfma_f32_16x16x32_bf16 v[118:121], v[172:175], v[188:191], v[118:121]
	v_mfma_f32_16x16x32_bf16 v[114:117], v[180:183], v[188:191], v[114:117]
	v_mfma_f32_16x16x32_bf16 v[102:105], v[172:175], v[210:213], v[102:105]
	v_mfma_f32_16x16x32_bf16 v[98:101], v[180:183], v[210:213], v[98:101]
	v_mfma_f32_16x16x32_bf16 v[86:89], v[172:175], v[218:221], v[86:89]
	v_mfma_f32_16x16x32_bf16 v[82:85], v[180:183], v[218:221], v[82:85]
	v_mfma_f32_16x16x32_bf16 v[70:73], v[172:175], v[226:229], v[70:73]
	s_barrier
	v_mfma_f32_16x16x32_bf16 v[66:69], v[180:183], v[226:229], v[66:69]
	s_setprio 2
	s_add_i32 s19, s60, s33
	v_lshl_add_u64 v[144:145], s[34:35], 0, v[132:133]
	s_mov_b32 m0, s19
	ds_read_b128 v[184:187], v150 offset:16384
	ds_read_b128 v[188:191], v150 offset:17408
	ds_read_b128 v[198:201], v150 offset:18432
	ds_read_b128 v[210:213], v150 offset:19456
	ds_read_b128 v[214:217], v150 offset:20480
	ds_read_b128 v[218:221], v150 offset:21504
	ds_read_b128 v[222:225], v150 offset:22528
	ds_read_b128 v[226:229], v150 offset:23552
	global_load_lds_dwordx4 v[144:145], off
	s_add_i32 m0, s19, 0x2000
	s_add_u32 s38, s34, 0x80000
	v_lshl_add_u64 v[192:193], s[34:35], 0, v[136:137]
	s_addc_u32 s39, s35, 0
	s_add_i32 s19, s61, s33
	global_load_lds_dwordx4 v[192:193], off
	v_lshl_add_u64 v[202:203], s[38:39], 0, v[132:133]
	s_mov_b32 m0, s19
	v_lshl_add_u64 v[206:207], s[36:37], 0, v[134:135]
	global_load_lds_dwordx4 v[202:203], off
	v_lshl_add_u64 v[202:203], s[38:39], 0, v[136:137]
	s_add_i32 m0, s19, 0x2000
	s_nop 0
	global_load_lds_dwordx4 v[202:203], off
	v_lshl_add_u64 v[202:203], s[36:37], 0, v[130:131]
	s_mov_b32 m0, s27
	s_nop 0
	global_load_lds_dwordx4 v[202:203], off
	s_mov_b32 m0, s41
	s_nop 0
	global_load_lds_dwordx4 v[206:207], off
	s_waitcnt vmcnt(8)
	s_waitcnt lgkmcnt(0)
	s_barrier
	s_setprio 1
	s_waitcnt lgkmcnt(0)
	v_mfma_f32_16x16x32_bf16 v[62:65], v[152:155], v[184:187], 0
	v_mfma_f32_16x16x32_bf16 v[58:61], v[160:163], v[184:187], 0
	v_mfma_f32_16x16x32_bf16 v[46:49], v[152:155], v[198:201], 0
	v_mfma_f32_16x16x32_bf16 v[42:45], v[160:163], v[198:201], 0
	v_mfma_f32_16x16x32_bf16 v[30:33], v[152:155], v[214:217], 0
	v_mfma_f32_16x16x32_bf16 v[26:29], v[160:163], v[214:217], 0
	v_mfma_f32_16x16x32_bf16 v[14:17], v[152:155], v[222:225], 0
	v_mfma_f32_16x16x32_bf16 v[10:13], v[160:163], v[222:225], 0
	v_mfma_f32_16x16x32_bf16 v[62:65], v[156:159], v[188:191], v[62:65]
	v_mfma_f32_16x16x32_bf16 v[58:61], v[164:167], v[188:191], v[58:61]
	v_mfma_f32_16x16x32_bf16 v[46:49], v[156:159], v[210:213], v[46:49]
	v_mfma_f32_16x16x32_bf16 v[42:45], v[164:167], v[210:213], v[42:45]
	v_mfma_f32_16x16x32_bf16 v[30:33], v[156:159], v[218:221], v[30:33]
	v_mfma_f32_16x16x32_bf16 v[26:29], v[164:167], v[218:221], v[26:29]
	v_mfma_f32_16x16x32_bf16 v[14:17], v[156:159], v[226:229], v[14:17]
	v_mfma_f32_16x16x32_bf16 v[10:13], v[164:167], v[226:229], v[10:13]
	v_mfma_f32_16x16x32_bf16 v[54:57], v[168:171], v[184:187], 0
	v_mfma_f32_16x16x32_bf16 v[50:53], v[176:179], v[184:187], 0
	v_mfma_f32_16x16x32_bf16 v[38:41], v[168:171], v[198:201], 0
	v_mfma_f32_16x16x32_bf16 v[34:37], v[176:179], v[198:201], 0
	v_mfma_f32_16x16x32_bf16 v[22:25], v[168:171], v[214:217], 0
	v_mfma_f32_16x16x32_bf16 v[18:21], v[176:179], v[214:217], 0
	v_mfma_f32_16x16x32_bf16 v[6:9], v[168:171], v[222:225], 0
	v_mfma_f32_16x16x32_bf16 v[2:5], v[176:179], v[222:225], 0
	v_mfma_f32_16x16x32_bf16 v[54:57], v[172:175], v[188:191], v[54:57]
	v_mfma_f32_16x16x32_bf16 v[50:53], v[180:183], v[188:191], v[50:53]
	v_mfma_f32_16x16x32_bf16 v[38:41], v[172:175], v[210:213], v[38:41]
	v_mfma_f32_16x16x32_bf16 v[34:37], v[180:183], v[210:213], v[34:37]
	v_mfma_f32_16x16x32_bf16 v[22:25], v[172:175], v[218:221], v[22:25]
	v_mfma_f32_16x16x32_bf16 v[18:21], v[180:183], v[218:221], v[18:21]
	v_mfma_f32_16x16x32_bf16 v[6:9], v[172:175], v[226:229], v[6:9]
	s_barrier
	v_mfma_f32_16x16x32_bf16 v[2:5], v[180:183], v[226:229], v[2:5]
	s_setprio 2
	s_add_i32 s19, 0, 0x18000
	s_add_i32 s38, 0, 0x1c000
	ds_read_b128 v[152:155], v250
	ds_read_b128 v[156:159], v250 offset:1024
	ds_read_b128 v[160:163], v250 offset:2048
	ds_read_b128 v[164:167], v250 offset:3072
	ds_read_b128 v[168:171], v250 offset:16384
	ds_read_b128 v[172:175], v250 offset:17408
	ds_read_b128 v[176:179], v250 offset:18432
	ds_read_b128 v[180:183], v250 offset:19456
	v_add_u32_e32 v151, s38, v146
	s_add_u32 s36, s36, 0x80000
	s_addc_u32 s37, s37, 0
	s_mov_b32 m0, s42
	v_lshl_add_u64 v[230:231], s[36:37], 0, v[130:131]
	ds_read_b128 v[184:187], v150 offset:32768
	ds_read_b128 v[188:191], v150 offset:33792
	ds_read_b128 v[198:201], v150 offset:34816
	ds_read_b128 v[210:213], v150 offset:35840
	ds_read_b128 v[214:217], v150 offset:36864
	ds_read_b128 v[218:221], v150 offset:37888
	ds_read_b128 v[222:225], v150 offset:38912
	ds_read_b128 v[226:229], v150 offset:39936
	global_load_lds_dwordx4 v[230:231], off
	v_lshl_add_u64 v[230:231], s[36:37], 0, v[134:135]
	s_mov_b32 m0, s43
	s_nop 0
	global_load_lds_dwordx4 v[230:231], off
	s_waitcnt vmcnt(8)
	s_waitcnt lgkmcnt(0)
	s_barrier
	s_setprio 1
	s_waitcnt lgkmcnt(0)
	v_mfma_f32_16x16x32_bf16 v[126:129], v[152:155], v[184:187], v[126:129]
	v_mfma_f32_16x16x32_bf16 v[122:125], v[160:163], v[184:187], v[122:125]
	v_mfma_f32_16x16x32_bf16 v[110:113], v[152:155], v[198:201], v[110:113]
	v_mfma_f32_16x16x32_bf16 v[106:109], v[160:163], v[198:201], v[106:109]
	v_mfma_f32_16x16x32_bf16 v[94:97], v[152:155], v[214:217], v[94:97]
	v_mfma_f32_16x16x32_bf16 v[90:93], v[160:163], v[214:217], v[90:93]
	v_mfma_f32_16x16x32_bf16 v[78:81], v[152:155], v[222:225], v[78:81]
	v_mfma_f32_16x16x32_bf16 v[74:77], v[160:163], v[222:225], v[74:77]
	v_mfma_f32_16x16x32_bf16 v[126:129], v[156:159], v[188:191], v[126:129]
	v_mfma_f32_16x16x32_bf16 v[122:125], v[164:167], v[188:191], v[122:125]
	v_mfma_f32_16x16x32_bf16 v[110:113], v[156:159], v[210:213], v[110:113]
	v_mfma_f32_16x16x32_bf16 v[106:109], v[164:167], v[210:213], v[106:109]
	v_mfma_f32_16x16x32_bf16 v[94:97], v[156:159], v[218:221], v[94:97]
	v_mfma_f32_16x16x32_bf16 v[90:93], v[164:167], v[218:221], v[90:93]
	v_mfma_f32_16x16x32_bf16 v[78:81], v[156:159], v[226:229], v[78:81]
	v_mfma_f32_16x16x32_bf16 v[74:77], v[164:167], v[226:229], v[74:77]
	v_mfma_f32_16x16x32_bf16 v[118:121], v[168:171], v[184:187], v[118:121]
	v_mfma_f32_16x16x32_bf16 v[114:117], v[176:179], v[184:187], v[114:117]
	v_mfma_f32_16x16x32_bf16 v[102:105], v[168:171], v[198:201], v[102:105]
	v_mfma_f32_16x16x32_bf16 v[98:101], v[176:179], v[198:201], v[98:101]
	v_mfma_f32_16x16x32_bf16 v[86:89], v[168:171], v[214:217], v[86:89]
	v_mfma_f32_16x16x32_bf16 v[82:85], v[176:179], v[214:217], v[82:85]
	v_mfma_f32_16x16x32_bf16 v[70:73], v[168:171], v[222:225], v[70:73]
	v_mfma_f32_16x16x32_bf16 v[66:69], v[176:179], v[222:225], v[66:69]
	v_mfma_f32_16x16x32_bf16 v[118:121], v[172:175], v[188:191], v[118:121]
	v_mfma_f32_16x16x32_bf16 v[114:117], v[180:183], v[188:191], v[114:117]
	v_mfma_f32_16x16x32_bf16 v[102:105], v[172:175], v[210:213], v[102:105]
	v_mfma_f32_16x16x32_bf16 v[98:101], v[180:183], v[210:213], v[98:101]
	v_mfma_f32_16x16x32_bf16 v[86:89], v[172:175], v[218:221], v[86:89]
	v_mfma_f32_16x16x32_bf16 v[82:85], v[180:183], v[218:221], v[82:85]
	v_mfma_f32_16x16x32_bf16 v[70:73], v[172:175], v[226:229], v[70:73]
	s_barrier
	v_mfma_f32_16x16x32_bf16 v[66:69], v[180:183], v[226:229], v[66:69]
	s_setprio 2
	s_add_i32 s19, s19, s33
	v_lshl_add_u64 v[144:145], v[144:145], 0, s[10:11]
	s_mov_b32 m0, s19
	ds_read_b128 v[184:187], v150 offset:49152
	ds_read_b128 v[188:191], v150 offset:50176
	ds_read_b128 v[198:201], v150 offset:51200
	ds_read_b128 v[210:213], v150 offset:52224
	ds_read_b128 v[214:217], v150 offset:53248
	ds_read_b128 v[218:221], v150 offset:54272
	ds_read_b128 v[222:225], v150 offset:55296
	ds_read_b128 v[226:229], v150 offset:56320
	global_load_lds_dwordx4 v[144:145], off
	s_add_i32 m0, s19, 0x2000
	s_add_u32 s34, s34, 0x80080
	v_lshl_add_u64 v[144:145], v[192:193], 0, s[10:11]
	s_addc_u32 s35, s35, 0
	s_add_i32 s19, s38, s33
	global_load_lds_dwordx4 v[144:145], off
	v_lshl_add_u64 v[144:145], s[34:35], 0, v[132:133]
	s_mov_b32 m0, s19
	s_nop 0
	global_load_lds_dwordx4 v[144:145], off
	v_lshl_add_u64 v[144:145], s[34:35], 0, v[136:137]
	s_add_i32 m0, s19, 0x2000
	s_nop 0
	global_load_lds_dwordx4 v[144:145], off
	v_lshl_add_u64 v[144:145], v[202:203], 0, s[10:11]
	s_mov_b32 m0, s51
	s_nop 0
	global_load_lds_dwordx4 v[144:145], off
	v_lshl_add_u64 v[144:145], v[206:207], 0, s[10:11]
	s_mov_b32 m0, s52
	s_nop 0
	global_load_lds_dwordx4 v[144:145], off
	s_waitcnt vmcnt(8)
	s_waitcnt lgkmcnt(0)
	s_barrier
	s_setprio 1
	s_waitcnt lgkmcnt(0)
	v_mfma_f32_16x16x32_bf16 v[62:65], v[152:155], v[184:187], v[62:65]
	v_mfma_f32_16x16x32_bf16 v[58:61], v[160:163], v[184:187], v[58:61]
	v_mfma_f32_16x16x32_bf16 v[46:49], v[152:155], v[198:201], v[46:49]
	v_mfma_f32_16x16x32_bf16 v[42:45], v[160:163], v[198:201], v[42:45]
	v_mfma_f32_16x16x32_bf16 v[30:33], v[152:155], v[214:217], v[30:33]
	v_mfma_f32_16x16x32_bf16 v[26:29], v[160:163], v[214:217], v[26:29]
	v_mfma_f32_16x16x32_bf16 v[14:17], v[152:155], v[222:225], v[14:17]
	v_mfma_f32_16x16x32_bf16 v[10:13], v[160:163], v[222:225], v[10:13]
	v_mfma_f32_16x16x32_bf16 v[62:65], v[156:159], v[188:191], v[62:65]
	v_mfma_f32_16x16x32_bf16 v[58:61], v[164:167], v[188:191], v[58:61]
	v_mfma_f32_16x16x32_bf16 v[46:49], v[156:159], v[210:213], v[46:49]
	v_mfma_f32_16x16x32_bf16 v[42:45], v[164:167], v[210:213], v[42:45]
	v_mfma_f32_16x16x32_bf16 v[30:33], v[156:159], v[218:221], v[30:33]
	v_mfma_f32_16x16x32_bf16 v[26:29], v[164:167], v[218:221], v[26:29]
	v_mfma_f32_16x16x32_bf16 v[14:17], v[156:159], v[226:229], v[14:17]
	v_mfma_f32_16x16x32_bf16 v[10:13], v[164:167], v[226:229], v[10:13]
	v_mfma_f32_16x16x32_bf16 v[54:57], v[168:171], v[184:187], v[54:57]
	v_mfma_f32_16x16x32_bf16 v[50:53], v[176:179], v[184:187], v[50:53]
	v_mfma_f32_16x16x32_bf16 v[38:41], v[168:171], v[198:201], v[38:41]
	v_mfma_f32_16x16x32_bf16 v[34:37], v[176:179], v[198:201], v[34:37]
	v_mfma_f32_16x16x32_bf16 v[22:25], v[168:171], v[214:217], v[22:25]
	v_mfma_f32_16x16x32_bf16 v[18:21], v[176:179], v[214:217], v[18:21]
	v_mfma_f32_16x16x32_bf16 v[6:9], v[168:171], v[222:225], v[6:9]
	v_mfma_f32_16x16x32_bf16 v[2:5], v[176:179], v[222:225], v[2:5]
	v_mfma_f32_16x16x32_bf16 v[54:57], v[172:175], v[188:191], v[54:57]
	v_mfma_f32_16x16x32_bf16 v[50:53], v[180:183], v[188:191], v[50:53]
	v_mfma_f32_16x16x32_bf16 v[38:41], v[172:175], v[210:213], v[38:41]
	v_mfma_f32_16x16x32_bf16 v[34:37], v[180:183], v[210:213], v[34:37]
	v_mfma_f32_16x16x32_bf16 v[22:25], v[172:175], v[218:221], v[22:25]
	v_mfma_f32_16x16x32_bf16 v[18:21], v[180:183], v[218:221], v[18:21]
	v_mfma_f32_16x16x32_bf16 v[6:9], v[172:175], v[226:229], v[6:9]
	s_barrier
	v_mfma_f32_16x16x32_bf16 v[2:5], v[180:183], v[226:229], v[2:5]
	s_setprio 2
	s_add_u32 s30, s30, 0x100
	s_addc_u32 s31, s31, 0
	s_add_u32 s15, s15, 0x100
	s_addc_u32 s17, s17, 0
	s_cmp_ge_i32 s29, s68
	s_mov_b32 s19, s29
	s_cbranch_scc0 .LBB0_1315
	s_branch .Lpeeldone_7
.LBB0_1315:
	ds_read_b128 v[152:155], v148
	ds_read_b128 v[156:159], v148 offset:1024
	ds_read_b128 v[160:163], v148 offset:2048
	ds_read_b128 v[164:167], v148 offset:3072
	ds_read_b128 v[168:171], v149
	ds_read_b128 v[172:175], v149 offset:1024
	ds_read_b128 v[176:179], v149 offset:2048
	ds_read_b128 v[180:183], v149 offset:3072
	s_add_i32 s29, s19, 2
	s_add_u32 s34, s30, 0xfff80080
	s_addc_u32 s35, s31, -1
	s_cmp_eq_u32 s28, s19
	s_cselect_b32 s37, s21, s35
	s_cselect_b32 s36, s20, s34
	s_cselect_b32 s35, s23, s17
	s_cselect_b32 s34, s22, s15
	v_lshl_add_u64 v[144:145], s[30:31], 0, v[140:141]
	s_add_i32 m0, s27, 0xc000
	ds_read_b128 v[184:187], v150
	ds_read_b128 v[188:191], v150 offset:1024
	ds_read_b128 v[198:201], v150 offset:2048
	ds_read_b128 v[210:213], v150 offset:3072
	ds_read_b128 v[214:217], v150 offset:4096
	ds_read_b128 v[218:221], v150 offset:5120
	ds_read_b128 v[222:225], v150 offset:6144
	ds_read_b128 v[226:229], v150 offset:7168
	global_load_lds_dwordx4 v[144:145], off
	v_lshl_add_u64 v[144:145], s[30:31], 0, v[142:143]
	s_add_i32 m0, s27, 0xe000
	s_nop 0
	global_load_lds_dwordx4 v[144:145], off
	s_waitcnt vmcnt(8)
	s_waitcnt lgkmcnt(0)
	s_barrier
	s_setprio 1
	s_waitcnt lgkmcnt(0)
	v_mfma_f32_16x16x32_bf16 v[126:129], v[152:155], v[184:187], v[126:129]
	v_mfma_f32_16x16x32_bf16 v[122:125], v[160:163], v[184:187], v[122:125]
	v_mfma_f32_16x16x32_bf16 v[110:113], v[152:155], v[198:201], v[110:113]
	v_mfma_f32_16x16x32_bf16 v[106:109], v[160:163], v[198:201], v[106:109]
	v_mfma_f32_16x16x32_bf16 v[94:97], v[152:155], v[214:217], v[94:97]
	v_mfma_f32_16x16x32_bf16 v[90:93], v[160:163], v[214:217], v[90:93]
	v_mfma_f32_16x16x32_bf16 v[78:81], v[152:155], v[222:225], v[78:81]
	v_mfma_f32_16x16x32_bf16 v[74:77], v[160:163], v[222:225], v[74:77]
	v_mfma_f32_16x16x32_bf16 v[126:129], v[156:159], v[188:191], v[126:129]
	v_mfma_f32_16x16x32_bf16 v[122:125], v[164:167], v[188:191], v[122:125]
	v_mfma_f32_16x16x32_bf16 v[110:113], v[156:159], v[210:213], v[110:113]
	v_mfma_f32_16x16x32_bf16 v[106:109], v[164:167], v[210:213], v[106:109]
	v_mfma_f32_16x16x32_bf16 v[94:97], v[156:159], v[218:221], v[94:97]
	v_mfma_f32_16x16x32_bf16 v[90:93], v[164:167], v[218:221], v[90:93]
	v_mfma_f32_16x16x32_bf16 v[78:81], v[156:159], v[226:229], v[78:81]
	v_mfma_f32_16x16x32_bf16 v[74:77], v[164:167], v[226:229], v[74:77]
	v_mfma_f32_16x16x32_bf16 v[118:121], v[168:171], v[184:187], v[118:121]
	v_mfma_f32_16x16x32_bf16 v[114:117], v[176:179], v[184:187], v[114:117]
	v_mfma_f32_16x16x32_bf16 v[102:105], v[168:171], v[198:201], v[102:105]
	v_mfma_f32_16x16x32_bf16 v[98:101], v[176:179], v[198:201], v[98:101]
	v_mfma_f32_16x16x32_bf16 v[86:89], v[168:171], v[214:217], v[86:89]
	v_mfma_f32_16x16x32_bf16 v[82:85], v[176:179], v[214:217], v[82:85]
	v_mfma_f32_16x16x32_bf16 v[70:73], v[168:171], v[222:225], v[70:73]
	v_mfma_f32_16x16x32_bf16 v[66:69], v[176:179], v[222:225], v[66:69]
	v_mfma_f32_16x16x32_bf16 v[118:121], v[172:175], v[188:191], v[118:121]
	v_mfma_f32_16x16x32_bf16 v[114:117], v[180:183], v[188:191], v[114:117]
	v_mfma_f32_16x16x32_bf16 v[102:105], v[172:175], v[210:213], v[102:105]
	v_mfma_f32_16x16x32_bf16 v[98:101], v[180:183], v[210:213], v[98:101]
	v_mfma_f32_16x16x32_bf16 v[86:89], v[172:175], v[218:221], v[86:89]
	v_mfma_f32_16x16x32_bf16 v[82:85], v[180:183], v[218:221], v[82:85]
	v_mfma_f32_16x16x32_bf16 v[70:73], v[172:175], v[226:229], v[70:73]
	s_barrier
	v_mfma_f32_16x16x32_bf16 v[66:69], v[180:183], v[226:229], v[66:69]
	s_setprio 2
	s_add_i32 s19, s60, s33
	v_lshl_add_u64 v[144:145], s[34:35], 0, v[132:133]
	s_mov_b32 m0, s19
	ds_read_b128 v[184:187], v150 offset:16384
	ds_read_b128 v[188:191], v150 offset:17408
	ds_read_b128 v[198:201], v150 offset:18432
	ds_read_b128 v[210:213], v150 offset:19456
	ds_read_b128 v[214:217], v150 offset:20480
	ds_read_b128 v[218:221], v150 offset:21504
	ds_read_b128 v[222:225], v150 offset:22528
	ds_read_b128 v[226:229], v150 offset:23552
	global_load_lds_dwordx4 v[144:145], off
	s_add_i32 m0, s19, 0x2000
	s_add_u32 s38, s34, 0x80000
	v_lshl_add_u64 v[192:193], s[34:35], 0, v[136:137]
	s_addc_u32 s39, s35, 0
	s_add_i32 s19, s61, s33
	global_load_lds_dwordx4 v[192:193], off
	v_lshl_add_u64 v[202:203], s[38:39], 0, v[132:133]
	s_mov_b32 m0, s19
	v_lshl_add_u64 v[206:207], s[36:37], 0, v[134:135]
	global_load_lds_dwordx4 v[202:203], off
	v_lshl_add_u64 v[202:203], s[38:39], 0, v[136:137]
	s_add_i32 m0, s19, 0x2000
	s_nop 0
	global_load_lds_dwordx4 v[202:203], off
	v_lshl_add_u64 v[202:203], s[36:37], 0, v[130:131]
	s_mov_b32 m0, s27
	s_nop 0
	global_load_lds_dwordx4 v[202:203], off
	s_mov_b32 m0, s41
	s_nop 0
	global_load_lds_dwordx4 v[206:207], off
	s_waitcnt vmcnt(8)
	s_waitcnt lgkmcnt(0)
	s_barrier
	s_setprio 1
	s_waitcnt lgkmcnt(0)
	v_mfma_f32_16x16x32_bf16 v[62:65], v[152:155], v[184:187], v[62:65]
	v_mfma_f32_16x16x32_bf16 v[58:61], v[160:163], v[184:187], v[58:61]
	v_mfma_f32_16x16x32_bf16 v[46:49], v[152:155], v[198:201], v[46:49]
	v_mfma_f32_16x16x32_bf16 v[42:45], v[160:163], v[198:201], v[42:45]
	v_mfma_f32_16x16x32_bf16 v[30:33], v[152:155], v[214:217], v[30:33]
	v_mfma_f32_16x16x32_bf16 v[26:29], v[160:163], v[214:217], v[26:29]
	v_mfma_f32_16x16x32_bf16 v[14:17], v[152:155], v[222:225], v[14:17]
	v_mfma_f32_16x16x32_bf16 v[10:13], v[160:163], v[222:225], v[10:13]
	v_mfma_f32_16x16x32_bf16 v[62:65], v[156:159], v[188:191], v[62:65]
	v_mfma_f32_16x16x32_bf16 v[58:61], v[164:167], v[188:191], v[58:61]
	v_mfma_f32_16x16x32_bf16 v[46:49], v[156:159], v[210:213], v[46:49]
	v_mfma_f32_16x16x32_bf16 v[42:45], v[164:167], v[210:213], v[42:45]
	v_mfma_f32_16x16x32_bf16 v[30:33], v[156:159], v[218:221], v[30:33]
	v_mfma_f32_16x16x32_bf16 v[26:29], v[164:167], v[218:221], v[26:29]
	v_mfma_f32_16x16x32_bf16 v[14:17], v[156:159], v[226:229], v[14:17]
	v_mfma_f32_16x16x32_bf16 v[10:13], v[164:167], v[226:229], v[10:13]
	v_mfma_f32_16x16x32_bf16 v[54:57], v[168:171], v[184:187], v[54:57]
	v_mfma_f32_16x16x32_bf16 v[50:53], v[176:179], v[184:187], v[50:53]
	v_mfma_f32_16x16x32_bf16 v[38:41], v[168:171], v[198:201], v[38:41]
	v_mfma_f32_16x16x32_bf16 v[34:37], v[176:179], v[198:201], v[34:37]
	v_mfma_f32_16x16x32_bf16 v[22:25], v[168:171], v[214:217], v[22:25]
	v_mfma_f32_16x16x32_bf16 v[18:21], v[176:179], v[214:217], v[18:21]
	v_mfma_f32_16x16x32_bf16 v[6:9], v[168:171], v[222:225], v[6:9]
	v_mfma_f32_16x16x32_bf16 v[2:5], v[176:179], v[222:225], v[2:5]
	v_mfma_f32_16x16x32_bf16 v[54:57], v[172:175], v[188:191], v[54:57]
	v_mfma_f32_16x16x32_bf16 v[50:53], v[180:183], v[188:191], v[50:53]
	v_mfma_f32_16x16x32_bf16 v[38:41], v[172:175], v[210:213], v[38:41]
	v_mfma_f32_16x16x32_bf16 v[34:37], v[180:183], v[210:213], v[34:37]
	v_mfma_f32_16x16x32_bf16 v[22:25], v[172:175], v[218:221], v[22:25]
	v_mfma_f32_16x16x32_bf16 v[18:21], v[180:183], v[218:221], v[18:21]
	v_mfma_f32_16x16x32_bf16 v[6:9], v[172:175], v[226:229], v[6:9]
	s_barrier
	v_mfma_f32_16x16x32_bf16 v[2:5], v[180:183], v[226:229], v[2:5]
	s_setprio 2
	s_add_i32 s19, 0, 0x18000
	s_add_i32 s38, 0, 0x1c000
	ds_read_b128 v[152:155], v250
	ds_read_b128 v[156:159], v250 offset:1024
	ds_read_b128 v[160:163], v250 offset:2048
	ds_read_b128 v[164:167], v250 offset:3072
	ds_read_b128 v[168:171], v250 offset:16384
	ds_read_b128 v[172:175], v250 offset:17408
	ds_read_b128 v[176:179], v250 offset:18432
	ds_read_b128 v[180:183], v250 offset:19456
	v_add_u32_e32 v151, s38, v146
	s_add_u32 s36, s36, 0x80000
	s_addc_u32 s37, s37, 0
	s_mov_b32 m0, s42
	v_lshl_add_u64 v[230:231], s[36:37], 0, v[130:131]
	ds_read_b128 v[184:187], v150 offset:32768
	ds_read_b128 v[188:191], v150 offset:33792
	ds_read_b128 v[198:201], v150 offset:34816
	ds_read_b128 v[210:213], v150 offset:35840
	ds_read_b128 v[214:217], v150 offset:36864
	ds_read_b128 v[218:221], v150 offset:37888
	ds_read_b128 v[222:225], v150 offset:38912
	ds_read_b128 v[226:229], v150 offset:39936
	global_load_lds_dwordx4 v[230:231], off
	v_lshl_add_u64 v[230:231], s[36:37], 0, v[134:135]
	s_mov_b32 m0, s43
	s_nop 0
	global_load_lds_dwordx4 v[230:231], off
	s_waitcnt vmcnt(8)
	s_waitcnt lgkmcnt(0)
	s_barrier
	s_setprio 1
	s_waitcnt lgkmcnt(0)
	v_mfma_f32_16x16x32_bf16 v[126:129], v[152:155], v[184:187], v[126:129]
	v_mfma_f32_16x16x32_bf16 v[122:125], v[160:163], v[184:187], v[122:125]
	v_mfma_f32_16x16x32_bf16 v[110:113], v[152:155], v[198:201], v[110:113]
	v_mfma_f32_16x16x32_bf16 v[106:109], v[160:163], v[198:201], v[106:109]
	v_mfma_f32_16x16x32_bf16 v[94:97], v[152:155], v[214:217], v[94:97]
	v_mfma_f32_16x16x32_bf16 v[90:93], v[160:163], v[214:217], v[90:93]
	v_mfma_f32_16x16x32_bf16 v[78:81], v[152:155], v[222:225], v[78:81]
	v_mfma_f32_16x16x32_bf16 v[74:77], v[160:163], v[222:225], v[74:77]
	v_mfma_f32_16x16x32_bf16 v[126:129], v[156:159], v[188:191], v[126:129]
	v_mfma_f32_16x16x32_bf16 v[122:125], v[164:167], v[188:191], v[122:125]
	v_mfma_f32_16x16x32_bf16 v[110:113], v[156:159], v[210:213], v[110:113]
	v_mfma_f32_16x16x32_bf16 v[106:109], v[164:167], v[210:213], v[106:109]
	v_mfma_f32_16x16x32_bf16 v[94:97], v[156:159], v[218:221], v[94:97]
	v_mfma_f32_16x16x32_bf16 v[90:93], v[164:167], v[218:221], v[90:93]
	v_mfma_f32_16x16x32_bf16 v[78:81], v[156:159], v[226:229], v[78:81]
	v_mfma_f32_16x16x32_bf16 v[74:77], v[164:167], v[226:229], v[74:77]
	v_mfma_f32_16x16x32_bf16 v[118:121], v[168:171], v[184:187], v[118:121]
	v_mfma_f32_16x16x32_bf16 v[114:117], v[176:179], v[184:187], v[114:117]
	v_mfma_f32_16x16x32_bf16 v[102:105], v[168:171], v[198:201], v[102:105]
	v_mfma_f32_16x16x32_bf16 v[98:101], v[176:179], v[198:201], v[98:101]
	v_mfma_f32_16x16x32_bf16 v[86:89], v[168:171], v[214:217], v[86:89]
	v_mfma_f32_16x16x32_bf16 v[82:85], v[176:179], v[214:217], v[82:85]
	v_mfma_f32_16x16x32_bf16 v[70:73], v[168:171], v[222:225], v[70:73]
	v_mfma_f32_16x16x32_bf16 v[66:69], v[176:179], v[222:225], v[66:69]
	v_mfma_f32_16x16x32_bf16 v[118:121], v[172:175], v[188:191], v[118:121]
	v_mfma_f32_16x16x32_bf16 v[114:117], v[180:183], v[188:191], v[114:117]
	v_mfma_f32_16x16x32_bf16 v[102:105], v[172:175], v[210:213], v[102:105]
	v_mfma_f32_16x16x32_bf16 v[98:101], v[180:183], v[210:213], v[98:101]
	v_mfma_f32_16x16x32_bf16 v[86:89], v[172:175], v[218:221], v[86:89]
	v_mfma_f32_16x16x32_bf16 v[82:85], v[180:183], v[218:221], v[82:85]
	v_mfma_f32_16x16x32_bf16 v[70:73], v[172:175], v[226:229], v[70:73]
	s_barrier
	v_mfma_f32_16x16x32_bf16 v[66:69], v[180:183], v[226:229], v[66:69]
	s_setprio 2
	s_add_i32 s19, s19, s33
	v_lshl_add_u64 v[144:145], v[144:145], 0, s[10:11]
	s_mov_b32 m0, s19
	ds_read_b128 v[184:187], v150 offset:49152
	ds_read_b128 v[188:191], v150 offset:50176
	ds_read_b128 v[198:201], v150 offset:51200
	ds_read_b128 v[210:213], v150 offset:52224
	ds_read_b128 v[214:217], v150 offset:53248
	ds_read_b128 v[218:221], v150 offset:54272
	ds_read_b128 v[222:225], v150 offset:55296
	ds_read_b128 v[226:229], v150 offset:56320
	global_load_lds_dwordx4 v[144:145], off
	s_add_i32 m0, s19, 0x2000
	s_add_u32 s34, s34, 0x80080
	v_lshl_add_u64 v[144:145], v[192:193], 0, s[10:11]
	s_addc_u32 s35, s35, 0
	s_add_i32 s19, s38, s33
	global_load_lds_dwordx4 v[144:145], off
	v_lshl_add_u64 v[144:145], s[34:35], 0, v[132:133]
	s_mov_b32 m0, s19
	s_nop 0
	global_load_lds_dwordx4 v[144:145], off
	v_lshl_add_u64 v[144:145], s[34:35], 0, v[136:137]
	s_add_i32 m0, s19, 0x2000
	s_nop 0
	global_load_lds_dwordx4 v[144:145], off
	v_lshl_add_u64 v[144:145], v[202:203], 0, s[10:11]
	s_mov_b32 m0, s51
	s_nop 0
	global_load_lds_dwordx4 v[144:145], off
	v_lshl_add_u64 v[144:145], v[206:207], 0, s[10:11]
	s_mov_b32 m0, s52
	s_nop 0
	global_load_lds_dwordx4 v[144:145], off
	s_waitcnt vmcnt(8)
	s_waitcnt lgkmcnt(0)
	s_barrier
	s_setprio 1
	s_waitcnt lgkmcnt(0)
	v_mfma_f32_16x16x32_bf16 v[62:65], v[152:155], v[184:187], v[62:65]
	v_mfma_f32_16x16x32_bf16 v[58:61], v[160:163], v[184:187], v[58:61]
	v_mfma_f32_16x16x32_bf16 v[46:49], v[152:155], v[198:201], v[46:49]
	v_mfma_f32_16x16x32_bf16 v[42:45], v[160:163], v[198:201], v[42:45]
	v_mfma_f32_16x16x32_bf16 v[30:33], v[152:155], v[214:217], v[30:33]
	v_mfma_f32_16x16x32_bf16 v[26:29], v[160:163], v[214:217], v[26:29]
	v_mfma_f32_16x16x32_bf16 v[14:17], v[152:155], v[222:225], v[14:17]
	v_mfma_f32_16x16x32_bf16 v[10:13], v[160:163], v[222:225], v[10:13]
	v_mfma_f32_16x16x32_bf16 v[62:65], v[156:159], v[188:191], v[62:65]
	v_mfma_f32_16x16x32_bf16 v[58:61], v[164:167], v[188:191], v[58:61]
	v_mfma_f32_16x16x32_bf16 v[46:49], v[156:159], v[210:213], v[46:49]
	v_mfma_f32_16x16x32_bf16 v[42:45], v[164:167], v[210:213], v[42:45]
	v_mfma_f32_16x16x32_bf16 v[30:33], v[156:159], v[218:221], v[30:33]
	v_mfma_f32_16x16x32_bf16 v[26:29], v[164:167], v[218:221], v[26:29]
	v_mfma_f32_16x16x32_bf16 v[14:17], v[156:159], v[226:229], v[14:17]
	v_mfma_f32_16x16x32_bf16 v[10:13], v[164:167], v[226:229], v[10:13]
	v_mfma_f32_16x16x32_bf16 v[54:57], v[168:171], v[184:187], v[54:57]
	v_mfma_f32_16x16x32_bf16 v[50:53], v[176:179], v[184:187], v[50:53]
	v_mfma_f32_16x16x32_bf16 v[38:41], v[168:171], v[198:201], v[38:41]
	v_mfma_f32_16x16x32_bf16 v[34:37], v[176:179], v[198:201], v[34:37]
	v_mfma_f32_16x16x32_bf16 v[22:25], v[168:171], v[214:217], v[22:25]
	v_mfma_f32_16x16x32_bf16 v[18:21], v[176:179], v[214:217], v[18:21]
	v_mfma_f32_16x16x32_bf16 v[6:9], v[168:171], v[222:225], v[6:9]
	v_mfma_f32_16x16x32_bf16 v[2:5], v[176:179], v[222:225], v[2:5]
	v_mfma_f32_16x16x32_bf16 v[54:57], v[172:175], v[188:191], v[54:57]
	v_mfma_f32_16x16x32_bf16 v[50:53], v[180:183], v[188:191], v[50:53]
	v_mfma_f32_16x16x32_bf16 v[38:41], v[172:175], v[210:213], v[38:41]
	v_mfma_f32_16x16x32_bf16 v[34:37], v[180:183], v[210:213], v[34:37]
	v_mfma_f32_16x16x32_bf16 v[22:25], v[172:175], v[218:221], v[22:25]
	v_mfma_f32_16x16x32_bf16 v[18:21], v[180:183], v[218:221], v[18:21]
	v_mfma_f32_16x16x32_bf16 v[6:9], v[172:175], v[226:229], v[6:9]
	s_barrier
	v_mfma_f32_16x16x32_bf16 v[2:5], v[180:183], v[226:229], v[2:5]
	s_setprio 2
	s_add_u32 s30, s30, 0x100
	s_addc_u32 s31, s31, 0
	s_add_u32 s15, s15, 0x100
	s_addc_u32 s17, s17, 0
	s_cmp_ge_i32 s29, s68
	s_mov_b32 s19, s29
	s_cbranch_scc0 .LBB0_1315

.Lpeel_6:
	v_add_u32_e32 v250, 0x18000, v164
	ds_read_b128 v[144:147], v166
	ds_read_b128 v[148:151], v166 offset:1024
	ds_read_b128 v[152:155], v166 offset:2048
	ds_read_b128 v[156:159], v166 offset:3072
	ds_read_b128 v[160:163], v167
	ds_read_b128 v[170:173], v167 offset:1024
	ds_read_b128 v[174:177], v167 offset:2048
	ds_read_b128 v[178:181], v167 offset:3072
	s_add_i32 s30, s26, 2
	s_add_u32 s27, s24, 0xffea0080
	s_addc_u32 s28, s25, -1
	s_cmp_eq_u32 s22, s26
	s_cselect_b32 s26, s20, s17
	s_cselect_b32 s29, s19, s28
	s_cselect_b32 s28, s18, s27
	s_cselect_b32 s27, s21, s23
	v_lshl_add_u64 v[202:203], s[24:25], 0, v[140:141]
	s_add_i32 m0, s34, 0xc000
	ds_read_b128 v[182:185], v168
	ds_read_b128 v[186:189], v168 offset:1024
	ds_read_b128 v[190:193], v168 offset:2048
	ds_read_b128 v[198:201], v168 offset:3072
	ds_read_b128 v[210:213], v168 offset:4096
	ds_read_b128 v[214:217], v168 offset:5120
	ds_read_b128 v[218:221], v168 offset:6144
	ds_read_b128 v[222:225], v168 offset:7168
	global_load_lds_dwordx4 v[202:203], off
	v_lshl_add_u64 v[202:203], s[24:25], 0, v[142:143]
	s_add_i32 m0, s34, 0xe000
	s_nop 0
	global_load_lds_dwordx4 v[202:203], off
	s_waitcnt vmcnt(8)
	s_waitcnt lgkmcnt(0)
	s_barrier
	s_setprio 1
	s_waitcnt lgkmcnt(0)
	v_mfma_f32_16x16x32_bf16 v[126:129], v[144:147], v[182:185], 0
	v_mfma_f32_16x16x32_bf16 v[122:125], v[152:155], v[182:185], 0
	v_mfma_f32_16x16x32_bf16 v[114:117], v[144:147], v[190:193], 0
	v_mfma_f32_16x16x32_bf16 v[106:109], v[152:155], v[190:193], 0
	v_mfma_f32_16x16x32_bf16 v[94:97], v[144:147], v[210:213], 0
	v_mfma_f32_16x16x32_bf16 v[90:93], v[152:155], v[210:213], 0
	v_mfma_f32_16x16x32_bf16 v[78:81], v[144:147], v[218:221], 0
	v_mfma_f32_16x16x32_bf16 v[74:77], v[152:155], v[218:221], 0
	v_mfma_f32_16x16x32_bf16 v[126:129], v[148:151], v[186:189], v[126:129]
	v_mfma_f32_16x16x32_bf16 v[122:125], v[156:159], v[186:189], v[122:125]
	v_mfma_f32_16x16x32_bf16 v[114:117], v[148:151], v[198:201], v[114:117]
	v_mfma_f32_16x16x32_bf16 v[106:109], v[156:159], v[198:201], v[106:109]
	v_mfma_f32_16x16x32_bf16 v[94:97], v[148:151], v[214:217], v[94:97]
	v_mfma_f32_16x16x32_bf16 v[90:93], v[156:159], v[214:217], v[90:93]
	v_mfma_f32_16x16x32_bf16 v[78:81], v[148:151], v[222:225], v[78:81]
	v_mfma_f32_16x16x32_bf16 v[74:77], v[156:159], v[222:225], v[74:77]
	v_mfma_f32_16x16x32_bf16 v[118:121], v[160:163], v[182:185], 0
	v_mfma_f32_16x16x32_bf16 v[110:113], v[174:177], v[182:185], 0
	v_mfma_f32_16x16x32_bf16 v[102:105], v[160:163], v[190:193], 0
	v_mfma_f32_16x16x32_bf16 v[98:101], v[174:177], v[190:193], 0
	v_mfma_f32_16x16x32_bf16 v[86:89], v[160:163], v[210:213], 0
	v_mfma_f32_16x16x32_bf16 v[82:85], v[174:177], v[210:213], 0
	v_mfma_f32_16x16x32_bf16 v[70:73], v[160:163], v[218:221], 0
	v_mfma_f32_16x16x32_bf16 v[66:69], v[174:177], v[218:221], 0
	v_mfma_f32_16x16x32_bf16 v[118:121], v[170:173], v[186:189], v[118:121]
	v_mfma_f32_16x16x32_bf16 v[110:113], v[178:181], v[186:189], v[110:113]
	v_mfma_f32_16x16x32_bf16 v[102:105], v[170:173], v[198:201], v[102:105]
	v_mfma_f32_16x16x32_bf16 v[98:101], v[178:181], v[198:201], v[98:101]
	v_mfma_f32_16x16x32_bf16 v[86:89], v[170:173], v[214:217], v[86:89]
	v_mfma_f32_16x16x32_bf16 v[82:85], v[178:181], v[214:217], v[82:85]
	v_mfma_f32_16x16x32_bf16 v[70:73], v[170:173], v[222:225], v[70:73]
	s_barrier
	v_mfma_f32_16x16x32_bf16 v[66:69], v[178:181], v[222:225], v[66:69]
	s_setprio 2
	s_add_i32 s31, s57, s33
	v_lshl_add_u64 v[202:203], s[26:27], 0, v[132:133]
	s_mov_b32 m0, s31
	ds_read_b128 v[182:185], v168 offset:16384
	ds_read_b128 v[186:189], v168 offset:17408
	ds_read_b128 v[190:193], v168 offset:18432
	ds_read_b128 v[198:201], v168 offset:19456
	ds_read_b128 v[210:213], v168 offset:20480
	ds_read_b128 v[214:217], v168 offset:21504
	ds_read_b128 v[218:221], v168 offset:22528
	ds_read_b128 v[222:225], v168 offset:23552
	global_load_lds_dwordx4 v[202:203], off
	s_add_i32 m0, s31, 0x2000
	s_add_u32 s68, s26, 0x160000
	v_lshl_add_u64 v[206:207], s[26:27], 0, v[136:137]
	s_addc_u32 s69, s27, 0
	s_add_i32 s31, s58, s33
	global_load_lds_dwordx4 v[206:207], off
	v_lshl_add_u64 v[226:227], s[68:69], 0, v[132:133]
	s_mov_b32 m0, s31
	v_lshl_add_u64 v[228:229], s[28:29], 0, v[134:135]
	global_load_lds_dwordx4 v[226:227], off
	v_lshl_add_u64 v[226:227], s[68:69], 0, v[136:137]
	s_add_i32 m0, s31, 0x2000
	s_nop 0
	global_load_lds_dwordx4 v[226:227], off
	v_lshl_add_u64 v[226:227], s[28:29], 0, v[130:131]
	s_mov_b32 m0, s34
	s_nop 0
	global_load_lds_dwordx4 v[226:227], off
	s_mov_b32 m0, s35
	s_nop 0
	global_load_lds_dwordx4 v[228:229], off
	s_waitcnt vmcnt(8)
	s_waitcnt lgkmcnt(0)
	s_barrier
	s_setprio 1
	s_waitcnt lgkmcnt(0)
	v_mfma_f32_16x16x32_bf16 v[62:65], v[144:147], v[182:185], 0
	v_mfma_f32_16x16x32_bf16 v[58:61], v[152:155], v[182:185], 0
	v_mfma_f32_16x16x32_bf16 v[46:49], v[144:147], v[190:193], 0
	v_mfma_f32_16x16x32_bf16 v[42:45], v[152:155], v[190:193], 0
	v_mfma_f32_16x16x32_bf16 v[30:33], v[144:147], v[210:213], 0
	v_mfma_f32_16x16x32_bf16 v[26:29], v[152:155], v[210:213], 0
	v_mfma_f32_16x16x32_bf16 v[14:17], v[144:147], v[218:221], 0
	v_mfma_f32_16x16x32_bf16 v[10:13], v[152:155], v[218:221], 0
	v_mfma_f32_16x16x32_bf16 v[62:65], v[148:151], v[186:189], v[62:65]
	v_mfma_f32_16x16x32_bf16 v[58:61], v[156:159], v[186:189], v[58:61]
	v_mfma_f32_16x16x32_bf16 v[46:49], v[148:151], v[198:201], v[46:49]
	v_mfma_f32_16x16x32_bf16 v[42:45], v[156:159], v[198:201], v[42:45]
	v_mfma_f32_16x16x32_bf16 v[30:33], v[148:151], v[214:217], v[30:33]
	v_mfma_f32_16x16x32_bf16 v[26:29], v[156:159], v[214:217], v[26:29]
	v_mfma_f32_16x16x32_bf16 v[14:17], v[148:151], v[222:225], v[14:17]
	v_mfma_f32_16x16x32_bf16 v[10:13], v[156:159], v[222:225], v[10:13]
	v_mfma_f32_16x16x32_bf16 v[54:57], v[160:163], v[182:185], 0
	v_mfma_f32_16x16x32_bf16 v[50:53], v[174:177], v[182:185], 0
	v_mfma_f32_16x16x32_bf16 v[38:41], v[160:163], v[190:193], 0
	v_mfma_f32_16x16x32_bf16 v[34:37], v[174:177], v[190:193], 0
	v_mfma_f32_16x16x32_bf16 v[22:25], v[160:163], v[210:213], 0
	v_mfma_f32_16x16x32_bf16 v[18:21], v[174:177], v[210:213], 0
	v_mfma_f32_16x16x32_bf16 v[6:9], v[160:163], v[218:221], 0
	v_mfma_f32_16x16x32_bf16 v[2:5], v[174:177], v[218:221], 0
	v_mfma_f32_16x16x32_bf16 v[54:57], v[170:173], v[186:189], v[54:57]
	v_mfma_f32_16x16x32_bf16 v[50:53], v[178:181], v[186:189], v[50:53]
	v_mfma_f32_16x16x32_bf16 v[38:41], v[170:173], v[198:201], v[38:41]
	v_mfma_f32_16x16x32_bf16 v[34:37], v[178:181], v[198:201], v[34:37]
	v_mfma_f32_16x16x32_bf16 v[22:25], v[170:173], v[214:217], v[22:25]
	v_mfma_f32_16x16x32_bf16 v[18:21], v[178:181], v[214:217], v[18:21]
	v_mfma_f32_16x16x32_bf16 v[6:9], v[170:173], v[222:225], v[6:9]
	s_barrier
	v_mfma_f32_16x16x32_bf16 v[2:5], v[178:181], v[222:225], v[2:5]
	s_setprio 2
	s_add_i32 s31, 0, 0x18000
	s_add_i32 s68, 0, 0x1c000
	ds_read_b128 v[144:147], v250
	ds_read_b128 v[148:151], v250 offset:1024
	ds_read_b128 v[152:155], v250 offset:2048
	ds_read_b128 v[156:159], v250 offset:3072
	ds_read_b128 v[160:163], v250 offset:16384
	ds_read_b128 v[170:173], v250 offset:17408
	ds_read_b128 v[174:177], v250 offset:18432
	ds_read_b128 v[178:181], v250 offset:19456
	v_add_u32_e32 v169, s68, v164
	s_add_u32 s28, s28, 0x160000
	s_addc_u32 s29, s29, 0
	s_mov_b32 m0, s36
	v_lshl_add_u64 v[230:231], s[28:29], 0, v[130:131]
	ds_read_b128 v[182:185], v168 offset:32768
	ds_read_b128 v[186:189], v168 offset:33792
	ds_read_b128 v[190:193], v168 offset:34816
	ds_read_b128 v[198:201], v168 offset:35840
	ds_read_b128 v[210:213], v168 offset:36864
	ds_read_b128 v[214:217], v168 offset:37888
	ds_read_b128 v[218:221], v168 offset:38912
	ds_read_b128 v[222:225], v168 offset:39936
	global_load_lds_dwordx4 v[230:231], off
	v_lshl_add_u64 v[230:231], s[28:29], 0, v[134:135]
	s_mov_b32 m0, s37
	s_nop 0
	global_load_lds_dwordx4 v[230:231], off
	s_waitcnt vmcnt(8)
	s_waitcnt lgkmcnt(0)
	s_barrier
	s_setprio 1
	s_waitcnt lgkmcnt(0)
	v_mfma_f32_16x16x32_bf16 v[126:129], v[144:147], v[182:185], v[126:129]
	v_mfma_f32_16x16x32_bf16 v[122:125], v[152:155], v[182:185], v[122:125]
	v_mfma_f32_16x16x32_bf16 v[114:117], v[144:147], v[190:193], v[114:117]
	v_mfma_f32_16x16x32_bf16 v[106:109], v[152:155], v[190:193], v[106:109]
	v_mfma_f32_16x16x32_bf16 v[94:97], v[144:147], v[210:213], v[94:97]
	v_mfma_f32_16x16x32_bf16 v[90:93], v[152:155], v[210:213], v[90:93]
	v_mfma_f32_16x16x32_bf16 v[78:81], v[144:147], v[218:221], v[78:81]
	v_mfma_f32_16x16x32_bf16 v[74:77], v[152:155], v[218:221], v[74:77]
	v_mfma_f32_16x16x32_bf16 v[126:129], v[148:151], v[186:189], v[126:129]
	v_mfma_f32_16x16x32_bf16 v[122:125], v[156:159], v[186:189], v[122:125]
	v_mfma_f32_16x16x32_bf16 v[114:117], v[148:151], v[198:201], v[114:117]
	v_mfma_f32_16x16x32_bf16 v[106:109], v[156:159], v[198:201], v[106:109]
	v_mfma_f32_16x16x32_bf16 v[94:97], v[148:151], v[214:217], v[94:97]
	v_mfma_f32_16x16x32_bf16 v[90:93], v[156:159], v[214:217], v[90:93]
	v_mfma_f32_16x16x32_bf16 v[78:81], v[148:151], v[222:225], v[78:81]
	v_mfma_f32_16x16x32_bf16 v[74:77], v[156:159], v[222:225], v[74:77]
	v_mfma_f32_16x16x32_bf16 v[118:121], v[160:163], v[182:185], v[118:121]
	v_mfma_f32_16x16x32_bf16 v[110:113], v[174:177], v[182:185], v[110:113]
	v_mfma_f32_16x16x32_bf16 v[102:105], v[160:163], v[190:193], v[102:105]
	v_mfma_f32_16x16x32_bf16 v[98:101], v[174:177], v[190:193], v[98:101]
	v_mfma_f32_16x16x32_bf16 v[86:89], v[160:163], v[210:213], v[86:89]
	v_mfma_f32_16x16x32_bf16 v[82:85], v[174:177], v[210:213], v[82:85]
	v_mfma_f32_16x16x32_bf16 v[70:73], v[160:163], v[218:221], v[70:73]
	v_mfma_f32_16x16x32_bf16 v[66:69], v[174:177], v[218:221], v[66:69]
	v_mfma_f32_16x16x32_bf16 v[118:121], v[170:173], v[186:189], v[118:121]
	v_mfma_f32_16x16x32_bf16 v[110:113], v[178:181], v[186:189], v[110:113]
	v_mfma_f32_16x16x32_bf16 v[102:105], v[170:173], v[198:201], v[102:105]
	v_mfma_f32_16x16x32_bf16 v[98:101], v[178:181], v[198:201], v[98:101]
	v_mfma_f32_16x16x32_bf16 v[86:89], v[170:173], v[214:217], v[86:89]
	v_mfma_f32_16x16x32_bf16 v[82:85], v[178:181], v[214:217], v[82:85]
	v_mfma_f32_16x16x32_bf16 v[70:73], v[170:173], v[222:225], v[70:73]
	s_barrier
	v_mfma_f32_16x16x32_bf16 v[66:69], v[178:181], v[222:225], v[66:69]
	s_setprio 2
	s_add_i32 s28, s31, s33
	v_lshl_add_u64 v[202:203], v[202:203], 0, s[12:13]
	s_mov_b32 m0, s28
	ds_read_b128 v[182:185], v168 offset:49152
	ds_read_b128 v[186:189], v168 offset:50176
	ds_read_b128 v[190:193], v168 offset:51200
	ds_read_b128 v[198:201], v168 offset:52224
	ds_read_b128 v[210:213], v168 offset:53248
	ds_read_b128 v[214:217], v168 offset:54272
	ds_read_b128 v[218:221], v168 offset:55296
	ds_read_b128 v[222:225], v168 offset:56320
	global_load_lds_dwordx4 v[202:203], off
	s_add_i32 m0, s28, 0x2000
	s_add_u32 s26, s26, 0x160080
	v_lshl_add_u64 v[202:203], v[206:207], 0, s[12:13]
	s_addc_u32 s27, s27, 0
	s_add_i32 s28, s68, s33
	global_load_lds_dwordx4 v[202:203], off
	v_lshl_add_u64 v[202:203], s[26:27], 0, v[132:133]
	s_mov_b32 m0, s28
	s_nop 0
	global_load_lds_dwordx4 v[202:203], off
	v_lshl_add_u64 v[202:203], s[26:27], 0, v[136:137]
	s_add_i32 m0, s28, 0x2000
	s_nop 0
	global_load_lds_dwordx4 v[202:203], off
	v_lshl_add_u64 v[202:203], v[226:227], 0, s[12:13]
	s_mov_b32 m0, s47
	s_nop 0
	global_load_lds_dwordx4 v[202:203], off
	v_lshl_add_u64 v[202:203], v[228:229], 0, s[12:13]
	s_mov_b32 m0, s48
	s_nop 0
	global_load_lds_dwordx4 v[202:203], off
	s_waitcnt vmcnt(8)
	s_waitcnt lgkmcnt(0)
	s_barrier
	s_setprio 1
	s_waitcnt lgkmcnt(0)
	v_mfma_f32_16x16x32_bf16 v[62:65], v[144:147], v[182:185], v[62:65]
	v_mfma_f32_16x16x32_bf16 v[58:61], v[152:155], v[182:185], v[58:61]
	v_mfma_f32_16x16x32_bf16 v[46:49], v[144:147], v[190:193], v[46:49]
	v_mfma_f32_16x16x32_bf16 v[42:45], v[152:155], v[190:193], v[42:45]
	v_mfma_f32_16x16x32_bf16 v[30:33], v[144:147], v[210:213], v[30:33]
	v_mfma_f32_16x16x32_bf16 v[26:29], v[152:155], v[210:213], v[26:29]
	v_mfma_f32_16x16x32_bf16 v[14:17], v[144:147], v[218:221], v[14:17]
	v_mfma_f32_16x16x32_bf16 v[10:13], v[152:155], v[218:221], v[10:13]
	v_mfma_f32_16x16x32_bf16 v[62:65], v[148:151], v[186:189], v[62:65]
	v_mfma_f32_16x16x32_bf16 v[58:61], v[156:159], v[186:189], v[58:61]
	v_mfma_f32_16x16x32_bf16 v[46:49], v[148:151], v[198:201], v[46:49]
	v_mfma_f32_16x16x32_bf16 v[42:45], v[156:159], v[198:201], v[42:45]
	v_mfma_f32_16x16x32_bf16 v[30:33], v[148:151], v[214:217], v[30:33]
	v_mfma_f32_16x16x32_bf16 v[26:29], v[156:159], v[214:217], v[26:29]
	v_mfma_f32_16x16x32_bf16 v[14:17], v[148:151], v[222:225], v[14:17]
	v_mfma_f32_16x16x32_bf16 v[10:13], v[156:159], v[222:225], v[10:13]
	v_mfma_f32_16x16x32_bf16 v[54:57], v[160:163], v[182:185], v[54:57]
	v_mfma_f32_16x16x32_bf16 v[50:53], v[174:177], v[182:185], v[50:53]
	v_mfma_f32_16x16x32_bf16 v[38:41], v[160:163], v[190:193], v[38:41]
	v_mfma_f32_16x16x32_bf16 v[34:37], v[174:177], v[190:193], v[34:37]
	v_mfma_f32_16x16x32_bf16 v[22:25], v[160:163], v[210:213], v[22:25]
	v_mfma_f32_16x16x32_bf16 v[18:21], v[174:177], v[210:213], v[18:21]
	v_mfma_f32_16x16x32_bf16 v[6:9], v[160:163], v[218:221], v[6:9]
	v_mfma_f32_16x16x32_bf16 v[2:5], v[174:177], v[218:221], v[2:5]
	v_mfma_f32_16x16x32_bf16 v[54:57], v[170:173], v[186:189], v[54:57]
	v_mfma_f32_16x16x32_bf16 v[50:53], v[178:181], v[186:189], v[50:53]
	v_mfma_f32_16x16x32_bf16 v[38:41], v[170:173], v[198:201], v[38:41]
	v_mfma_f32_16x16x32_bf16 v[34:37], v[178:181], v[198:201], v[34:37]
	v_mfma_f32_16x16x32_bf16 v[22:25], v[170:173], v[214:217], v[22:25]
	v_mfma_f32_16x16x32_bf16 v[18:21], v[178:181], v[214:217], v[18:21]
	v_mfma_f32_16x16x32_bf16 v[6:9], v[170:173], v[222:225], v[6:9]
	s_barrier
	v_mfma_f32_16x16x32_bf16 v[2:5], v[178:181], v[222:225], v[2:5]
	s_setprio 2
	s_add_u32 s24, s24, 0x100
	s_addc_u32 s25, s25, 0
	s_add_u32 s17, s17, 0x100
	s_addc_u32 s23, s23, 0
	s_cmp_ge_i32 s30, s67
	s_mov_b32 s26, s30
	s_cbranch_scc0 .LBB0_1451
	s_branch .Lpeeldone_6
.LBB0_1451:
	ds_read_b128 v[144:147], v166
	ds_read_b128 v[148:151], v166 offset:1024
	ds_read_b128 v[152:155], v166 offset:2048
	ds_read_b128 v[156:159], v166 offset:3072
	ds_read_b128 v[160:163], v167
	ds_read_b128 v[170:173], v167 offset:1024
	ds_read_b128 v[174:177], v167 offset:2048
	ds_read_b128 v[178:181], v167 offset:3072
	s_add_i32 s30, s26, 2
	s_add_u32 s27, s24, 0xffea0080
	s_addc_u32 s28, s25, -1
	s_cmp_eq_u32 s22, s26
	s_cselect_b32 s26, s20, s17
	s_cselect_b32 s29, s19, s28
	s_cselect_b32 s28, s18, s27
	s_cselect_b32 s27, s21, s23
	v_lshl_add_u64 v[202:203], s[24:25], 0, v[140:141]
	s_add_i32 m0, s34, 0xc000
	ds_read_b128 v[182:185], v168
	ds_read_b128 v[186:189], v168 offset:1024
	ds_read_b128 v[190:193], v168 offset:2048
	ds_read_b128 v[198:201], v168 offset:3072
	ds_read_b128 v[210:213], v168 offset:4096
	ds_read_b128 v[214:217], v168 offset:5120
	ds_read_b128 v[218:221], v168 offset:6144
	ds_read_b128 v[222:225], v168 offset:7168
	global_load_lds_dwordx4 v[202:203], off
	v_lshl_add_u64 v[202:203], s[24:25], 0, v[142:143]
	s_add_i32 m0, s34, 0xe000
	s_nop 0
	global_load_lds_dwordx4 v[202:203], off
	s_waitcnt vmcnt(8)
	s_waitcnt lgkmcnt(0)
	s_barrier
	s_setprio 1
	s_waitcnt lgkmcnt(0)
	v_mfma_f32_16x16x32_bf16 v[126:129], v[144:147], v[182:185], v[126:129]
	v_mfma_f32_16x16x32_bf16 v[122:125], v[152:155], v[182:185], v[122:125]
	v_mfma_f32_16x16x32_bf16 v[114:117], v[144:147], v[190:193], v[114:117]
	v_mfma_f32_16x16x32_bf16 v[106:109], v[152:155], v[190:193], v[106:109]
	v_mfma_f32_16x16x32_bf16 v[94:97], v[144:147], v[210:213], v[94:97]
	v_mfma_f32_16x16x32_bf16 v[90:93], v[152:155], v[210:213], v[90:93]
	v_mfma_f32_16x16x32_bf16 v[78:81], v[144:147], v[218:221], v[78:81]
	v_mfma_f32_16x16x32_bf16 v[74:77], v[152:155], v[218:221], v[74:77]
	v_mfma_f32_16x16x32_bf16 v[126:129], v[148:151], v[186:189], v[126:129]
	v_mfma_f32_16x16x32_bf16 v[122:125], v[156:159], v[186:189], v[122:125]
	v_mfma_f32_16x16x32_bf16 v[114:117], v[148:151], v[198:201], v[114:117]
	v_mfma_f32_16x16x32_bf16 v[106:109], v[156:159], v[198:201], v[106:109]
	v_mfma_f32_16x16x32_bf16 v[94:97], v[148:151], v[214:217], v[94:97]
	v_mfma_f32_16x16x32_bf16 v[90:93], v[156:159], v[214:217], v[90:93]
	v_mfma_f32_16x16x32_bf16 v[78:81], v[148:151], v[222:225], v[78:81]
	v_mfma_f32_16x16x32_bf16 v[74:77], v[156:159], v[222:225], v[74:77]
	v_mfma_f32_16x16x32_bf16 v[118:121], v[160:163], v[182:185], v[118:121]
	v_mfma_f32_16x16x32_bf16 v[110:113], v[174:177], v[182:185], v[110:113]
	v_mfma_f32_16x16x32_bf16 v[102:105], v[160:163], v[190:193], v[102:105]
	v_mfma_f32_16x16x32_bf16 v[98:101], v[174:177], v[190:193], v[98:101]
	v_mfma_f32_16x16x32_bf16 v[86:89], v[160:163], v[210:213], v[86:89]
	v_mfma_f32_16x16x32_bf16 v[82:85], v[174:177], v[210:213], v[82:85]
	v_mfma_f32_16x16x32_bf16 v[70:73], v[160:163], v[218:221], v[70:73]
	v_mfma_f32_16x16x32_bf16 v[66:69], v[174:177], v[218:221], v[66:69]
	v_mfma_f32_16x16x32_bf16 v[118:121], v[170:173], v[186:189], v[118:121]
	v_mfma_f32_16x16x32_bf16 v[110:113], v[178:181], v[186:189], v[110:113]
	v_mfma_f32_16x16x32_bf16 v[102:105], v[170:173], v[198:201], v[102:105]
	v_mfma_f32_16x16x32_bf16 v[98:101], v[178:181], v[198:201], v[98:101]
	v_mfma_f32_16x16x32_bf16 v[86:89], v[170:173], v[214:217], v[86:89]
	v_mfma_f32_16x16x32_bf16 v[82:85], v[178:181], v[214:217], v[82:85]
	v_mfma_f32_16x16x32_bf16 v[70:73], v[170:173], v[222:225], v[70:73]
	s_barrier
	v_mfma_f32_16x16x32_bf16 v[66:69], v[178:181], v[222:225], v[66:69]
	s_setprio 2
	s_add_i32 s31, s57, s33
	v_lshl_add_u64 v[202:203], s[26:27], 0, v[132:133]
	s_mov_b32 m0, s31
	ds_read_b128 v[182:185], v168 offset:16384
	ds_read_b128 v[186:189], v168 offset:17408
	ds_read_b128 v[190:193], v168 offset:18432
	ds_read_b128 v[198:201], v168 offset:19456
	ds_read_b128 v[210:213], v168 offset:20480
	ds_read_b128 v[214:217], v168 offset:21504
	ds_read_b128 v[218:221], v168 offset:22528
	ds_read_b128 v[222:225], v168 offset:23552
	global_load_lds_dwordx4 v[202:203], off
	s_add_i32 m0, s31, 0x2000
	s_add_u32 s68, s26, 0x160000
	v_lshl_add_u64 v[206:207], s[26:27], 0, v[136:137]
	s_addc_u32 s69, s27, 0
	s_add_i32 s31, s58, s33
	global_load_lds_dwordx4 v[206:207], off
	v_lshl_add_u64 v[226:227], s[68:69], 0, v[132:133]
	s_mov_b32 m0, s31
	v_lshl_add_u64 v[228:229], s[28:29], 0, v[134:135]
	global_load_lds_dwordx4 v[226:227], off
	v_lshl_add_u64 v[226:227], s[68:69], 0, v[136:137]
	s_add_i32 m0, s31, 0x2000
	s_nop 0
	global_load_lds_dwordx4 v[226:227], off
	v_lshl_add_u64 v[226:227], s[28:29], 0, v[130:131]
	s_mov_b32 m0, s34
	s_nop 0
	global_load_lds_dwordx4 v[226:227], off
	s_mov_b32 m0, s35
	s_nop 0
	global_load_lds_dwordx4 v[228:229], off
	s_waitcnt vmcnt(8)
	s_waitcnt lgkmcnt(0)
	s_barrier
	s_setprio 1
	s_waitcnt lgkmcnt(0)
	v_mfma_f32_16x16x32_bf16 v[62:65], v[144:147], v[182:185], v[62:65]
	v_mfma_f32_16x16x32_bf16 v[58:61], v[152:155], v[182:185], v[58:61]
	v_mfma_f32_16x16x32_bf16 v[46:49], v[144:147], v[190:193], v[46:49]
	v_mfma_f32_16x16x32_bf16 v[42:45], v[152:155], v[190:193], v[42:45]
	v_mfma_f32_16x16x32_bf16 v[30:33], v[144:147], v[210:213], v[30:33]
	v_mfma_f32_16x16x32_bf16 v[26:29], v[152:155], v[210:213], v[26:29]
	v_mfma_f32_16x16x32_bf16 v[14:17], v[144:147], v[218:221], v[14:17]
	v_mfma_f32_16x16x32_bf16 v[10:13], v[152:155], v[218:221], v[10:13]
	v_mfma_f32_16x16x32_bf16 v[62:65], v[148:151], v[186:189], v[62:65]
	v_mfma_f32_16x16x32_bf16 v[58:61], v[156:159], v[186:189], v[58:61]
	v_mfma_f32_16x16x32_bf16 v[46:49], v[148:151], v[198:201], v[46:49]
	v_mfma_f32_16x16x32_bf16 v[42:45], v[156:159], v[198:201], v[42:45]
	v_mfma_f32_16x16x32_bf16 v[30:33], v[148:151], v[214:217], v[30:33]
	v_mfma_f32_16x16x32_bf16 v[26:29], v[156:159], v[214:217], v[26:29]
	v_mfma_f32_16x16x32_bf16 v[14:17], v[148:151], v[222:225], v[14:17]
	v_mfma_f32_16x16x32_bf16 v[10:13], v[156:159], v[222:225], v[10:13]
	v_mfma_f32_16x16x32_bf16 v[54:57], v[160:163], v[182:185], v[54:57]
	v_mfma_f32_16x16x32_bf16 v[50:53], v[174:177], v[182:185], v[50:53]
	v_mfma_f32_16x16x32_bf16 v[38:41], v[160:163], v[190:193], v[38:41]
	v_mfma_f32_16x16x32_bf16 v[34:37], v[174:177], v[190:193], v[34:37]
	v_mfma_f32_16x16x32_bf16 v[22:25], v[160:163], v[210:213], v[22:25]
	v_mfma_f32_16x16x32_bf16 v[18:21], v[174:177], v[210:213], v[18:21]
	v_mfma_f32_16x16x32_bf16 v[6:9], v[160:163], v[218:221], v[6:9]
	v_mfma_f32_16x16x32_bf16 v[2:5], v[174:177], v[218:221], v[2:5]
	v_mfma_f32_16x16x32_bf16 v[54:57], v[170:173], v[186:189], v[54:57]
	v_mfma_f32_16x16x32_bf16 v[50:53], v[178:181], v[186:189], v[50:53]
	v_mfma_f32_16x16x32_bf16 v[38:41], v[170:173], v[198:201], v[38:41]
	v_mfma_f32_16x16x32_bf16 v[34:37], v[178:181], v[198:201], v[34:37]
	v_mfma_f32_16x16x32_bf16 v[22:25], v[170:173], v[214:217], v[22:25]
	v_mfma_f32_16x16x32_bf16 v[18:21], v[178:181], v[214:217], v[18:21]
	v_mfma_f32_16x16x32_bf16 v[6:9], v[170:173], v[222:225], v[6:9]
	s_barrier
	v_mfma_f32_16x16x32_bf16 v[2:5], v[178:181], v[222:225], v[2:5]
	s_setprio 2
	s_add_i32 s31, 0, 0x18000
	s_add_i32 s68, 0, 0x1c000
	ds_read_b128 v[144:147], v250
	ds_read_b128 v[148:151], v250 offset:1024
	ds_read_b128 v[152:155], v250 offset:2048
	ds_read_b128 v[156:159], v250 offset:3072
	ds_read_b128 v[160:163], v250 offset:16384
	ds_read_b128 v[170:173], v250 offset:17408
	ds_read_b128 v[174:177], v250 offset:18432
	ds_read_b128 v[178:181], v250 offset:19456
	v_add_u32_e32 v169, s68, v164
	s_add_u32 s28, s28, 0x160000
	s_addc_u32 s29, s29, 0
	s_mov_b32 m0, s36
	v_lshl_add_u64 v[230:231], s[28:29], 0, v[130:131]
	ds_read_b128 v[182:185], v168 offset:32768
	ds_read_b128 v[186:189], v168 offset:33792
	ds_read_b128 v[190:193], v168 offset:34816
	ds_read_b128 v[198:201], v168 offset:35840
	ds_read_b128 v[210:213], v168 offset:36864
	ds_read_b128 v[214:217], v168 offset:37888
	ds_read_b128 v[218:221], v168 offset:38912
	ds_read_b128 v[222:225], v168 offset:39936
	global_load_lds_dwordx4 v[230:231], off
	v_lshl_add_u64 v[230:231], s[28:29], 0, v[134:135]
	s_mov_b32 m0, s37
	s_nop 0
	global_load_lds_dwordx4 v[230:231], off
	s_waitcnt vmcnt(8)
	s_waitcnt lgkmcnt(0)
	s_barrier
	s_setprio 1
	s_waitcnt lgkmcnt(0)
	v_mfma_f32_16x16x32_bf16 v[126:129], v[144:147], v[182:185], v[126:129]
	v_mfma_f32_16x16x32_bf16 v[122:125], v[152:155], v[182:185], v[122:125]
	v_mfma_f32_16x16x32_bf16 v[114:117], v[144:147], v[190:193], v[114:117]
	v_mfma_f32_16x16x32_bf16 v[106:109], v[152:155], v[190:193], v[106:109]
	v_mfma_f32_16x16x32_bf16 v[94:97], v[144:147], v[210:213], v[94:97]
	v_mfma_f32_16x16x32_bf16 v[90:93], v[152:155], v[210:213], v[90:93]
	v_mfma_f32_16x16x32_bf16 v[78:81], v[144:147], v[218:221], v[78:81]
	v_mfma_f32_16x16x32_bf16 v[74:77], v[152:155], v[218:221], v[74:77]
	v_mfma_f32_16x16x32_bf16 v[126:129], v[148:151], v[186:189], v[126:129]
	v_mfma_f32_16x16x32_bf16 v[122:125], v[156:159], v[186:189], v[122:125]
	v_mfma_f32_16x16x32_bf16 v[114:117], v[148:151], v[198:201], v[114:117]
	v_mfma_f32_16x16x32_bf16 v[106:109], v[156:159], v[198:201], v[106:109]
	v_mfma_f32_16x16x32_bf16 v[94:97], v[148:151], v[214:217], v[94:97]
	v_mfma_f32_16x16x32_bf16 v[90:93], v[156:159], v[214:217], v[90:93]
	v_mfma_f32_16x16x32_bf16 v[78:81], v[148:151], v[222:225], v[78:81]
	v_mfma_f32_16x16x32_bf16 v[74:77], v[156:159], v[222:225], v[74:77]
	v_mfma_f32_16x16x32_bf16 v[118:121], v[160:163], v[182:185], v[118:121]
	v_mfma_f32_16x16x32_bf16 v[110:113], v[174:177], v[182:185], v[110:113]
	v_mfma_f32_16x16x32_bf16 v[102:105], v[160:163], v[190:193], v[102:105]
	v_mfma_f32_16x16x32_bf16 v[98:101], v[174:177], v[190:193], v[98:101]
	v_mfma_f32_16x16x32_bf16 v[86:89], v[160:163], v[210:213], v[86:89]
	v_mfma_f32_16x16x32_bf16 v[82:85], v[174:177], v[210:213], v[82:85]
	v_mfma_f32_16x16x32_bf16 v[70:73], v[160:163], v[218:221], v[70:73]
	v_mfma_f32_16x16x32_bf16 v[66:69], v[174:177], v[218:221], v[66:69]
	v_mfma_f32_16x16x32_bf16 v[118:121], v[170:173], v[186:189], v[118:121]
	v_mfma_f32_16x16x32_bf16 v[110:113], v[178:181], v[186:189], v[110:113]
	v_mfma_f32_16x16x32_bf16 v[102:105], v[170:173], v[198:201], v[102:105]
	v_mfma_f32_16x16x32_bf16 v[98:101], v[178:181], v[198:201], v[98:101]
	v_mfma_f32_16x16x32_bf16 v[86:89], v[170:173], v[214:217], v[86:89]
	v_mfma_f32_16x16x32_bf16 v[82:85], v[178:181], v[214:217], v[82:85]
	v_mfma_f32_16x16x32_bf16 v[70:73], v[170:173], v[222:225], v[70:73]
	s_barrier
	v_mfma_f32_16x16x32_bf16 v[66:69], v[178:181], v[222:225], v[66:69]
	s_setprio 2
	s_add_i32 s28, s31, s33
	v_lshl_add_u64 v[202:203], v[202:203], 0, s[12:13]
	s_mov_b32 m0, s28
	ds_read_b128 v[182:185], v168 offset:49152
	ds_read_b128 v[186:189], v168 offset:50176
	ds_read_b128 v[190:193], v168 offset:51200
	ds_read_b128 v[198:201], v168 offset:52224
	ds_read_b128 v[210:213], v168 offset:53248
	ds_read_b128 v[214:217], v168 offset:54272
	ds_read_b128 v[218:221], v168 offset:55296
	ds_read_b128 v[222:225], v168 offset:56320
	global_load_lds_dwordx4 v[202:203], off
	s_add_i32 m0, s28, 0x2000
	s_add_u32 s26, s26, 0x160080
	v_lshl_add_u64 v[202:203], v[206:207], 0, s[12:13]
	s_addc_u32 s27, s27, 0
	s_add_i32 s28, s68, s33
	global_load_lds_dwordx4 v[202:203], off
	v_lshl_add_u64 v[202:203], s[26:27], 0, v[132:133]
	s_mov_b32 m0, s28
	s_nop 0
	global_load_lds_dwordx4 v[202:203], off
	v_lshl_add_u64 v[202:203], s[26:27], 0, v[136:137]
	s_add_i32 m0, s28, 0x2000
	s_nop 0
	global_load_lds_dwordx4 v[202:203], off
	v_lshl_add_u64 v[202:203], v[226:227], 0, s[12:13]
	s_mov_b32 m0, s47
	s_nop 0
	global_load_lds_dwordx4 v[202:203], off
	v_lshl_add_u64 v[202:203], v[228:229], 0, s[12:13]
	s_mov_b32 m0, s48
	s_nop 0
	global_load_lds_dwordx4 v[202:203], off
	s_waitcnt vmcnt(8)
	s_waitcnt lgkmcnt(0)
	s_barrier
	s_setprio 1
	s_waitcnt lgkmcnt(0)
	v_mfma_f32_16x16x32_bf16 v[62:65], v[144:147], v[182:185], v[62:65]
	v_mfma_f32_16x16x32_bf16 v[58:61], v[152:155], v[182:185], v[58:61]
	v_mfma_f32_16x16x32_bf16 v[46:49], v[144:147], v[190:193], v[46:49]
	v_mfma_f32_16x16x32_bf16 v[42:45], v[152:155], v[190:193], v[42:45]
	v_mfma_f32_16x16x32_bf16 v[30:33], v[144:147], v[210:213], v[30:33]
	v_mfma_f32_16x16x32_bf16 v[26:29], v[152:155], v[210:213], v[26:29]
	v_mfma_f32_16x16x32_bf16 v[14:17], v[144:147], v[218:221], v[14:17]
	v_mfma_f32_16x16x32_bf16 v[10:13], v[152:155], v[218:221], v[10:13]
	v_mfma_f32_16x16x32_bf16 v[62:65], v[148:151], v[186:189], v[62:65]
	v_mfma_f32_16x16x32_bf16 v[58:61], v[156:159], v[186:189], v[58:61]
	v_mfma_f32_16x16x32_bf16 v[46:49], v[148:151], v[198:201], v[46:49]
	v_mfma_f32_16x16x32_bf16 v[42:45], v[156:159], v[198:201], v[42:45]
	v_mfma_f32_16x16x32_bf16 v[30:33], v[148:151], v[214:217], v[30:33]
	v_mfma_f32_16x16x32_bf16 v[26:29], v[156:159], v[214:217], v[26:29]
	v_mfma_f32_16x16x32_bf16 v[14:17], v[148:151], v[222:225], v[14:17]
	v_mfma_f32_16x16x32_bf16 v[10:13], v[156:159], v[222:225], v[10:13]
	v_mfma_f32_16x16x32_bf16 v[54:57], v[160:163], v[182:185], v[54:57]
	v_mfma_f32_16x16x32_bf16 v[50:53], v[174:177], v[182:185], v[50:53]
	v_mfma_f32_16x16x32_bf16 v[38:41], v[160:163], v[190:193], v[38:41]
	v_mfma_f32_16x16x32_bf16 v[34:37], v[174:177], v[190:193], v[34:37]
	v_mfma_f32_16x16x32_bf16 v[22:25], v[160:163], v[210:213], v[22:25]
	v_mfma_f32_16x16x32_bf16 v[18:21], v[174:177], v[210:213], v[18:21]
	v_mfma_f32_16x16x32_bf16 v[6:9], v[160:163], v[218:221], v[6:9]
	v_mfma_f32_16x16x32_bf16 v[2:5], v[174:177], v[218:221], v[2:5]
	v_mfma_f32_16x16x32_bf16 v[54:57], v[170:173], v[186:189], v[54:57]
	v_mfma_f32_16x16x32_bf16 v[50:53], v[178:181], v[186:189], v[50:53]
	v_mfma_f32_16x16x32_bf16 v[38:41], v[170:173], v[198:201], v[38:41]
	v_mfma_f32_16x16x32_bf16 v[34:37], v[178:181], v[198:201], v[34:37]
	v_mfma_f32_16x16x32_bf16 v[22:25], v[170:173], v[214:217], v[22:25]
	v_mfma_f32_16x16x32_bf16 v[18:21], v[178:181], v[214:217], v[18:21]
	v_mfma_f32_16x16x32_bf16 v[6:9], v[170:173], v[222:225], v[6:9]
	s_barrier
	v_mfma_f32_16x16x32_bf16 v[2:5], v[178:181], v[222:225], v[2:5]
	s_setprio 2
	s_add_u32 s24, s24, 0x100
	s_addc_u32 s25, s25, 0
	s_add_u32 s17, s17, 0x100
	s_addc_u32 s23, s23, 0
	s_cmp_ge_i32 s30, s67
	s_mov_b32 s26, s30
	s_cbranch_scc0 .LBB0_1451

.Lpeel_3:
	v_add_u32_e32 v250, 0x18000, v144
	s_add_i32 s29, s23, 2
	s_add_u32 s34, s30, 0xfff80080
	s_addc_u32 s35, s31, -1
	s_cmp_eq_u32 s28, s23
	s_cselect_b32 s37, s25, s35
	s_cselect_b32 s36, s24, s34
	s_cselect_b32 s35, s27, s21
	s_cselect_b32 s34, s26, s19
	v_lshl_add_u64 v[202:203], s[30:31], 0, v[140:141]
	s_add_i32 m0, s15, 0xc000
	global_load_lds_dwordx4 v[202:203], off
	v_lshl_add_u64 v[202:203], s[30:31], 0, v[142:143]
	s_add_i32 m0, s15, 0xe000
	s_nop 0
	global_load_lds_dwordx4 v[202:203], off
	s_waitcnt vmcnt(8)
	s_waitcnt lgkmcnt(0)
	s_barrier
	s_setprio 1
	s_waitcnt lgkmcnt(0)
	v_mfma_f32_16x16x32_bf16 v[126:129], v[150:153], v[182:185], 0
	v_mfma_f32_16x16x32_bf16 v[122:125], v[158:161], v[182:185], 0
	v_mfma_f32_16x16x32_bf16 v[118:121], v[150:153], v[190:193], 0
	v_mfma_f32_16x16x32_bf16 v[114:117], v[158:161], v[190:193], 0
	v_mfma_f32_16x16x32_bf16 v[110:113], v[150:153], v[210:213], 0
	v_mfma_f32_16x16x32_bf16 v[106:109], v[158:161], v[210:213], 0
	v_mfma_f32_16x16x32_bf16 v[102:105], v[150:153], v[218:221], 0
	v_mfma_f32_16x16x32_bf16 v[98:101], v[158:161], v[218:221], 0
	v_mfma_f32_16x16x32_bf16 v[126:129], v[154:157], v[186:189], v[126:129]
	v_mfma_f32_16x16x32_bf16 v[122:125], v[162:165], v[186:189], v[122:125]
	v_mfma_f32_16x16x32_bf16 v[118:121], v[154:157], v[198:201], v[118:121]
	v_mfma_f32_16x16x32_bf16 v[114:117], v[162:165], v[198:201], v[114:117]
	v_mfma_f32_16x16x32_bf16 v[110:113], v[154:157], v[214:217], v[110:113]
	v_mfma_f32_16x16x32_bf16 v[106:109], v[162:165], v[214:217], v[106:109]
	v_mfma_f32_16x16x32_bf16 v[102:105], v[154:157], v[222:225], v[102:105]
	v_mfma_f32_16x16x32_bf16 v[98:101], v[162:165], v[222:225], v[98:101]
	v_mfma_f32_16x16x32_bf16 v[94:97], v[166:169], v[182:185], 0
	v_mfma_f32_16x16x32_bf16 v[90:93], v[174:177], v[182:185], 0
	v_mfma_f32_16x16x32_bf16 v[86:89], v[166:169], v[190:193], 0
	v_mfma_f32_16x16x32_bf16 v[82:85], v[174:177], v[190:193], 0
	v_mfma_f32_16x16x32_bf16 v[78:81], v[166:169], v[210:213], 0
	v_mfma_f32_16x16x32_bf16 v[74:77], v[174:177], v[210:213], 0
	v_mfma_f32_16x16x32_bf16 v[70:73], v[166:169], v[218:221], 0
	v_mfma_f32_16x16x32_bf16 v[66:69], v[174:177], v[218:221], 0
	v_mfma_f32_16x16x32_bf16 v[94:97], v[170:173], v[186:189], v[94:97]
	v_mfma_f32_16x16x32_bf16 v[90:93], v[178:181], v[186:189], v[90:93]
	v_mfma_f32_16x16x32_bf16 v[86:89], v[170:173], v[198:201], v[86:89]
	v_mfma_f32_16x16x32_bf16 v[82:85], v[178:181], v[198:201], v[82:85]
	v_mfma_f32_16x16x32_bf16 v[78:81], v[170:173], v[214:217], v[78:81]
	v_mfma_f32_16x16x32_bf16 v[74:77], v[178:181], v[214:217], v[74:77]
	v_mfma_f32_16x16x32_bf16 v[70:73], v[170:173], v[222:225], v[70:73]
	s_barrier
	v_mfma_f32_16x16x32_bf16 v[66:69], v[178:181], v[222:225], v[66:69]
	s_setprio 2
	s_add_i32 s23, s60, s33
	v_lshl_add_u64 v[202:203], s[34:35], 0, v[132:133]
	s_mov_b32 m0, s23
	ds_read_b128 v[182:185], v148 offset:16384
	ds_read_b128 v[186:189], v148 offset:17408
	ds_read_b128 v[190:193], v148 offset:18432
	ds_read_b128 v[198:201], v148 offset:19456
	ds_read_b128 v[210:213], v148 offset:20480
	ds_read_b128 v[214:217], v148 offset:21504
	ds_read_b128 v[218:221], v148 offset:22528
	ds_read_b128 v[222:225], v148 offset:23552
	global_load_lds_dwordx4 v[202:203], off
	s_add_i32 m0, s23, 0x2000
	s_add_u32 s38, s34, 0x80000
	v_lshl_add_u64 v[206:207], s[34:35], 0, v[136:137]
	s_addc_u32 s39, s35, 0
	s_add_i32 s23, s61, s33
	global_load_lds_dwordx4 v[206:207], off
	v_lshl_add_u64 v[226:227], s[38:39], 0, v[132:133]
	s_mov_b32 m0, s23
	v_lshl_add_u64 v[228:229], s[36:37], 0, v[134:135]
	global_load_lds_dwordx4 v[226:227], off
	v_lshl_add_u64 v[226:227], s[38:39], 0, v[136:137]
	s_add_i32 m0, s23, 0x2000
	s_nop 0
	global_load_lds_dwordx4 v[226:227], off
	v_lshl_add_u64 v[226:227], s[36:37], 0, v[130:131]
	s_mov_b32 m0, s15
	s_nop 0
	global_load_lds_dwordx4 v[226:227], off
	s_mov_b32 m0, s41
	s_nop 0
	global_load_lds_dwordx4 v[228:229], off
	s_waitcnt vmcnt(8)
	s_waitcnt lgkmcnt(0)
	s_barrier
	s_setprio 1
	s_waitcnt lgkmcnt(0)
	v_mfma_f32_16x16x32_bf16 v[62:65], v[150:153], v[182:185], 0
	v_mfma_f32_16x16x32_bf16 v[58:61], v[158:161], v[182:185], 0
	v_mfma_f32_16x16x32_bf16 v[54:57], v[150:153], v[190:193], 0
	v_mfma_f32_16x16x32_bf16 v[50:53], v[158:161], v[190:193], 0
	v_mfma_f32_16x16x32_bf16 v[46:49], v[150:153], v[210:213], 0
	v_mfma_f32_16x16x32_bf16 v[42:45], v[158:161], v[210:213], 0
	v_mfma_f32_16x16x32_bf16 v[38:41], v[150:153], v[218:221], 0
	v_mfma_f32_16x16x32_bf16 v[34:37], v[158:161], v[218:221], 0
	v_mfma_f32_16x16x32_bf16 v[62:65], v[154:157], v[186:189], v[62:65]
	v_mfma_f32_16x16x32_bf16 v[58:61], v[162:165], v[186:189], v[58:61]
	v_mfma_f32_16x16x32_bf16 v[54:57], v[154:157], v[198:201], v[54:57]
	v_mfma_f32_16x16x32_bf16 v[50:53], v[162:165], v[198:201], v[50:53]
	v_mfma_f32_16x16x32_bf16 v[46:49], v[154:157], v[214:217], v[46:49]
	v_mfma_f32_16x16x32_bf16 v[42:45], v[162:165], v[214:217], v[42:45]
	v_mfma_f32_16x16x32_bf16 v[38:41], v[154:157], v[222:225], v[38:41]
	v_mfma_f32_16x16x32_bf16 v[34:37], v[162:165], v[222:225], v[34:37]
	v_mfma_f32_16x16x32_bf16 v[30:33], v[166:169], v[182:185], 0
	v_mfma_f32_16x16x32_bf16 v[26:29], v[174:177], v[182:185], 0
	v_mfma_f32_16x16x32_bf16 v[22:25], v[166:169], v[190:193], 0
	v_mfma_f32_16x16x32_bf16 v[18:21], v[174:177], v[190:193], 0
	v_mfma_f32_16x16x32_bf16 v[14:17], v[166:169], v[210:213], 0
	v_mfma_f32_16x16x32_bf16 v[10:13], v[174:177], v[210:213], 0
	v_mfma_f32_16x16x32_bf16 v[6:9], v[166:169], v[218:221], 0
	v_mfma_f32_16x16x32_bf16 v[2:5], v[174:177], v[218:221], 0
	v_mfma_f32_16x16x32_bf16 v[30:33], v[170:173], v[186:189], v[30:33]
	v_mfma_f32_16x16x32_bf16 v[26:29], v[178:181], v[186:189], v[26:29]
	v_mfma_f32_16x16x32_bf16 v[22:25], v[170:173], v[198:201], v[22:25]
	v_mfma_f32_16x16x32_bf16 v[18:21], v[178:181], v[198:201], v[18:21]
	v_mfma_f32_16x16x32_bf16 v[14:17], v[170:173], v[214:217], v[14:17]
	v_mfma_f32_16x16x32_bf16 v[10:13], v[178:181], v[214:217], v[10:13]
	v_mfma_f32_16x16x32_bf16 v[6:9], v[170:173], v[222:225], v[6:9]
	s_barrier
	v_mfma_f32_16x16x32_bf16 v[2:5], v[178:181], v[222:225], v[2:5]
	s_setprio 2
	s_add_i32 s23, 0, 0x18000
	s_add_i32 s38, 0, 0x1c000
	ds_read_b128 v[150:153], v250
	ds_read_b128 v[154:157], v250 offset:1024
	ds_read_b128 v[158:161], v250 offset:2048
	ds_read_b128 v[162:165], v250 offset:3072
	ds_read_b128 v[166:169], v250 offset:16384
	ds_read_b128 v[170:173], v250 offset:17408
	ds_read_b128 v[174:177], v250 offset:18432
	ds_read_b128 v[178:181], v250 offset:19456
	v_add_u32_e32 v149, s38, v144
	s_add_u32 s36, s36, 0x80000
	s_addc_u32 s37, s37, 0
	s_mov_b32 m0, s42
	v_lshl_add_u64 v[230:231], s[36:37], 0, v[130:131]
	ds_read_b128 v[182:185], v148 offset:32768
	ds_read_b128 v[186:189], v148 offset:33792
	ds_read_b128 v[190:193], v148 offset:34816
	ds_read_b128 v[198:201], v148 offset:35840
	ds_read_b128 v[210:213], v148 offset:36864
	ds_read_b128 v[214:217], v148 offset:37888
	ds_read_b128 v[218:221], v148 offset:38912
	ds_read_b128 v[222:225], v148 offset:39936
	global_load_lds_dwordx4 v[230:231], off
	v_lshl_add_u64 v[230:231], s[36:37], 0, v[134:135]
	s_mov_b32 m0, s43
	s_nop 0
	global_load_lds_dwordx4 v[230:231], off
	s_waitcnt vmcnt(8)
	s_waitcnt lgkmcnt(0)
	s_barrier
	s_setprio 1
	s_waitcnt lgkmcnt(0)
	v_mfma_f32_16x16x32_bf16 v[126:129], v[150:153], v[182:185], v[126:129]
	v_mfma_f32_16x16x32_bf16 v[122:125], v[158:161], v[182:185], v[122:125]
	v_mfma_f32_16x16x32_bf16 v[118:121], v[150:153], v[190:193], v[118:121]
	v_mfma_f32_16x16x32_bf16 v[114:117], v[158:161], v[190:193], v[114:117]
	v_mfma_f32_16x16x32_bf16 v[110:113], v[150:153], v[210:213], v[110:113]
	v_mfma_f32_16x16x32_bf16 v[106:109], v[158:161], v[210:213], v[106:109]
	v_mfma_f32_16x16x32_bf16 v[102:105], v[150:153], v[218:221], v[102:105]
	v_mfma_f32_16x16x32_bf16 v[98:101], v[158:161], v[218:221], v[98:101]
	v_mfma_f32_16x16x32_bf16 v[126:129], v[154:157], v[186:189], v[126:129]
	v_mfma_f32_16x16x32_bf16 v[122:125], v[162:165], v[186:189], v[122:125]
	v_mfma_f32_16x16x32_bf16 v[118:121], v[154:157], v[198:201], v[118:121]
	v_mfma_f32_16x16x32_bf16 v[114:117], v[162:165], v[198:201], v[114:117]
	v_mfma_f32_16x16x32_bf16 v[110:113], v[154:157], v[214:217], v[110:113]
	v_mfma_f32_16x16x32_bf16 v[106:109], v[162:165], v[214:217], v[106:109]
	v_mfma_f32_16x16x32_bf16 v[102:105], v[154:157], v[222:225], v[102:105]
	v_mfma_f32_16x16x32_bf16 v[98:101], v[162:165], v[222:225], v[98:101]
	v_mfma_f32_16x16x32_bf16 v[94:97], v[166:169], v[182:185], v[94:97]
	v_mfma_f32_16x16x32_bf16 v[90:93], v[174:177], v[182:185], v[90:93]
	v_mfma_f32_16x16x32_bf16 v[86:89], v[166:169], v[190:193], v[86:89]
	v_mfma_f32_16x16x32_bf16 v[82:85], v[174:177], v[190:193], v[82:85]
	v_mfma_f32_16x16x32_bf16 v[78:81], v[166:169], v[210:213], v[78:81]
	v_mfma_f32_16x16x32_bf16 v[74:77], v[174:177], v[210:213], v[74:77]
	v_mfma_f32_16x16x32_bf16 v[70:73], v[166:169], v[218:221], v[70:73]
	v_mfma_f32_16x16x32_bf16 v[66:69], v[174:177], v[218:221], v[66:69]
	v_mfma_f32_16x16x32_bf16 v[94:97], v[170:173], v[186:189], v[94:97]
	v_mfma_f32_16x16x32_bf16 v[90:93], v[178:181], v[186:189], v[90:93]
	v_mfma_f32_16x16x32_bf16 v[86:89], v[170:173], v[198:201], v[86:89]
	v_mfma_f32_16x16x32_bf16 v[82:85], v[178:181], v[198:201], v[82:85]
	v_mfma_f32_16x16x32_bf16 v[78:81], v[170:173], v[214:217], v[78:81]
	v_mfma_f32_16x16x32_bf16 v[74:77], v[178:181], v[214:217], v[74:77]
	v_mfma_f32_16x16x32_bf16 v[70:73], v[170:173], v[222:225], v[70:73]
	s_barrier
	v_mfma_f32_16x16x32_bf16 v[66:69], v[178:181], v[222:225], v[66:69]
	s_setprio 2
	s_add_i32 s23, s23, s33
	v_lshl_add_u64 v[202:203], v[202:203], 0, s[10:11]
	s_mov_b32 m0, s23
	ds_read_b128 v[182:185], v148 offset:49152
	ds_read_b128 v[186:189], v148 offset:50176
	ds_read_b128 v[190:193], v148 offset:51200
	ds_read_b128 v[198:201], v148 offset:52224
	ds_read_b128 v[210:213], v148 offset:53248
	ds_read_b128 v[214:217], v148 offset:54272
	ds_read_b128 v[218:221], v148 offset:55296
	ds_read_b128 v[222:225], v148 offset:56320
	global_load_lds_dwordx4 v[202:203], off
	s_add_i32 m0, s23, 0x2000
	s_add_u32 s34, s34, 0x80080
	v_lshl_add_u64 v[202:203], v[206:207], 0, s[10:11]
	s_addc_u32 s35, s35, 0
	s_add_i32 s23, s38, s33
	global_load_lds_dwordx4 v[202:203], off
	v_lshl_add_u64 v[202:203], s[34:35], 0, v[132:133]
	s_mov_b32 m0, s23
	s_nop 0
	global_load_lds_dwordx4 v[202:203], off
	v_lshl_add_u64 v[202:203], s[34:35], 0, v[136:137]
	s_add_i32 m0, s23, 0x2000
	s_nop 0
	global_load_lds_dwordx4 v[202:203], off
	v_lshl_add_u64 v[202:203], v[226:227], 0, s[10:11]
	s_mov_b32 m0, s51
	s_nop 0
	global_load_lds_dwordx4 v[202:203], off
	v_lshl_add_u64 v[202:203], v[228:229], 0, s[10:11]
	s_mov_b32 m0, s52
	s_nop 0
	global_load_lds_dwordx4 v[202:203], off
	s_waitcnt vmcnt(8)
	s_waitcnt lgkmcnt(0)
	s_barrier
	s_setprio 1
	s_waitcnt lgkmcnt(0)
	v_mfma_f32_16x16x32_bf16 v[62:65], v[150:153], v[182:185], v[62:65]
	v_mfma_f32_16x16x32_bf16 v[58:61], v[158:161], v[182:185], v[58:61]
	v_mfma_f32_16x16x32_bf16 v[54:57], v[150:153], v[190:193], v[54:57]
	v_mfma_f32_16x16x32_bf16 v[50:53], v[158:161], v[190:193], v[50:53]
	v_mfma_f32_16x16x32_bf16 v[46:49], v[150:153], v[210:213], v[46:49]
	v_mfma_f32_16x16x32_bf16 v[42:45], v[158:161], v[210:213], v[42:45]
	v_mfma_f32_16x16x32_bf16 v[38:41], v[150:153], v[218:221], v[38:41]
	v_mfma_f32_16x16x32_bf16 v[34:37], v[158:161], v[218:221], v[34:37]
	v_mfma_f32_16x16x32_bf16 v[62:65], v[154:157], v[186:189], v[62:65]
	v_mfma_f32_16x16x32_bf16 v[58:61], v[162:165], v[186:189], v[58:61]
	v_mfma_f32_16x16x32_bf16 v[54:57], v[154:157], v[198:201], v[54:57]
	v_mfma_f32_16x16x32_bf16 v[50:53], v[162:165], v[198:201], v[50:53]
	v_mfma_f32_16x16x32_bf16 v[46:49], v[154:157], v[214:217], v[46:49]
	v_mfma_f32_16x16x32_bf16 v[42:45], v[162:165], v[214:217], v[42:45]
	v_mfma_f32_16x16x32_bf16 v[38:41], v[154:157], v[222:225], v[38:41]
	v_mfma_f32_16x16x32_bf16 v[34:37], v[162:165], v[222:225], v[34:37]
	v_mfma_f32_16x16x32_bf16 v[30:33], v[166:169], v[182:185], v[30:33]
	v_mfma_f32_16x16x32_bf16 v[26:29], v[174:177], v[182:185], v[26:29]
	v_mfma_f32_16x16x32_bf16 v[22:25], v[166:169], v[190:193], v[22:25]
	v_mfma_f32_16x16x32_bf16 v[18:21], v[174:177], v[190:193], v[18:21]
	v_mfma_f32_16x16x32_bf16 v[14:17], v[166:169], v[210:213], v[14:17]
	v_mfma_f32_16x16x32_bf16 v[10:13], v[174:177], v[210:213], v[10:13]
	v_mfma_f32_16x16x32_bf16 v[6:9], v[166:169], v[218:221], v[6:9]
	v_mfma_f32_16x16x32_bf16 v[2:5], v[174:177], v[218:221], v[2:5]
	v_mfma_f32_16x16x32_bf16 v[30:33], v[170:173], v[186:189], v[30:33]
	v_mfma_f32_16x16x32_bf16 v[26:29], v[178:181], v[186:189], v[26:29]
	v_mfma_f32_16x16x32_bf16 v[22:25], v[170:173], v[198:201], v[22:25]
	v_mfma_f32_16x16x32_bf16 v[18:21], v[178:181], v[198:201], v[18:21]
	v_mfma_f32_16x16x32_bf16 v[14:17], v[170:173], v[214:217], v[14:17]
	v_mfma_f32_16x16x32_bf16 v[10:13], v[178:181], v[214:217], v[10:13]
	v_mfma_f32_16x16x32_bf16 v[6:9], v[170:173], v[222:225], v[6:9]
	s_barrier
	v_mfma_f32_16x16x32_bf16 v[2:5], v[178:181], v[222:225], v[2:5]
	s_setprio 2
	s_add_u32 s30, s30, 0x100
	s_addc_u32 s31, s31, 0
	s_add_u32 s19, s19, 0x100
	s_addc_u32 s21, s21, 0
	s_cmp_ge_i32 s29, s68
	s_mov_b32 s23, s29
	s_cbranch_scc0 .LBB0_1973
	s_branch .Lpeeldone_3
.LBB0_1973:
	ds_read_b128 v[150:153], v146
	ds_read_b128 v[154:157], v146 offset:1024
	ds_read_b128 v[158:161], v146 offset:2048
	ds_read_b128 v[162:165], v146 offset:3072
	ds_read_b128 v[166:169], v147
	ds_read_b128 v[170:173], v147 offset:1024
	ds_read_b128 v[174:177], v147 offset:2048
	ds_read_b128 v[178:181], v147 offset:3072
	s_add_i32 s29, s23, 2
	s_add_u32 s34, s30, 0xfff80080
	s_addc_u32 s35, s31, -1
	s_cmp_eq_u32 s28, s23
	s_cselect_b32 s37, s25, s35
	s_cselect_b32 s36, s24, s34
	s_cselect_b32 s35, s27, s21
	s_cselect_b32 s34, s26, s19
	v_lshl_add_u64 v[202:203], s[30:31], 0, v[140:141]
	s_add_i32 m0, s15, 0xc000
	ds_read_b128 v[182:185], v148
	ds_read_b128 v[186:189], v148 offset:1024
	ds_read_b128 v[190:193], v148 offset:2048
	ds_read_b128 v[198:201], v148 offset:3072
	ds_read_b128 v[210:213], v148 offset:4096
	ds_read_b128 v[214:217], v148 offset:5120
	ds_read_b128 v[218:221], v148 offset:6144
	ds_read_b128 v[222:225], v148 offset:7168
	global_load_lds_dwordx4 v[202:203], off
	v_lshl_add_u64 v[202:203], s[30:31], 0, v[142:143]
	s_add_i32 m0, s15, 0xe000
	s_nop 0
	global_load_lds_dwordx4 v[202:203], off
	s_waitcnt vmcnt(8)
	s_waitcnt lgkmcnt(0)
	s_barrier
	s_setprio 1
	s_waitcnt lgkmcnt(0)
	v_mfma_f32_16x16x32_bf16 v[126:129], v[150:153], v[182:185], v[126:129]
	v_mfma_f32_16x16x32_bf16 v[122:125], v[158:161], v[182:185], v[122:125]
	v_mfma_f32_16x16x32_bf16 v[118:121], v[150:153], v[190:193], v[118:121]
	v_mfma_f32_16x16x32_bf16 v[114:117], v[158:161], v[190:193], v[114:117]
	v_mfma_f32_16x16x32_bf16 v[110:113], v[150:153], v[210:213], v[110:113]
	v_mfma_f32_16x16x32_bf16 v[106:109], v[158:161], v[210:213], v[106:109]
	v_mfma_f32_16x16x32_bf16 v[102:105], v[150:153], v[218:221], v[102:105]
	v_mfma_f32_16x16x32_bf16 v[98:101], v[158:161], v[218:221], v[98:101]
	v_mfma_f32_16x16x32_bf16 v[126:129], v[154:157], v[186:189], v[126:129]
	v_mfma_f32_16x16x32_bf16 v[122:125], v[162:165], v[186:189], v[122:125]
	v_mfma_f32_16x16x32_bf16 v[118:121], v[154:157], v[198:201], v[118:121]
	v_mfma_f32_16x16x32_bf16 v[114:117], v[162:165], v[198:201], v[114:117]
	v_mfma_f32_16x16x32_bf16 v[110:113], v[154:157], v[214:217], v[110:113]
	v_mfma_f32_16x16x32_bf16 v[106:109], v[162:165], v[214:217], v[106:109]
	v_mfma_f32_16x16x32_bf16 v[102:105], v[154:157], v[222:225], v[102:105]
	v_mfma_f32_16x16x32_bf16 v[98:101], v[162:165], v[222:225], v[98:101]
	v_mfma_f32_16x16x32_bf16 v[94:97], v[166:169], v[182:185], v[94:97]
	v_mfma_f32_16x16x32_bf16 v[90:93], v[174:177], v[182:185], v[90:93]
	v_mfma_f32_16x16x32_bf16 v[86:89], v[166:169], v[190:193], v[86:89]
	v_mfma_f32_16x16x32_bf16 v[82:85], v[174:177], v[190:193], v[82:85]
	v_mfma_f32_16x16x32_bf16 v[78:81], v[166:169], v[210:213], v[78:81]
	v_mfma_f32_16x16x32_bf16 v[74:77], v[174:177], v[210:213], v[74:77]
	v_mfma_f32_16x16x32_bf16 v[70:73], v[166:169], v[218:221], v[70:73]
	v_mfma_f32_16x16x32_bf16 v[66:69], v[174:177], v[218:221], v[66:69]
	v_mfma_f32_16x16x32_bf16 v[94:97], v[170:173], v[186:189], v[94:97]
	v_mfma_f32_16x16x32_bf16 v[90:93], v[178:181], v[186:189], v[90:93]
	v_mfma_f32_16x16x32_bf16 v[86:89], v[170:173], v[198:201], v[86:89]
	v_mfma_f32_16x16x32_bf16 v[82:85], v[178:181], v[198:201], v[82:85]
	v_mfma_f32_16x16x32_bf16 v[78:81], v[170:173], v[214:217], v[78:81]
	v_mfma_f32_16x16x32_bf16 v[74:77], v[178:181], v[214:217], v[74:77]
	v_mfma_f32_16x16x32_bf16 v[70:73], v[170:173], v[222:225], v[70:73]
	s_barrier
	v_mfma_f32_16x16x32_bf16 v[66:69], v[178:181], v[222:225], v[66:69]
	s_setprio 2
	s_add_i32 s23, s60, s33
	v_lshl_add_u64 v[202:203], s[34:35], 0, v[132:133]
	s_mov_b32 m0, s23
	ds_read_b128 v[182:185], v148 offset:16384
	ds_read_b128 v[186:189], v148 offset:17408
	ds_read_b128 v[190:193], v148 offset:18432
	ds_read_b128 v[198:201], v148 offset:19456
	ds_read_b128 v[210:213], v148 offset:20480
	ds_read_b128 v[214:217], v148 offset:21504
	ds_read_b128 v[218:221], v148 offset:22528
	ds_read_b128 v[222:225], v148 offset:23552
	global_load_lds_dwordx4 v[202:203], off
	s_add_i32 m0, s23, 0x2000
	s_add_u32 s38, s34, 0x80000
	v_lshl_add_u64 v[206:207], s[34:35], 0, v[136:137]
	s_addc_u32 s39, s35, 0
	s_add_i32 s23, s61, s33
	global_load_lds_dwordx4 v[206:207], off
	v_lshl_add_u64 v[226:227], s[38:39], 0, v[132:133]
	s_mov_b32 m0, s23
	v_lshl_add_u64 v[228:229], s[36:37], 0, v[134:135]
	global_load_lds_dwordx4 v[226:227], off
	v_lshl_add_u64 v[226:227], s[38:39], 0, v[136:137]
	s_add_i32 m0, s23, 0x2000
	s_nop 0
	global_load_lds_dwordx4 v[226:227], off
	v_lshl_add_u64 v[226:227], s[36:37], 0, v[130:131]
	s_mov_b32 m0, s15
	s_nop 0
	global_load_lds_dwordx4 v[226:227], off
	s_mov_b32 m0, s41
	s_nop 0
	global_load_lds_dwordx4 v[228:229], off
	s_waitcnt vmcnt(8)
	s_waitcnt lgkmcnt(0)
	s_barrier
	s_setprio 1
	s_waitcnt lgkmcnt(0)
	v_mfma_f32_16x16x32_bf16 v[62:65], v[150:153], v[182:185], v[62:65]
	v_mfma_f32_16x16x32_bf16 v[58:61], v[158:161], v[182:185], v[58:61]
	v_mfma_f32_16x16x32_bf16 v[54:57], v[150:153], v[190:193], v[54:57]
	v_mfma_f32_16x16x32_bf16 v[50:53], v[158:161], v[190:193], v[50:53]
	v_mfma_f32_16x16x32_bf16 v[46:49], v[150:153], v[210:213], v[46:49]
	v_mfma_f32_16x16x32_bf16 v[42:45], v[158:161], v[210:213], v[42:45]
	v_mfma_f32_16x16x32_bf16 v[38:41], v[150:153], v[218:221], v[38:41]
	v_mfma_f32_16x16x32_bf16 v[34:37], v[158:161], v[218:221], v[34:37]
	v_mfma_f32_16x16x32_bf16 v[62:65], v[154:157], v[186:189], v[62:65]
	v_mfma_f32_16x16x32_bf16 v[58:61], v[162:165], v[186:189], v[58:61]
	v_mfma_f32_16x16x32_bf16 v[54:57], v[154:157], v[198:201], v[54:57]
	v_mfma_f32_16x16x32_bf16 v[50:53], v[162:165], v[198:201], v[50:53]
	v_mfma_f32_16x16x32_bf16 v[46:49], v[154:157], v[214:217], v[46:49]
	v_mfma_f32_16x16x32_bf16 v[42:45], v[162:165], v[214:217], v[42:45]
	v_mfma_f32_16x16x32_bf16 v[38:41], v[154:157], v[222:225], v[38:41]
	v_mfma_f32_16x16x32_bf16 v[34:37], v[162:165], v[222:225], v[34:37]
	v_mfma_f32_16x16x32_bf16 v[30:33], v[166:169], v[182:185], v[30:33]
	v_mfma_f32_16x16x32_bf16 v[26:29], v[174:177], v[182:185], v[26:29]
	v_mfma_f32_16x16x32_bf16 v[22:25], v[166:169], v[190:193], v[22:25]
	v_mfma_f32_16x16x32_bf16 v[18:21], v[174:177], v[190:193], v[18:21]
	v_mfma_f32_16x16x32_bf16 v[14:17], v[166:169], v[210:213], v[14:17]
	v_mfma_f32_16x16x32_bf16 v[10:13], v[174:177], v[210:213], v[10:13]
	v_mfma_f32_16x16x32_bf16 v[6:9], v[166:169], v[218:221], v[6:9]
	v_mfma_f32_16x16x32_bf16 v[2:5], v[174:177], v[218:221], v[2:5]
	v_mfma_f32_16x16x32_bf16 v[30:33], v[170:173], v[186:189], v[30:33]
	v_mfma_f32_16x16x32_bf16 v[26:29], v[178:181], v[186:189], v[26:29]
	v_mfma_f32_16x16x32_bf16 v[22:25], v[170:173], v[198:201], v[22:25]
	v_mfma_f32_16x16x32_bf16 v[18:21], v[178:181], v[198:201], v[18:21]
	v_mfma_f32_16x16x32_bf16 v[14:17], v[170:173], v[214:217], v[14:17]
	v_mfma_f32_16x16x32_bf16 v[10:13], v[178:181], v[214:217], v[10:13]
	v_mfma_f32_16x16x32_bf16 v[6:9], v[170:173], v[222:225], v[6:9]
	s_barrier
	v_mfma_f32_16x16x32_bf16 v[2:5], v[178:181], v[222:225], v[2:5]
	s_setprio 2
	s_add_i32 s23, 0, 0x18000
	s_add_i32 s38, 0, 0x1c000
	ds_read_b128 v[150:153], v250
	ds_read_b128 v[154:157], v250 offset:1024
	ds_read_b128 v[158:161], v250 offset:2048
	ds_read_b128 v[162:165], v250 offset:3072
	ds_read_b128 v[166:169], v250 offset:16384
	ds_read_b128 v[170:173], v250 offset:17408
	ds_read_b128 v[174:177], v250 offset:18432
	ds_read_b128 v[178:181], v250 offset:19456
	v_add_u32_e32 v149, s38, v144
	s_add_u32 s36, s36, 0x80000
	s_addc_u32 s37, s37, 0
	s_mov_b32 m0, s42
	v_lshl_add_u64 v[230:231], s[36:37], 0, v[130:131]
	ds_read_b128 v[182:185], v148 offset:32768
	ds_read_b128 v[186:189], v148 offset:33792
	ds_read_b128 v[190:193], v148 offset:34816
	ds_read_b128 v[198:201], v148 offset:35840
	ds_read_b128 v[210:213], v148 offset:36864
	ds_read_b128 v[214:217], v148 offset:37888
	ds_read_b128 v[218:221], v148 offset:38912
	ds_read_b128 v[222:225], v148 offset:39936
	global_load_lds_dwordx4 v[230:231], off
	v_lshl_add_u64 v[230:231], s[36:37], 0, v[134:135]
	s_mov_b32 m0, s43
	s_nop 0
	global_load_lds_dwordx4 v[230:231], off
	s_waitcnt vmcnt(8)
	s_waitcnt lgkmcnt(0)
	s_barrier
	s_setprio 1
	s_waitcnt lgkmcnt(0)
	v_mfma_f32_16x16x32_bf16 v[126:129], v[150:153], v[182:185], v[126:129]
	v_mfma_f32_16x16x32_bf16 v[122:125], v[158:161], v[182:185], v[122:125]
	v_mfma_f32_16x16x32_bf16 v[118:121], v[150:153], v[190:193], v[118:121]
	v_mfma_f32_16x16x32_bf16 v[114:117], v[158:161], v[190:193], v[114:117]
	v_mfma_f32_16x16x32_bf16 v[110:113], v[150:153], v[210:213], v[110:113]
	v_mfma_f32_16x16x32_bf16 v[106:109], v[158:161], v[210:213], v[106:109]
	v_mfma_f32_16x16x32_bf16 v[102:105], v[150:153], v[218:221], v[102:105]
	v_mfma_f32_16x16x32_bf16 v[98:101], v[158:161], v[218:221], v[98:101]
	v_mfma_f32_16x16x32_bf16 v[126:129], v[154:157], v[186:189], v[126:129]
	v_mfma_f32_16x16x32_bf16 v[122:125], v[162:165], v[186:189], v[122:125]
	v_mfma_f32_16x16x32_bf16 v[118:121], v[154:157], v[198:201], v[118:121]
	v_mfma_f32_16x16x32_bf16 v[114:117], v[162:165], v[198:201], v[114:117]
	v_mfma_f32_16x16x32_bf16 v[110:113], v[154:157], v[214:217], v[110:113]
	v_mfma_f32_16x16x32_bf16 v[106:109], v[162:165], v[214:217], v[106:109]
	v_mfma_f32_16x16x32_bf16 v[102:105], v[154:157], v[222:225], v[102:105]
	v_mfma_f32_16x16x32_bf16 v[98:101], v[162:165], v[222:225], v[98:101]
	v_mfma_f32_16x16x32_bf16 v[94:97], v[166:169], v[182:185], v[94:97]
	v_mfma_f32_16x16x32_bf16 v[90:93], v[174:177], v[182:185], v[90:93]
	v_mfma_f32_16x16x32_bf16 v[86:89], v[166:169], v[190:193], v[86:89]
	v_mfma_f32_16x16x32_bf16 v[82:85], v[174:177], v[190:193], v[82:85]
	v_mfma_f32_16x16x32_bf16 v[78:81], v[166:169], v[210:213], v[78:81]
	v_mfma_f32_16x16x32_bf16 v[74:77], v[174:177], v[210:213], v[74:77]
	v_mfma_f32_16x16x32_bf16 v[70:73], v[166:169], v[218:221], v[70:73]
	v_mfma_f32_16x16x32_bf16 v[66:69], v[174:177], v[218:221], v[66:69]
	v_mfma_f32_16x16x32_bf16 v[94:97], v[170:173], v[186:189], v[94:97]
	v_mfma_f32_16x16x32_bf16 v[90:93], v[178:181], v[186:189], v[90:93]
	v_mfma_f32_16x16x32_bf16 v[86:89], v[170:173], v[198:201], v[86:89]
	v_mfma_f32_16x16x32_bf16 v[82:85], v[178:181], v[198:201], v[82:85]
	v_mfma_f32_16x16x32_bf16 v[78:81], v[170:173], v[214:217], v[78:81]
	v_mfma_f32_16x16x32_bf16 v[74:77], v[178:181], v[214:217], v[74:77]
	v_mfma_f32_16x16x32_bf16 v[70:73], v[170:173], v[222:225], v[70:73]
	s_barrier
	v_mfma_f32_16x16x32_bf16 v[66:69], v[178:181], v[222:225], v[66:69]
	s_setprio 2
	s_add_i32 s23, s23, s33
	v_lshl_add_u64 v[202:203], v[202:203], 0, s[10:11]
	s_mov_b32 m0, s23
	ds_read_b128 v[182:185], v148 offset:49152
	ds_read_b128 v[186:189], v148 offset:50176
	ds_read_b128 v[190:193], v148 offset:51200
	ds_read_b128 v[198:201], v148 offset:52224
	ds_read_b128 v[210:213], v148 offset:53248
	ds_read_b128 v[214:217], v148 offset:54272
	ds_read_b128 v[218:221], v148 offset:55296
	ds_read_b128 v[222:225], v148 offset:56320
	global_load_lds_dwordx4 v[202:203], off
	s_add_i32 m0, s23, 0x2000
	s_add_u32 s34, s34, 0x80080
	v_lshl_add_u64 v[202:203], v[206:207], 0, s[10:11]
	s_addc_u32 s35, s35, 0
	s_add_i32 s23, s38, s33
	global_load_lds_dwordx4 v[202:203], off
	v_lshl_add_u64 v[202:203], s[34:35], 0, v[132:133]
	s_mov_b32 m0, s23
	s_nop 0
	global_load_lds_dwordx4 v[202:203], off
	v_lshl_add_u64 v[202:203], s[34:35], 0, v[136:137]
	s_add_i32 m0, s23, 0x2000
	s_nop 0
	global_load_lds_dwordx4 v[202:203], off
	v_lshl_add_u64 v[202:203], v[226:227], 0, s[10:11]
	s_mov_b32 m0, s51
	s_nop 0
	global_load_lds_dwordx4 v[202:203], off
	v_lshl_add_u64 v[202:203], v[228:229], 0, s[10:11]
	s_mov_b32 m0, s52
	s_nop 0
	global_load_lds_dwordx4 v[202:203], off
	s_waitcnt vmcnt(8)
	s_waitcnt lgkmcnt(0)
	s_barrier
	s_setprio 1
	s_waitcnt lgkmcnt(0)
	v_mfma_f32_16x16x32_bf16 v[62:65], v[150:153], v[182:185], v[62:65]
	v_mfma_f32_16x16x32_bf16 v[58:61], v[158:161], v[182:185], v[58:61]
	v_mfma_f32_16x16x32_bf16 v[54:57], v[150:153], v[190:193], v[54:57]
	v_mfma_f32_16x16x32_bf16 v[50:53], v[158:161], v[190:193], v[50:53]
	v_mfma_f32_16x16x32_bf16 v[46:49], v[150:153], v[210:213], v[46:49]
	v_mfma_f32_16x16x32_bf16 v[42:45], v[158:161], v[210:213], v[42:45]
	v_mfma_f32_16x16x32_bf16 v[38:41], v[150:153], v[218:221], v[38:41]
	v_mfma_f32_16x16x32_bf16 v[34:37], v[158:161], v[218:221], v[34:37]
	v_mfma_f32_16x16x32_bf16 v[62:65], v[154:157], v[186:189], v[62:65]
	v_mfma_f32_16x16x32_bf16 v[58:61], v[162:165], v[186:189], v[58:61]
	v_mfma_f32_16x16x32_bf16 v[54:57], v[154:157], v[198:201], v[54:57]
	v_mfma_f32_16x16x32_bf16 v[50:53], v[162:165], v[198:201], v[50:53]
	v_mfma_f32_16x16x32_bf16 v[46:49], v[154:157], v[214:217], v[46:49]
	v_mfma_f32_16x16x32_bf16 v[42:45], v[162:165], v[214:217], v[42:45]
	v_mfma_f32_16x16x32_bf16 v[38:41], v[154:157], v[222:225], v[38:41]
	v_mfma_f32_16x16x32_bf16 v[34:37], v[162:165], v[222:225], v[34:37]
	v_mfma_f32_16x16x32_bf16 v[30:33], v[166:169], v[182:185], v[30:33]
	v_mfma_f32_16x16x32_bf16 v[26:29], v[174:177], v[182:185], v[26:29]
	v_mfma_f32_16x16x32_bf16 v[22:25], v[166:169], v[190:193], v[22:25]
	v_mfma_f32_16x16x32_bf16 v[18:21], v[174:177], v[190:193], v[18:21]
	v_mfma_f32_16x16x32_bf16 v[14:17], v[166:169], v[210:213], v[14:17]
	v_mfma_f32_16x16x32_bf16 v[10:13], v[174:177], v[210:213], v[10:13]
	v_mfma_f32_16x16x32_bf16 v[6:9], v[166:169], v[218:221], v[6:9]
	v_mfma_f32_16x16x32_bf16 v[2:5], v[174:177], v[218:221], v[2:5]
	v_mfma_f32_16x16x32_bf16 v[30:33], v[170:173], v[186:189], v[30:33]
	v_mfma_f32_16x16x32_bf16 v[26:29], v[178:181], v[186:189], v[26:29]
	v_mfma_f32_16x16x32_bf16 v[22:25], v[170:173], v[198:201], v[22:25]
	v_mfma_f32_16x16x32_bf16 v[18:21], v[178:181], v[198:201], v[18:21]
	v_mfma_f32_16x16x32_bf16 v[14:17], v[170:173], v[214:217], v[14:17]
	v_mfma_f32_16x16x32_bf16 v[10:13], v[178:181], v[214:217], v[10:13]
	v_mfma_f32_16x16x32_bf16 v[6:9], v[170:173], v[222:225], v[6:9]
	s_barrier
	v_mfma_f32_16x16x32_bf16 v[2:5], v[178:181], v[222:225], v[2:5]
	s_setprio 2
	s_add_u32 s30, s30, 0x100
	s_addc_u32 s31, s31, 0
	s_add_u32 s19, s19, 0x100
	s_addc_u32 s21, s21, 0
	s_cmp_ge_i32 s29, s68
	s_mov_b32 s23, s29
	s_cbranch_scc0 .LBB0_1973

.Lpeel_1:
	v_add_u32_e32 v250, 0x18000, v146
	ds_read_b128 v[152:155], v148
	ds_read_b128 v[156:159], v148 offset:1024
	s_add_i32 s29, s19, 2
	s_add_u32 s34, s30, 0xfff80080
	s_addc_u32 s35, s31, -1
	s_cmp_eq_u32 s28, s19
	s_cselect_b32 s37, s21, s35
	s_cselect_b32 s36, s20, s34
	s_cselect_b32 s35, s23, s17
	s_cselect_b32 s34, s22, s15
	v_lshl_add_u64 v[144:145], s[30:31], 0, v[140:141]
	s_add_i32 m0, s27, 0xc000
	global_load_lds_dwordx4 v[144:145], off
	v_lshl_add_u64 v[144:145], s[30:31], 0, v[142:143]
	s_add_i32 m0, s27, 0xe000
	s_nop 0
	global_load_lds_dwordx4 v[144:145], off
	s_waitcnt vmcnt(8)
	s_waitcnt lgkmcnt(0)
	s_barrier
	s_setprio 1
	s_waitcnt lgkmcnt(0)
	v_mfma_f32_16x16x32_bf16 v[126:129], v[152:155], v[184:187], 0
	v_mfma_f32_16x16x32_bf16 v[122:125], v[160:163], v[184:187], 0
	v_mfma_f32_16x16x32_bf16 v[110:113], v[152:155], v[192:195], 0
	v_mfma_f32_16x16x32_bf16 v[106:109], v[160:163], v[192:195], 0
	v_mfma_f32_16x16x32_bf16 v[94:97], v[152:155], v[210:213], 0
	v_mfma_f32_16x16x32_bf16 v[90:93], v[160:163], v[210:213], 0
	v_mfma_f32_16x16x32_bf16 v[78:81], v[152:155], v[218:221], 0
	v_mfma_f32_16x16x32_bf16 v[74:77], v[160:163], v[218:221], 0
	v_mfma_f32_16x16x32_bf16 v[126:129], v[156:159], v[188:191], v[126:129]
	v_mfma_f32_16x16x32_bf16 v[122:125], v[164:167], v[188:191], v[122:125]
	v_mfma_f32_16x16x32_bf16 v[110:113], v[156:159], v[198:201], v[110:113]
	v_mfma_f32_16x16x32_bf16 v[106:109], v[164:167], v[198:201], v[106:109]
	v_mfma_f32_16x16x32_bf16 v[94:97], v[156:159], v[214:217], v[94:97]
	v_mfma_f32_16x16x32_bf16 v[90:93], v[164:167], v[214:217], v[90:93]
	v_mfma_f32_16x16x32_bf16 v[78:81], v[156:159], v[222:225], v[78:81]
	v_mfma_f32_16x16x32_bf16 v[74:77], v[164:167], v[222:225], v[74:77]
	v_mfma_f32_16x16x32_bf16 v[118:121], v[168:171], v[184:187], 0
	v_mfma_f32_16x16x32_bf16 v[114:117], v[176:179], v[184:187], 0
	v_mfma_f32_16x16x32_bf16 v[102:105], v[168:171], v[192:195], 0
	v_mfma_f32_16x16x32_bf16 v[98:101], v[176:179], v[192:195], 0
	v_mfma_f32_16x16x32_bf16 v[86:89], v[168:171], v[210:213], 0
	v_mfma_f32_16x16x32_bf16 v[82:85], v[176:179], v[210:213], 0
	v_mfma_f32_16x16x32_bf16 v[70:73], v[168:171], v[218:221], 0
	v_mfma_f32_16x16x32_bf16 v[66:69], v[176:179], v[218:221], 0
	v_mfma_f32_16x16x32_bf16 v[118:121], v[172:175], v[188:191], v[118:121]
	v_mfma_f32_16x16x32_bf16 v[114:117], v[180:183], v[188:191], v[114:117]
	v_mfma_f32_16x16x32_bf16 v[102:105], v[172:175], v[198:201], v[102:105]
	v_mfma_f32_16x16x32_bf16 v[98:101], v[180:183], v[198:201], v[98:101]
	v_mfma_f32_16x16x32_bf16 v[86:89], v[172:175], v[214:217], v[86:89]
	v_mfma_f32_16x16x32_bf16 v[82:85], v[180:183], v[214:217], v[82:85]
	v_mfma_f32_16x16x32_bf16 v[70:73], v[172:175], v[222:225], v[70:73]
	s_barrier
	v_mfma_f32_16x16x32_bf16 v[66:69], v[180:183], v[222:225], v[66:69]
	s_setprio 2
	s_add_i32 s19, s60, s33
	v_lshl_add_u64 v[144:145], s[34:35], 0, v[132:133]
	s_mov_b32 m0, s19
	ds_read_b128 v[184:187], v150 offset:16384
	ds_read_b128 v[188:191], v150 offset:17408
	ds_read_b128 v[192:195], v150 offset:18432
	ds_read_b128 v[198:201], v150 offset:19456
	ds_read_b128 v[210:213], v150 offset:20480
	ds_read_b128 v[214:217], v150 offset:21504
	ds_read_b128 v[218:221], v150 offset:22528
	ds_read_b128 v[222:225], v150 offset:23552
	global_load_lds_dwordx4 v[144:145], off
	s_add_i32 m0, s19, 0x2000
	s_add_u32 s38, s34, 0x80000
	v_lshl_add_u64 v[202:203], s[34:35], 0, v[136:137]
	s_addc_u32 s39, s35, 0
	s_add_i32 s19, s61, s33
	global_load_lds_dwordx4 v[202:203], off
	v_lshl_add_u64 v[206:207], s[38:39], 0, v[132:133]
	s_mov_b32 m0, s19
	v_lshl_add_u64 v[226:227], s[36:37], 0, v[134:135]
	global_load_lds_dwordx4 v[206:207], off
	v_lshl_add_u64 v[206:207], s[38:39], 0, v[136:137]
	s_add_i32 m0, s19, 0x2000
	s_nop 0
	global_load_lds_dwordx4 v[206:207], off
	v_lshl_add_u64 v[206:207], s[36:37], 0, v[130:131]
	s_mov_b32 m0, s27
	s_nop 0
	global_load_lds_dwordx4 v[206:207], off
	s_mov_b32 m0, s41
	s_nop 0
	global_load_lds_dwordx4 v[226:227], off
	s_waitcnt vmcnt(8)
	s_waitcnt lgkmcnt(0)
	s_barrier
	s_setprio 1
	s_waitcnt lgkmcnt(0)
	v_mfma_f32_16x16x32_bf16 v[62:65], v[152:155], v[184:187], 0
	v_mfma_f32_16x16x32_bf16 v[58:61], v[160:163], v[184:187], 0
	v_mfma_f32_16x16x32_bf16 v[46:49], v[152:155], v[192:195], 0
	v_mfma_f32_16x16x32_bf16 v[42:45], v[160:163], v[192:195], 0
	v_mfma_f32_16x16x32_bf16 v[30:33], v[152:155], v[210:213], 0
	v_mfma_f32_16x16x32_bf16 v[26:29], v[160:163], v[210:213], 0
	v_mfma_f32_16x16x32_bf16 v[14:17], v[152:155], v[218:221], 0
	v_mfma_f32_16x16x32_bf16 v[10:13], v[160:163], v[218:221], 0
	v_mfma_f32_16x16x32_bf16 v[62:65], v[156:159], v[188:191], v[62:65]
	v_mfma_f32_16x16x32_bf16 v[58:61], v[164:167], v[188:191], v[58:61]
	v_mfma_f32_16x16x32_bf16 v[46:49], v[156:159], v[198:201], v[46:49]
	v_mfma_f32_16x16x32_bf16 v[42:45], v[164:167], v[198:201], v[42:45]
	v_mfma_f32_16x16x32_bf16 v[30:33], v[156:159], v[214:217], v[30:33]
	v_mfma_f32_16x16x32_bf16 v[26:29], v[164:167], v[214:217], v[26:29]
	v_mfma_f32_16x16x32_bf16 v[14:17], v[156:159], v[222:225], v[14:17]
	v_mfma_f32_16x16x32_bf16 v[10:13], v[164:167], v[222:225], v[10:13]
	v_mfma_f32_16x16x32_bf16 v[54:57], v[168:171], v[184:187], 0
	v_mfma_f32_16x16x32_bf16 v[50:53], v[176:179], v[184:187], 0
	v_mfma_f32_16x16x32_bf16 v[38:41], v[168:171], v[192:195], 0
	v_mfma_f32_16x16x32_bf16 v[34:37], v[176:179], v[192:195], 0
	v_mfma_f32_16x16x32_bf16 v[22:25], v[168:171], v[210:213], 0
	v_mfma_f32_16x16x32_bf16 v[18:21], v[176:179], v[210:213], 0
	v_mfma_f32_16x16x32_bf16 v[6:9], v[168:171], v[218:221], 0
	v_mfma_f32_16x16x32_bf16 v[2:5], v[176:179], v[218:221], 0
	v_mfma_f32_16x16x32_bf16 v[54:57], v[172:175], v[188:191], v[54:57]
	v_mfma_f32_16x16x32_bf16 v[50:53], v[180:183], v[188:191], v[50:53]
	v_mfma_f32_16x16x32_bf16 v[38:41], v[172:175], v[198:201], v[38:41]
	v_mfma_f32_16x16x32_bf16 v[34:37], v[180:183], v[198:201], v[34:37]
	v_mfma_f32_16x16x32_bf16 v[22:25], v[172:175], v[214:217], v[22:25]
	v_mfma_f32_16x16x32_bf16 v[18:21], v[180:183], v[214:217], v[18:21]
	v_mfma_f32_16x16x32_bf16 v[6:9], v[172:175], v[222:225], v[6:9]
	s_barrier
	v_mfma_f32_16x16x32_bf16 v[2:5], v[180:183], v[222:225], v[2:5]
	s_setprio 2
	s_add_i32 s19, 0, 0x18000
	s_add_i32 s38, 0, 0x1c000
	ds_read_b128 v[152:155], v250
	ds_read_b128 v[156:159], v250 offset:1024
	ds_read_b128 v[160:163], v250 offset:2048
	ds_read_b128 v[164:167], v250 offset:3072
	ds_read_b128 v[168:171], v250 offset:16384
	ds_read_b128 v[172:175], v250 offset:17408
	ds_read_b128 v[176:179], v250 offset:18432
	ds_read_b128 v[180:183], v250 offset:19456
	v_add_u32_e32 v151, s38, v146
	s_add_u32 s36, s36, 0x80000
	s_addc_u32 s37, s37, 0
	s_mov_b32 m0, s42
	v_lshl_add_u64 v[228:229], s[36:37], 0, v[130:131]
	ds_read_b128 v[184:187], v150 offset:32768
	ds_read_b128 v[188:191], v150 offset:33792
	ds_read_b128 v[192:195], v150 offset:34816
	ds_read_b128 v[198:201], v150 offset:35840
	ds_read_b128 v[210:213], v150 offset:36864
	ds_read_b128 v[214:217], v150 offset:37888
	ds_read_b128 v[218:221], v150 offset:38912
	ds_read_b128 v[222:225], v150 offset:39936
	global_load_lds_dwordx4 v[228:229], off
	v_lshl_add_u64 v[228:229], s[36:37], 0, v[134:135]
	s_mov_b32 m0, s43
	s_nop 0
	global_load_lds_dwordx4 v[228:229], off
	s_waitcnt vmcnt(8)
	s_waitcnt lgkmcnt(0)
	s_barrier
	s_setprio 1
	s_waitcnt lgkmcnt(0)
	v_mfma_f32_16x16x32_bf16 v[126:129], v[152:155], v[184:187], v[126:129]
	v_mfma_f32_16x16x32_bf16 v[122:125], v[160:163], v[184:187], v[122:125]
	v_mfma_f32_16x16x32_bf16 v[110:113], v[152:155], v[192:195], v[110:113]
	v_mfma_f32_16x16x32_bf16 v[106:109], v[160:163], v[192:195], v[106:109]
	v_mfma_f32_16x16x32_bf16 v[94:97], v[152:155], v[210:213], v[94:97]
	v_mfma_f32_16x16x32_bf16 v[90:93], v[160:163], v[210:213], v[90:93]
	v_mfma_f32_16x16x32_bf16 v[78:81], v[152:155], v[218:221], v[78:81]
	v_mfma_f32_16x16x32_bf16 v[74:77], v[160:163], v[218:221], v[74:77]
	v_mfma_f32_16x16x32_bf16 v[126:129], v[156:159], v[188:191], v[126:129]
	v_mfma_f32_16x16x32_bf16 v[122:125], v[164:167], v[188:191], v[122:125]
	v_mfma_f32_16x16x32_bf16 v[110:113], v[156:159], v[198:201], v[110:113]
	v_mfma_f32_16x16x32_bf16 v[106:109], v[164:167], v[198:201], v[106:109]
	v_mfma_f32_16x16x32_bf16 v[94:97], v[156:159], v[214:217], v[94:97]
	v_mfma_f32_16x16x32_bf16 v[90:93], v[164:167], v[214:217], v[90:93]
	v_mfma_f32_16x16x32_bf16 v[78:81], v[156:159], v[222:225], v[78:81]
	v_mfma_f32_16x16x32_bf16 v[74:77], v[164:167], v[222:225], v[74:77]
	v_mfma_f32_16x16x32_bf16 v[118:121], v[168:171], v[184:187], v[118:121]
	v_mfma_f32_16x16x32_bf16 v[114:117], v[176:179], v[184:187], v[114:117]
	v_mfma_f32_16x16x32_bf16 v[102:105], v[168:171], v[192:195], v[102:105]
	v_mfma_f32_16x16x32_bf16 v[98:101], v[176:179], v[192:195], v[98:101]
	v_mfma_f32_16x16x32_bf16 v[86:89], v[168:171], v[210:213], v[86:89]
	v_mfma_f32_16x16x32_bf16 v[82:85], v[176:179], v[210:213], v[82:85]
	v_mfma_f32_16x16x32_bf16 v[70:73], v[168:171], v[218:221], v[70:73]
	v_mfma_f32_16x16x32_bf16 v[66:69], v[176:179], v[218:221], v[66:69]
	v_mfma_f32_16x16x32_bf16 v[118:121], v[172:175], v[188:191], v[118:121]
	v_mfma_f32_16x16x32_bf16 v[114:117], v[180:183], v[188:191], v[114:117]
	v_mfma_f32_16x16x32_bf16 v[102:105], v[172:175], v[198:201], v[102:105]
	v_mfma_f32_16x16x32_bf16 v[98:101], v[180:183], v[198:201], v[98:101]
	v_mfma_f32_16x16x32_bf16 v[86:89], v[172:175], v[214:217], v[86:89]
	v_mfma_f32_16x16x32_bf16 v[82:85], v[180:183], v[214:217], v[82:85]
	v_mfma_f32_16x16x32_bf16 v[70:73], v[172:175], v[222:225], v[70:73]
	s_barrier
	v_mfma_f32_16x16x32_bf16 v[66:69], v[180:183], v[222:225], v[66:69]
	s_setprio 2
	s_add_i32 s19, s19, s33
	v_lshl_add_u64 v[144:145], v[144:145], 0, s[10:11]
	s_mov_b32 m0, s19
	ds_read_b128 v[184:187], v150 offset:49152
	ds_read_b128 v[188:191], v150 offset:50176
	ds_read_b128 v[192:195], v150 offset:51200
	ds_read_b128 v[198:201], v150 offset:52224
	ds_read_b128 v[210:213], v150 offset:53248
	ds_read_b128 v[214:217], v150 offset:54272
	ds_read_b128 v[218:221], v150 offset:55296
	ds_read_b128 v[222:225], v150 offset:56320
	global_load_lds_dwordx4 v[144:145], off
	s_add_i32 m0, s19, 0x2000
	s_add_u32 s34, s34, 0x80080
	v_lshl_add_u64 v[144:145], v[202:203], 0, s[10:11]
	s_addc_u32 s35, s35, 0
	s_add_i32 s19, s38, s33
	global_load_lds_dwordx4 v[144:145], off
	v_lshl_add_u64 v[144:145], s[34:35], 0, v[132:133]
	s_mov_b32 m0, s19
	s_nop 0
	global_load_lds_dwordx4 v[144:145], off
	v_lshl_add_u64 v[144:145], s[34:35], 0, v[136:137]
	s_add_i32 m0, s19, 0x2000
	s_nop 0
	global_load_lds_dwordx4 v[144:145], off
	v_lshl_add_u64 v[144:145], v[206:207], 0, s[10:11]
	s_mov_b32 m0, s51
	s_nop 0
	global_load_lds_dwordx4 v[144:145], off
	v_lshl_add_u64 v[144:145], v[226:227], 0, s[10:11]
	s_mov_b32 m0, s52
	s_nop 0
	global_load_lds_dwordx4 v[144:145], off
	s_waitcnt vmcnt(8)
	s_waitcnt lgkmcnt(0)
	s_barrier
	s_setprio 1
	s_waitcnt lgkmcnt(0)
	v_mfma_f32_16x16x32_bf16 v[62:65], v[152:155], v[184:187], v[62:65]
	v_mfma_f32_16x16x32_bf16 v[58:61], v[160:163], v[184:187], v[58:61]
	v_mfma_f32_16x16x32_bf16 v[46:49], v[152:155], v[192:195], v[46:49]
	v_mfma_f32_16x16x32_bf16 v[42:45], v[160:163], v[192:195], v[42:45]
	v_mfma_f32_16x16x32_bf16 v[30:33], v[152:155], v[210:213], v[30:33]
	v_mfma_f32_16x16x32_bf16 v[26:29], v[160:163], v[210:213], v[26:29]
	v_mfma_f32_16x16x32_bf16 v[14:17], v[152:155], v[218:221], v[14:17]
	v_mfma_f32_16x16x32_bf16 v[10:13], v[160:163], v[218:221], v[10:13]
	v_mfma_f32_16x16x32_bf16 v[62:65], v[156:159], v[188:191], v[62:65]
	v_mfma_f32_16x16x32_bf16 v[58:61], v[164:167], v[188:191], v[58:61]
	v_mfma_f32_16x16x32_bf16 v[46:49], v[156:159], v[198:201], v[46:49]
	v_mfma_f32_16x16x32_bf16 v[42:45], v[164:167], v[198:201], v[42:45]
	v_mfma_f32_16x16x32_bf16 v[30:33], v[156:159], v[214:217], v[30:33]
	v_mfma_f32_16x16x32_bf16 v[26:29], v[164:167], v[214:217], v[26:29]
	v_mfma_f32_16x16x32_bf16 v[14:17], v[156:159], v[222:225], v[14:17]
	v_mfma_f32_16x16x32_bf16 v[10:13], v[164:167], v[222:225], v[10:13]
	v_mfma_f32_16x16x32_bf16 v[54:57], v[168:171], v[184:187], v[54:57]
	v_mfma_f32_16x16x32_bf16 v[50:53], v[176:179], v[184:187], v[50:53]
	v_mfma_f32_16x16x32_bf16 v[38:41], v[168:171], v[192:195], v[38:41]
	v_mfma_f32_16x16x32_bf16 v[34:37], v[176:179], v[192:195], v[34:37]
	v_mfma_f32_16x16x32_bf16 v[22:25], v[168:171], v[210:213], v[22:25]
	v_mfma_f32_16x16x32_bf16 v[18:21], v[176:179], v[210:213], v[18:21]
	v_mfma_f32_16x16x32_bf16 v[6:9], v[168:171], v[218:221], v[6:9]
	v_mfma_f32_16x16x32_bf16 v[2:5], v[176:179], v[218:221], v[2:5]
	v_mfma_f32_16x16x32_bf16 v[54:57], v[172:175], v[188:191], v[54:57]
	v_mfma_f32_16x16x32_bf16 v[50:53], v[180:183], v[188:191], v[50:53]
	v_mfma_f32_16x16x32_bf16 v[38:41], v[172:175], v[198:201], v[38:41]
	v_mfma_f32_16x16x32_bf16 v[34:37], v[180:183], v[198:201], v[34:37]
	v_mfma_f32_16x16x32_bf16 v[22:25], v[172:175], v[214:217], v[22:25]
	v_mfma_f32_16x16x32_bf16 v[18:21], v[180:183], v[214:217], v[18:21]
	v_mfma_f32_16x16x32_bf16 v[6:9], v[172:175], v[222:225], v[6:9]
	s_barrier
	v_mfma_f32_16x16x32_bf16 v[2:5], v[180:183], v[222:225], v[2:5]
	s_setprio 2
	s_add_u32 s30, s30, 0x100
	s_addc_u32 s31, s31, 0
	s_add_u32 s15, s15, 0x100
	s_addc_u32 s17, s17, 0
	s_cmp_ge_i32 s29, s68
	s_mov_b32 s19, s29
	s_cbranch_scc0 .LBB0_2547
	s_branch .Lpeeldone_1
.LBB0_2547:
	ds_read_b128 v[152:155], v148
	ds_read_b128 v[156:159], v148 offset:1024
	ds_read_b128 v[160:163], v148 offset:2048
	ds_read_b128 v[164:167], v148 offset:3072
	ds_read_b128 v[168:171], v149
	ds_read_b128 v[172:175], v149 offset:1024
	ds_read_b128 v[176:179], v149 offset:2048
	ds_read_b128 v[180:183], v149 offset:3072
	s_add_i32 s29, s19, 2
	s_add_u32 s34, s30, 0xfff80080
	s_addc_u32 s35, s31, -1
	s_cmp_eq_u32 s28, s19
	s_cselect_b32 s37, s21, s35
	s_cselect_b32 s36, s20, s34
	s_cselect_b32 s35, s23, s17
	s_cselect_b32 s34, s22, s15
	v_lshl_add_u64 v[144:145], s[30:31], 0, v[140:141]
	s_add_i32 m0, s27, 0xc000
	ds_read_b128 v[184:187], v150
	ds_read_b128 v[188:191], v150 offset:1024
	ds_read_b128 v[192:195], v150 offset:2048
	ds_read_b128 v[198:201], v150 offset:3072
	ds_read_b128 v[210:213], v150 offset:4096
	ds_read_b128 v[214:217], v150 offset:5120
	ds_read_b128 v[218:221], v150 offset:6144
	ds_read_b128 v[222:225], v150 offset:7168
	global_load_lds_dwordx4 v[144:145], off
	v_lshl_add_u64 v[144:145], s[30:31], 0, v[142:143]
	s_add_i32 m0, s27, 0xe000
	s_nop 0
	global_load_lds_dwordx4 v[144:145], off
	s_waitcnt vmcnt(8)
	s_waitcnt lgkmcnt(0)
	s_barrier
	s_setprio 1
	s_waitcnt lgkmcnt(0)
	v_mfma_f32_16x16x32_bf16 v[126:129], v[152:155], v[184:187], v[126:129]
	v_mfma_f32_16x16x32_bf16 v[122:125], v[160:163], v[184:187], v[122:125]
	v_mfma_f32_16x16x32_bf16 v[110:113], v[152:155], v[192:195], v[110:113]
	v_mfma_f32_16x16x32_bf16 v[106:109], v[160:163], v[192:195], v[106:109]
	v_mfma_f32_16x16x32_bf16 v[94:97], v[152:155], v[210:213], v[94:97]
	v_mfma_f32_16x16x32_bf16 v[90:93], v[160:163], v[210:213], v[90:93]
	v_mfma_f32_16x16x32_bf16 v[78:81], v[152:155], v[218:221], v[78:81]
	v_mfma_f32_16x16x32_bf16 v[74:77], v[160:163], v[218:221], v[74:77]
	v_mfma_f32_16x16x32_bf16 v[126:129], v[156:159], v[188:191], v[126:129]
	v_mfma_f32_16x16x32_bf16 v[122:125], v[164:167], v[188:191], v[122:125]
	v_mfma_f32_16x16x32_bf16 v[110:113], v[156:159], v[198:201], v[110:113]
	v_mfma_f32_16x16x32_bf16 v[106:109], v[164:167], v[198:201], v[106:109]
	v_mfma_f32_16x16x32_bf16 v[94:97], v[156:159], v[214:217], v[94:97]
	v_mfma_f32_16x16x32_bf16 v[90:93], v[164:167], v[214:217], v[90:93]
	v_mfma_f32_16x16x32_bf16 v[78:81], v[156:159], v[222:225], v[78:81]
	v_mfma_f32_16x16x32_bf16 v[74:77], v[164:167], v[222:225], v[74:77]
	v_mfma_f32_16x16x32_bf16 v[118:121], v[168:171], v[184:187], v[118:121]
	v_mfma_f32_16x16x32_bf16 v[114:117], v[176:179], v[184:187], v[114:117]
	v_mfma_f32_16x16x32_bf16 v[102:105], v[168:171], v[192:195], v[102:105]
	v_mfma_f32_16x16x32_bf16 v[98:101], v[176:179], v[192:195], v[98:101]
	v_mfma_f32_16x16x32_bf16 v[86:89], v[168:171], v[210:213], v[86:89]
	v_mfma_f32_16x16x32_bf16 v[82:85], v[176:179], v[210:213], v[82:85]
	v_mfma_f32_16x16x32_bf16 v[70:73], v[168:171], v[218:221], v[70:73]
	v_mfma_f32_16x16x32_bf16 v[66:69], v[176:179], v[218:221], v[66:69]
	v_mfma_f32_16x16x32_bf16 v[118:121], v[172:175], v[188:191], v[118:121]
	v_mfma_f32_16x16x32_bf16 v[114:117], v[180:183], v[188:191], v[114:117]
	v_mfma_f32_16x16x32_bf16 v[102:105], v[172:175], v[198:201], v[102:105]
	v_mfma_f32_16x16x32_bf16 v[98:101], v[180:183], v[198:201], v[98:101]
	v_mfma_f32_16x16x32_bf16 v[86:89], v[172:175], v[214:217], v[86:89]
	v_mfma_f32_16x16x32_bf16 v[82:85], v[180:183], v[214:217], v[82:85]
	v_mfma_f32_16x16x32_bf16 v[70:73], v[172:175], v[222:225], v[70:73]
	s_barrier
	v_mfma_f32_16x16x32_bf16 v[66:69], v[180:183], v[222:225], v[66:69]
	s_setprio 2
	s_add_i32 s19, s60, s33
	v_lshl_add_u64 v[144:145], s[34:35], 0, v[132:133]
	s_mov_b32 m0, s19
	ds_read_b128 v[184:187], v150 offset:16384
	ds_read_b128 v[188:191], v150 offset:17408
	ds_read_b128 v[192:195], v150 offset:18432
	ds_read_b128 v[198:201], v150 offset:19456
	ds_read_b128 v[210:213], v150 offset:20480
	ds_read_b128 v[214:217], v150 offset:21504
	ds_read_b128 v[218:221], v150 offset:22528
	ds_read_b128 v[222:225], v150 offset:23552
	global_load_lds_dwordx4 v[144:145], off
	s_add_i32 m0, s19, 0x2000
	s_add_u32 s38, s34, 0x80000
	v_lshl_add_u64 v[202:203], s[34:35], 0, v[136:137]
	s_addc_u32 s39, s35, 0
	s_add_i32 s19, s61, s33
	global_load_lds_dwordx4 v[202:203], off
	v_lshl_add_u64 v[206:207], s[38:39], 0, v[132:133]
	s_mov_b32 m0, s19
	v_lshl_add_u64 v[226:227], s[36:37], 0, v[134:135]
	global_load_lds_dwordx4 v[206:207], off
	v_lshl_add_u64 v[206:207], s[38:39], 0, v[136:137]
	s_add_i32 m0, s19, 0x2000
	s_nop 0
	global_load_lds_dwordx4 v[206:207], off
	v_lshl_add_u64 v[206:207], s[36:37], 0, v[130:131]
	s_mov_b32 m0, s27
	s_nop 0
	global_load_lds_dwordx4 v[206:207], off
	s_mov_b32 m0, s41
	s_nop 0
	global_load_lds_dwordx4 v[226:227], off
	s_waitcnt vmcnt(8)
	s_waitcnt lgkmcnt(0)
	s_barrier
	s_setprio 1
	s_waitcnt lgkmcnt(0)
	v_mfma_f32_16x16x32_bf16 v[62:65], v[152:155], v[184:187], v[62:65]
	v_mfma_f32_16x16x32_bf16 v[58:61], v[160:163], v[184:187], v[58:61]
	v_mfma_f32_16x16x32_bf16 v[46:49], v[152:155], v[192:195], v[46:49]
	v_mfma_f32_16x16x32_bf16 v[42:45], v[160:163], v[192:195], v[42:45]
	v_mfma_f32_16x16x32_bf16 v[30:33], v[152:155], v[210:213], v[30:33]
	v_mfma_f32_16x16x32_bf16 v[26:29], v[160:163], v[210:213], v[26:29]
	v_mfma_f32_16x16x32_bf16 v[14:17], v[152:155], v[218:221], v[14:17]
	v_mfma_f32_16x16x32_bf16 v[10:13], v[160:163], v[218:221], v[10:13]
	v_mfma_f32_16x16x32_bf16 v[62:65], v[156:159], v[188:191], v[62:65]
	v_mfma_f32_16x16x32_bf16 v[58:61], v[164:167], v[188:191], v[58:61]
	v_mfma_f32_16x16x32_bf16 v[46:49], v[156:159], v[198:201], v[46:49]
	v_mfma_f32_16x16x32_bf16 v[42:45], v[164:167], v[198:201], v[42:45]
	v_mfma_f32_16x16x32_bf16 v[30:33], v[156:159], v[214:217], v[30:33]
	v_mfma_f32_16x16x32_bf16 v[26:29], v[164:167], v[214:217], v[26:29]
	v_mfma_f32_16x16x32_bf16 v[14:17], v[156:159], v[222:225], v[14:17]
	v_mfma_f32_16x16x32_bf16 v[10:13], v[164:167], v[222:225], v[10:13]
	v_mfma_f32_16x16x32_bf16 v[54:57], v[168:171], v[184:187], v[54:57]
	v_mfma_f32_16x16x32_bf16 v[50:53], v[176:179], v[184:187], v[50:53]
	v_mfma_f32_16x16x32_bf16 v[38:41], v[168:171], v[192:195], v[38:41]
	v_mfma_f32_16x16x32_bf16 v[34:37], v[176:179], v[192:195], v[34:37]
	v_mfma_f32_16x16x32_bf16 v[22:25], v[168:171], v[210:213], v[22:25]
	v_mfma_f32_16x16x32_bf16 v[18:21], v[176:179], v[210:213], v[18:21]
	v_mfma_f32_16x16x32_bf16 v[6:9], v[168:171], v[218:221], v[6:9]
	v_mfma_f32_16x16x32_bf16 v[2:5], v[176:179], v[218:221], v[2:5]
	v_mfma_f32_16x16x32_bf16 v[54:57], v[172:175], v[188:191], v[54:57]
	v_mfma_f32_16x16x32_bf16 v[50:53], v[180:183], v[188:191], v[50:53]
	v_mfma_f32_16x16x32_bf16 v[38:41], v[172:175], v[198:201], v[38:41]
	v_mfma_f32_16x16x32_bf16 v[34:37], v[180:183], v[198:201], v[34:37]
	v_mfma_f32_16x16x32_bf16 v[22:25], v[172:175], v[214:217], v[22:25]
	v_mfma_f32_16x16x32_bf16 v[18:21], v[180:183], v[214:217], v[18:21]
	v_mfma_f32_16x16x32_bf16 v[6:9], v[172:175], v[222:225], v[6:9]
	s_barrier
	v_mfma_f32_16x16x32_bf16 v[2:5], v[180:183], v[222:225], v[2:5]
	s_setprio 2
	s_add_i32 s19, 0, 0x18000
	s_add_i32 s38, 0, 0x1c000
	ds_read_b128 v[152:155], v250
	ds_read_b128 v[156:159], v250 offset:1024
	ds_read_b128 v[160:163], v250 offset:2048
	ds_read_b128 v[164:167], v250 offset:3072
	ds_read_b128 v[168:171], v250 offset:16384
	ds_read_b128 v[172:175], v250 offset:17408
	ds_read_b128 v[176:179], v250 offset:18432
	ds_read_b128 v[180:183], v250 offset:19456
	v_add_u32_e32 v151, s38, v146
	s_add_u32 s36, s36, 0x80000
	s_addc_u32 s37, s37, 0
	s_mov_b32 m0, s42
	v_lshl_add_u64 v[228:229], s[36:37], 0, v[130:131]
	ds_read_b128 v[184:187], v150 offset:32768
	ds_read_b128 v[188:191], v150 offset:33792
	ds_read_b128 v[192:195], v150 offset:34816
	ds_read_b128 v[198:201], v150 offset:35840
	ds_read_b128 v[210:213], v150 offset:36864
	ds_read_b128 v[214:217], v150 offset:37888
	ds_read_b128 v[218:221], v150 offset:38912
	ds_read_b128 v[222:225], v150 offset:39936
	global_load_lds_dwordx4 v[228:229], off
	v_lshl_add_u64 v[228:229], s[36:37], 0, v[134:135]
	s_mov_b32 m0, s43
	s_nop 0
	global_load_lds_dwordx4 v[228:229], off
	s_waitcnt vmcnt(8)
	s_waitcnt lgkmcnt(0)
	s_barrier
	s_setprio 1
	s_waitcnt lgkmcnt(0)
	v_mfma_f32_16x16x32_bf16 v[126:129], v[152:155], v[184:187], v[126:129]
	v_mfma_f32_16x16x32_bf16 v[122:125], v[160:163], v[184:187], v[122:125]
	v_mfma_f32_16x16x32_bf16 v[110:113], v[152:155], v[192:195], v[110:113]
	v_mfma_f32_16x16x32_bf16 v[106:109], v[160:163], v[192:195], v[106:109]
	v_mfma_f32_16x16x32_bf16 v[94:97], v[152:155], v[210:213], v[94:97]
	v_mfma_f32_16x16x32_bf16 v[90:93], v[160:163], v[210:213], v[90:93]
	v_mfma_f32_16x16x32_bf16 v[78:81], v[152:155], v[218:221], v[78:81]
	v_mfma_f32_16x16x32_bf16 v[74:77], v[160:163], v[218:221], v[74:77]
	v_mfma_f32_16x16x32_bf16 v[126:129], v[156:159], v[188:191], v[126:129]
	v_mfma_f32_16x16x32_bf16 v[122:125], v[164:167], v[188:191], v[122:125]
	v_mfma_f32_16x16x32_bf16 v[110:113], v[156:159], v[198:201], v[110:113]
	v_mfma_f32_16x16x32_bf16 v[106:109], v[164:167], v[198:201], v[106:109]
	v_mfma_f32_16x16x32_bf16 v[94:97], v[156:159], v[214:217], v[94:97]
	v_mfma_f32_16x16x32_bf16 v[90:93], v[164:167], v[214:217], v[90:93]
	v_mfma_f32_16x16x32_bf16 v[78:81], v[156:159], v[222:225], v[78:81]
	v_mfma_f32_16x16x32_bf16 v[74:77], v[164:167], v[222:225], v[74:77]
	v_mfma_f32_16x16x32_bf16 v[118:121], v[168:171], v[184:187], v[118:121]
	v_mfma_f32_16x16x32_bf16 v[114:117], v[176:179], v[184:187], v[114:117]
	v_mfma_f32_16x16x32_bf16 v[102:105], v[168:171], v[192:195], v[102:105]
	v_mfma_f32_16x16x32_bf16 v[98:101], v[176:179], v[192:195], v[98:101]
	v_mfma_f32_16x16x32_bf16 v[86:89], v[168:171], v[210:213], v[86:89]
	v_mfma_f32_16x16x32_bf16 v[82:85], v[176:179], v[210:213], v[82:85]
	v_mfma_f32_16x16x32_bf16 v[70:73], v[168:171], v[218:221], v[70:73]
	v_mfma_f32_16x16x32_bf16 v[66:69], v[176:179], v[218:221], v[66:69]
	v_mfma_f32_16x16x32_bf16 v[118:121], v[172:175], v[188:191], v[118:121]
	v_mfma_f32_16x16x32_bf16 v[114:117], v[180:183], v[188:191], v[114:117]
	v_mfma_f32_16x16x32_bf16 v[102:105], v[172:175], v[198:201], v[102:105]
	v_mfma_f32_16x16x32_bf16 v[98:101], v[180:183], v[198:201], v[98:101]
	v_mfma_f32_16x16x32_bf16 v[86:89], v[172:175], v[214:217], v[86:89]
	v_mfma_f32_16x16x32_bf16 v[82:85], v[180:183], v[214:217], v[82:85]
	v_mfma_f32_16x16x32_bf16 v[70:73], v[172:175], v[222:225], v[70:73]
	s_barrier
	v_mfma_f32_16x16x32_bf16 v[66:69], v[180:183], v[222:225], v[66:69]
	s_setprio 2
	s_add_i32 s19, s19, s33
	v_lshl_add_u64 v[144:145], v[144:145], 0, s[10:11]
	s_mov_b32 m0, s19
	ds_read_b128 v[184:187], v150 offset:49152
	ds_read_b128 v[188:191], v150 offset:50176
	ds_read_b128 v[192:195], v150 offset:51200
	ds_read_b128 v[198:201], v150 offset:52224
	ds_read_b128 v[210:213], v150 offset:53248
	ds_read_b128 v[214:217], v150 offset:54272
	ds_read_b128 v[218:221], v150 offset:55296
	ds_read_b128 v[222:225], v150 offset:56320
	global_load_lds_dwordx4 v[144:145], off
	s_add_i32 m0, s19, 0x2000
	s_add_u32 s34, s34, 0x80080
	v_lshl_add_u64 v[144:145], v[202:203], 0, s[10:11]
	s_addc_u32 s35, s35, 0
	s_add_i32 s19, s38, s33
	global_load_lds_dwordx4 v[144:145], off
	v_lshl_add_u64 v[144:145], s[34:35], 0, v[132:133]
	s_mov_b32 m0, s19
	s_nop 0
	global_load_lds_dwordx4 v[144:145], off
	v_lshl_add_u64 v[144:145], s[34:35], 0, v[136:137]
	s_add_i32 m0, s19, 0x2000
	s_nop 0
	global_load_lds_dwordx4 v[144:145], off
	v_lshl_add_u64 v[144:145], v[206:207], 0, s[10:11]
	s_mov_b32 m0, s51
	s_nop 0
	global_load_lds_dwordx4 v[144:145], off
	v_lshl_add_u64 v[144:145], v[226:227], 0, s[10:11]
	s_mov_b32 m0, s52
	s_nop 0
	global_load_lds_dwordx4 v[144:145], off
	s_waitcnt vmcnt(8)
	s_waitcnt lgkmcnt(0)
	s_barrier
	s_setprio 1
	s_waitcnt lgkmcnt(0)
	v_mfma_f32_16x16x32_bf16 v[62:65], v[152:155], v[184:187], v[62:65]
	v_mfma_f32_16x16x32_bf16 v[58:61], v[160:163], v[184:187], v[58:61]
	v_mfma_f32_16x16x32_bf16 v[46:49], v[152:155], v[192:195], v[46:49]
	v_mfma_f32_16x16x32_bf16 v[42:45], v[160:163], v[192:195], v[42:45]
	v_mfma_f32_16x16x32_bf16 v[30:33], v[152:155], v[210:213], v[30:33]
	v_mfma_f32_16x16x32_bf16 v[26:29], v[160:163], v[210:213], v[26:29]
	v_mfma_f32_16x16x32_bf16 v[14:17], v[152:155], v[218:221], v[14:17]
	v_mfma_f32_16x16x32_bf16 v[10:13], v[160:163], v[218:221], v[10:13]
	v_mfma_f32_16x16x32_bf16 v[62:65], v[156:159], v[188:191], v[62:65]
	v_mfma_f32_16x16x32_bf16 v[58:61], v[164:167], v[188:191], v[58:61]
	v_mfma_f32_16x16x32_bf16 v[46:49], v[156:159], v[198:201], v[46:49]
	v_mfma_f32_16x16x32_bf16 v[42:45], v[164:167], v[198:201], v[42:45]
	v_mfma_f32_16x16x32_bf16 v[30:33], v[156:159], v[214:217], v[30:33]
	v_mfma_f32_16x16x32_bf16 v[26:29], v[164:167], v[214:217], v[26:29]
	v_mfma_f32_16x16x32_bf16 v[14:17], v[156:159], v[222:225], v[14:17]
	v_mfma_f32_16x16x32_bf16 v[10:13], v[164:167], v[222:225], v[10:13]
	v_mfma_f32_16x16x32_bf16 v[54:57], v[168:171], v[184:187], v[54:57]
	v_mfma_f32_16x16x32_bf16 v[50:53], v[176:179], v[184:187], v[50:53]
	v_mfma_f32_16x16x32_bf16 v[38:41], v[168:171], v[192:195], v[38:41]
	v_mfma_f32_16x16x32_bf16 v[34:37], v[176:179], v[192:195], v[34:37]
	v_mfma_f32_16x16x32_bf16 v[22:25], v[168:171], v[210:213], v[22:25]
	v_mfma_f32_16x16x32_bf16 v[18:21], v[176:179], v[210:213], v[18:21]
	v_mfma_f32_16x16x32_bf16 v[6:9], v[168:171], v[218:221], v[6:9]
	v_mfma_f32_16x16x32_bf16 v[2:5], v[176:179], v[218:221], v[2:5]
	v_mfma_f32_16x16x32_bf16 v[54:57], v[172:175], v[188:191], v[54:57]
	v_mfma_f32_16x16x32_bf16 v[50:53], v[180:183], v[188:191], v[50:53]
	v_mfma_f32_16x16x32_bf16 v[38:41], v[172:175], v[198:201], v[38:41]
	v_mfma_f32_16x16x32_bf16 v[34:37], v[180:183], v[198:201], v[34:37]
	v_mfma_f32_16x16x32_bf16 v[22:25], v[172:175], v[214:217], v[22:25]
	v_mfma_f32_16x16x32_bf16 v[18:21], v[180:183], v[214:217], v[18:21]
	v_mfma_f32_16x16x32_bf16 v[6:9], v[172:175], v[222:225], v[6:9]
	s_barrier
	v_mfma_f32_16x16x32_bf16 v[2:5], v[180:183], v[222:225], v[2:5]
	s_setprio 2
	s_add_u32 s30, s30, 0x100
	s_addc_u32 s31, s31, 0
	s_add_u32 s15, s15, 0x100
	s_addc_u32 s17, s17, 0
	s_cmp_ge_i32 s29, s68
	s_mov_b32 s19, s29
	s_cbranch_scc0 .LBB0_2547

.Lpeel_0:
	v_add_u32_e32 v250, 0x18000, v168
	ds_read_b128 v[144:147], v170
	ds_read_b128 v[148:151], v170 offset:1024
	ds_read_b128 v[152:155], v170 offset:2048
	ds_read_b128 v[156:159], v170 offset:3072
	ds_read_b128 v[160:163], v171
	ds_read_b128 v[164:167], v171 offset:1024
	ds_read_b128 v[174:177], v171 offset:2048
	ds_read_b128 v[178:181], v171 offset:3072
	s_add_i32 s30, s26, 2
	s_add_u32 s27, s24, 0xffea0080
	s_addc_u32 s28, s25, -1
	s_cmp_eq_u32 s22, s26
	s_cselect_b32 s26, s20, s17
	s_cselect_b32 s29, s19, s28
	s_cselect_b32 s28, s18, s27
	s_cselect_b32 s27, s21, s23
	v_lshl_add_u64 v[214:215], s[24:25], 0, v[140:141]
	s_add_i32 m0, s34, 0xc000
	ds_read_b128 v[182:185], v172
	ds_read_b128 v[186:189], v172 offset:1024
	ds_read_b128 v[190:193], v172 offset:2048
	ds_read_b128 v[194:197], v172 offset:3072
	ds_read_b128 v[198:201], v172 offset:4096
	ds_read_b128 v[202:205], v172 offset:5120
	ds_read_b128 v[206:209], v172 offset:6144
	ds_read_b128 v[210:213], v172 offset:7168
	global_load_lds_dwordx4 v[214:215], off
	v_lshl_add_u64 v[214:215], s[24:25], 0, v[142:143]
	s_add_i32 m0, s34, 0xe000
	s_nop 0
	global_load_lds_dwordx4 v[214:215], off
	s_waitcnt vmcnt(8)
	s_waitcnt lgkmcnt(0)
	s_barrier
	s_setprio 1
	s_waitcnt lgkmcnt(0)
	v_mfma_f32_16x16x32_bf16 v[126:129], v[144:147], v[182:185], 0
	v_mfma_f32_16x16x32_bf16 v[122:125], v[152:155], v[182:185], 0
	v_mfma_f32_16x16x32_bf16 v[118:121], v[144:147], v[190:193], 0
	v_mfma_f32_16x16x32_bf16 v[110:113], v[152:155], v[190:193], 0
	v_mfma_f32_16x16x32_bf16 v[94:97], v[144:147], v[198:201], 0
	v_mfma_f32_16x16x32_bf16 v[90:93], v[152:155], v[198:201], 0
	v_mfma_f32_16x16x32_bf16 v[82:85], v[144:147], v[206:209], 0
	v_mfma_f32_16x16x32_bf16 v[74:77], v[152:155], v[206:209], 0
	v_mfma_f32_16x16x32_bf16 v[126:129], v[148:151], v[186:189], v[126:129]
	v_mfma_f32_16x16x32_bf16 v[122:125], v[156:159], v[186:189], v[122:125]
	v_mfma_f32_16x16x32_bf16 v[118:121], v[148:151], v[194:197], v[118:121]
	v_mfma_f32_16x16x32_bf16 v[110:113], v[156:159], v[194:197], v[110:113]
	v_mfma_f32_16x16x32_bf16 v[94:97], v[148:151], v[202:205], v[94:97]
	v_mfma_f32_16x16x32_bf16 v[90:93], v[156:159], v[202:205], v[90:93]
	v_mfma_f32_16x16x32_bf16 v[82:85], v[148:151], v[210:213], v[82:85]
	v_mfma_f32_16x16x32_bf16 v[74:77], v[156:159], v[210:213], v[74:77]
	v_mfma_f32_16x16x32_bf16 v[114:117], v[160:163], v[182:185], 0
	v_mfma_f32_16x16x32_bf16 v[106:109], v[174:177], v[182:185], 0
	v_mfma_f32_16x16x32_bf16 v[102:105], v[160:163], v[190:193], 0
	v_mfma_f32_16x16x32_bf16 v[98:101], v[174:177], v[190:193], 0
	v_mfma_f32_16x16x32_bf16 v[86:89], v[160:163], v[198:201], 0
	v_mfma_f32_16x16x32_bf16 v[78:81], v[174:177], v[198:201], 0
	v_mfma_f32_16x16x32_bf16 v[70:73], v[160:163], v[206:209], 0
	v_mfma_f32_16x16x32_bf16 v[66:69], v[174:177], v[206:209], 0
	v_mfma_f32_16x16x32_bf16 v[114:117], v[164:167], v[186:189], v[114:117]
	v_mfma_f32_16x16x32_bf16 v[106:109], v[178:181], v[186:189], v[106:109]
	v_mfma_f32_16x16x32_bf16 v[102:105], v[164:167], v[194:197], v[102:105]
	v_mfma_f32_16x16x32_bf16 v[98:101], v[178:181], v[194:197], v[98:101]
	v_mfma_f32_16x16x32_bf16 v[86:89], v[164:167], v[202:205], v[86:89]
	v_mfma_f32_16x16x32_bf16 v[78:81], v[178:181], v[202:205], v[78:81]
	v_mfma_f32_16x16x32_bf16 v[70:73], v[164:167], v[210:213], v[70:73]
	s_barrier
	v_mfma_f32_16x16x32_bf16 v[66:69], v[178:181], v[210:213], v[66:69]
	s_setprio 2
	s_add_i32 s31, s57, s33
	v_lshl_add_u64 v[214:215], s[26:27], 0, v[132:133]
	s_mov_b32 m0, s31
	ds_read_b128 v[182:185], v172 offset:16384
	ds_read_b128 v[186:189], v172 offset:17408
	ds_read_b128 v[190:193], v172 offset:18432
	ds_read_b128 v[194:197], v172 offset:19456
	ds_read_b128 v[198:201], v172 offset:20480
	ds_read_b128 v[202:205], v172 offset:21504
	ds_read_b128 v[206:209], v172 offset:22528
	ds_read_b128 v[210:213], v172 offset:23552
	global_load_lds_dwordx4 v[214:215], off
	s_add_i32 m0, s31, 0x2000
	s_add_u32 s68, s26, 0x160000
	v_lshl_add_u64 v[216:217], s[26:27], 0, v[136:137]
	s_addc_u32 s69, s27, 0
	s_add_i32 s31, s58, s33
	global_load_lds_dwordx4 v[216:217], off
	v_lshl_add_u64 v[218:219], s[68:69], 0, v[132:133]
	s_mov_b32 m0, s31
	v_lshl_add_u64 v[220:221], s[28:29], 0, v[134:135]
	global_load_lds_dwordx4 v[218:219], off
	v_lshl_add_u64 v[218:219], s[68:69], 0, v[136:137]
	s_add_i32 m0, s31, 0x2000
	s_nop 0
	global_load_lds_dwordx4 v[218:219], off
	v_lshl_add_u64 v[218:219], s[28:29], 0, v[130:131]
	s_mov_b32 m0, s34
	s_nop 0
	global_load_lds_dwordx4 v[218:219], off
	s_mov_b32 m0, s35
	s_nop 0
	global_load_lds_dwordx4 v[220:221], off
	s_waitcnt vmcnt(8)
	s_waitcnt lgkmcnt(0)
	s_barrier
	s_setprio 1
	s_waitcnt lgkmcnt(0)
	v_mfma_f32_16x16x32_bf16 v[62:65], v[144:147], v[182:185], 0
	v_mfma_f32_16x16x32_bf16 v[58:61], v[152:155], v[182:185], 0
	v_mfma_f32_16x16x32_bf16 v[50:53], v[144:147], v[190:193], 0
	v_mfma_f32_16x16x32_bf16 v[42:45], v[152:155], v[190:193], 0
	v_mfma_f32_16x16x32_bf16 v[30:33], v[144:147], v[198:201], 0
	v_mfma_f32_16x16x32_bf16 v[26:29], v[152:155], v[198:201], 0
	v_mfma_f32_16x16x32_bf16 v[18:21], v[144:147], v[206:209], 0
	v_mfma_f32_16x16x32_bf16 v[10:13], v[152:155], v[206:209], 0
	v_mfma_f32_16x16x32_bf16 v[62:65], v[148:151], v[186:189], v[62:65]
	v_mfma_f32_16x16x32_bf16 v[58:61], v[156:159], v[186:189], v[58:61]
	v_mfma_f32_16x16x32_bf16 v[50:53], v[148:151], v[194:197], v[50:53]
	v_mfma_f32_16x16x32_bf16 v[42:45], v[156:159], v[194:197], v[42:45]
	v_mfma_f32_16x16x32_bf16 v[30:33], v[148:151], v[202:205], v[30:33]
	v_mfma_f32_16x16x32_bf16 v[26:29], v[156:159], v[202:205], v[26:29]
	v_mfma_f32_16x16x32_bf16 v[18:21], v[148:151], v[210:213], v[18:21]
	v_mfma_f32_16x16x32_bf16 v[10:13], v[156:159], v[210:213], v[10:13]
	v_mfma_f32_16x16x32_bf16 v[54:57], v[160:163], v[182:185], 0
	v_mfma_f32_16x16x32_bf16 v[46:49], v[174:177], v[182:185], 0
	v_mfma_f32_16x16x32_bf16 v[38:41], v[160:163], v[190:193], 0
	v_mfma_f32_16x16x32_bf16 v[34:37], v[174:177], v[190:193], 0
	v_mfma_f32_16x16x32_bf16 v[22:25], v[160:163], v[198:201], 0
	v_mfma_f32_16x16x32_bf16 v[14:17], v[174:177], v[198:201], 0
	v_mfma_f32_16x16x32_bf16 v[6:9], v[160:163], v[206:209], 0
	v_mfma_f32_16x16x32_bf16 v[2:5], v[174:177], v[206:209], 0
	v_mfma_f32_16x16x32_bf16 v[54:57], v[164:167], v[186:189], v[54:57]
	v_mfma_f32_16x16x32_bf16 v[46:49], v[178:181], v[186:189], v[46:49]
	v_mfma_f32_16x16x32_bf16 v[38:41], v[164:167], v[194:197], v[38:41]
	v_mfma_f32_16x16x32_bf16 v[34:37], v[178:181], v[194:197], v[34:37]
	v_mfma_f32_16x16x32_bf16 v[22:25], v[164:167], v[202:205], v[22:25]
	v_mfma_f32_16x16x32_bf16 v[14:17], v[178:181], v[202:205], v[14:17]
	v_mfma_f32_16x16x32_bf16 v[6:9], v[164:167], v[210:213], v[6:9]
	s_barrier
	v_mfma_f32_16x16x32_bf16 v[2:5], v[178:181], v[210:213], v[2:5]
	s_setprio 2
	s_add_i32 s31, 0, 0x18000
	s_add_i32 s68, 0, 0x1c000
	ds_read_b128 v[144:147], v250
	ds_read_b128 v[148:151], v250 offset:1024
	ds_read_b128 v[152:155], v250 offset:2048
	ds_read_b128 v[156:159], v250 offset:3072
	ds_read_b128 v[160:163], v250 offset:16384
	ds_read_b128 v[164:167], v250 offset:17408
	ds_read_b128 v[174:177], v250 offset:18432
	ds_read_b128 v[178:181], v250 offset:19456
	v_add_u32_e32 v173, s68, v168
	s_add_u32 s28, s28, 0x160000
	s_addc_u32 s29, s29, 0
	s_mov_b32 m0, s36
	v_lshl_add_u64 v[222:223], s[28:29], 0, v[130:131]
	ds_read_b128 v[182:185], v172 offset:32768
	ds_read_b128 v[186:189], v172 offset:33792
	ds_read_b128 v[190:193], v172 offset:34816
	ds_read_b128 v[194:197], v172 offset:35840
	ds_read_b128 v[198:201], v172 offset:36864
	ds_read_b128 v[202:205], v172 offset:37888
	ds_read_b128 v[206:209], v172 offset:38912
	ds_read_b128 v[210:213], v172 offset:39936
	global_load_lds_dwordx4 v[222:223], off
	v_lshl_add_u64 v[222:223], s[28:29], 0, v[134:135]
	s_mov_b32 m0, s37
	s_nop 0
	global_load_lds_dwordx4 v[222:223], off
	s_waitcnt vmcnt(8)
	s_waitcnt lgkmcnt(0)
	s_barrier
	s_setprio 1
	s_waitcnt lgkmcnt(0)
	v_mfma_f32_16x16x32_bf16 v[126:129], v[144:147], v[182:185], v[126:129]
	v_mfma_f32_16x16x32_bf16 v[122:125], v[152:155], v[182:185], v[122:125]
	v_mfma_f32_16x16x32_bf16 v[118:121], v[144:147], v[190:193], v[118:121]
	v_mfma_f32_16x16x32_bf16 v[110:113], v[152:155], v[190:193], v[110:113]
	v_mfma_f32_16x16x32_bf16 v[94:97], v[144:147], v[198:201], v[94:97]
	v_mfma_f32_16x16x32_bf16 v[90:93], v[152:155], v[198:201], v[90:93]
	v_mfma_f32_16x16x32_bf16 v[82:85], v[144:147], v[206:209], v[82:85]
	v_mfma_f32_16x16x32_bf16 v[74:77], v[152:155], v[206:209], v[74:77]
	v_mfma_f32_16x16x32_bf16 v[126:129], v[148:151], v[186:189], v[126:129]
	v_mfma_f32_16x16x32_bf16 v[122:125], v[156:159], v[186:189], v[122:125]
	v_mfma_f32_16x16x32_bf16 v[118:121], v[148:151], v[194:197], v[118:121]
	v_mfma_f32_16x16x32_bf16 v[110:113], v[156:159], v[194:197], v[110:113]
	v_mfma_f32_16x16x32_bf16 v[94:97], v[148:151], v[202:205], v[94:97]
	v_mfma_f32_16x16x32_bf16 v[90:93], v[156:159], v[202:205], v[90:93]
	v_mfma_f32_16x16x32_bf16 v[82:85], v[148:151], v[210:213], v[82:85]
	v_mfma_f32_16x16x32_bf16 v[74:77], v[156:159], v[210:213], v[74:77]
	v_mfma_f32_16x16x32_bf16 v[114:117], v[160:163], v[182:185], v[114:117]
	v_mfma_f32_16x16x32_bf16 v[106:109], v[174:177], v[182:185], v[106:109]
	v_mfma_f32_16x16x32_bf16 v[102:105], v[160:163], v[190:193], v[102:105]
	v_mfma_f32_16x16x32_bf16 v[98:101], v[174:177], v[190:193], v[98:101]
	v_mfma_f32_16x16x32_bf16 v[86:89], v[160:163], v[198:201], v[86:89]
	v_mfma_f32_16x16x32_bf16 v[78:81], v[174:177], v[198:201], v[78:81]
	v_mfma_f32_16x16x32_bf16 v[70:73], v[160:163], v[206:209], v[70:73]
	v_mfma_f32_16x16x32_bf16 v[66:69], v[174:177], v[206:209], v[66:69]
	v_mfma_f32_16x16x32_bf16 v[114:117], v[164:167], v[186:189], v[114:117]
	v_mfma_f32_16x16x32_bf16 v[106:109], v[178:181], v[186:189], v[106:109]
	v_mfma_f32_16x16x32_bf16 v[102:105], v[164:167], v[194:197], v[102:105]
	v_mfma_f32_16x16x32_bf16 v[98:101], v[178:181], v[194:197], v[98:101]
	v_mfma_f32_16x16x32_bf16 v[86:89], v[164:167], v[202:205], v[86:89]
	v_mfma_f32_16x16x32_bf16 v[78:81], v[178:181], v[202:205], v[78:81]
	v_mfma_f32_16x16x32_bf16 v[70:73], v[164:167], v[210:213], v[70:73]
	s_barrier
	v_mfma_f32_16x16x32_bf16 v[66:69], v[178:181], v[210:213], v[66:69]
	s_setprio 2
	s_add_i32 s28, s31, s33
	v_lshl_add_u64 v[214:215], v[214:215], 0, s[12:13]
	s_mov_b32 m0, s28
	ds_read_b128 v[182:185], v172 offset:49152
	ds_read_b128 v[186:189], v172 offset:50176
	ds_read_b128 v[190:193], v172 offset:51200
	ds_read_b128 v[194:197], v172 offset:52224
	ds_read_b128 v[198:201], v172 offset:53248
	ds_read_b128 v[202:205], v172 offset:54272
	ds_read_b128 v[206:209], v172 offset:55296
	ds_read_b128 v[210:213], v172 offset:56320
	global_load_lds_dwordx4 v[214:215], off
	s_add_i32 m0, s28, 0x2000
	s_add_u32 s26, s26, 0x160080
	v_lshl_add_u64 v[214:215], v[216:217], 0, s[12:13]
	s_addc_u32 s27, s27, 0
	s_add_i32 s28, s68, s33
	global_load_lds_dwordx4 v[214:215], off
	v_lshl_add_u64 v[214:215], s[26:27], 0, v[132:133]
	s_mov_b32 m0, s28
	s_nop 0
	global_load_lds_dwordx4 v[214:215], off
	v_lshl_add_u64 v[214:215], s[26:27], 0, v[136:137]
	s_add_i32 m0, s28, 0x2000
	s_nop 0
	global_load_lds_dwordx4 v[214:215], off
	v_lshl_add_u64 v[214:215], v[218:219], 0, s[12:13]
	s_mov_b32 m0, s47
	s_nop 0
	global_load_lds_dwordx4 v[214:215], off
	v_lshl_add_u64 v[214:215], v[220:221], 0, s[12:13]
	s_mov_b32 m0, s48
	s_nop 0
	global_load_lds_dwordx4 v[214:215], off
	s_waitcnt vmcnt(8)
	s_waitcnt lgkmcnt(0)
	s_barrier
	s_setprio 1
	s_waitcnt lgkmcnt(0)
	v_mfma_f32_16x16x32_bf16 v[62:65], v[144:147], v[182:185], v[62:65]
	v_mfma_f32_16x16x32_bf16 v[58:61], v[152:155], v[182:185], v[58:61]
	v_mfma_f32_16x16x32_bf16 v[50:53], v[144:147], v[190:193], v[50:53]
	v_mfma_f32_16x16x32_bf16 v[42:45], v[152:155], v[190:193], v[42:45]
	v_mfma_f32_16x16x32_bf16 v[30:33], v[144:147], v[198:201], v[30:33]
	v_mfma_f32_16x16x32_bf16 v[26:29], v[152:155], v[198:201], v[26:29]
	v_mfma_f32_16x16x32_bf16 v[18:21], v[144:147], v[206:209], v[18:21]
	v_mfma_f32_16x16x32_bf16 v[10:13], v[152:155], v[206:209], v[10:13]
	v_mfma_f32_16x16x32_bf16 v[62:65], v[148:151], v[186:189], v[62:65]
	v_mfma_f32_16x16x32_bf16 v[58:61], v[156:159], v[186:189], v[58:61]
	v_mfma_f32_16x16x32_bf16 v[50:53], v[148:151], v[194:197], v[50:53]
	v_mfma_f32_16x16x32_bf16 v[42:45], v[156:159], v[194:197], v[42:45]
	v_mfma_f32_16x16x32_bf16 v[30:33], v[148:151], v[202:205], v[30:33]
	v_mfma_f32_16x16x32_bf16 v[26:29], v[156:159], v[202:205], v[26:29]
	v_mfma_f32_16x16x32_bf16 v[18:21], v[148:151], v[210:213], v[18:21]
	v_mfma_f32_16x16x32_bf16 v[10:13], v[156:159], v[210:213], v[10:13]
	v_mfma_f32_16x16x32_bf16 v[54:57], v[160:163], v[182:185], v[54:57]
	v_mfma_f32_16x16x32_bf16 v[46:49], v[174:177], v[182:185], v[46:49]
	v_mfma_f32_16x16x32_bf16 v[38:41], v[160:163], v[190:193], v[38:41]
	v_mfma_f32_16x16x32_bf16 v[34:37], v[174:177], v[190:193], v[34:37]
	v_mfma_f32_16x16x32_bf16 v[22:25], v[160:163], v[198:201], v[22:25]
	v_mfma_f32_16x16x32_bf16 v[14:17], v[174:177], v[198:201], v[14:17]
	v_mfma_f32_16x16x32_bf16 v[6:9], v[160:163], v[206:209], v[6:9]
	v_mfma_f32_16x16x32_bf16 v[2:5], v[174:177], v[206:209], v[2:5]
	v_mfma_f32_16x16x32_bf16 v[54:57], v[164:167], v[186:189], v[54:57]
	v_mfma_f32_16x16x32_bf16 v[46:49], v[178:181], v[186:189], v[46:49]
	v_mfma_f32_16x16x32_bf16 v[38:41], v[164:167], v[194:197], v[38:41]
	v_mfma_f32_16x16x32_bf16 v[34:37], v[178:181], v[194:197], v[34:37]
	v_mfma_f32_16x16x32_bf16 v[22:25], v[164:167], v[202:205], v[22:25]
	v_mfma_f32_16x16x32_bf16 v[14:17], v[178:181], v[202:205], v[14:17]
	v_mfma_f32_16x16x32_bf16 v[6:9], v[164:167], v[210:213], v[6:9]
	s_barrier
	v_mfma_f32_16x16x32_bf16 v[2:5], v[178:181], v[210:213], v[2:5]
	s_setprio 2
	s_add_u32 s24, s24, 0x100
	s_addc_u32 s25, s25, 0
	s_add_u32 s17, s17, 0x100
	s_addc_u32 s23, s23, 0
	s_cmp_ge_i32 s30, s67
	s_mov_b32 s26, s30
	s_cbranch_scc0 .LBB0_2683
	s_branch .Lpeeldone_0
.LBB0_2683:
	ds_read_b128 v[144:147], v170
	ds_read_b128 v[148:151], v170 offset:1024
	ds_read_b128 v[152:155], v170 offset:2048
	ds_read_b128 v[156:159], v170 offset:3072
	ds_read_b128 v[160:163], v171
	ds_read_b128 v[164:167], v171 offset:1024
	ds_read_b128 v[174:177], v171 offset:2048
	ds_read_b128 v[178:181], v171 offset:3072
	s_add_i32 s30, s26, 2
	s_add_u32 s27, s24, 0xffea0080
	s_addc_u32 s28, s25, -1
	s_cmp_eq_u32 s22, s26
	s_cselect_b32 s26, s20, s17
	s_cselect_b32 s29, s19, s28
	s_cselect_b32 s28, s18, s27
	s_cselect_b32 s27, s21, s23
	v_lshl_add_u64 v[214:215], s[24:25], 0, v[140:141]
	s_add_i32 m0, s34, 0xc000
	ds_read_b128 v[182:185], v172
	ds_read_b128 v[186:189], v172 offset:1024
	ds_read_b128 v[190:193], v172 offset:2048
	ds_read_b128 v[194:197], v172 offset:3072
	ds_read_b128 v[198:201], v172 offset:4096
	ds_read_b128 v[202:205], v172 offset:5120
	ds_read_b128 v[206:209], v172 offset:6144
	ds_read_b128 v[210:213], v172 offset:7168
	global_load_lds_dwordx4 v[214:215], off
	v_lshl_add_u64 v[214:215], s[24:25], 0, v[142:143]
	s_add_i32 m0, s34, 0xe000
	s_nop 0
	global_load_lds_dwordx4 v[214:215], off
	s_waitcnt vmcnt(8)
	s_waitcnt lgkmcnt(0)
	s_barrier
	s_setprio 1
	s_waitcnt lgkmcnt(0)
	v_mfma_f32_16x16x32_bf16 v[126:129], v[144:147], v[182:185], v[126:129]
	v_mfma_f32_16x16x32_bf16 v[122:125], v[152:155], v[182:185], v[122:125]
	v_mfma_f32_16x16x32_bf16 v[118:121], v[144:147], v[190:193], v[118:121]
	v_mfma_f32_16x16x32_bf16 v[110:113], v[152:155], v[190:193], v[110:113]
	v_mfma_f32_16x16x32_bf16 v[94:97], v[144:147], v[198:201], v[94:97]
	v_mfma_f32_16x16x32_bf16 v[90:93], v[152:155], v[198:201], v[90:93]
	v_mfma_f32_16x16x32_bf16 v[82:85], v[144:147], v[206:209], v[82:85]
	v_mfma_f32_16x16x32_bf16 v[74:77], v[152:155], v[206:209], v[74:77]
	v_mfma_f32_16x16x32_bf16 v[126:129], v[148:151], v[186:189], v[126:129]
	v_mfma_f32_16x16x32_bf16 v[122:125], v[156:159], v[186:189], v[122:125]
	v_mfma_f32_16x16x32_bf16 v[118:121], v[148:151], v[194:197], v[118:121]
	v_mfma_f32_16x16x32_bf16 v[110:113], v[156:159], v[194:197], v[110:113]
	v_mfma_f32_16x16x32_bf16 v[94:97], v[148:151], v[202:205], v[94:97]
	v_mfma_f32_16x16x32_bf16 v[90:93], v[156:159], v[202:205], v[90:93]
	v_mfma_f32_16x16x32_bf16 v[82:85], v[148:151], v[210:213], v[82:85]
	v_mfma_f32_16x16x32_bf16 v[74:77], v[156:159], v[210:213], v[74:77]
	v_mfma_f32_16x16x32_bf16 v[114:117], v[160:163], v[182:185], v[114:117]
	v_mfma_f32_16x16x32_bf16 v[106:109], v[174:177], v[182:185], v[106:109]
	v_mfma_f32_16x16x32_bf16 v[102:105], v[160:163], v[190:193], v[102:105]
	v_mfma_f32_16x16x32_bf16 v[98:101], v[174:177], v[190:193], v[98:101]
	v_mfma_f32_16x16x32_bf16 v[86:89], v[160:163], v[198:201], v[86:89]
	v_mfma_f32_16x16x32_bf16 v[78:81], v[174:177], v[198:201], v[78:81]
	v_mfma_f32_16x16x32_bf16 v[70:73], v[160:163], v[206:209], v[70:73]
	v_mfma_f32_16x16x32_bf16 v[66:69], v[174:177], v[206:209], v[66:69]
	v_mfma_f32_16x16x32_bf16 v[114:117], v[164:167], v[186:189], v[114:117]
	v_mfma_f32_16x16x32_bf16 v[106:109], v[178:181], v[186:189], v[106:109]
	v_mfma_f32_16x16x32_bf16 v[102:105], v[164:167], v[194:197], v[102:105]
	v_mfma_f32_16x16x32_bf16 v[98:101], v[178:181], v[194:197], v[98:101]
	v_mfma_f32_16x16x32_bf16 v[86:89], v[164:167], v[202:205], v[86:89]
	v_mfma_f32_16x16x32_bf16 v[78:81], v[178:181], v[202:205], v[78:81]
	v_mfma_f32_16x16x32_bf16 v[70:73], v[164:167], v[210:213], v[70:73]
	s_barrier
	v_mfma_f32_16x16x32_bf16 v[66:69], v[178:181], v[210:213], v[66:69]
	s_setprio 2
	s_add_i32 s31, s57, s33
	v_lshl_add_u64 v[214:215], s[26:27], 0, v[132:133]
	s_mov_b32 m0, s31
	ds_read_b128 v[182:185], v172 offset:16384
	ds_read_b128 v[186:189], v172 offset:17408
	ds_read_b128 v[190:193], v172 offset:18432
	ds_read_b128 v[194:197], v172 offset:19456
	ds_read_b128 v[198:201], v172 offset:20480
	ds_read_b128 v[202:205], v172 offset:21504
	ds_read_b128 v[206:209], v172 offset:22528
	ds_read_b128 v[210:213], v172 offset:23552
	global_load_lds_dwordx4 v[214:215], off
	s_add_i32 m0, s31, 0x2000
	s_add_u32 s68, s26, 0x160000
	v_lshl_add_u64 v[216:217], s[26:27], 0, v[136:137]
	s_addc_u32 s69, s27, 0
	s_add_i32 s31, s58, s33
	global_load_lds_dwordx4 v[216:217], off
	v_lshl_add_u64 v[218:219], s[68:69], 0, v[132:133]
	s_mov_b32 m0, s31
	v_lshl_add_u64 v[220:221], s[28:29], 0, v[134:135]
	global_load_lds_dwordx4 v[218:219], off
	v_lshl_add_u64 v[218:219], s[68:69], 0, v[136:137]
	s_add_i32 m0, s31, 0x2000
	s_nop 0
	global_load_lds_dwordx4 v[218:219], off
	v_lshl_add_u64 v[218:219], s[28:29], 0, v[130:131]
	s_mov_b32 m0, s34
	s_nop 0
	global_load_lds_dwordx4 v[218:219], off
	s_mov_b32 m0, s35
	s_nop 0
	global_load_lds_dwordx4 v[220:221], off
	s_waitcnt vmcnt(8)
	s_waitcnt lgkmcnt(0)
	s_barrier
	s_setprio 1
	s_waitcnt lgkmcnt(0)
	v_mfma_f32_16x16x32_bf16 v[62:65], v[144:147], v[182:185], v[62:65]
	v_mfma_f32_16x16x32_bf16 v[58:61], v[152:155], v[182:185], v[58:61]
	v_mfma_f32_16x16x32_bf16 v[50:53], v[144:147], v[190:193], v[50:53]
	v_mfma_f32_16x16x32_bf16 v[42:45], v[152:155], v[190:193], v[42:45]
	v_mfma_f32_16x16x32_bf16 v[30:33], v[144:147], v[198:201], v[30:33]
	v_mfma_f32_16x16x32_bf16 v[26:29], v[152:155], v[198:201], v[26:29]
	v_mfma_f32_16x16x32_bf16 v[18:21], v[144:147], v[206:209], v[18:21]
	v_mfma_f32_16x16x32_bf16 v[10:13], v[152:155], v[206:209], v[10:13]
	v_mfma_f32_16x16x32_bf16 v[62:65], v[148:151], v[186:189], v[62:65]
	v_mfma_f32_16x16x32_bf16 v[58:61], v[156:159], v[186:189], v[58:61]
	v_mfma_f32_16x16x32_bf16 v[50:53], v[148:151], v[194:197], v[50:53]
	v_mfma_f32_16x16x32_bf16 v[42:45], v[156:159], v[194:197], v[42:45]
	v_mfma_f32_16x16x32_bf16 v[30:33], v[148:151], v[202:205], v[30:33]
	v_mfma_f32_16x16x32_bf16 v[26:29], v[156:159], v[202:205], v[26:29]
	v_mfma_f32_16x16x32_bf16 v[18:21], v[148:151], v[210:213], v[18:21]
	v_mfma_f32_16x16x32_bf16 v[10:13], v[156:159], v[210:213], v[10:13]
	v_mfma_f32_16x16x32_bf16 v[54:57], v[160:163], v[182:185], v[54:57]
	v_mfma_f32_16x16x32_bf16 v[46:49], v[174:177], v[182:185], v[46:49]
	v_mfma_f32_16x16x32_bf16 v[38:41], v[160:163], v[190:193], v[38:41]
	v_mfma_f32_16x16x32_bf16 v[34:37], v[174:177], v[190:193], v[34:37]
	v_mfma_f32_16x16x32_bf16 v[22:25], v[160:163], v[198:201], v[22:25]
	v_mfma_f32_16x16x32_bf16 v[14:17], v[174:177], v[198:201], v[14:17]
	v_mfma_f32_16x16x32_bf16 v[6:9], v[160:163], v[206:209], v[6:9]
	v_mfma_f32_16x16x32_bf16 v[2:5], v[174:177], v[206:209], v[2:5]
	v_mfma_f32_16x16x32_bf16 v[54:57], v[164:167], v[186:189], v[54:57]
	v_mfma_f32_16x16x32_bf16 v[46:49], v[178:181], v[186:189], v[46:49]
	v_mfma_f32_16x16x32_bf16 v[38:41], v[164:167], v[194:197], v[38:41]
	v_mfma_f32_16x16x32_bf16 v[34:37], v[178:181], v[194:197], v[34:37]
	v_mfma_f32_16x16x32_bf16 v[22:25], v[164:167], v[202:205], v[22:25]
	v_mfma_f32_16x16x32_bf16 v[14:17], v[178:181], v[202:205], v[14:17]
	v_mfma_f32_16x16x32_bf16 v[6:9], v[164:167], v[210:213], v[6:9]
	s_barrier
	v_mfma_f32_16x16x32_bf16 v[2:5], v[178:181], v[210:213], v[2:5]
	s_setprio 2
	s_add_i32 s31, 0, 0x18000
	s_add_i32 s68, 0, 0x1c000
	ds_read_b128 v[144:147], v250
	ds_read_b128 v[148:151], v250 offset:1024
	ds_read_b128 v[152:155], v250 offset:2048
	ds_read_b128 v[156:159], v250 offset:3072
	ds_read_b128 v[160:163], v250 offset:16384
	ds_read_b128 v[164:167], v250 offset:17408
	ds_read_b128 v[174:177], v250 offset:18432
	ds_read_b128 v[178:181], v250 offset:19456
	v_add_u32_e32 v173, s68, v168
	s_add_u32 s28, s28, 0x160000
	s_addc_u32 s29, s29, 0
	s_mov_b32 m0, s36
	v_lshl_add_u64 v[222:223], s[28:29], 0, v[130:131]
	ds_read_b128 v[182:185], v172 offset:32768
	ds_read_b128 v[186:189], v172 offset:33792
	ds_read_b128 v[190:193], v172 offset:34816
	ds_read_b128 v[194:197], v172 offset:35840
	ds_read_b128 v[198:201], v172 offset:36864
	ds_read_b128 v[202:205], v172 offset:37888
	ds_read_b128 v[206:209], v172 offset:38912
	ds_read_b128 v[210:213], v172 offset:39936
	global_load_lds_dwordx4 v[222:223], off
	v_lshl_add_u64 v[222:223], s[28:29], 0, v[134:135]
	s_mov_b32 m0, s37
	s_nop 0
	global_load_lds_dwordx4 v[222:223], off
	s_waitcnt vmcnt(8)
	s_waitcnt lgkmcnt(0)
	s_barrier
	s_setprio 1
	s_waitcnt lgkmcnt(0)
	v_mfma_f32_16x16x32_bf16 v[126:129], v[144:147], v[182:185], v[126:129]
	v_mfma_f32_16x16x32_bf16 v[122:125], v[152:155], v[182:185], v[122:125]
	v_mfma_f32_16x16x32_bf16 v[118:121], v[144:147], v[190:193], v[118:121]
	v_mfma_f32_16x16x32_bf16 v[110:113], v[152:155], v[190:193], v[110:113]
	v_mfma_f32_16x16x32_bf16 v[94:97], v[144:147], v[198:201], v[94:97]
	v_mfma_f32_16x16x32_bf16 v[90:93], v[152:155], v[198:201], v[90:93]
	v_mfma_f32_16x16x32_bf16 v[82:85], v[144:147], v[206:209], v[82:85]
	v_mfma_f32_16x16x32_bf16 v[74:77], v[152:155], v[206:209], v[74:77]
	v_mfma_f32_16x16x32_bf16 v[126:129], v[148:151], v[186:189], v[126:129]
	v_mfma_f32_16x16x32_bf16 v[122:125], v[156:159], v[186:189], v[122:125]
	v_mfma_f32_16x16x32_bf16 v[118:121], v[148:151], v[194:197], v[118:121]
	v_mfma_f32_16x16x32_bf16 v[110:113], v[156:159], v[194:197], v[110:113]
	v_mfma_f32_16x16x32_bf16 v[94:97], v[148:151], v[202:205], v[94:97]
	v_mfma_f32_16x16x32_bf16 v[90:93], v[156:159], v[202:205], v[90:93]
	v_mfma_f32_16x16x32_bf16 v[82:85], v[148:151], v[210:213], v[82:85]
	v_mfma_f32_16x16x32_bf16 v[74:77], v[156:159], v[210:213], v[74:77]
	v_mfma_f32_16x16x32_bf16 v[114:117], v[160:163], v[182:185], v[114:117]
	v_mfma_f32_16x16x32_bf16 v[106:109], v[174:177], v[182:185], v[106:109]
	v_mfma_f32_16x16x32_bf16 v[102:105], v[160:163], v[190:193], v[102:105]
	v_mfma_f32_16x16x32_bf16 v[98:101], v[174:177], v[190:193], v[98:101]
	v_mfma_f32_16x16x32_bf16 v[86:89], v[160:163], v[198:201], v[86:89]
	v_mfma_f32_16x16x32_bf16 v[78:81], v[174:177], v[198:201], v[78:81]
	v_mfma_f32_16x16x32_bf16 v[70:73], v[160:163], v[206:209], v[70:73]
	v_mfma_f32_16x16x32_bf16 v[66:69], v[174:177], v[206:209], v[66:69]
	v_mfma_f32_16x16x32_bf16 v[114:117], v[164:167], v[186:189], v[114:117]
	v_mfma_f32_16x16x32_bf16 v[106:109], v[178:181], v[186:189], v[106:109]
	v_mfma_f32_16x16x32_bf16 v[102:105], v[164:167], v[194:197], v[102:105]
	v_mfma_f32_16x16x32_bf16 v[98:101], v[178:181], v[194:197], v[98:101]
	v_mfma_f32_16x16x32_bf16 v[86:89], v[164:167], v[202:205], v[86:89]
	v_mfma_f32_16x16x32_bf16 v[78:81], v[178:181], v[202:205], v[78:81]
	v_mfma_f32_16x16x32_bf16 v[70:73], v[164:167], v[210:213], v[70:73]
	s_barrier
	v_mfma_f32_16x16x32_bf16 v[66:69], v[178:181], v[210:213], v[66:69]
	s_setprio 2
	s_add_i32 s28, s31, s33
	v_lshl_add_u64 v[214:215], v[214:215], 0, s[12:13]
	s_mov_b32 m0, s28
	ds_read_b128 v[182:185], v172 offset:49152
	ds_read_b128 v[186:189], v172 offset:50176
	ds_read_b128 v[190:193], v172 offset:51200
	ds_read_b128 v[194:197], v172 offset:52224
	ds_read_b128 v[198:201], v172 offset:53248
	ds_read_b128 v[202:205], v172 offset:54272
	ds_read_b128 v[206:209], v172 offset:55296
	ds_read_b128 v[210:213], v172 offset:56320
	global_load_lds_dwordx4 v[214:215], off
	s_add_i32 m0, s28, 0x2000
	s_add_u32 s26, s26, 0x160080
	v_lshl_add_u64 v[214:215], v[216:217], 0, s[12:13]
	s_addc_u32 s27, s27, 0
	s_add_i32 s28, s68, s33
	global_load_lds_dwordx4 v[214:215], off
	v_lshl_add_u64 v[214:215], s[26:27], 0, v[132:133]
	s_mov_b32 m0, s28
	s_nop 0
	global_load_lds_dwordx4 v[214:215], off
	v_lshl_add_u64 v[214:215], s[26:27], 0, v[136:137]
	s_add_i32 m0, s28, 0x2000
	s_nop 0
	global_load_lds_dwordx4 v[214:215], off
	v_lshl_add_u64 v[214:215], v[218:219], 0, s[12:13]
	s_mov_b32 m0, s47
	s_nop 0
	global_load_lds_dwordx4 v[214:215], off
	v_lshl_add_u64 v[214:215], v[220:221], 0, s[12:13]
	s_mov_b32 m0, s48
	s_nop 0
	global_load_lds_dwordx4 v[214:215], off
	s_waitcnt vmcnt(8)
	s_waitcnt lgkmcnt(0)
	s_barrier
	s_setprio 1
	s_waitcnt lgkmcnt(0)
	v_mfma_f32_16x16x32_bf16 v[62:65], v[144:147], v[182:185], v[62:65]
	v_mfma_f32_16x16x32_bf16 v[58:61], v[152:155], v[182:185], v[58:61]
	v_mfma_f32_16x16x32_bf16 v[50:53], v[144:147], v[190:193], v[50:53]
	v_mfma_f32_16x16x32_bf16 v[42:45], v[152:155], v[190:193], v[42:45]
	v_mfma_f32_16x16x32_bf16 v[30:33], v[144:147], v[198:201], v[30:33]
	v_mfma_f32_16x16x32_bf16 v[26:29], v[152:155], v[198:201], v[26:29]
	v_mfma_f32_16x16x32_bf16 v[18:21], v[144:147], v[206:209], v[18:21]
	v_mfma_f32_16x16x32_bf16 v[10:13], v[152:155], v[206:209], v[10:13]
	v_mfma_f32_16x16x32_bf16 v[62:65], v[148:151], v[186:189], v[62:65]
	v_mfma_f32_16x16x32_bf16 v[58:61], v[156:159], v[186:189], v[58:61]
	v_mfma_f32_16x16x32_bf16 v[50:53], v[148:151], v[194:197], v[50:53]
	v_mfma_f32_16x16x32_bf16 v[42:45], v[156:159], v[194:197], v[42:45]
	v_mfma_f32_16x16x32_bf16 v[30:33], v[148:151], v[202:205], v[30:33]
	v_mfma_f32_16x16x32_bf16 v[26:29], v[156:159], v[202:205], v[26:29]
	v_mfma_f32_16x16x32_bf16 v[18:21], v[148:151], v[210:213], v[18:21]
	v_mfma_f32_16x16x32_bf16 v[10:13], v[156:159], v[210:213], v[10:13]
	v_mfma_f32_16x16x32_bf16 v[54:57], v[160:163], v[182:185], v[54:57]
	v_mfma_f32_16x16x32_bf16 v[46:49], v[174:177], v[182:185], v[46:49]
	v_mfma_f32_16x16x32_bf16 v[38:41], v[160:163], v[190:193], v[38:41]
	v_mfma_f32_16x16x32_bf16 v[34:37], v[174:177], v[190:193], v[34:37]
	v_mfma_f32_16x16x32_bf16 v[22:25], v[160:163], v[198:201], v[22:25]
	v_mfma_f32_16x16x32_bf16 v[14:17], v[174:177], v[198:201], v[14:17]
	v_mfma_f32_16x16x32_bf16 v[6:9], v[160:163], v[206:209], v[6:9]
	v_mfma_f32_16x16x32_bf16 v[2:5], v[174:177], v[206:209], v[2:5]
	v_mfma_f32_16x16x32_bf16 v[54:57], v[164:167], v[186:189], v[54:57]
	v_mfma_f32_16x16x32_bf16 v[46:49], v[178:181], v[186:189], v[46:49]
	v_mfma_f32_16x16x32_bf16 v[38:41], v[164:167], v[194:197], v[38:41]
	v_mfma_f32_16x16x32_bf16 v[34:37], v[178:181], v[194:197], v[34:37]
	v_mfma_f32_16x16x32_bf16 v[22:25], v[164:167], v[202:205], v[22:25]
	v_mfma_f32_16x16x32_bf16 v[14:17], v[178:181], v[202:205], v[14:17]
	v_mfma_f32_16x16x32_bf16 v[6:9], v[164:167], v[210:213], v[6:9]
	s_barrier
	v_mfma_f32_16x16x32_bf16 v[2:5], v[178:181], v[210:213], v[2:5]
	s_setprio 2
	s_add_u32 s24, s24, 0x100
	s_addc_u32 s25, s25, 0
	s_add_u32 s17, s17, 0x100
	s_addc_u32 s23, s23, 0
	s_cmp_ge_i32 s30, s67
	s_mov_b32 s26, s30
	s_cbranch_scc0 .LBB0_2683

	.amdhsa_kernel _Z10fwd_kernel4Args
		.amdhsa_group_segment_fixed_size 0
		.amdhsa_private_segment_fixed_size 0
		.amdhsa_kernarg_size 504
		.amdhsa_user_sgpr_count 2
		.amdhsa_user_sgpr_dispatch_ptr 0
		.amdhsa_user_sgpr_queue_ptr 0
		.amdhsa_user_sgpr_kernarg_segment_ptr 1
		.amdhsa_user_sgpr_dispatch_id 0
		.amdhsa_user_sgpr_kernarg_preload_length 0
		.amdhsa_user_sgpr_kernarg_preload_offset 0
		.amdhsa_user_sgpr_private_segment_size 0
		.amdhsa_uses_dynamic_stack 0
		.amdhsa_enable_private_segment 0
		.amdhsa_system_sgpr_workgroup_id_x 1
		.amdhsa_system_sgpr_workgroup_id_y 0
		.amdhsa_system_sgpr_workgroup_id_z 0
		.amdhsa_system_sgpr_workgroup_info 0
		.amdhsa_system_vgpr_workitem_id 0
		.amdhsa_next_free_vgpr 251
		.amdhsa_next_free_sgpr 102
		.amdhsa_accum_offset 252
		.amdhsa_reserve_vcc 1
		.amdhsa_float_round_mode_32 0
		.amdhsa_float_round_mode_16_64 0
		.amdhsa_float_denorm_mode_32 3
		.amdhsa_float_denorm_mode_16_64 3
		.amdhsa_dx10_clamp 1
		.amdhsa_ieee_mode 1
		.amdhsa_fp16_overflow 0
		.amdhsa_tg_split 0
		.amdhsa_exception_fp_ieee_invalid_op 0
		.amdhsa_exception_fp_denorm_src 0
		.amdhsa_exception_fp_ieee_div_zero 0
		.amdhsa_exception_fp_ieee_overflow 0
		.amdhsa_exception_fp_ieee_underflow 0
		.amdhsa_exception_fp_ieee_inexact 0
		.amdhsa_exception_int_div_zero 0
	.end_amdhsa_kernel

.Lfunc_end0:
	.size	_Z10fwd_kernel4Args, .Lfunc_end0-_Z10fwd_kernel4Args
	.set _Z10fwd_kernel4Args.num_vgpr, 251
	.set _Z10fwd_kernel4Args.num_agpr, 0
	.set _Z10fwd_kernel4Args.numbered_sgpr, 98
	.set _Z10fwd_kernel4Args.num_named_barrier, 0
	.set _Z10fwd_kernel4Args.private_seg_size, 0
	.set _Z10fwd_kernel4Args.uses_vcc, 1
	.set _Z10fwd_kernel4Args.uses_flat_scratch, 0
	.set _Z10fwd_kernel4Args.has_dyn_sized_stack, 0
	.set _Z10fwd_kernel4Args.has_recursion, 0
	.set _Z10fwd_kernel4Args.has_indirect_call, 0

amdhsa.kernels:
  - .agpr_count:     0
    .args:
      - .offset:         0
        .size:           248
        .value_kind:     by_value
      - .offset:         248
        .size:           4
        .value_kind:     hidden_block_count_x
      - .offset:         252
        .size:           4
        .value_kind:     hidden_block_count_y
      - .offset:         256
        .size:           4
        .value_kind:     hidden_block_count_z
      - .offset:         260
        .size:           2
        .value_kind:     hidden_group_size_x
      - .offset:         262
        .size:           2
        .value_kind:     hidden_group_size_y
      - .offset:         264
        .size:           2
        .value_kind:     hidden_group_size_z
      - .offset:         266
        .size:           2
        .value_kind:     hidden_remainder_x
      - .offset:         268
        .size:           2
        .value_kind:     hidden_remainder_y
      - .offset:         270
        .size:           2
        .value_kind:     hidden_remainder_z
      - .offset:         288
        .size:           8
        .value_kind:     hidden_global_offset_x
      - .offset:         296
        .size:           8
        .value_kind:     hidden_global_offset_y
      - .offset:         304
        .size:           8
        .value_kind:     hidden_global_offset_z
      - .offset:         312
        .size:           2
        .value_kind:     hidden_grid_dims
      - .offset:         368
        .size:           4
        .value_kind:     hidden_dynamic_lds_size
    .group_segment_fixed_size: 0
    .kernarg_segment_align: 8
    .kernarg_segment_size: 504
    .language:       OpenCL C
    .language_version:
      - 2
      - 0
    .max_flat_workgroup_size: 512
    .name:           _Z10fwd_kernel4Args
    .private_segment_fixed_size: 0
    .sgpr_count:     108
    .sgpr_spill_count: 138
    .symbol:         _Z10fwd_kernel4Args.kd
    .uniform_work_group_size: 1
    .uses_dynamic_stack: false
    .vgpr_count:     251
    .vgpr_spill_count: 0
    .wavefront_size: 64
